# K-loop load phases: fragment reads instead of s_nop as the m0 -> LDS-DMA wait state (12 nops per iteration removed)
# speedup vs baseline: 1.0016x; 1.0016x over previous
.Lmy_nb_0:
	s_nop 0
	v_readfirstlane_b32 s86, v152
	v_readfirstlane_b32 s87, v153
	v_readfirstlane_b32 s88, v150
	v_readfirstlane_b32 s89, v151
	v_readfirstlane_b32 s90, v146
	v_readfirstlane_b32 s91, v147
	v_readfirstlane_b32 s92, v148
	v_readfirstlane_b32 s93, v149
	v_readfirstlane_b32 s100, v154
	v_readfirstlane_b32 s101, v138
	v_add_u32_e32 v230, s76, v141
	v_add_u32_e32 v231, s77, v141
	v_add_u32_e32 v232, 0x18000, v141
	v_add_u32_e32 v233, 0x1c000, v141
	s_add_u32 s98, s86, 0xfffc0080
	s_addc_u32 s99, s87, -1
	s_cmp_eq_u32 s7, s100
	s_cselect_b64 s[94:95], s[90:91], s[98:99]
	s_cselect_b64 s[96:97], s[92:93], s[88:89]
	s_add_i32 s51, s7, 2
	s_mov_b32 m0, s78
	ds_read_b128 v[164:167], v230
	global_load_lds_dwordx4 v144, s[86:87]
	s_mov_b32 m0, s79
	ds_read_b128 v[168:171], v230 offset:1024
	global_load_lds_dwordx4 v142, s[86:87]
	ds_read_b128 v[172:175], v230 offset:2048
	ds_read_b128 v[176:179], v230 offset:3072
	ds_read_b128 v[180:183], v231
	ds_read_b128 v[184:187], v231 offset:1024
	ds_read_b128 v[188:191], v231 offset:2048
	ds_read_b128 v[192:195], v231 offset:3072
	ds_read_b128 v[196:199], v160
	ds_read_b128 v[200:203], v160 offset:1024
	ds_read_b128 v[204:207], v160 offset:2048
	ds_read_b128 v[208:211], v160 offset:3072
	ds_read_b128 v[212:215], v160 offset:4096
	ds_read_b128 v[216:219], v160 offset:5120
	ds_read_b128 v[220:223], v160 offset:6144
	ds_read_b128 v[224:227], v160 offset:7168
	s_waitcnt vmcnt(8)
	s_waitcnt lgkmcnt(0)
	s_setprio 1
	s_barrier
	v_mfma_f32_16x16x32_bf16 v[122:125], v[164:167], v[196:199], 0
	v_mfma_f32_16x16x32_bf16 v[118:121], v[172:175], v[196:199], 0
	v_mfma_f32_16x16x32_bf16 v[110:113], v[164:167], v[204:207], 0
	v_mfma_f32_16x16x32_bf16 v[102:105], v[172:175], v[204:207], 0
	v_mfma_f32_16x16x32_bf16 v[94:97], v[164:167], v[212:215], 0
	v_mfma_f32_16x16x32_bf16 v[86:89], v[172:175], v[212:215], 0
	v_mfma_f32_16x16x32_bf16 v[78:81], v[164:167], v[220:223], 0
	v_mfma_f32_16x16x32_bf16 v[70:73], v[172:175], v[220:223], 0
	v_mfma_f32_16x16x32_bf16 v[122:125], v[168:171], v[200:203], v[122:125]
	v_mfma_f32_16x16x32_bf16 v[118:121], v[176:179], v[200:203], v[118:121]
	v_mfma_f32_16x16x32_bf16 v[110:113], v[168:171], v[208:211], v[110:113]
	v_mfma_f32_16x16x32_bf16 v[102:105], v[176:179], v[208:211], v[102:105]
	v_mfma_f32_16x16x32_bf16 v[94:97], v[168:171], v[216:219], v[94:97]
	v_mfma_f32_16x16x32_bf16 v[86:89], v[176:179], v[216:219], v[86:89]
	v_mfma_f32_16x16x32_bf16 v[78:81], v[168:171], v[224:227], v[78:81]
	v_mfma_f32_16x16x32_bf16 v[70:73], v[176:179], v[224:227], v[70:73]
	s_setprio 0
	s_setprio 1
	v_mfma_f32_16x16x32_bf16 v[126:129], v[180:183], v[196:199], 0
	v_mfma_f32_16x16x32_bf16 v[114:117], v[188:191], v[196:199], 0
	v_mfma_f32_16x16x32_bf16 v[106:109], v[180:183], v[204:207], 0
	v_mfma_f32_16x16x32_bf16 v[98:101], v[188:191], v[204:207], 0
	v_mfma_f32_16x16x32_bf16 v[90:93], v[180:183], v[212:215], 0
	v_mfma_f32_16x16x32_bf16 v[82:85], v[188:191], v[212:215], 0
	v_mfma_f32_16x16x32_bf16 v[74:77], v[180:183], v[220:223], 0
	v_mfma_f32_16x16x32_bf16 v[66:69], v[188:191], v[220:223], 0
	v_mfma_f32_16x16x32_bf16 v[126:129], v[184:187], v[200:203], v[126:129]
	v_mfma_f32_16x16x32_bf16 v[114:117], v[192:195], v[200:203], v[114:117]
	v_mfma_f32_16x16x32_bf16 v[106:109], v[184:187], v[208:211], v[106:109]
	v_mfma_f32_16x16x32_bf16 v[98:101], v[192:195], v[208:211], v[98:101]
	v_mfma_f32_16x16x32_bf16 v[90:93], v[184:187], v[216:219], v[90:93]
	v_mfma_f32_16x16x32_bf16 v[82:85], v[192:195], v[216:219], v[82:85]
	v_mfma_f32_16x16x32_bf16 v[74:77], v[184:187], v[224:227], v[74:77]
	v_mfma_f32_16x16x32_bf16 v[66:69], v[192:195], v[224:227], v[66:69]
	s_barrier
	s_setprio 0
	s_add_u32 s98, s96, 0x40000
	s_addc_u32 s99, s97, 0
	s_mov_b32 m0, s80
	ds_read_b128 v[196:199], v160 offset:16384
	global_load_lds_dwordx4 v132, s[96:97]
	s_mov_b32 m0, s81
	s_add_i32 s7, s77, s47
	global_load_lds_dwordx4 v136, s[96:97]
	s_mov_b32 m0, s7
	ds_read_b128 v[200:203], v160 offset:17408
	global_load_lds_dwordx4 v132, s[98:99]
	s_add_i32 m0, s7, 0x2000
	ds_read_b128 v[204:207], v160 offset:18432
	global_load_lds_dwordx4 v136, s[98:99]
	s_mov_b32 m0, s57
	ds_read_b128 v[208:211], v160 offset:19456
	global_load_lds_dwordx4 v130, s[94:95]
	s_mov_b32 m0, s62
	ds_read_b128 v[212:215], v160 offset:20480
	global_load_lds_dwordx4 v134, s[94:95]
	ds_read_b128 v[216:219], v160 offset:21504
	ds_read_b128 v[220:223], v160 offset:22528
	ds_read_b128 v[224:227], v160 offset:23552
	s_waitcnt vmcnt(8)
	s_waitcnt lgkmcnt(0)
	s_setprio 1
	s_barrier
	v_mfma_f32_16x16x32_bf16 v[62:65], v[164:167], v[196:199], 0
	v_mfma_f32_16x16x32_bf16 v[54:57], v[172:175], v[196:199], 0
	v_mfma_f32_16x16x32_bf16 v[46:49], v[164:167], v[204:207], 0
	v_mfma_f32_16x16x32_bf16 v[38:41], v[172:175], v[204:207], 0
	v_mfma_f32_16x16x32_bf16 v[30:33], v[164:167], v[212:215], 0
	v_mfma_f32_16x16x32_bf16 v[22:25], v[172:175], v[212:215], 0
	v_mfma_f32_16x16x32_bf16 v[14:17], v[164:167], v[220:223], 0
	v_mfma_f32_16x16x32_bf16 v[6:9], v[172:175], v[220:223], 0
	v_mfma_f32_16x16x32_bf16 v[62:65], v[168:171], v[200:203], v[62:65]
	v_mfma_f32_16x16x32_bf16 v[54:57], v[176:179], v[200:203], v[54:57]
	v_mfma_f32_16x16x32_bf16 v[46:49], v[168:171], v[208:211], v[46:49]
	v_mfma_f32_16x16x32_bf16 v[38:41], v[176:179], v[208:211], v[38:41]
	v_mfma_f32_16x16x32_bf16 v[30:33], v[168:171], v[216:219], v[30:33]
	v_mfma_f32_16x16x32_bf16 v[22:25], v[176:179], v[216:219], v[22:25]
	v_mfma_f32_16x16x32_bf16 v[14:17], v[168:171], v[224:227], v[14:17]
	v_mfma_f32_16x16x32_bf16 v[6:9], v[176:179], v[224:227], v[6:9]
	s_setprio 0
	s_setprio 1
	v_mfma_f32_16x16x32_bf16 v[58:61], v[180:183], v[196:199], 0
	v_mfma_f32_16x16x32_bf16 v[50:53], v[188:191], v[196:199], 0
	v_mfma_f32_16x16x32_bf16 v[42:45], v[180:183], v[204:207], 0
	v_mfma_f32_16x16x32_bf16 v[34:37], v[188:191], v[204:207], 0
	v_mfma_f32_16x16x32_bf16 v[26:29], v[180:183], v[212:215], 0
	v_mfma_f32_16x16x32_bf16 v[18:21], v[188:191], v[212:215], 0
	v_mfma_f32_16x16x32_bf16 v[10:13], v[180:183], v[220:223], 0
	v_mfma_f32_16x16x32_bf16 v[2:5], v[188:191], v[220:223], 0
	v_mfma_f32_16x16x32_bf16 v[58:61], v[184:187], v[200:203], v[58:61]
	v_mfma_f32_16x16x32_bf16 v[50:53], v[192:195], v[200:203], v[50:53]
	v_mfma_f32_16x16x32_bf16 v[42:45], v[184:187], v[208:211], v[42:45]
	v_mfma_f32_16x16x32_bf16 v[34:37], v[192:195], v[208:211], v[34:37]
	v_mfma_f32_16x16x32_bf16 v[26:29], v[184:187], v[216:219], v[26:29]
	v_mfma_f32_16x16x32_bf16 v[18:21], v[192:195], v[216:219], v[18:21]
	v_mfma_f32_16x16x32_bf16 v[10:13], v[184:187], v[224:227], v[10:13]
	v_mfma_f32_16x16x32_bf16 v[2:5], v[192:195], v[224:227], v[2:5]
	s_barrier
	s_setprio 0
	s_add_u32 s98, s94, 0x40000
	s_addc_u32 s99, s95, 0
	s_add_i32 s7, 0, 0x18000
	s_add_i32 s55, 0, 0x1c000
	s_mov_b32 m0, s63
	ds_read_b128 v[164:167], v232
	global_load_lds_dwordx4 v130, s[98:99]
	s_mov_b32 m0, s64
	ds_read_b128 v[168:171], v232 offset:1024
	global_load_lds_dwordx4 v134, s[98:99]
	ds_read_b128 v[172:175], v232 offset:2048
	ds_read_b128 v[176:179], v232 offset:3072
	ds_read_b128 v[180:183], v233
	ds_read_b128 v[184:187], v233 offset:1024
	ds_read_b128 v[188:191], v233 offset:2048
	ds_read_b128 v[192:195], v233 offset:3072
	ds_read_b128 v[196:199], v160 offset:32768
	ds_read_b128 v[200:203], v160 offset:33792
	ds_read_b128 v[204:207], v160 offset:34816
	ds_read_b128 v[208:211], v160 offset:35840
	ds_read_b128 v[212:215], v160 offset:36864
	ds_read_b128 v[216:219], v160 offset:37888
	ds_read_b128 v[220:223], v160 offset:38912
	ds_read_b128 v[224:227], v160 offset:39936
	s_waitcnt vmcnt(8)
	s_waitcnt lgkmcnt(0)
	s_setprio 1
	s_barrier
	v_mfma_f32_16x16x32_bf16 v[122:125], v[164:167], v[196:199], v[122:125]
	v_mfma_f32_16x16x32_bf16 v[118:121], v[172:175], v[196:199], v[118:121]
	v_mfma_f32_16x16x32_bf16 v[110:113], v[164:167], v[204:207], v[110:113]
	v_mfma_f32_16x16x32_bf16 v[102:105], v[172:175], v[204:207], v[102:105]
	v_mfma_f32_16x16x32_bf16 v[94:97], v[164:167], v[212:215], v[94:97]
	v_mfma_f32_16x16x32_bf16 v[86:89], v[172:175], v[212:215], v[86:89]
	v_mfma_f32_16x16x32_bf16 v[78:81], v[164:167], v[220:223], v[78:81]
	v_mfma_f32_16x16x32_bf16 v[70:73], v[172:175], v[220:223], v[70:73]
	v_mfma_f32_16x16x32_bf16 v[122:125], v[168:171], v[200:203], v[122:125]
	v_mfma_f32_16x16x32_bf16 v[118:121], v[176:179], v[200:203], v[118:121]
	v_mfma_f32_16x16x32_bf16 v[110:113], v[168:171], v[208:211], v[110:113]
	v_mfma_f32_16x16x32_bf16 v[102:105], v[176:179], v[208:211], v[102:105]
	v_mfma_f32_16x16x32_bf16 v[94:97], v[168:171], v[216:219], v[94:97]
	v_mfma_f32_16x16x32_bf16 v[86:89], v[176:179], v[216:219], v[86:89]
	v_mfma_f32_16x16x32_bf16 v[78:81], v[168:171], v[224:227], v[78:81]
	v_mfma_f32_16x16x32_bf16 v[70:73], v[176:179], v[224:227], v[70:73]
	s_setprio 0
	s_setprio 1
	v_mfma_f32_16x16x32_bf16 v[126:129], v[180:183], v[196:199], v[126:129]
	v_mfma_f32_16x16x32_bf16 v[114:117], v[188:191], v[196:199], v[114:117]
	v_mfma_f32_16x16x32_bf16 v[106:109], v[180:183], v[204:207], v[106:109]
	v_mfma_f32_16x16x32_bf16 v[98:101], v[188:191], v[204:207], v[98:101]
	v_mfma_f32_16x16x32_bf16 v[90:93], v[180:183], v[212:215], v[90:93]
	v_mfma_f32_16x16x32_bf16 v[82:85], v[188:191], v[212:215], v[82:85]
	v_mfma_f32_16x16x32_bf16 v[74:77], v[180:183], v[220:223], v[74:77]
	v_mfma_f32_16x16x32_bf16 v[66:69], v[188:191], v[220:223], v[66:69]
	v_mfma_f32_16x16x32_bf16 v[126:129], v[184:187], v[200:203], v[126:129]
	v_mfma_f32_16x16x32_bf16 v[114:117], v[192:195], v[200:203], v[114:117]
	v_mfma_f32_16x16x32_bf16 v[106:109], v[184:187], v[208:211], v[106:109]
	v_mfma_f32_16x16x32_bf16 v[98:101], v[192:195], v[208:211], v[98:101]
	v_mfma_f32_16x16x32_bf16 v[90:93], v[184:187], v[216:219], v[90:93]
	v_mfma_f32_16x16x32_bf16 v[82:85], v[192:195], v[216:219], v[82:85]
	v_mfma_f32_16x16x32_bf16 v[74:77], v[184:187], v[224:227], v[74:77]
	v_mfma_f32_16x16x32_bf16 v[66:69], v[192:195], v[224:227], v[66:69]
	s_barrier
	s_setprio 0
	s_add_u32 s96, s96, 0x80
	s_addc_u32 s97, s97, 0
	s_add_u32 s98, s96, 0x40000
	s_addc_u32 s99, s97, 0
	s_add_u32 s94, s94, 0x80
	s_addc_u32 s95, s95, 0
	s_add_i32 s7, s7, s47
	s_mov_b32 m0, s7
	ds_read_b128 v[196:199], v160 offset:49152
	global_load_lds_dwordx4 v132, s[96:97]
	s_add_i32 m0, s7, 0x2000
	s_add_i32 s7, s55, s47
	global_load_lds_dwordx4 v136, s[96:97]
	s_mov_b32 m0, s7
	ds_read_b128 v[200:203], v160 offset:50176
	global_load_lds_dwordx4 v132, s[98:99]
	s_add_i32 m0, s7, 0x2000
	ds_read_b128 v[204:207], v160 offset:51200
	global_load_lds_dwordx4 v136, s[98:99]
	s_mov_b32 m0, s65
	ds_read_b128 v[208:211], v160 offset:52224
	global_load_lds_dwordx4 v130, s[94:95]
	s_mov_b32 m0, s66
	ds_read_b128 v[212:215], v160 offset:53248
	global_load_lds_dwordx4 v134, s[94:95]
	ds_read_b128 v[216:219], v160 offset:54272
	ds_read_b128 v[220:223], v160 offset:55296
	ds_read_b128 v[224:227], v160 offset:56320
	s_waitcnt vmcnt(8)
	s_waitcnt lgkmcnt(0)
	s_setprio 1
	s_barrier
	v_mfma_f32_16x16x32_bf16 v[62:65], v[164:167], v[196:199], v[62:65]
	v_mfma_f32_16x16x32_bf16 v[54:57], v[172:175], v[196:199], v[54:57]
	v_mfma_f32_16x16x32_bf16 v[46:49], v[164:167], v[204:207], v[46:49]
	v_mfma_f32_16x16x32_bf16 v[38:41], v[172:175], v[204:207], v[38:41]
	v_mfma_f32_16x16x32_bf16 v[30:33], v[164:167], v[212:215], v[30:33]
	v_mfma_f32_16x16x32_bf16 v[22:25], v[172:175], v[212:215], v[22:25]
	v_mfma_f32_16x16x32_bf16 v[14:17], v[164:167], v[220:223], v[14:17]
	v_mfma_f32_16x16x32_bf16 v[6:9], v[172:175], v[220:223], v[6:9]
	v_mfma_f32_16x16x32_bf16 v[62:65], v[168:171], v[200:203], v[62:65]
	v_mfma_f32_16x16x32_bf16 v[54:57], v[176:179], v[200:203], v[54:57]
	v_mfma_f32_16x16x32_bf16 v[46:49], v[168:171], v[208:211], v[46:49]
	v_mfma_f32_16x16x32_bf16 v[38:41], v[176:179], v[208:211], v[38:41]
	v_mfma_f32_16x16x32_bf16 v[30:33], v[168:171], v[216:219], v[30:33]
	v_mfma_f32_16x16x32_bf16 v[22:25], v[176:179], v[216:219], v[22:25]
	v_mfma_f32_16x16x32_bf16 v[14:17], v[168:171], v[224:227], v[14:17]
	v_mfma_f32_16x16x32_bf16 v[6:9], v[176:179], v[224:227], v[6:9]
	s_setprio 0
	s_setprio 1
	v_mfma_f32_16x16x32_bf16 v[58:61], v[180:183], v[196:199], v[58:61]
	v_mfma_f32_16x16x32_bf16 v[50:53], v[188:191], v[196:199], v[50:53]
	v_mfma_f32_16x16x32_bf16 v[42:45], v[180:183], v[204:207], v[42:45]
	v_mfma_f32_16x16x32_bf16 v[34:37], v[188:191], v[204:207], v[34:37]
	v_mfma_f32_16x16x32_bf16 v[26:29], v[180:183], v[212:215], v[26:29]
	v_mfma_f32_16x16x32_bf16 v[18:21], v[188:191], v[212:215], v[18:21]
	v_mfma_f32_16x16x32_bf16 v[10:13], v[180:183], v[220:223], v[10:13]
	v_mfma_f32_16x16x32_bf16 v[2:5], v[188:191], v[220:223], v[2:5]
	v_mfma_f32_16x16x32_bf16 v[58:61], v[184:187], v[200:203], v[58:61]
	v_mfma_f32_16x16x32_bf16 v[50:53], v[192:195], v[200:203], v[50:53]
	v_mfma_f32_16x16x32_bf16 v[42:45], v[184:187], v[208:211], v[42:45]
	v_mfma_f32_16x16x32_bf16 v[34:37], v[192:195], v[208:211], v[34:37]
	v_mfma_f32_16x16x32_bf16 v[26:29], v[184:187], v[216:219], v[26:29]
	v_mfma_f32_16x16x32_bf16 v[18:21], v[192:195], v[216:219], v[18:21]
	v_mfma_f32_16x16x32_bf16 v[10:13], v[184:187], v[224:227], v[10:13]
	v_mfma_f32_16x16x32_bf16 v[2:5], v[192:195], v[224:227], v[2:5]
	s_barrier
	s_setprio 0
	s_mov_b32 s7, s51
	s_add_u32 s88, s88, 0x100
	s_addc_u32 s89, s89, 0
	s_add_u32 s86, s86, 0x100
	s_addc_u32 s87, s87, 0
	s_cmp_ge_i32 s51, s101
	s_cbranch_scc1 .Lmy_kexit_0
.LBB0_171:
	s_add_u32 s98, s86, 0xfffc0080
	s_addc_u32 s99, s87, -1
	s_cmp_eq_u32 s7, s100
	s_cselect_b64 s[94:95], s[90:91], s[98:99]
	s_cselect_b64 s[96:97], s[92:93], s[88:89]
	s_add_i32 s51, s7, 2
	s_mov_b32 m0, s78
	ds_read_b128 v[164:167], v230
	global_load_lds_dwordx4 v144, s[86:87]
	s_mov_b32 m0, s79
	ds_read_b128 v[168:171], v230 offset:1024
	global_load_lds_dwordx4 v142, s[86:87]
	ds_read_b128 v[172:175], v230 offset:2048
	ds_read_b128 v[176:179], v230 offset:3072
	ds_read_b128 v[180:183], v231
	ds_read_b128 v[184:187], v231 offset:1024
	ds_read_b128 v[188:191], v231 offset:2048
	ds_read_b128 v[192:195], v231 offset:3072
	ds_read_b128 v[196:199], v160
	ds_read_b128 v[200:203], v160 offset:1024
	ds_read_b128 v[204:207], v160 offset:2048
	ds_read_b128 v[208:211], v160 offset:3072
	ds_read_b128 v[212:215], v160 offset:4096
	ds_read_b128 v[216:219], v160 offset:5120
	ds_read_b128 v[220:223], v160 offset:6144
	ds_read_b128 v[224:227], v160 offset:7168
	s_waitcnt vmcnt(8)
	s_waitcnt lgkmcnt(0)
	s_setprio 1
	s_barrier
	v_mfma_f32_16x16x32_bf16 v[122:125], v[164:167], v[196:199], v[122:125]
	v_mfma_f32_16x16x32_bf16 v[118:121], v[172:175], v[196:199], v[118:121]
	v_mfma_f32_16x16x32_bf16 v[110:113], v[164:167], v[204:207], v[110:113]
	v_mfma_f32_16x16x32_bf16 v[102:105], v[172:175], v[204:207], v[102:105]
	v_mfma_f32_16x16x32_bf16 v[94:97], v[164:167], v[212:215], v[94:97]
	v_mfma_f32_16x16x32_bf16 v[86:89], v[172:175], v[212:215], v[86:89]
	v_mfma_f32_16x16x32_bf16 v[78:81], v[164:167], v[220:223], v[78:81]
	v_mfma_f32_16x16x32_bf16 v[70:73], v[172:175], v[220:223], v[70:73]
	v_mfma_f32_16x16x32_bf16 v[122:125], v[168:171], v[200:203], v[122:125]
	v_mfma_f32_16x16x32_bf16 v[118:121], v[176:179], v[200:203], v[118:121]
	v_mfma_f32_16x16x32_bf16 v[110:113], v[168:171], v[208:211], v[110:113]
	v_mfma_f32_16x16x32_bf16 v[102:105], v[176:179], v[208:211], v[102:105]
	v_mfma_f32_16x16x32_bf16 v[94:97], v[168:171], v[216:219], v[94:97]
	v_mfma_f32_16x16x32_bf16 v[86:89], v[176:179], v[216:219], v[86:89]
	v_mfma_f32_16x16x32_bf16 v[78:81], v[168:171], v[224:227], v[78:81]
	v_mfma_f32_16x16x32_bf16 v[70:73], v[176:179], v[224:227], v[70:73]
	s_setprio 0
	s_setprio 1
	v_mfma_f32_16x16x32_bf16 v[126:129], v[180:183], v[196:199], v[126:129]
	v_mfma_f32_16x16x32_bf16 v[114:117], v[188:191], v[196:199], v[114:117]
	v_mfma_f32_16x16x32_bf16 v[106:109], v[180:183], v[204:207], v[106:109]
	v_mfma_f32_16x16x32_bf16 v[98:101], v[188:191], v[204:207], v[98:101]
	v_mfma_f32_16x16x32_bf16 v[90:93], v[180:183], v[212:215], v[90:93]
	v_mfma_f32_16x16x32_bf16 v[82:85], v[188:191], v[212:215], v[82:85]
	v_mfma_f32_16x16x32_bf16 v[74:77], v[180:183], v[220:223], v[74:77]
	v_mfma_f32_16x16x32_bf16 v[66:69], v[188:191], v[220:223], v[66:69]
	v_mfma_f32_16x16x32_bf16 v[126:129], v[184:187], v[200:203], v[126:129]
	v_mfma_f32_16x16x32_bf16 v[114:117], v[192:195], v[200:203], v[114:117]
	v_mfma_f32_16x16x32_bf16 v[106:109], v[184:187], v[208:211], v[106:109]
	v_mfma_f32_16x16x32_bf16 v[98:101], v[192:195], v[208:211], v[98:101]
	v_mfma_f32_16x16x32_bf16 v[90:93], v[184:187], v[216:219], v[90:93]
	v_mfma_f32_16x16x32_bf16 v[82:85], v[192:195], v[216:219], v[82:85]
	v_mfma_f32_16x16x32_bf16 v[74:77], v[184:187], v[224:227], v[74:77]
	v_mfma_f32_16x16x32_bf16 v[66:69], v[192:195], v[224:227], v[66:69]
	s_barrier
	s_setprio 0
	s_add_u32 s98, s96, 0x40000
	s_addc_u32 s99, s97, 0
	s_mov_b32 m0, s80
	ds_read_b128 v[196:199], v160 offset:16384
	global_load_lds_dwordx4 v132, s[96:97]
	s_mov_b32 m0, s81
	s_add_i32 s7, s77, s47
	global_load_lds_dwordx4 v136, s[96:97]
	s_mov_b32 m0, s7
	ds_read_b128 v[200:203], v160 offset:17408
	global_load_lds_dwordx4 v132, s[98:99]
	s_add_i32 m0, s7, 0x2000
	ds_read_b128 v[204:207], v160 offset:18432
	global_load_lds_dwordx4 v136, s[98:99]
	s_mov_b32 m0, s57
	ds_read_b128 v[208:211], v160 offset:19456
	global_load_lds_dwordx4 v130, s[94:95]
	s_mov_b32 m0, s62
	ds_read_b128 v[212:215], v160 offset:20480
	global_load_lds_dwordx4 v134, s[94:95]
	ds_read_b128 v[216:219], v160 offset:21504
	ds_read_b128 v[220:223], v160 offset:22528
	ds_read_b128 v[224:227], v160 offset:23552
	s_waitcnt vmcnt(8)
	s_waitcnt lgkmcnt(0)
	s_setprio 1
	s_barrier
	v_mfma_f32_16x16x32_bf16 v[62:65], v[164:167], v[196:199], v[62:65]
	v_mfma_f32_16x16x32_bf16 v[54:57], v[172:175], v[196:199], v[54:57]
	v_mfma_f32_16x16x32_bf16 v[46:49], v[164:167], v[204:207], v[46:49]
	v_mfma_f32_16x16x32_bf16 v[38:41], v[172:175], v[204:207], v[38:41]
	v_mfma_f32_16x16x32_bf16 v[30:33], v[164:167], v[212:215], v[30:33]
	v_mfma_f32_16x16x32_bf16 v[22:25], v[172:175], v[212:215], v[22:25]
	v_mfma_f32_16x16x32_bf16 v[14:17], v[164:167], v[220:223], v[14:17]
	v_mfma_f32_16x16x32_bf16 v[6:9], v[172:175], v[220:223], v[6:9]
	v_mfma_f32_16x16x32_bf16 v[62:65], v[168:171], v[200:203], v[62:65]
	v_mfma_f32_16x16x32_bf16 v[54:57], v[176:179], v[200:203], v[54:57]
	v_mfma_f32_16x16x32_bf16 v[46:49], v[168:171], v[208:211], v[46:49]
	v_mfma_f32_16x16x32_bf16 v[38:41], v[176:179], v[208:211], v[38:41]
	v_mfma_f32_16x16x32_bf16 v[30:33], v[168:171], v[216:219], v[30:33]
	v_mfma_f32_16x16x32_bf16 v[22:25], v[176:179], v[216:219], v[22:25]
	v_mfma_f32_16x16x32_bf16 v[14:17], v[168:171], v[224:227], v[14:17]
	v_mfma_f32_16x16x32_bf16 v[6:9], v[176:179], v[224:227], v[6:9]
	s_setprio 0
	s_setprio 1
	v_mfma_f32_16x16x32_bf16 v[58:61], v[180:183], v[196:199], v[58:61]
	v_mfma_f32_16x16x32_bf16 v[50:53], v[188:191], v[196:199], v[50:53]
	v_mfma_f32_16x16x32_bf16 v[42:45], v[180:183], v[204:207], v[42:45]
	v_mfma_f32_16x16x32_bf16 v[34:37], v[188:191], v[204:207], v[34:37]
	v_mfma_f32_16x16x32_bf16 v[26:29], v[180:183], v[212:215], v[26:29]
	v_mfma_f32_16x16x32_bf16 v[18:21], v[188:191], v[212:215], v[18:21]
	v_mfma_f32_16x16x32_bf16 v[10:13], v[180:183], v[220:223], v[10:13]
	v_mfma_f32_16x16x32_bf16 v[2:5], v[188:191], v[220:223], v[2:5]
	v_mfma_f32_16x16x32_bf16 v[58:61], v[184:187], v[200:203], v[58:61]
	v_mfma_f32_16x16x32_bf16 v[50:53], v[192:195], v[200:203], v[50:53]
	v_mfma_f32_16x16x32_bf16 v[42:45], v[184:187], v[208:211], v[42:45]
	v_mfma_f32_16x16x32_bf16 v[34:37], v[192:195], v[208:211], v[34:37]
	v_mfma_f32_16x16x32_bf16 v[26:29], v[184:187], v[216:219], v[26:29]
	v_mfma_f32_16x16x32_bf16 v[18:21], v[192:195], v[216:219], v[18:21]
	v_mfma_f32_16x16x32_bf16 v[10:13], v[184:187], v[224:227], v[10:13]
	v_mfma_f32_16x16x32_bf16 v[2:5], v[192:195], v[224:227], v[2:5]
	s_barrier
	s_setprio 0
	s_add_u32 s98, s94, 0x40000
	s_addc_u32 s99, s95, 0
	s_add_i32 s7, 0, 0x18000
	s_add_i32 s55, 0, 0x1c000
	s_mov_b32 m0, s63
	ds_read_b128 v[164:167], v232
	global_load_lds_dwordx4 v130, s[98:99]
	s_mov_b32 m0, s64
	ds_read_b128 v[168:171], v232 offset:1024
	global_load_lds_dwordx4 v134, s[98:99]
	ds_read_b128 v[172:175], v232 offset:2048
	ds_read_b128 v[176:179], v232 offset:3072
	ds_read_b128 v[180:183], v233
	ds_read_b128 v[184:187], v233 offset:1024
	ds_read_b128 v[188:191], v233 offset:2048
	ds_read_b128 v[192:195], v233 offset:3072
	ds_read_b128 v[196:199], v160 offset:32768
	ds_read_b128 v[200:203], v160 offset:33792
	ds_read_b128 v[204:207], v160 offset:34816
	ds_read_b128 v[208:211], v160 offset:35840
	ds_read_b128 v[212:215], v160 offset:36864
	ds_read_b128 v[216:219], v160 offset:37888
	ds_read_b128 v[220:223], v160 offset:38912
	ds_read_b128 v[224:227], v160 offset:39936
	s_waitcnt vmcnt(8)
	s_waitcnt lgkmcnt(0)
	s_setprio 1
	s_barrier
	v_mfma_f32_16x16x32_bf16 v[122:125], v[164:167], v[196:199], v[122:125]
	v_mfma_f32_16x16x32_bf16 v[118:121], v[172:175], v[196:199], v[118:121]
	v_mfma_f32_16x16x32_bf16 v[110:113], v[164:167], v[204:207], v[110:113]
	v_mfma_f32_16x16x32_bf16 v[102:105], v[172:175], v[204:207], v[102:105]
	v_mfma_f32_16x16x32_bf16 v[94:97], v[164:167], v[212:215], v[94:97]
	v_mfma_f32_16x16x32_bf16 v[86:89], v[172:175], v[212:215], v[86:89]
	v_mfma_f32_16x16x32_bf16 v[78:81], v[164:167], v[220:223], v[78:81]
	v_mfma_f32_16x16x32_bf16 v[70:73], v[172:175], v[220:223], v[70:73]
	v_mfma_f32_16x16x32_bf16 v[122:125], v[168:171], v[200:203], v[122:125]
	v_mfma_f32_16x16x32_bf16 v[118:121], v[176:179], v[200:203], v[118:121]
	v_mfma_f32_16x16x32_bf16 v[110:113], v[168:171], v[208:211], v[110:113]
	v_mfma_f32_16x16x32_bf16 v[102:105], v[176:179], v[208:211], v[102:105]
	v_mfma_f32_16x16x32_bf16 v[94:97], v[168:171], v[216:219], v[94:97]
	v_mfma_f32_16x16x32_bf16 v[86:89], v[176:179], v[216:219], v[86:89]
	v_mfma_f32_16x16x32_bf16 v[78:81], v[168:171], v[224:227], v[78:81]
	v_mfma_f32_16x16x32_bf16 v[70:73], v[176:179], v[224:227], v[70:73]
	s_setprio 0
	s_setprio 1
	v_mfma_f32_16x16x32_bf16 v[126:129], v[180:183], v[196:199], v[126:129]
	v_mfma_f32_16x16x32_bf16 v[114:117], v[188:191], v[196:199], v[114:117]
	v_mfma_f32_16x16x32_bf16 v[106:109], v[180:183], v[204:207], v[106:109]
	v_mfma_f32_16x16x32_bf16 v[98:101], v[188:191], v[204:207], v[98:101]
	v_mfma_f32_16x16x32_bf16 v[90:93], v[180:183], v[212:215], v[90:93]
	v_mfma_f32_16x16x32_bf16 v[82:85], v[188:191], v[212:215], v[82:85]
	v_mfma_f32_16x16x32_bf16 v[74:77], v[180:183], v[220:223], v[74:77]
	v_mfma_f32_16x16x32_bf16 v[66:69], v[188:191], v[220:223], v[66:69]
	v_mfma_f32_16x16x32_bf16 v[126:129], v[184:187], v[200:203], v[126:129]
	v_mfma_f32_16x16x32_bf16 v[114:117], v[192:195], v[200:203], v[114:117]
	v_mfma_f32_16x16x32_bf16 v[106:109], v[184:187], v[208:211], v[106:109]
	v_mfma_f32_16x16x32_bf16 v[98:101], v[192:195], v[208:211], v[98:101]
	v_mfma_f32_16x16x32_bf16 v[90:93], v[184:187], v[216:219], v[90:93]
	v_mfma_f32_16x16x32_bf16 v[82:85], v[192:195], v[216:219], v[82:85]
	v_mfma_f32_16x16x32_bf16 v[74:77], v[184:187], v[224:227], v[74:77]
	v_mfma_f32_16x16x32_bf16 v[66:69], v[192:195], v[224:227], v[66:69]
	s_barrier
	s_setprio 0
	s_add_u32 s96, s96, 0x80
	s_addc_u32 s97, s97, 0
	s_add_u32 s98, s96, 0x40000
	s_addc_u32 s99, s97, 0
	s_add_u32 s94, s94, 0x80
	s_addc_u32 s95, s95, 0
	s_add_i32 s7, s7, s47
	s_mov_b32 m0, s7
	ds_read_b128 v[196:199], v160 offset:49152
	global_load_lds_dwordx4 v132, s[96:97]
	s_add_i32 m0, s7, 0x2000
	s_add_i32 s7, s55, s47
	global_load_lds_dwordx4 v136, s[96:97]
	s_mov_b32 m0, s7
	ds_read_b128 v[200:203], v160 offset:50176
	global_load_lds_dwordx4 v132, s[98:99]
	s_add_i32 m0, s7, 0x2000
	ds_read_b128 v[204:207], v160 offset:51200
	global_load_lds_dwordx4 v136, s[98:99]
	s_mov_b32 m0, s65
	ds_read_b128 v[208:211], v160 offset:52224
	global_load_lds_dwordx4 v130, s[94:95]
	s_mov_b32 m0, s66
	ds_read_b128 v[212:215], v160 offset:53248
	global_load_lds_dwordx4 v134, s[94:95]
	ds_read_b128 v[216:219], v160 offset:54272
	ds_read_b128 v[220:223], v160 offset:55296
	ds_read_b128 v[224:227], v160 offset:56320
	s_waitcnt vmcnt(8)
	s_waitcnt lgkmcnt(0)
	s_setprio 1
	s_barrier
	v_mfma_f32_16x16x32_bf16 v[62:65], v[164:167], v[196:199], v[62:65]
	v_mfma_f32_16x16x32_bf16 v[54:57], v[172:175], v[196:199], v[54:57]
	v_mfma_f32_16x16x32_bf16 v[46:49], v[164:167], v[204:207], v[46:49]
	v_mfma_f32_16x16x32_bf16 v[38:41], v[172:175], v[204:207], v[38:41]
	v_mfma_f32_16x16x32_bf16 v[30:33], v[164:167], v[212:215], v[30:33]
	v_mfma_f32_16x16x32_bf16 v[22:25], v[172:175], v[212:215], v[22:25]
	v_mfma_f32_16x16x32_bf16 v[14:17], v[164:167], v[220:223], v[14:17]
	v_mfma_f32_16x16x32_bf16 v[6:9], v[172:175], v[220:223], v[6:9]
	v_mfma_f32_16x16x32_bf16 v[62:65], v[168:171], v[200:203], v[62:65]
	v_mfma_f32_16x16x32_bf16 v[54:57], v[176:179], v[200:203], v[54:57]
	v_mfma_f32_16x16x32_bf16 v[46:49], v[168:171], v[208:211], v[46:49]
	v_mfma_f32_16x16x32_bf16 v[38:41], v[176:179], v[208:211], v[38:41]
	v_mfma_f32_16x16x32_bf16 v[30:33], v[168:171], v[216:219], v[30:33]
	v_mfma_f32_16x16x32_bf16 v[22:25], v[176:179], v[216:219], v[22:25]
	v_mfma_f32_16x16x32_bf16 v[14:17], v[168:171], v[224:227], v[14:17]
	v_mfma_f32_16x16x32_bf16 v[6:9], v[176:179], v[224:227], v[6:9]
	s_setprio 0
	s_setprio 1
	v_mfma_f32_16x16x32_bf16 v[58:61], v[180:183], v[196:199], v[58:61]
	v_mfma_f32_16x16x32_bf16 v[50:53], v[188:191], v[196:199], v[50:53]
	v_mfma_f32_16x16x32_bf16 v[42:45], v[180:183], v[204:207], v[42:45]
	v_mfma_f32_16x16x32_bf16 v[34:37], v[188:191], v[204:207], v[34:37]
	v_mfma_f32_16x16x32_bf16 v[26:29], v[180:183], v[212:215], v[26:29]
	v_mfma_f32_16x16x32_bf16 v[18:21], v[188:191], v[212:215], v[18:21]
	v_mfma_f32_16x16x32_bf16 v[10:13], v[180:183], v[220:223], v[10:13]
	v_mfma_f32_16x16x32_bf16 v[2:5], v[188:191], v[220:223], v[2:5]
	v_mfma_f32_16x16x32_bf16 v[58:61], v[184:187], v[200:203], v[58:61]
	v_mfma_f32_16x16x32_bf16 v[50:53], v[192:195], v[200:203], v[50:53]
	v_mfma_f32_16x16x32_bf16 v[42:45], v[184:187], v[208:211], v[42:45]
	v_mfma_f32_16x16x32_bf16 v[34:37], v[192:195], v[208:211], v[34:37]
	v_mfma_f32_16x16x32_bf16 v[26:29], v[184:187], v[216:219], v[26:29]
	v_mfma_f32_16x16x32_bf16 v[18:21], v[192:195], v[216:219], v[18:21]
	v_mfma_f32_16x16x32_bf16 v[10:13], v[184:187], v[224:227], v[10:13]
	v_mfma_f32_16x16x32_bf16 v[2:5], v[192:195], v[224:227], v[2:5]
	s_barrier
	s_setprio 0
	s_mov_b32 s7, s51
	s_add_u32 s88, s88, 0x100
	s_addc_u32 s89, s89, 0
	s_add_u32 s86, s86, 0x100
	s_addc_u32 s87, s87, 0
	s_cmp_ge_i32 s51, s101
	s_cbranch_scc0 .LBB0_171

.Lmy_nb_1:
	s_nop 0
	v_readfirstlane_b32 s86, v152
	v_readfirstlane_b32 s87, v153
	v_readfirstlane_b32 s88, v154
	v_readfirstlane_b32 s89, v155
	v_readfirstlane_b32 s90, v148
	v_readfirstlane_b32 s91, v149
	v_readfirstlane_b32 s92, v150
	v_readfirstlane_b32 s93, v151
	v_readfirstlane_b32 s100, v138
	v_readfirstlane_b32 s101, v141
	v_add_u32_e32 v230, s69, v160
	v_add_u32_e32 v231, s72, v160
	v_add_u32_e32 v232, 0x18000, v160
	v_add_u32_e32 v233, 0x1c000, v160
	s_add_u32 s98, s86, 0x100
	s_addc_u32 s99, s87, 0
	s_cmp_eq_u32 s8, s100
	s_cselect_b64 s[94:95], s[90:91], s[98:99]
	s_cselect_b64 s[96:97], s[92:93], s[88:89]
	s_add_i32 s9, s8, 2
	s_add_i32 m0, s55, 0xc000
	ds_read_b128 v[166:169], v230
	global_load_lds_dwordx4 v144, s[86:87]
	s_add_i32 m0, s55, 0xe000
	ds_read_b128 v[170:173], v230 offset:1024
	global_load_lds_dwordx4 v142, s[86:87]
	ds_read_b128 v[174:177], v230 offset:2048
	ds_read_b128 v[178:181], v230 offset:3072
	ds_read_b128 v[182:185], v231
	ds_read_b128 v[186:189], v231 offset:1024
	ds_read_b128 v[190:193], v231 offset:2048
	ds_read_b128 v[194:197], v231 offset:3072
	ds_read_b128 v[198:201], v163
	ds_read_b128 v[202:205], v163 offset:1024
	ds_read_b128 v[206:209], v163 offset:2048
	ds_read_b128 v[210:213], v163 offset:3072
	ds_read_b128 v[214:217], v163 offset:4096
	ds_read_b128 v[218:221], v163 offset:5120
	ds_read_b128 v[222:225], v163 offset:6144
	ds_read_b128 v[226:229], v163 offset:7168
	s_waitcnt vmcnt(8)
	s_waitcnt lgkmcnt(0)
	s_setprio 1
	s_barrier
	v_mfma_f32_16x16x32_bf16 v[122:125], v[166:169], v[198:201], 0
	v_mfma_f32_16x16x32_bf16 v[118:121], v[174:177], v[198:201], 0
	v_mfma_f32_16x16x32_bf16 v[110:113], v[166:169], v[206:209], 0
	v_mfma_f32_16x16x32_bf16 v[102:105], v[174:177], v[206:209], 0
	v_mfma_f32_16x16x32_bf16 v[94:97], v[166:169], v[214:217], 0
	v_mfma_f32_16x16x32_bf16 v[86:89], v[174:177], v[214:217], 0
	v_mfma_f32_16x16x32_bf16 v[78:81], v[166:169], v[222:225], 0
	v_mfma_f32_16x16x32_bf16 v[70:73], v[174:177], v[222:225], 0
	v_mfma_f32_16x16x32_bf16 v[122:125], v[170:173], v[202:205], v[122:125]
	v_mfma_f32_16x16x32_bf16 v[118:121], v[178:181], v[202:205], v[118:121]
	v_mfma_f32_16x16x32_bf16 v[110:113], v[170:173], v[210:213], v[110:113]
	v_mfma_f32_16x16x32_bf16 v[102:105], v[178:181], v[210:213], v[102:105]
	v_mfma_f32_16x16x32_bf16 v[94:97], v[170:173], v[218:221], v[94:97]
	v_mfma_f32_16x16x32_bf16 v[86:89], v[178:181], v[218:221], v[86:89]
	v_mfma_f32_16x16x32_bf16 v[78:81], v[170:173], v[226:229], v[78:81]
	v_mfma_f32_16x16x32_bf16 v[70:73], v[178:181], v[226:229], v[70:73]
	s_setprio 0
	s_setprio 1
	v_mfma_f32_16x16x32_bf16 v[126:129], v[182:185], v[198:201], 0
	v_mfma_f32_16x16x32_bf16 v[114:117], v[190:193], v[198:201], 0
	v_mfma_f32_16x16x32_bf16 v[106:109], v[182:185], v[206:209], 0
	v_mfma_f32_16x16x32_bf16 v[98:101], v[190:193], v[206:209], 0
	v_mfma_f32_16x16x32_bf16 v[90:93], v[182:185], v[214:217], 0
	v_mfma_f32_16x16x32_bf16 v[82:85], v[190:193], v[214:217], 0
	v_mfma_f32_16x16x32_bf16 v[74:77], v[182:185], v[222:225], 0
	v_mfma_f32_16x16x32_bf16 v[66:69], v[190:193], v[222:225], 0
	v_mfma_f32_16x16x32_bf16 v[126:129], v[186:189], v[202:205], v[126:129]
	v_mfma_f32_16x16x32_bf16 v[114:117], v[194:197], v[202:205], v[114:117]
	v_mfma_f32_16x16x32_bf16 v[106:109], v[186:189], v[210:213], v[106:109]
	v_mfma_f32_16x16x32_bf16 v[98:101], v[194:197], v[210:213], v[98:101]
	v_mfma_f32_16x16x32_bf16 v[90:93], v[186:189], v[218:221], v[90:93]
	v_mfma_f32_16x16x32_bf16 v[82:85], v[194:197], v[218:221], v[82:85]
	v_mfma_f32_16x16x32_bf16 v[74:77], v[186:189], v[226:229], v[74:77]
	v_mfma_f32_16x16x32_bf16 v[66:69], v[194:197], v[226:229], v[66:69]
	s_barrier
	s_setprio 0
	s_add_u32 s98, s96, 0xb0000
	s_addc_u32 s99, s97, 0
	s_add_i32 s8, s69, s54
	s_mov_b32 m0, s8
	ds_read_b128 v[198:201], v163 offset:16384
	global_load_lds_dwordx4 v132, s[96:97]
	s_add_i32 m0, s8, 0x2000
	s_add_i32 s8, s72, s54
	global_load_lds_dwordx4 v136, s[96:97]
	s_mov_b32 m0, s8
	ds_read_b128 v[202:205], v163 offset:17408
	global_load_lds_dwordx4 v132, s[98:99]
	s_add_i32 m0, s8, 0x2000
	ds_read_b128 v[206:209], v163 offset:18432
	global_load_lds_dwordx4 v136, s[98:99]
	s_mov_b32 m0, s55
	ds_read_b128 v[210:213], v163 offset:19456
	global_load_lds_dwordx4 v130, s[94:95]
	s_mov_b32 m0, s56
	ds_read_b128 v[214:217], v163 offset:20480
	global_load_lds_dwordx4 v134, s[94:95]
	ds_read_b128 v[218:221], v163 offset:21504
	ds_read_b128 v[222:225], v163 offset:22528
	ds_read_b128 v[226:229], v163 offset:23552
	s_waitcnt vmcnt(8)
	s_waitcnt lgkmcnt(0)
	s_setprio 1
	s_barrier
	v_mfma_f32_16x16x32_bf16 v[62:65], v[166:169], v[198:201], 0
	v_mfma_f32_16x16x32_bf16 v[54:57], v[174:177], v[198:201], 0
	v_mfma_f32_16x16x32_bf16 v[46:49], v[166:169], v[206:209], 0
	v_mfma_f32_16x16x32_bf16 v[38:41], v[174:177], v[206:209], 0
	v_mfma_f32_16x16x32_bf16 v[30:33], v[166:169], v[214:217], 0
	v_mfma_f32_16x16x32_bf16 v[22:25], v[174:177], v[214:217], 0
	v_mfma_f32_16x16x32_bf16 v[14:17], v[166:169], v[222:225], 0
	v_mfma_f32_16x16x32_bf16 v[6:9], v[174:177], v[222:225], 0
	v_mfma_f32_16x16x32_bf16 v[62:65], v[170:173], v[202:205], v[62:65]
	v_mfma_f32_16x16x32_bf16 v[54:57], v[178:181], v[202:205], v[54:57]
	v_mfma_f32_16x16x32_bf16 v[46:49], v[170:173], v[210:213], v[46:49]
	v_mfma_f32_16x16x32_bf16 v[38:41], v[178:181], v[210:213], v[38:41]
	v_mfma_f32_16x16x32_bf16 v[30:33], v[170:173], v[218:221], v[30:33]
	v_mfma_f32_16x16x32_bf16 v[22:25], v[178:181], v[218:221], v[22:25]
	v_mfma_f32_16x16x32_bf16 v[14:17], v[170:173], v[226:229], v[14:17]
	v_mfma_f32_16x16x32_bf16 v[6:9], v[178:181], v[226:229], v[6:9]
	s_setprio 0
	s_setprio 1
	v_mfma_f32_16x16x32_bf16 v[58:61], v[182:185], v[198:201], 0
	v_mfma_f32_16x16x32_bf16 v[50:53], v[190:193], v[198:201], 0
	v_mfma_f32_16x16x32_bf16 v[42:45], v[182:185], v[206:209], 0
	v_mfma_f32_16x16x32_bf16 v[34:37], v[190:193], v[206:209], 0
	v_mfma_f32_16x16x32_bf16 v[26:29], v[182:185], v[214:217], 0
	v_mfma_f32_16x16x32_bf16 v[18:21], v[190:193], v[214:217], 0
	v_mfma_f32_16x16x32_bf16 v[10:13], v[182:185], v[222:225], 0
	v_mfma_f32_16x16x32_bf16 v[2:5], v[190:193], v[222:225], 0
	v_mfma_f32_16x16x32_bf16 v[58:61], v[186:189], v[202:205], v[58:61]
	v_mfma_f32_16x16x32_bf16 v[50:53], v[194:197], v[202:205], v[50:53]
	v_mfma_f32_16x16x32_bf16 v[42:45], v[186:189], v[210:213], v[42:45]
	v_mfma_f32_16x16x32_bf16 v[34:37], v[194:197], v[210:213], v[34:37]
	v_mfma_f32_16x16x32_bf16 v[26:29], v[186:189], v[218:221], v[26:29]
	v_mfma_f32_16x16x32_bf16 v[18:21], v[194:197], v[218:221], v[18:21]
	v_mfma_f32_16x16x32_bf16 v[10:13], v[186:189], v[226:229], v[10:13]
	v_mfma_f32_16x16x32_bf16 v[2:5], v[194:197], v[226:229], v[2:5]
	s_barrier
	s_setprio 0
	s_add_u32 s98, s94, 0xb0000
	s_addc_u32 s99, s95, 0
	s_add_i32 s8, 0, 0x18000
	s_add_i32 s50, 0, 0x1c000
	s_mov_b32 m0, s57
	ds_read_b128 v[166:169], v232
	global_load_lds_dwordx4 v130, s[98:99]
	s_mov_b32 m0, s58
	ds_read_b128 v[170:173], v232 offset:1024
	global_load_lds_dwordx4 v134, s[98:99]
	ds_read_b128 v[174:177], v232 offset:2048
	ds_read_b128 v[178:181], v232 offset:3072
	ds_read_b128 v[182:185], v233
	ds_read_b128 v[186:189], v233 offset:1024
	ds_read_b128 v[190:193], v233 offset:2048
	ds_read_b128 v[194:197], v233 offset:3072
	ds_read_b128 v[198:201], v163 offset:32768
	ds_read_b128 v[202:205], v163 offset:33792
	ds_read_b128 v[206:209], v163 offset:34816
	ds_read_b128 v[210:213], v163 offset:35840
	ds_read_b128 v[214:217], v163 offset:36864
	ds_read_b128 v[218:221], v163 offset:37888
	ds_read_b128 v[222:225], v163 offset:38912
	ds_read_b128 v[226:229], v163 offset:39936
	s_waitcnt vmcnt(8)
	s_waitcnt lgkmcnt(0)
	s_setprio 1
	s_barrier
	v_mfma_f32_16x16x32_bf16 v[122:125], v[166:169], v[198:201], v[122:125]
	v_mfma_f32_16x16x32_bf16 v[118:121], v[174:177], v[198:201], v[118:121]
	v_mfma_f32_16x16x32_bf16 v[110:113], v[166:169], v[206:209], v[110:113]
	v_mfma_f32_16x16x32_bf16 v[102:105], v[174:177], v[206:209], v[102:105]
	v_mfma_f32_16x16x32_bf16 v[94:97], v[166:169], v[214:217], v[94:97]
	v_mfma_f32_16x16x32_bf16 v[86:89], v[174:177], v[214:217], v[86:89]
	v_mfma_f32_16x16x32_bf16 v[78:81], v[166:169], v[222:225], v[78:81]
	v_mfma_f32_16x16x32_bf16 v[70:73], v[174:177], v[222:225], v[70:73]
	v_mfma_f32_16x16x32_bf16 v[122:125], v[170:173], v[202:205], v[122:125]
	v_mfma_f32_16x16x32_bf16 v[118:121], v[178:181], v[202:205], v[118:121]
	v_mfma_f32_16x16x32_bf16 v[110:113], v[170:173], v[210:213], v[110:113]
	v_mfma_f32_16x16x32_bf16 v[102:105], v[178:181], v[210:213], v[102:105]
	v_mfma_f32_16x16x32_bf16 v[94:97], v[170:173], v[218:221], v[94:97]
	v_mfma_f32_16x16x32_bf16 v[86:89], v[178:181], v[218:221], v[86:89]
	v_mfma_f32_16x16x32_bf16 v[78:81], v[170:173], v[226:229], v[78:81]
	v_mfma_f32_16x16x32_bf16 v[70:73], v[178:181], v[226:229], v[70:73]
	s_setprio 0
	s_setprio 1
	v_mfma_f32_16x16x32_bf16 v[126:129], v[182:185], v[198:201], v[126:129]
	v_mfma_f32_16x16x32_bf16 v[114:117], v[190:193], v[198:201], v[114:117]
	v_mfma_f32_16x16x32_bf16 v[106:109], v[182:185], v[206:209], v[106:109]
	v_mfma_f32_16x16x32_bf16 v[98:101], v[190:193], v[206:209], v[98:101]
	v_mfma_f32_16x16x32_bf16 v[90:93], v[182:185], v[214:217], v[90:93]
	v_mfma_f32_16x16x32_bf16 v[82:85], v[190:193], v[214:217], v[82:85]
	v_mfma_f32_16x16x32_bf16 v[74:77], v[182:185], v[222:225], v[74:77]
	v_mfma_f32_16x16x32_bf16 v[66:69], v[190:193], v[222:225], v[66:69]
	v_mfma_f32_16x16x32_bf16 v[126:129], v[186:189], v[202:205], v[126:129]
	v_mfma_f32_16x16x32_bf16 v[114:117], v[194:197], v[202:205], v[114:117]
	v_mfma_f32_16x16x32_bf16 v[106:109], v[186:189], v[210:213], v[106:109]
	v_mfma_f32_16x16x32_bf16 v[98:101], v[194:197], v[210:213], v[98:101]
	v_mfma_f32_16x16x32_bf16 v[90:93], v[186:189], v[218:221], v[90:93]
	v_mfma_f32_16x16x32_bf16 v[82:85], v[194:197], v[218:221], v[82:85]
	v_mfma_f32_16x16x32_bf16 v[74:77], v[186:189], v[226:229], v[74:77]
	v_mfma_f32_16x16x32_bf16 v[66:69], v[194:197], v[226:229], v[66:69]
	s_barrier
	s_setprio 0
	s_add_u32 s96, s96, 0x80
	s_addc_u32 s97, s97, 0
	s_add_u32 s98, s96, 0xb0000
	s_addc_u32 s99, s97, 0
	s_add_u32 s94, s94, 0x80
	s_addc_u32 s95, s95, 0
	s_add_i32 s8, s8, s54
	s_mov_b32 m0, s8
	ds_read_b128 v[198:201], v163 offset:49152
	global_load_lds_dwordx4 v132, s[96:97]
	s_add_i32 m0, s8, 0x2000
	s_add_i32 s8, s50, s54
	global_load_lds_dwordx4 v136, s[96:97]
	s_mov_b32 m0, s8
	ds_read_b128 v[202:205], v163 offset:50176
	global_load_lds_dwordx4 v132, s[98:99]
	s_add_i32 m0, s8, 0x2000
	ds_read_b128 v[206:209], v163 offset:51200
	global_load_lds_dwordx4 v136, s[98:99]
	s_mov_b32 m0, s64
	ds_read_b128 v[210:213], v163 offset:52224
	global_load_lds_dwordx4 v130, s[94:95]
	s_mov_b32 m0, s65
	ds_read_b128 v[214:217], v163 offset:53248
	global_load_lds_dwordx4 v134, s[94:95]
	ds_read_b128 v[218:221], v163 offset:54272
	ds_read_b128 v[222:225], v163 offset:55296
	ds_read_b128 v[226:229], v163 offset:56320
	s_waitcnt vmcnt(8)
	s_waitcnt lgkmcnt(0)
	s_setprio 1
	s_barrier
	v_mfma_f32_16x16x32_bf16 v[62:65], v[166:169], v[198:201], v[62:65]
	v_mfma_f32_16x16x32_bf16 v[54:57], v[174:177], v[198:201], v[54:57]
	v_mfma_f32_16x16x32_bf16 v[46:49], v[166:169], v[206:209], v[46:49]
	v_mfma_f32_16x16x32_bf16 v[38:41], v[174:177], v[206:209], v[38:41]
	v_mfma_f32_16x16x32_bf16 v[30:33], v[166:169], v[214:217], v[30:33]
	v_mfma_f32_16x16x32_bf16 v[22:25], v[174:177], v[214:217], v[22:25]
	v_mfma_f32_16x16x32_bf16 v[14:17], v[166:169], v[222:225], v[14:17]
	v_mfma_f32_16x16x32_bf16 v[6:9], v[174:177], v[222:225], v[6:9]
	v_mfma_f32_16x16x32_bf16 v[62:65], v[170:173], v[202:205], v[62:65]
	v_mfma_f32_16x16x32_bf16 v[54:57], v[178:181], v[202:205], v[54:57]
	v_mfma_f32_16x16x32_bf16 v[46:49], v[170:173], v[210:213], v[46:49]
	v_mfma_f32_16x16x32_bf16 v[38:41], v[178:181], v[210:213], v[38:41]
	v_mfma_f32_16x16x32_bf16 v[30:33], v[170:173], v[218:221], v[30:33]
	v_mfma_f32_16x16x32_bf16 v[22:25], v[178:181], v[218:221], v[22:25]
	v_mfma_f32_16x16x32_bf16 v[14:17], v[170:173], v[226:229], v[14:17]
	v_mfma_f32_16x16x32_bf16 v[6:9], v[178:181], v[226:229], v[6:9]
	s_setprio 0
	s_setprio 1
	v_mfma_f32_16x16x32_bf16 v[58:61], v[182:185], v[198:201], v[58:61]
	v_mfma_f32_16x16x32_bf16 v[50:53], v[190:193], v[198:201], v[50:53]
	v_mfma_f32_16x16x32_bf16 v[42:45], v[182:185], v[206:209], v[42:45]
	v_mfma_f32_16x16x32_bf16 v[34:37], v[190:193], v[206:209], v[34:37]
	v_mfma_f32_16x16x32_bf16 v[26:29], v[182:185], v[214:217], v[26:29]
	v_mfma_f32_16x16x32_bf16 v[18:21], v[190:193], v[214:217], v[18:21]
	v_mfma_f32_16x16x32_bf16 v[10:13], v[182:185], v[222:225], v[10:13]
	v_mfma_f32_16x16x32_bf16 v[2:5], v[190:193], v[222:225], v[2:5]
	v_mfma_f32_16x16x32_bf16 v[58:61], v[186:189], v[202:205], v[58:61]
	v_mfma_f32_16x16x32_bf16 v[50:53], v[194:197], v[202:205], v[50:53]
	v_mfma_f32_16x16x32_bf16 v[42:45], v[186:189], v[210:213], v[42:45]
	v_mfma_f32_16x16x32_bf16 v[34:37], v[194:197], v[210:213], v[34:37]
	v_mfma_f32_16x16x32_bf16 v[26:29], v[186:189], v[218:221], v[26:29]
	v_mfma_f32_16x16x32_bf16 v[18:21], v[194:197], v[218:221], v[18:21]
	v_mfma_f32_16x16x32_bf16 v[10:13], v[186:189], v[226:229], v[10:13]
	v_mfma_f32_16x16x32_bf16 v[2:5], v[194:197], v[226:229], v[2:5]
	s_barrier
	s_setprio 0
	s_mov_b32 s8, s9
	s_add_u32 s88, s88, 0x100
	s_addc_u32 s89, s89, 0
	s_add_u32 s86, s86, 0x100
	s_addc_u32 s87, s87, 0
	s_cmp_ge_i32 s9, s101
	s_cbranch_scc1 .Lmy_kexit_1
.LBB0_310:
	s_add_u32 s98, s86, 0x100
	s_addc_u32 s99, s87, 0
	s_cmp_eq_u32 s8, s100
	s_cselect_b64 s[94:95], s[90:91], s[98:99]
	s_cselect_b64 s[96:97], s[92:93], s[88:89]
	s_add_i32 s9, s8, 2
	s_add_i32 m0, s55, 0xc000
	ds_read_b128 v[166:169], v230
	global_load_lds_dwordx4 v144, s[86:87]
	s_add_i32 m0, s55, 0xe000
	ds_read_b128 v[170:173], v230 offset:1024
	global_load_lds_dwordx4 v142, s[86:87]
	ds_read_b128 v[174:177], v230 offset:2048
	ds_read_b128 v[178:181], v230 offset:3072
	ds_read_b128 v[182:185], v231
	ds_read_b128 v[186:189], v231 offset:1024
	ds_read_b128 v[190:193], v231 offset:2048
	ds_read_b128 v[194:197], v231 offset:3072
	ds_read_b128 v[198:201], v163
	ds_read_b128 v[202:205], v163 offset:1024
	ds_read_b128 v[206:209], v163 offset:2048
	ds_read_b128 v[210:213], v163 offset:3072
	ds_read_b128 v[214:217], v163 offset:4096
	ds_read_b128 v[218:221], v163 offset:5120
	ds_read_b128 v[222:225], v163 offset:6144
	ds_read_b128 v[226:229], v163 offset:7168
	s_waitcnt vmcnt(8)
	s_waitcnt lgkmcnt(0)
	s_setprio 1
	s_barrier
	v_mfma_f32_16x16x32_bf16 v[122:125], v[166:169], v[198:201], v[122:125]
	v_mfma_f32_16x16x32_bf16 v[118:121], v[174:177], v[198:201], v[118:121]
	v_mfma_f32_16x16x32_bf16 v[110:113], v[166:169], v[206:209], v[110:113]
	v_mfma_f32_16x16x32_bf16 v[102:105], v[174:177], v[206:209], v[102:105]
	v_mfma_f32_16x16x32_bf16 v[94:97], v[166:169], v[214:217], v[94:97]
	v_mfma_f32_16x16x32_bf16 v[86:89], v[174:177], v[214:217], v[86:89]
	v_mfma_f32_16x16x32_bf16 v[78:81], v[166:169], v[222:225], v[78:81]
	v_mfma_f32_16x16x32_bf16 v[70:73], v[174:177], v[222:225], v[70:73]
	v_mfma_f32_16x16x32_bf16 v[122:125], v[170:173], v[202:205], v[122:125]
	v_mfma_f32_16x16x32_bf16 v[118:121], v[178:181], v[202:205], v[118:121]
	v_mfma_f32_16x16x32_bf16 v[110:113], v[170:173], v[210:213], v[110:113]
	v_mfma_f32_16x16x32_bf16 v[102:105], v[178:181], v[210:213], v[102:105]
	v_mfma_f32_16x16x32_bf16 v[94:97], v[170:173], v[218:221], v[94:97]
	v_mfma_f32_16x16x32_bf16 v[86:89], v[178:181], v[218:221], v[86:89]
	v_mfma_f32_16x16x32_bf16 v[78:81], v[170:173], v[226:229], v[78:81]
	v_mfma_f32_16x16x32_bf16 v[70:73], v[178:181], v[226:229], v[70:73]
	s_setprio 0
	s_setprio 1
	v_mfma_f32_16x16x32_bf16 v[126:129], v[182:185], v[198:201], v[126:129]
	v_mfma_f32_16x16x32_bf16 v[114:117], v[190:193], v[198:201], v[114:117]
	v_mfma_f32_16x16x32_bf16 v[106:109], v[182:185], v[206:209], v[106:109]
	v_mfma_f32_16x16x32_bf16 v[98:101], v[190:193], v[206:209], v[98:101]
	v_mfma_f32_16x16x32_bf16 v[90:93], v[182:185], v[214:217], v[90:93]
	v_mfma_f32_16x16x32_bf16 v[82:85], v[190:193], v[214:217], v[82:85]
	v_mfma_f32_16x16x32_bf16 v[74:77], v[182:185], v[222:225], v[74:77]
	v_mfma_f32_16x16x32_bf16 v[66:69], v[190:193], v[222:225], v[66:69]
	v_mfma_f32_16x16x32_bf16 v[126:129], v[186:189], v[202:205], v[126:129]
	v_mfma_f32_16x16x32_bf16 v[114:117], v[194:197], v[202:205], v[114:117]
	v_mfma_f32_16x16x32_bf16 v[106:109], v[186:189], v[210:213], v[106:109]
	v_mfma_f32_16x16x32_bf16 v[98:101], v[194:197], v[210:213], v[98:101]
	v_mfma_f32_16x16x32_bf16 v[90:93], v[186:189], v[218:221], v[90:93]
	v_mfma_f32_16x16x32_bf16 v[82:85], v[194:197], v[218:221], v[82:85]
	v_mfma_f32_16x16x32_bf16 v[74:77], v[186:189], v[226:229], v[74:77]
	v_mfma_f32_16x16x32_bf16 v[66:69], v[194:197], v[226:229], v[66:69]
	s_barrier
	s_setprio 0
	s_add_u32 s98, s96, 0xb0000
	s_addc_u32 s99, s97, 0
	s_add_i32 s8, s69, s54
	s_mov_b32 m0, s8
	ds_read_b128 v[198:201], v163 offset:16384
	global_load_lds_dwordx4 v132, s[96:97]
	s_add_i32 m0, s8, 0x2000
	s_add_i32 s8, s72, s54
	global_load_lds_dwordx4 v136, s[96:97]
	s_mov_b32 m0, s8
	ds_read_b128 v[202:205], v163 offset:17408
	global_load_lds_dwordx4 v132, s[98:99]
	s_add_i32 m0, s8, 0x2000
	ds_read_b128 v[206:209], v163 offset:18432
	global_load_lds_dwordx4 v136, s[98:99]
	s_mov_b32 m0, s55
	ds_read_b128 v[210:213], v163 offset:19456
	global_load_lds_dwordx4 v130, s[94:95]
	s_mov_b32 m0, s56
	ds_read_b128 v[214:217], v163 offset:20480
	global_load_lds_dwordx4 v134, s[94:95]
	ds_read_b128 v[218:221], v163 offset:21504
	ds_read_b128 v[222:225], v163 offset:22528
	ds_read_b128 v[226:229], v163 offset:23552
	s_waitcnt vmcnt(8)
	s_waitcnt lgkmcnt(0)
	s_setprio 1
	s_barrier
	v_mfma_f32_16x16x32_bf16 v[62:65], v[166:169], v[198:201], v[62:65]
	v_mfma_f32_16x16x32_bf16 v[54:57], v[174:177], v[198:201], v[54:57]
	v_mfma_f32_16x16x32_bf16 v[46:49], v[166:169], v[206:209], v[46:49]
	v_mfma_f32_16x16x32_bf16 v[38:41], v[174:177], v[206:209], v[38:41]
	v_mfma_f32_16x16x32_bf16 v[30:33], v[166:169], v[214:217], v[30:33]
	v_mfma_f32_16x16x32_bf16 v[22:25], v[174:177], v[214:217], v[22:25]
	v_mfma_f32_16x16x32_bf16 v[14:17], v[166:169], v[222:225], v[14:17]
	v_mfma_f32_16x16x32_bf16 v[6:9], v[174:177], v[222:225], v[6:9]
	v_mfma_f32_16x16x32_bf16 v[62:65], v[170:173], v[202:205], v[62:65]
	v_mfma_f32_16x16x32_bf16 v[54:57], v[178:181], v[202:205], v[54:57]
	v_mfma_f32_16x16x32_bf16 v[46:49], v[170:173], v[210:213], v[46:49]
	v_mfma_f32_16x16x32_bf16 v[38:41], v[178:181], v[210:213], v[38:41]
	v_mfma_f32_16x16x32_bf16 v[30:33], v[170:173], v[218:221], v[30:33]
	v_mfma_f32_16x16x32_bf16 v[22:25], v[178:181], v[218:221], v[22:25]
	v_mfma_f32_16x16x32_bf16 v[14:17], v[170:173], v[226:229], v[14:17]
	v_mfma_f32_16x16x32_bf16 v[6:9], v[178:181], v[226:229], v[6:9]
	s_setprio 0
	s_setprio 1
	v_mfma_f32_16x16x32_bf16 v[58:61], v[182:185], v[198:201], v[58:61]
	v_mfma_f32_16x16x32_bf16 v[50:53], v[190:193], v[198:201], v[50:53]
	v_mfma_f32_16x16x32_bf16 v[42:45], v[182:185], v[206:209], v[42:45]
	v_mfma_f32_16x16x32_bf16 v[34:37], v[190:193], v[206:209], v[34:37]
	v_mfma_f32_16x16x32_bf16 v[26:29], v[182:185], v[214:217], v[26:29]
	v_mfma_f32_16x16x32_bf16 v[18:21], v[190:193], v[214:217], v[18:21]
	v_mfma_f32_16x16x32_bf16 v[10:13], v[182:185], v[222:225], v[10:13]
	v_mfma_f32_16x16x32_bf16 v[2:5], v[190:193], v[222:225], v[2:5]
	v_mfma_f32_16x16x32_bf16 v[58:61], v[186:189], v[202:205], v[58:61]
	v_mfma_f32_16x16x32_bf16 v[50:53], v[194:197], v[202:205], v[50:53]
	v_mfma_f32_16x16x32_bf16 v[42:45], v[186:189], v[210:213], v[42:45]
	v_mfma_f32_16x16x32_bf16 v[34:37], v[194:197], v[210:213], v[34:37]
	v_mfma_f32_16x16x32_bf16 v[26:29], v[186:189], v[218:221], v[26:29]
	v_mfma_f32_16x16x32_bf16 v[18:21], v[194:197], v[218:221], v[18:21]
	v_mfma_f32_16x16x32_bf16 v[10:13], v[186:189], v[226:229], v[10:13]
	v_mfma_f32_16x16x32_bf16 v[2:5], v[194:197], v[226:229], v[2:5]
	s_barrier
	s_setprio 0
	s_add_u32 s98, s94, 0xb0000
	s_addc_u32 s99, s95, 0
	s_add_i32 s8, 0, 0x18000
	s_add_i32 s50, 0, 0x1c000
	s_mov_b32 m0, s57
	ds_read_b128 v[166:169], v232
	global_load_lds_dwordx4 v130, s[98:99]
	s_mov_b32 m0, s58
	ds_read_b128 v[170:173], v232 offset:1024
	global_load_lds_dwordx4 v134, s[98:99]
	ds_read_b128 v[174:177], v232 offset:2048
	ds_read_b128 v[178:181], v232 offset:3072
	ds_read_b128 v[182:185], v233
	ds_read_b128 v[186:189], v233 offset:1024
	ds_read_b128 v[190:193], v233 offset:2048
	ds_read_b128 v[194:197], v233 offset:3072
	ds_read_b128 v[198:201], v163 offset:32768
	ds_read_b128 v[202:205], v163 offset:33792
	ds_read_b128 v[206:209], v163 offset:34816
	ds_read_b128 v[210:213], v163 offset:35840
	ds_read_b128 v[214:217], v163 offset:36864
	ds_read_b128 v[218:221], v163 offset:37888
	ds_read_b128 v[222:225], v163 offset:38912
	ds_read_b128 v[226:229], v163 offset:39936
	s_waitcnt vmcnt(8)
	s_waitcnt lgkmcnt(0)
	s_setprio 1
	s_barrier
	v_mfma_f32_16x16x32_bf16 v[122:125], v[166:169], v[198:201], v[122:125]
	v_mfma_f32_16x16x32_bf16 v[118:121], v[174:177], v[198:201], v[118:121]
	v_mfma_f32_16x16x32_bf16 v[110:113], v[166:169], v[206:209], v[110:113]
	v_mfma_f32_16x16x32_bf16 v[102:105], v[174:177], v[206:209], v[102:105]
	v_mfma_f32_16x16x32_bf16 v[94:97], v[166:169], v[214:217], v[94:97]
	v_mfma_f32_16x16x32_bf16 v[86:89], v[174:177], v[214:217], v[86:89]
	v_mfma_f32_16x16x32_bf16 v[78:81], v[166:169], v[222:225], v[78:81]
	v_mfma_f32_16x16x32_bf16 v[70:73], v[174:177], v[222:225], v[70:73]
	v_mfma_f32_16x16x32_bf16 v[122:125], v[170:173], v[202:205], v[122:125]
	v_mfma_f32_16x16x32_bf16 v[118:121], v[178:181], v[202:205], v[118:121]
	v_mfma_f32_16x16x32_bf16 v[110:113], v[170:173], v[210:213], v[110:113]
	v_mfma_f32_16x16x32_bf16 v[102:105], v[178:181], v[210:213], v[102:105]
	v_mfma_f32_16x16x32_bf16 v[94:97], v[170:173], v[218:221], v[94:97]
	v_mfma_f32_16x16x32_bf16 v[86:89], v[178:181], v[218:221], v[86:89]
	v_mfma_f32_16x16x32_bf16 v[78:81], v[170:173], v[226:229], v[78:81]
	v_mfma_f32_16x16x32_bf16 v[70:73], v[178:181], v[226:229], v[70:73]
	s_setprio 0
	s_setprio 1
	v_mfma_f32_16x16x32_bf16 v[126:129], v[182:185], v[198:201], v[126:129]
	v_mfma_f32_16x16x32_bf16 v[114:117], v[190:193], v[198:201], v[114:117]
	v_mfma_f32_16x16x32_bf16 v[106:109], v[182:185], v[206:209], v[106:109]
	v_mfma_f32_16x16x32_bf16 v[98:101], v[190:193], v[206:209], v[98:101]
	v_mfma_f32_16x16x32_bf16 v[90:93], v[182:185], v[214:217], v[90:93]
	v_mfma_f32_16x16x32_bf16 v[82:85], v[190:193], v[214:217], v[82:85]
	v_mfma_f32_16x16x32_bf16 v[74:77], v[182:185], v[222:225], v[74:77]
	v_mfma_f32_16x16x32_bf16 v[66:69], v[190:193], v[222:225], v[66:69]
	v_mfma_f32_16x16x32_bf16 v[126:129], v[186:189], v[202:205], v[126:129]
	v_mfma_f32_16x16x32_bf16 v[114:117], v[194:197], v[202:205], v[114:117]
	v_mfma_f32_16x16x32_bf16 v[106:109], v[186:189], v[210:213], v[106:109]
	v_mfma_f32_16x16x32_bf16 v[98:101], v[194:197], v[210:213], v[98:101]
	v_mfma_f32_16x16x32_bf16 v[90:93], v[186:189], v[218:221], v[90:93]
	v_mfma_f32_16x16x32_bf16 v[82:85], v[194:197], v[218:221], v[82:85]
	v_mfma_f32_16x16x32_bf16 v[74:77], v[186:189], v[226:229], v[74:77]
	v_mfma_f32_16x16x32_bf16 v[66:69], v[194:197], v[226:229], v[66:69]
	s_barrier
	s_setprio 0
	s_add_u32 s96, s96, 0x80
	s_addc_u32 s97, s97, 0
	s_add_u32 s98, s96, 0xb0000
	s_addc_u32 s99, s97, 0
	s_add_u32 s94, s94, 0x80
	s_addc_u32 s95, s95, 0
	s_add_i32 s8, s8, s54
	s_mov_b32 m0, s8
	ds_read_b128 v[198:201], v163 offset:49152
	global_load_lds_dwordx4 v132, s[96:97]
	s_add_i32 m0, s8, 0x2000
	s_add_i32 s8, s50, s54
	global_load_lds_dwordx4 v136, s[96:97]
	s_mov_b32 m0, s8
	ds_read_b128 v[202:205], v163 offset:50176
	global_load_lds_dwordx4 v132, s[98:99]
	s_add_i32 m0, s8, 0x2000
	ds_read_b128 v[206:209], v163 offset:51200
	global_load_lds_dwordx4 v136, s[98:99]
	s_mov_b32 m0, s64
	ds_read_b128 v[210:213], v163 offset:52224
	global_load_lds_dwordx4 v130, s[94:95]
	s_mov_b32 m0, s65
	ds_read_b128 v[214:217], v163 offset:53248
	global_load_lds_dwordx4 v134, s[94:95]
	ds_read_b128 v[218:221], v163 offset:54272
	ds_read_b128 v[222:225], v163 offset:55296
	ds_read_b128 v[226:229], v163 offset:56320
	s_waitcnt vmcnt(8)
	s_waitcnt lgkmcnt(0)
	s_setprio 1
	s_barrier
	v_mfma_f32_16x16x32_bf16 v[62:65], v[166:169], v[198:201], v[62:65]
	v_mfma_f32_16x16x32_bf16 v[54:57], v[174:177], v[198:201], v[54:57]
	v_mfma_f32_16x16x32_bf16 v[46:49], v[166:169], v[206:209], v[46:49]
	v_mfma_f32_16x16x32_bf16 v[38:41], v[174:177], v[206:209], v[38:41]
	v_mfma_f32_16x16x32_bf16 v[30:33], v[166:169], v[214:217], v[30:33]
	v_mfma_f32_16x16x32_bf16 v[22:25], v[174:177], v[214:217], v[22:25]
	v_mfma_f32_16x16x32_bf16 v[14:17], v[166:169], v[222:225], v[14:17]
	v_mfma_f32_16x16x32_bf16 v[6:9], v[174:177], v[222:225], v[6:9]
	v_mfma_f32_16x16x32_bf16 v[62:65], v[170:173], v[202:205], v[62:65]
	v_mfma_f32_16x16x32_bf16 v[54:57], v[178:181], v[202:205], v[54:57]
	v_mfma_f32_16x16x32_bf16 v[46:49], v[170:173], v[210:213], v[46:49]
	v_mfma_f32_16x16x32_bf16 v[38:41], v[178:181], v[210:213], v[38:41]
	v_mfma_f32_16x16x32_bf16 v[30:33], v[170:173], v[218:221], v[30:33]
	v_mfma_f32_16x16x32_bf16 v[22:25], v[178:181], v[218:221], v[22:25]
	v_mfma_f32_16x16x32_bf16 v[14:17], v[170:173], v[226:229], v[14:17]
	v_mfma_f32_16x16x32_bf16 v[6:9], v[178:181], v[226:229], v[6:9]
	s_setprio 0
	s_setprio 1
	v_mfma_f32_16x16x32_bf16 v[58:61], v[182:185], v[198:201], v[58:61]
	v_mfma_f32_16x16x32_bf16 v[50:53], v[190:193], v[198:201], v[50:53]
	v_mfma_f32_16x16x32_bf16 v[42:45], v[182:185], v[206:209], v[42:45]
	v_mfma_f32_16x16x32_bf16 v[34:37], v[190:193], v[206:209], v[34:37]
	v_mfma_f32_16x16x32_bf16 v[26:29], v[182:185], v[214:217], v[26:29]
	v_mfma_f32_16x16x32_bf16 v[18:21], v[190:193], v[214:217], v[18:21]
	v_mfma_f32_16x16x32_bf16 v[10:13], v[182:185], v[222:225], v[10:13]
	v_mfma_f32_16x16x32_bf16 v[2:5], v[190:193], v[222:225], v[2:5]
	v_mfma_f32_16x16x32_bf16 v[58:61], v[186:189], v[202:205], v[58:61]
	v_mfma_f32_16x16x32_bf16 v[50:53], v[194:197], v[202:205], v[50:53]
	v_mfma_f32_16x16x32_bf16 v[42:45], v[186:189], v[210:213], v[42:45]
	v_mfma_f32_16x16x32_bf16 v[34:37], v[194:197], v[210:213], v[34:37]
	v_mfma_f32_16x16x32_bf16 v[26:29], v[186:189], v[218:221], v[26:29]
	v_mfma_f32_16x16x32_bf16 v[18:21], v[194:197], v[218:221], v[18:21]
	v_mfma_f32_16x16x32_bf16 v[10:13], v[186:189], v[226:229], v[10:13]
	v_mfma_f32_16x16x32_bf16 v[2:5], v[194:197], v[226:229], v[2:5]
	s_barrier
	s_setprio 0
	s_mov_b32 s8, s9
	s_add_u32 s88, s88, 0x100
	s_addc_u32 s89, s89, 0
	s_add_u32 s86, s86, 0x100
	s_addc_u32 s87, s87, 0
	s_cmp_ge_i32 s9, s101
	s_cbranch_scc0 .LBB0_310

.Lmy_nb_2:
	s_nop 0
	v_readfirstlane_b32 s86, v154
	v_readfirstlane_b32 s87, v155
	v_readfirstlane_b32 s88, v152
	v_readfirstlane_b32 s89, v153
	v_readfirstlane_b32 s90, v148
	v_readfirstlane_b32 s91, v149
	v_readfirstlane_b32 s92, v150
	v_readfirstlane_b32 s93, v151
	v_readfirstlane_b32 s100, v138
	v_readfirstlane_b32 s101, v141
	v_add_u32_e32 v230, s77, v160
	v_add_u32_e32 v231, s78, v160
	v_add_u32_e32 v232, 0x18000, v160
	v_add_u32_e32 v233, 0x1c000, v160
	s_add_u32 s98, s86, 0xfffc0080
	s_addc_u32 s99, s87, -1
	s_cmp_eq_u32 s7, s100
	s_cselect_b64 s[94:95], s[90:91], s[98:99]
	s_cselect_b64 s[96:97], s[92:93], s[88:89]
	s_add_i32 s45, s7, 2
	s_add_i32 m0, s49, 0xc000
	ds_read_b128 v[156:159], v230
	global_load_lds_dwordx4 v144, s[86:87]
	s_add_i32 m0, s49, 0xe000
	ds_read_b128 v[166:169], v230 offset:1024
	global_load_lds_dwordx4 v142, s[86:87]
	ds_read_b128 v[170:173], v230 offset:2048
	ds_read_b128 v[174:177], v230 offset:3072
	ds_read_b128 v[178:181], v231
	ds_read_b128 v[182:185], v231 offset:1024
	ds_read_b128 v[186:189], v231 offset:2048
	ds_read_b128 v[190:193], v231 offset:3072
	ds_read_b128 v[194:197], v163
	ds_read_b128 v[198:201], v163 offset:1024
	ds_read_b128 v[202:205], v163 offset:2048
	ds_read_b128 v[206:209], v163 offset:3072
	ds_read_b128 v[210:213], v163 offset:4096
	ds_read_b128 v[214:217], v163 offset:5120
	ds_read_b128 v[218:221], v163 offset:6144
	ds_read_b128 v[222:225], v163 offset:7168
	s_waitcnt vmcnt(8)
	s_waitcnt lgkmcnt(0)
	s_setprio 1
	s_barrier
	v_mfma_f32_16x16x32_bf16 v[122:125], v[156:159], v[194:197], 0
	v_mfma_f32_16x16x32_bf16 v[118:121], v[170:173], v[194:197], 0
	v_mfma_f32_16x16x32_bf16 v[110:113], v[156:159], v[202:205], 0
	v_mfma_f32_16x16x32_bf16 v[102:105], v[170:173], v[202:205], 0
	v_mfma_f32_16x16x32_bf16 v[94:97], v[156:159], v[210:213], 0
	v_mfma_f32_16x16x32_bf16 v[86:89], v[170:173], v[210:213], 0
	v_mfma_f32_16x16x32_bf16 v[78:81], v[156:159], v[218:221], 0
	v_mfma_f32_16x16x32_bf16 v[70:73], v[170:173], v[218:221], 0
	v_mfma_f32_16x16x32_bf16 v[122:125], v[166:169], v[198:201], v[122:125]
	v_mfma_f32_16x16x32_bf16 v[118:121], v[174:177], v[198:201], v[118:121]
	v_mfma_f32_16x16x32_bf16 v[110:113], v[166:169], v[206:209], v[110:113]
	v_mfma_f32_16x16x32_bf16 v[102:105], v[174:177], v[206:209], v[102:105]
	v_mfma_f32_16x16x32_bf16 v[94:97], v[166:169], v[214:217], v[94:97]
	v_mfma_f32_16x16x32_bf16 v[86:89], v[174:177], v[214:217], v[86:89]
	v_mfma_f32_16x16x32_bf16 v[78:81], v[166:169], v[222:225], v[78:81]
	v_mfma_f32_16x16x32_bf16 v[70:73], v[174:177], v[222:225], v[70:73]
	s_setprio 0
	s_setprio 1
	v_mfma_f32_16x16x32_bf16 v[126:129], v[178:181], v[194:197], 0
	v_mfma_f32_16x16x32_bf16 v[114:117], v[186:189], v[194:197], 0
	v_mfma_f32_16x16x32_bf16 v[106:109], v[178:181], v[202:205], 0
	v_mfma_f32_16x16x32_bf16 v[98:101], v[186:189], v[202:205], 0
	v_mfma_f32_16x16x32_bf16 v[90:93], v[178:181], v[210:213], 0
	v_mfma_f32_16x16x32_bf16 v[82:85], v[186:189], v[210:213], 0
	v_mfma_f32_16x16x32_bf16 v[74:77], v[178:181], v[218:221], 0
	v_mfma_f32_16x16x32_bf16 v[66:69], v[186:189], v[218:221], 0
	v_mfma_f32_16x16x32_bf16 v[126:129], v[182:185], v[198:201], v[126:129]
	v_mfma_f32_16x16x32_bf16 v[114:117], v[190:193], v[198:201], v[114:117]
	v_mfma_f32_16x16x32_bf16 v[106:109], v[182:185], v[206:209], v[106:109]
	v_mfma_f32_16x16x32_bf16 v[98:101], v[190:193], v[206:209], v[98:101]
	v_mfma_f32_16x16x32_bf16 v[90:93], v[182:185], v[214:217], v[90:93]
	v_mfma_f32_16x16x32_bf16 v[82:85], v[190:193], v[214:217], v[82:85]
	v_mfma_f32_16x16x32_bf16 v[74:77], v[182:185], v[222:225], v[74:77]
	v_mfma_f32_16x16x32_bf16 v[66:69], v[190:193], v[222:225], v[66:69]
	s_barrier
	s_setprio 0
	s_add_u32 s98, s96, 0x40000
	s_addc_u32 s99, s97, 0
	s_add_i32 s7, s77, s25
	s_mov_b32 m0, s7
	ds_read_b128 v[194:197], v163 offset:16384
	global_load_lds_dwordx4 v132, s[96:97]
	s_add_i32 m0, s7, 0x2000
	s_add_i32 s7, s78, s25
	global_load_lds_dwordx4 v136, s[96:97]
	s_mov_b32 m0, s7
	ds_read_b128 v[198:201], v163 offset:17408
	global_load_lds_dwordx4 v132, s[98:99]
	s_add_i32 m0, s7, 0x2000
	ds_read_b128 v[202:205], v163 offset:18432
	global_load_lds_dwordx4 v136, s[98:99]
	s_mov_b32 m0, s49
	ds_read_b128 v[206:209], v163 offset:19456
	global_load_lds_dwordx4 v130, s[94:95]
	s_mov_b32 m0, s58
	ds_read_b128 v[210:213], v163 offset:20480
	global_load_lds_dwordx4 v134, s[94:95]
	ds_read_b128 v[214:217], v163 offset:21504
	ds_read_b128 v[218:221], v163 offset:22528
	ds_read_b128 v[222:225], v163 offset:23552
	s_waitcnt vmcnt(8)
	s_waitcnt lgkmcnt(0)
	s_setprio 1
	s_barrier
	v_mfma_f32_16x16x32_bf16 v[62:65], v[156:159], v[194:197], 0
	v_mfma_f32_16x16x32_bf16 v[54:57], v[170:173], v[194:197], 0
	v_mfma_f32_16x16x32_bf16 v[46:49], v[156:159], v[202:205], 0
	v_mfma_f32_16x16x32_bf16 v[38:41], v[170:173], v[202:205], 0
	v_mfma_f32_16x16x32_bf16 v[30:33], v[156:159], v[210:213], 0
	v_mfma_f32_16x16x32_bf16 v[22:25], v[170:173], v[210:213], 0
	v_mfma_f32_16x16x32_bf16 v[14:17], v[156:159], v[218:221], 0
	v_mfma_f32_16x16x32_bf16 v[6:9], v[170:173], v[218:221], 0
	v_mfma_f32_16x16x32_bf16 v[62:65], v[166:169], v[198:201], v[62:65]
	v_mfma_f32_16x16x32_bf16 v[54:57], v[174:177], v[198:201], v[54:57]
	v_mfma_f32_16x16x32_bf16 v[46:49], v[166:169], v[206:209], v[46:49]
	v_mfma_f32_16x16x32_bf16 v[38:41], v[174:177], v[206:209], v[38:41]
	v_mfma_f32_16x16x32_bf16 v[30:33], v[166:169], v[214:217], v[30:33]
	v_mfma_f32_16x16x32_bf16 v[22:25], v[174:177], v[214:217], v[22:25]
	v_mfma_f32_16x16x32_bf16 v[14:17], v[166:169], v[222:225], v[14:17]
	v_mfma_f32_16x16x32_bf16 v[6:9], v[174:177], v[222:225], v[6:9]
	s_setprio 0
	s_setprio 1
	v_mfma_f32_16x16x32_bf16 v[58:61], v[178:181], v[194:197], 0
	v_mfma_f32_16x16x32_bf16 v[50:53], v[186:189], v[194:197], 0
	v_mfma_f32_16x16x32_bf16 v[42:45], v[178:181], v[202:205], 0
	v_mfma_f32_16x16x32_bf16 v[34:37], v[186:189], v[202:205], 0
	v_mfma_f32_16x16x32_bf16 v[26:29], v[178:181], v[210:213], 0
	v_mfma_f32_16x16x32_bf16 v[18:21], v[186:189], v[210:213], 0
	v_mfma_f32_16x16x32_bf16 v[10:13], v[178:181], v[218:221], 0
	v_mfma_f32_16x16x32_bf16 v[2:5], v[186:189], v[218:221], 0
	v_mfma_f32_16x16x32_bf16 v[58:61], v[182:185], v[198:201], v[58:61]
	v_mfma_f32_16x16x32_bf16 v[50:53], v[190:193], v[198:201], v[50:53]
	v_mfma_f32_16x16x32_bf16 v[42:45], v[182:185], v[206:209], v[42:45]
	v_mfma_f32_16x16x32_bf16 v[34:37], v[190:193], v[206:209], v[34:37]
	v_mfma_f32_16x16x32_bf16 v[26:29], v[182:185], v[214:217], v[26:29]
	v_mfma_f32_16x16x32_bf16 v[18:21], v[190:193], v[214:217], v[18:21]
	v_mfma_f32_16x16x32_bf16 v[10:13], v[182:185], v[222:225], v[10:13]
	v_mfma_f32_16x16x32_bf16 v[2:5], v[190:193], v[222:225], v[2:5]
	s_barrier
	s_setprio 0
	s_add_u32 s98, s94, 0x40000
	s_addc_u32 s99, s95, 0
	s_add_i32 s7, 0, 0x18000
	s_add_i32 s47, 0, 0x1c000
	s_mov_b32 m0, s59
	ds_read_b128 v[156:159], v232
	global_load_lds_dwordx4 v130, s[98:99]
	s_mov_b32 m0, s60
	ds_read_b128 v[166:169], v232 offset:1024
	global_load_lds_dwordx4 v134, s[98:99]
	ds_read_b128 v[170:173], v232 offset:2048
	ds_read_b128 v[174:177], v232 offset:3072
	ds_read_b128 v[178:181], v233
	ds_read_b128 v[182:185], v233 offset:1024
	ds_read_b128 v[186:189], v233 offset:2048
	ds_read_b128 v[190:193], v233 offset:3072
	ds_read_b128 v[194:197], v163 offset:32768
	ds_read_b128 v[198:201], v163 offset:33792
	ds_read_b128 v[202:205], v163 offset:34816
	ds_read_b128 v[206:209], v163 offset:35840
	ds_read_b128 v[210:213], v163 offset:36864
	ds_read_b128 v[214:217], v163 offset:37888
	ds_read_b128 v[218:221], v163 offset:38912
	ds_read_b128 v[222:225], v163 offset:39936
	s_waitcnt vmcnt(8)
	s_waitcnt lgkmcnt(0)
	s_setprio 1
	s_barrier
	v_mfma_f32_16x16x32_bf16 v[122:125], v[156:159], v[194:197], v[122:125]
	v_mfma_f32_16x16x32_bf16 v[118:121], v[170:173], v[194:197], v[118:121]
	v_mfma_f32_16x16x32_bf16 v[110:113], v[156:159], v[202:205], v[110:113]
	v_mfma_f32_16x16x32_bf16 v[102:105], v[170:173], v[202:205], v[102:105]
	v_mfma_f32_16x16x32_bf16 v[94:97], v[156:159], v[210:213], v[94:97]
	v_mfma_f32_16x16x32_bf16 v[86:89], v[170:173], v[210:213], v[86:89]
	v_mfma_f32_16x16x32_bf16 v[78:81], v[156:159], v[218:221], v[78:81]
	v_mfma_f32_16x16x32_bf16 v[70:73], v[170:173], v[218:221], v[70:73]
	v_mfma_f32_16x16x32_bf16 v[122:125], v[166:169], v[198:201], v[122:125]
	v_mfma_f32_16x16x32_bf16 v[118:121], v[174:177], v[198:201], v[118:121]
	v_mfma_f32_16x16x32_bf16 v[110:113], v[166:169], v[206:209], v[110:113]
	v_mfma_f32_16x16x32_bf16 v[102:105], v[174:177], v[206:209], v[102:105]
	v_mfma_f32_16x16x32_bf16 v[94:97], v[166:169], v[214:217], v[94:97]
	v_mfma_f32_16x16x32_bf16 v[86:89], v[174:177], v[214:217], v[86:89]
	v_mfma_f32_16x16x32_bf16 v[78:81], v[166:169], v[222:225], v[78:81]
	v_mfma_f32_16x16x32_bf16 v[70:73], v[174:177], v[222:225], v[70:73]
	s_setprio 0
	s_setprio 1
	v_mfma_f32_16x16x32_bf16 v[126:129], v[178:181], v[194:197], v[126:129]
	v_mfma_f32_16x16x32_bf16 v[114:117], v[186:189], v[194:197], v[114:117]
	v_mfma_f32_16x16x32_bf16 v[106:109], v[178:181], v[202:205], v[106:109]
	v_mfma_f32_16x16x32_bf16 v[98:101], v[186:189], v[202:205], v[98:101]
	v_mfma_f32_16x16x32_bf16 v[90:93], v[178:181], v[210:213], v[90:93]
	v_mfma_f32_16x16x32_bf16 v[82:85], v[186:189], v[210:213], v[82:85]
	v_mfma_f32_16x16x32_bf16 v[74:77], v[178:181], v[218:221], v[74:77]
	v_mfma_f32_16x16x32_bf16 v[66:69], v[186:189], v[218:221], v[66:69]
	v_mfma_f32_16x16x32_bf16 v[126:129], v[182:185], v[198:201], v[126:129]
	v_mfma_f32_16x16x32_bf16 v[114:117], v[190:193], v[198:201], v[114:117]
	v_mfma_f32_16x16x32_bf16 v[106:109], v[182:185], v[206:209], v[106:109]
	v_mfma_f32_16x16x32_bf16 v[98:101], v[190:193], v[206:209], v[98:101]
	v_mfma_f32_16x16x32_bf16 v[90:93], v[182:185], v[214:217], v[90:93]
	v_mfma_f32_16x16x32_bf16 v[82:85], v[190:193], v[214:217], v[82:85]
	v_mfma_f32_16x16x32_bf16 v[74:77], v[182:185], v[222:225], v[74:77]
	v_mfma_f32_16x16x32_bf16 v[66:69], v[190:193], v[222:225], v[66:69]
	s_barrier
	s_setprio 0
	s_add_u32 s96, s96, 0x80
	s_addc_u32 s97, s97, 0
	s_add_u32 s98, s96, 0x40000
	s_addc_u32 s99, s97, 0
	s_add_u32 s94, s94, 0x80
	s_addc_u32 s95, s95, 0
	s_add_i32 s7, s7, s25
	s_mov_b32 m0, s7
	ds_read_b128 v[194:197], v163 offset:49152
	global_load_lds_dwordx4 v132, s[96:97]
	s_add_i32 m0, s7, 0x2000
	s_add_i32 s7, s47, s25
	global_load_lds_dwordx4 v136, s[96:97]
	s_mov_b32 m0, s7
	ds_read_b128 v[198:201], v163 offset:50176
	global_load_lds_dwordx4 v132, s[98:99]
	s_add_i32 m0, s7, 0x2000
	ds_read_b128 v[202:205], v163 offset:51200
	global_load_lds_dwordx4 v136, s[98:99]
	s_mov_b32 m0, s66
	ds_read_b128 v[206:209], v163 offset:52224
	global_load_lds_dwordx4 v130, s[94:95]
	s_mov_b32 m0, s67
	ds_read_b128 v[210:213], v163 offset:53248
	global_load_lds_dwordx4 v134, s[94:95]
	ds_read_b128 v[214:217], v163 offset:54272
	ds_read_b128 v[218:221], v163 offset:55296
	ds_read_b128 v[222:225], v163 offset:56320
	s_waitcnt vmcnt(8)
	s_waitcnt lgkmcnt(0)
	s_setprio 1
	s_barrier
	v_mfma_f32_16x16x32_bf16 v[62:65], v[156:159], v[194:197], v[62:65]
	v_mfma_f32_16x16x32_bf16 v[54:57], v[170:173], v[194:197], v[54:57]
	v_mfma_f32_16x16x32_bf16 v[46:49], v[156:159], v[202:205], v[46:49]
	v_mfma_f32_16x16x32_bf16 v[38:41], v[170:173], v[202:205], v[38:41]
	v_mfma_f32_16x16x32_bf16 v[30:33], v[156:159], v[210:213], v[30:33]
	v_mfma_f32_16x16x32_bf16 v[22:25], v[170:173], v[210:213], v[22:25]
	v_mfma_f32_16x16x32_bf16 v[14:17], v[156:159], v[218:221], v[14:17]
	v_mfma_f32_16x16x32_bf16 v[6:9], v[170:173], v[218:221], v[6:9]
	v_mfma_f32_16x16x32_bf16 v[62:65], v[166:169], v[198:201], v[62:65]
	v_mfma_f32_16x16x32_bf16 v[54:57], v[174:177], v[198:201], v[54:57]
	v_mfma_f32_16x16x32_bf16 v[46:49], v[166:169], v[206:209], v[46:49]
	v_mfma_f32_16x16x32_bf16 v[38:41], v[174:177], v[206:209], v[38:41]
	v_mfma_f32_16x16x32_bf16 v[30:33], v[166:169], v[214:217], v[30:33]
	v_mfma_f32_16x16x32_bf16 v[22:25], v[174:177], v[214:217], v[22:25]
	v_mfma_f32_16x16x32_bf16 v[14:17], v[166:169], v[222:225], v[14:17]
	v_mfma_f32_16x16x32_bf16 v[6:9], v[174:177], v[222:225], v[6:9]
	s_setprio 0
	s_setprio 1
	v_mfma_f32_16x16x32_bf16 v[58:61], v[178:181], v[194:197], v[58:61]
	v_mfma_f32_16x16x32_bf16 v[50:53], v[186:189], v[194:197], v[50:53]
	v_mfma_f32_16x16x32_bf16 v[42:45], v[178:181], v[202:205], v[42:45]
	v_mfma_f32_16x16x32_bf16 v[34:37], v[186:189], v[202:205], v[34:37]
	v_mfma_f32_16x16x32_bf16 v[26:29], v[178:181], v[210:213], v[26:29]
	v_mfma_f32_16x16x32_bf16 v[18:21], v[186:189], v[210:213], v[18:21]
	v_mfma_f32_16x16x32_bf16 v[10:13], v[178:181], v[218:221], v[10:13]
	v_mfma_f32_16x16x32_bf16 v[2:5], v[186:189], v[218:221], v[2:5]
	v_mfma_f32_16x16x32_bf16 v[58:61], v[182:185], v[198:201], v[58:61]
	v_mfma_f32_16x16x32_bf16 v[50:53], v[190:193], v[198:201], v[50:53]
	v_mfma_f32_16x16x32_bf16 v[42:45], v[182:185], v[206:209], v[42:45]
	v_mfma_f32_16x16x32_bf16 v[34:37], v[190:193], v[206:209], v[34:37]
	v_mfma_f32_16x16x32_bf16 v[26:29], v[182:185], v[214:217], v[26:29]
	v_mfma_f32_16x16x32_bf16 v[18:21], v[190:193], v[214:217], v[18:21]
	v_mfma_f32_16x16x32_bf16 v[10:13], v[182:185], v[222:225], v[10:13]
	v_mfma_f32_16x16x32_bf16 v[2:5], v[190:193], v[222:225], v[2:5]
	s_barrier
	s_setprio 0
	s_mov_b32 s7, s45
	s_add_u32 s88, s88, 0x100
	s_addc_u32 s89, s89, 0
	s_add_u32 s86, s86, 0x100
	s_addc_u32 s87, s87, 0
	s_cmp_ge_i32 s45, s101
	s_cbranch_scc1 .Lmy_kexit_2
.LBB0_499:
	s_add_u32 s98, s86, 0xfffc0080
	s_addc_u32 s99, s87, -1
	s_cmp_eq_u32 s7, s100
	s_cselect_b64 s[94:95], s[90:91], s[98:99]
	s_cselect_b64 s[96:97], s[92:93], s[88:89]
	s_add_i32 s45, s7, 2
	s_add_i32 m0, s49, 0xc000
	ds_read_b128 v[156:159], v230
	global_load_lds_dwordx4 v144, s[86:87]
	s_add_i32 m0, s49, 0xe000
	ds_read_b128 v[166:169], v230 offset:1024
	global_load_lds_dwordx4 v142, s[86:87]
	ds_read_b128 v[170:173], v230 offset:2048
	ds_read_b128 v[174:177], v230 offset:3072
	ds_read_b128 v[178:181], v231
	ds_read_b128 v[182:185], v231 offset:1024
	ds_read_b128 v[186:189], v231 offset:2048
	ds_read_b128 v[190:193], v231 offset:3072
	ds_read_b128 v[194:197], v163
	ds_read_b128 v[198:201], v163 offset:1024
	ds_read_b128 v[202:205], v163 offset:2048
	ds_read_b128 v[206:209], v163 offset:3072
	ds_read_b128 v[210:213], v163 offset:4096
	ds_read_b128 v[214:217], v163 offset:5120
	ds_read_b128 v[218:221], v163 offset:6144
	ds_read_b128 v[222:225], v163 offset:7168
	s_waitcnt vmcnt(8)
	s_waitcnt lgkmcnt(0)
	s_setprio 1
	s_barrier
	v_mfma_f32_16x16x32_bf16 v[122:125], v[156:159], v[194:197], v[122:125]
	v_mfma_f32_16x16x32_bf16 v[118:121], v[170:173], v[194:197], v[118:121]
	v_mfma_f32_16x16x32_bf16 v[110:113], v[156:159], v[202:205], v[110:113]
	v_mfma_f32_16x16x32_bf16 v[102:105], v[170:173], v[202:205], v[102:105]
	v_mfma_f32_16x16x32_bf16 v[94:97], v[156:159], v[210:213], v[94:97]
	v_mfma_f32_16x16x32_bf16 v[86:89], v[170:173], v[210:213], v[86:89]
	v_mfma_f32_16x16x32_bf16 v[78:81], v[156:159], v[218:221], v[78:81]
	v_mfma_f32_16x16x32_bf16 v[70:73], v[170:173], v[218:221], v[70:73]
	v_mfma_f32_16x16x32_bf16 v[122:125], v[166:169], v[198:201], v[122:125]
	v_mfma_f32_16x16x32_bf16 v[118:121], v[174:177], v[198:201], v[118:121]
	v_mfma_f32_16x16x32_bf16 v[110:113], v[166:169], v[206:209], v[110:113]
	v_mfma_f32_16x16x32_bf16 v[102:105], v[174:177], v[206:209], v[102:105]
	v_mfma_f32_16x16x32_bf16 v[94:97], v[166:169], v[214:217], v[94:97]
	v_mfma_f32_16x16x32_bf16 v[86:89], v[174:177], v[214:217], v[86:89]
	v_mfma_f32_16x16x32_bf16 v[78:81], v[166:169], v[222:225], v[78:81]
	v_mfma_f32_16x16x32_bf16 v[70:73], v[174:177], v[222:225], v[70:73]
	s_setprio 0
	s_setprio 1
	v_mfma_f32_16x16x32_bf16 v[126:129], v[178:181], v[194:197], v[126:129]
	v_mfma_f32_16x16x32_bf16 v[114:117], v[186:189], v[194:197], v[114:117]
	v_mfma_f32_16x16x32_bf16 v[106:109], v[178:181], v[202:205], v[106:109]
	v_mfma_f32_16x16x32_bf16 v[98:101], v[186:189], v[202:205], v[98:101]
	v_mfma_f32_16x16x32_bf16 v[90:93], v[178:181], v[210:213], v[90:93]
	v_mfma_f32_16x16x32_bf16 v[82:85], v[186:189], v[210:213], v[82:85]
	v_mfma_f32_16x16x32_bf16 v[74:77], v[178:181], v[218:221], v[74:77]
	v_mfma_f32_16x16x32_bf16 v[66:69], v[186:189], v[218:221], v[66:69]
	v_mfma_f32_16x16x32_bf16 v[126:129], v[182:185], v[198:201], v[126:129]
	v_mfma_f32_16x16x32_bf16 v[114:117], v[190:193], v[198:201], v[114:117]
	v_mfma_f32_16x16x32_bf16 v[106:109], v[182:185], v[206:209], v[106:109]
	v_mfma_f32_16x16x32_bf16 v[98:101], v[190:193], v[206:209], v[98:101]
	v_mfma_f32_16x16x32_bf16 v[90:93], v[182:185], v[214:217], v[90:93]
	v_mfma_f32_16x16x32_bf16 v[82:85], v[190:193], v[214:217], v[82:85]
	v_mfma_f32_16x16x32_bf16 v[74:77], v[182:185], v[222:225], v[74:77]
	v_mfma_f32_16x16x32_bf16 v[66:69], v[190:193], v[222:225], v[66:69]
	s_barrier
	s_setprio 0
	s_add_u32 s98, s96, 0x40000
	s_addc_u32 s99, s97, 0
	s_add_i32 s7, s77, s25
	s_mov_b32 m0, s7
	ds_read_b128 v[194:197], v163 offset:16384
	global_load_lds_dwordx4 v132, s[96:97]
	s_add_i32 m0, s7, 0x2000
	s_add_i32 s7, s78, s25
	global_load_lds_dwordx4 v136, s[96:97]
	s_mov_b32 m0, s7
	ds_read_b128 v[198:201], v163 offset:17408
	global_load_lds_dwordx4 v132, s[98:99]
	s_add_i32 m0, s7, 0x2000
	ds_read_b128 v[202:205], v163 offset:18432
	global_load_lds_dwordx4 v136, s[98:99]
	s_mov_b32 m0, s49
	ds_read_b128 v[206:209], v163 offset:19456
	global_load_lds_dwordx4 v130, s[94:95]
	s_mov_b32 m0, s58
	ds_read_b128 v[210:213], v163 offset:20480
	global_load_lds_dwordx4 v134, s[94:95]
	ds_read_b128 v[214:217], v163 offset:21504
	ds_read_b128 v[218:221], v163 offset:22528
	ds_read_b128 v[222:225], v163 offset:23552
	s_waitcnt vmcnt(8)
	s_waitcnt lgkmcnt(0)
	s_setprio 1
	s_barrier
	v_mfma_f32_16x16x32_bf16 v[62:65], v[156:159], v[194:197], v[62:65]
	v_mfma_f32_16x16x32_bf16 v[54:57], v[170:173], v[194:197], v[54:57]
	v_mfma_f32_16x16x32_bf16 v[46:49], v[156:159], v[202:205], v[46:49]
	v_mfma_f32_16x16x32_bf16 v[38:41], v[170:173], v[202:205], v[38:41]
	v_mfma_f32_16x16x32_bf16 v[30:33], v[156:159], v[210:213], v[30:33]
	v_mfma_f32_16x16x32_bf16 v[22:25], v[170:173], v[210:213], v[22:25]
	v_mfma_f32_16x16x32_bf16 v[14:17], v[156:159], v[218:221], v[14:17]
	v_mfma_f32_16x16x32_bf16 v[6:9], v[170:173], v[218:221], v[6:9]
	v_mfma_f32_16x16x32_bf16 v[62:65], v[166:169], v[198:201], v[62:65]
	v_mfma_f32_16x16x32_bf16 v[54:57], v[174:177], v[198:201], v[54:57]
	v_mfma_f32_16x16x32_bf16 v[46:49], v[166:169], v[206:209], v[46:49]
	v_mfma_f32_16x16x32_bf16 v[38:41], v[174:177], v[206:209], v[38:41]
	v_mfma_f32_16x16x32_bf16 v[30:33], v[166:169], v[214:217], v[30:33]
	v_mfma_f32_16x16x32_bf16 v[22:25], v[174:177], v[214:217], v[22:25]
	v_mfma_f32_16x16x32_bf16 v[14:17], v[166:169], v[222:225], v[14:17]
	v_mfma_f32_16x16x32_bf16 v[6:9], v[174:177], v[222:225], v[6:9]
	s_setprio 0
	s_setprio 1
	v_mfma_f32_16x16x32_bf16 v[58:61], v[178:181], v[194:197], v[58:61]
	v_mfma_f32_16x16x32_bf16 v[50:53], v[186:189], v[194:197], v[50:53]
	v_mfma_f32_16x16x32_bf16 v[42:45], v[178:181], v[202:205], v[42:45]
	v_mfma_f32_16x16x32_bf16 v[34:37], v[186:189], v[202:205], v[34:37]
	v_mfma_f32_16x16x32_bf16 v[26:29], v[178:181], v[210:213], v[26:29]
	v_mfma_f32_16x16x32_bf16 v[18:21], v[186:189], v[210:213], v[18:21]
	v_mfma_f32_16x16x32_bf16 v[10:13], v[178:181], v[218:221], v[10:13]
	v_mfma_f32_16x16x32_bf16 v[2:5], v[186:189], v[218:221], v[2:5]
	v_mfma_f32_16x16x32_bf16 v[58:61], v[182:185], v[198:201], v[58:61]
	v_mfma_f32_16x16x32_bf16 v[50:53], v[190:193], v[198:201], v[50:53]
	v_mfma_f32_16x16x32_bf16 v[42:45], v[182:185], v[206:209], v[42:45]
	v_mfma_f32_16x16x32_bf16 v[34:37], v[190:193], v[206:209], v[34:37]
	v_mfma_f32_16x16x32_bf16 v[26:29], v[182:185], v[214:217], v[26:29]
	v_mfma_f32_16x16x32_bf16 v[18:21], v[190:193], v[214:217], v[18:21]
	v_mfma_f32_16x16x32_bf16 v[10:13], v[182:185], v[222:225], v[10:13]
	v_mfma_f32_16x16x32_bf16 v[2:5], v[190:193], v[222:225], v[2:5]
	s_barrier
	s_setprio 0
	s_add_u32 s98, s94, 0x40000
	s_addc_u32 s99, s95, 0
	s_add_i32 s7, 0, 0x18000
	s_add_i32 s47, 0, 0x1c000
	s_mov_b32 m0, s59
	ds_read_b128 v[156:159], v232
	global_load_lds_dwordx4 v130, s[98:99]
	s_mov_b32 m0, s60
	ds_read_b128 v[166:169], v232 offset:1024
	global_load_lds_dwordx4 v134, s[98:99]
	ds_read_b128 v[170:173], v232 offset:2048
	ds_read_b128 v[174:177], v232 offset:3072
	ds_read_b128 v[178:181], v233
	ds_read_b128 v[182:185], v233 offset:1024
	ds_read_b128 v[186:189], v233 offset:2048
	ds_read_b128 v[190:193], v233 offset:3072
	ds_read_b128 v[194:197], v163 offset:32768
	ds_read_b128 v[198:201], v163 offset:33792
	ds_read_b128 v[202:205], v163 offset:34816
	ds_read_b128 v[206:209], v163 offset:35840
	ds_read_b128 v[210:213], v163 offset:36864
	ds_read_b128 v[214:217], v163 offset:37888
	ds_read_b128 v[218:221], v163 offset:38912
	ds_read_b128 v[222:225], v163 offset:39936
	s_waitcnt vmcnt(8)
	s_waitcnt lgkmcnt(0)
	s_setprio 1
	s_barrier
	v_mfma_f32_16x16x32_bf16 v[122:125], v[156:159], v[194:197], v[122:125]
	v_mfma_f32_16x16x32_bf16 v[118:121], v[170:173], v[194:197], v[118:121]
	v_mfma_f32_16x16x32_bf16 v[110:113], v[156:159], v[202:205], v[110:113]
	v_mfma_f32_16x16x32_bf16 v[102:105], v[170:173], v[202:205], v[102:105]
	v_mfma_f32_16x16x32_bf16 v[94:97], v[156:159], v[210:213], v[94:97]
	v_mfma_f32_16x16x32_bf16 v[86:89], v[170:173], v[210:213], v[86:89]
	v_mfma_f32_16x16x32_bf16 v[78:81], v[156:159], v[218:221], v[78:81]
	v_mfma_f32_16x16x32_bf16 v[70:73], v[170:173], v[218:221], v[70:73]
	v_mfma_f32_16x16x32_bf16 v[122:125], v[166:169], v[198:201], v[122:125]
	v_mfma_f32_16x16x32_bf16 v[118:121], v[174:177], v[198:201], v[118:121]
	v_mfma_f32_16x16x32_bf16 v[110:113], v[166:169], v[206:209], v[110:113]
	v_mfma_f32_16x16x32_bf16 v[102:105], v[174:177], v[206:209], v[102:105]
	v_mfma_f32_16x16x32_bf16 v[94:97], v[166:169], v[214:217], v[94:97]
	v_mfma_f32_16x16x32_bf16 v[86:89], v[174:177], v[214:217], v[86:89]
	v_mfma_f32_16x16x32_bf16 v[78:81], v[166:169], v[222:225], v[78:81]
	v_mfma_f32_16x16x32_bf16 v[70:73], v[174:177], v[222:225], v[70:73]
	s_setprio 0
	s_setprio 1
	v_mfma_f32_16x16x32_bf16 v[126:129], v[178:181], v[194:197], v[126:129]
	v_mfma_f32_16x16x32_bf16 v[114:117], v[186:189], v[194:197], v[114:117]
	v_mfma_f32_16x16x32_bf16 v[106:109], v[178:181], v[202:205], v[106:109]
	v_mfma_f32_16x16x32_bf16 v[98:101], v[186:189], v[202:205], v[98:101]
	v_mfma_f32_16x16x32_bf16 v[90:93], v[178:181], v[210:213], v[90:93]
	v_mfma_f32_16x16x32_bf16 v[82:85], v[186:189], v[210:213], v[82:85]
	v_mfma_f32_16x16x32_bf16 v[74:77], v[178:181], v[218:221], v[74:77]
	v_mfma_f32_16x16x32_bf16 v[66:69], v[186:189], v[218:221], v[66:69]
	v_mfma_f32_16x16x32_bf16 v[126:129], v[182:185], v[198:201], v[126:129]
	v_mfma_f32_16x16x32_bf16 v[114:117], v[190:193], v[198:201], v[114:117]
	v_mfma_f32_16x16x32_bf16 v[106:109], v[182:185], v[206:209], v[106:109]
	v_mfma_f32_16x16x32_bf16 v[98:101], v[190:193], v[206:209], v[98:101]
	v_mfma_f32_16x16x32_bf16 v[90:93], v[182:185], v[214:217], v[90:93]
	v_mfma_f32_16x16x32_bf16 v[82:85], v[190:193], v[214:217], v[82:85]
	v_mfma_f32_16x16x32_bf16 v[74:77], v[182:185], v[222:225], v[74:77]
	v_mfma_f32_16x16x32_bf16 v[66:69], v[190:193], v[222:225], v[66:69]
	s_barrier
	s_setprio 0
	s_add_u32 s96, s96, 0x80
	s_addc_u32 s97, s97, 0
	s_add_u32 s98, s96, 0x40000
	s_addc_u32 s99, s97, 0
	s_add_u32 s94, s94, 0x80
	s_addc_u32 s95, s95, 0
	s_add_i32 s7, s7, s25
	s_mov_b32 m0, s7
	ds_read_b128 v[194:197], v163 offset:49152
	global_load_lds_dwordx4 v132, s[96:97]
	s_add_i32 m0, s7, 0x2000
	s_add_i32 s7, s47, s25
	global_load_lds_dwordx4 v136, s[96:97]
	s_mov_b32 m0, s7
	ds_read_b128 v[198:201], v163 offset:50176
	global_load_lds_dwordx4 v132, s[98:99]
	s_add_i32 m0, s7, 0x2000
	ds_read_b128 v[202:205], v163 offset:51200
	global_load_lds_dwordx4 v136, s[98:99]
	s_mov_b32 m0, s66
	ds_read_b128 v[206:209], v163 offset:52224
	global_load_lds_dwordx4 v130, s[94:95]
	s_mov_b32 m0, s67
	ds_read_b128 v[210:213], v163 offset:53248
	global_load_lds_dwordx4 v134, s[94:95]
	ds_read_b128 v[214:217], v163 offset:54272
	ds_read_b128 v[218:221], v163 offset:55296
	ds_read_b128 v[222:225], v163 offset:56320
	s_waitcnt vmcnt(8)
	s_waitcnt lgkmcnt(0)
	s_setprio 1
	s_barrier
	v_mfma_f32_16x16x32_bf16 v[62:65], v[156:159], v[194:197], v[62:65]
	v_mfma_f32_16x16x32_bf16 v[54:57], v[170:173], v[194:197], v[54:57]
	v_mfma_f32_16x16x32_bf16 v[46:49], v[156:159], v[202:205], v[46:49]
	v_mfma_f32_16x16x32_bf16 v[38:41], v[170:173], v[202:205], v[38:41]
	v_mfma_f32_16x16x32_bf16 v[30:33], v[156:159], v[210:213], v[30:33]
	v_mfma_f32_16x16x32_bf16 v[22:25], v[170:173], v[210:213], v[22:25]
	v_mfma_f32_16x16x32_bf16 v[14:17], v[156:159], v[218:221], v[14:17]
	v_mfma_f32_16x16x32_bf16 v[6:9], v[170:173], v[218:221], v[6:9]
	v_mfma_f32_16x16x32_bf16 v[62:65], v[166:169], v[198:201], v[62:65]
	v_mfma_f32_16x16x32_bf16 v[54:57], v[174:177], v[198:201], v[54:57]
	v_mfma_f32_16x16x32_bf16 v[46:49], v[166:169], v[206:209], v[46:49]
	v_mfma_f32_16x16x32_bf16 v[38:41], v[174:177], v[206:209], v[38:41]
	v_mfma_f32_16x16x32_bf16 v[30:33], v[166:169], v[214:217], v[30:33]
	v_mfma_f32_16x16x32_bf16 v[22:25], v[174:177], v[214:217], v[22:25]
	v_mfma_f32_16x16x32_bf16 v[14:17], v[166:169], v[222:225], v[14:17]
	v_mfma_f32_16x16x32_bf16 v[6:9], v[174:177], v[222:225], v[6:9]
	s_setprio 0
	s_setprio 1
	v_mfma_f32_16x16x32_bf16 v[58:61], v[178:181], v[194:197], v[58:61]
	v_mfma_f32_16x16x32_bf16 v[50:53], v[186:189], v[194:197], v[50:53]
	v_mfma_f32_16x16x32_bf16 v[42:45], v[178:181], v[202:205], v[42:45]
	v_mfma_f32_16x16x32_bf16 v[34:37], v[186:189], v[202:205], v[34:37]
	v_mfma_f32_16x16x32_bf16 v[26:29], v[178:181], v[210:213], v[26:29]
	v_mfma_f32_16x16x32_bf16 v[18:21], v[186:189], v[210:213], v[18:21]
	v_mfma_f32_16x16x32_bf16 v[10:13], v[178:181], v[218:221], v[10:13]
	v_mfma_f32_16x16x32_bf16 v[2:5], v[186:189], v[218:221], v[2:5]
	v_mfma_f32_16x16x32_bf16 v[58:61], v[182:185], v[198:201], v[58:61]
	v_mfma_f32_16x16x32_bf16 v[50:53], v[190:193], v[198:201], v[50:53]
	v_mfma_f32_16x16x32_bf16 v[42:45], v[182:185], v[206:209], v[42:45]
	v_mfma_f32_16x16x32_bf16 v[34:37], v[190:193], v[206:209], v[34:37]
	v_mfma_f32_16x16x32_bf16 v[26:29], v[182:185], v[214:217], v[26:29]
	v_mfma_f32_16x16x32_bf16 v[18:21], v[190:193], v[214:217], v[18:21]
	v_mfma_f32_16x16x32_bf16 v[10:13], v[182:185], v[222:225], v[10:13]
	v_mfma_f32_16x16x32_bf16 v[2:5], v[190:193], v[222:225], v[2:5]
	s_barrier
	s_setprio 0
	s_mov_b32 s7, s45
	s_add_u32 s88, s88, 0x100
	s_addc_u32 s89, s89, 0
	s_add_u32 s86, s86, 0x100
	s_addc_u32 s87, s87, 0
	s_cmp_ge_i32 s45, s101
	s_cbranch_scc0 .LBB0_499

.Lmy_nb_3:
	s_nop 0
	v_readfirstlane_b32 s86, v152
	v_readfirstlane_b32 s87, v153
	v_readfirstlane_b32 s88, v150
	v_readfirstlane_b32 s89, v151
	v_readfirstlane_b32 s90, v146
	v_readfirstlane_b32 s91, v147
	v_readfirstlane_b32 s92, v148
	v_readfirstlane_b32 s93, v149
	v_readfirstlane_b32 s100, v154
	v_readfirstlane_b32 s101, v138
	v_add_u32_e32 v230, s76, v141
	v_add_u32_e32 v231, s77, v141
	v_add_u32_e32 v232, 0x18000, v141
	v_add_u32_e32 v233, 0x1c000, v141
	s_add_u32 s98, s86, 0xfffc0080
	s_addc_u32 s99, s87, -1
	s_cmp_eq_u32 s7, s100
	s_cselect_b64 s[94:95], s[90:91], s[98:99]
	s_cselect_b64 s[96:97], s[92:93], s[88:89]
	s_add_i32 s45, s7, 2
	s_add_i32 m0, s49, 0xc000
	ds_read_b128 v[164:167], v230
	global_load_lds_dwordx4 v144, s[86:87]
	s_add_i32 m0, s49, 0xe000
	ds_read_b128 v[168:171], v230 offset:1024
	global_load_lds_dwordx4 v142, s[86:87]
	ds_read_b128 v[172:175], v230 offset:2048
	ds_read_b128 v[176:179], v230 offset:3072
	ds_read_b128 v[180:183], v231
	ds_read_b128 v[184:187], v231 offset:1024
	ds_read_b128 v[188:191], v231 offset:2048
	ds_read_b128 v[192:195], v231 offset:3072
	ds_read_b128 v[196:199], v160
	ds_read_b128 v[200:203], v160 offset:1024
	ds_read_b128 v[204:207], v160 offset:2048
	ds_read_b128 v[208:211], v160 offset:3072
	ds_read_b128 v[212:215], v160 offset:4096
	ds_read_b128 v[216:219], v160 offset:5120
	ds_read_b128 v[220:223], v160 offset:6144
	ds_read_b128 v[224:227], v160 offset:7168
	s_waitcnt vmcnt(8)
	s_waitcnt lgkmcnt(0)
	s_setprio 1
	s_barrier
	v_mfma_f32_16x16x32_bf16 v[122:125], v[164:167], v[196:199], 0
	v_mfma_f32_16x16x32_bf16 v[118:121], v[172:175], v[196:199], 0
	v_mfma_f32_16x16x32_bf16 v[110:113], v[164:167], v[204:207], 0
	v_mfma_f32_16x16x32_bf16 v[102:105], v[172:175], v[204:207], 0
	v_mfma_f32_16x16x32_bf16 v[94:97], v[164:167], v[212:215], 0
	v_mfma_f32_16x16x32_bf16 v[86:89], v[172:175], v[212:215], 0
	v_mfma_f32_16x16x32_bf16 v[78:81], v[164:167], v[220:223], 0
	v_mfma_f32_16x16x32_bf16 v[70:73], v[172:175], v[220:223], 0
	v_mfma_f32_16x16x32_bf16 v[122:125], v[168:171], v[200:203], v[122:125]
	v_mfma_f32_16x16x32_bf16 v[118:121], v[176:179], v[200:203], v[118:121]
	v_mfma_f32_16x16x32_bf16 v[110:113], v[168:171], v[208:211], v[110:113]
	v_mfma_f32_16x16x32_bf16 v[102:105], v[176:179], v[208:211], v[102:105]
	v_mfma_f32_16x16x32_bf16 v[94:97], v[168:171], v[216:219], v[94:97]
	v_mfma_f32_16x16x32_bf16 v[86:89], v[176:179], v[216:219], v[86:89]
	v_mfma_f32_16x16x32_bf16 v[78:81], v[168:171], v[224:227], v[78:81]
	v_mfma_f32_16x16x32_bf16 v[70:73], v[176:179], v[224:227], v[70:73]
	s_setprio 0
	s_setprio 1
	v_mfma_f32_16x16x32_bf16 v[126:129], v[180:183], v[196:199], 0
	v_mfma_f32_16x16x32_bf16 v[114:117], v[188:191], v[196:199], 0
	v_mfma_f32_16x16x32_bf16 v[106:109], v[180:183], v[204:207], 0
	v_mfma_f32_16x16x32_bf16 v[98:101], v[188:191], v[204:207], 0
	v_mfma_f32_16x16x32_bf16 v[90:93], v[180:183], v[212:215], 0
	v_mfma_f32_16x16x32_bf16 v[82:85], v[188:191], v[212:215], 0
	v_mfma_f32_16x16x32_bf16 v[74:77], v[180:183], v[220:223], 0
	v_mfma_f32_16x16x32_bf16 v[66:69], v[188:191], v[220:223], 0
	v_mfma_f32_16x16x32_bf16 v[126:129], v[184:187], v[200:203], v[126:129]
	v_mfma_f32_16x16x32_bf16 v[114:117], v[192:195], v[200:203], v[114:117]
	v_mfma_f32_16x16x32_bf16 v[106:109], v[184:187], v[208:211], v[106:109]
	v_mfma_f32_16x16x32_bf16 v[98:101], v[192:195], v[208:211], v[98:101]
	v_mfma_f32_16x16x32_bf16 v[90:93], v[184:187], v[216:219], v[90:93]
	v_mfma_f32_16x16x32_bf16 v[82:85], v[192:195], v[216:219], v[82:85]
	v_mfma_f32_16x16x32_bf16 v[74:77], v[184:187], v[224:227], v[74:77]
	v_mfma_f32_16x16x32_bf16 v[66:69], v[192:195], v[224:227], v[66:69]
	s_barrier
	s_setprio 0
	s_add_u32 s98, s96, 0x40000
	s_addc_u32 s99, s97, 0
	s_add_i32 s7, s76, s25
	s_mov_b32 m0, s7
	ds_read_b128 v[196:199], v160 offset:16384
	global_load_lds_dwordx4 v132, s[96:97]
	s_add_i32 m0, s7, 0x2000
	s_add_i32 s7, s77, s25
	global_load_lds_dwordx4 v136, s[96:97]
	s_mov_b32 m0, s7
	ds_read_b128 v[200:203], v160 offset:17408
	global_load_lds_dwordx4 v132, s[98:99]
	s_add_i32 m0, s7, 0x2000
	ds_read_b128 v[204:207], v160 offset:18432
	global_load_lds_dwordx4 v136, s[98:99]
	s_mov_b32 m0, s49
	ds_read_b128 v[208:211], v160 offset:19456
	global_load_lds_dwordx4 v130, s[94:95]
	s_mov_b32 m0, s58
	ds_read_b128 v[212:215], v160 offset:20480
	global_load_lds_dwordx4 v134, s[94:95]
	ds_read_b128 v[216:219], v160 offset:21504
	ds_read_b128 v[220:223], v160 offset:22528
	ds_read_b128 v[224:227], v160 offset:23552
	s_waitcnt vmcnt(8)
	s_waitcnt lgkmcnt(0)
	s_setprio 1
	s_barrier
	v_mfma_f32_16x16x32_bf16 v[62:65], v[164:167], v[196:199], 0
	v_mfma_f32_16x16x32_bf16 v[54:57], v[172:175], v[196:199], 0
	v_mfma_f32_16x16x32_bf16 v[46:49], v[164:167], v[204:207], 0
	v_mfma_f32_16x16x32_bf16 v[38:41], v[172:175], v[204:207], 0
	v_mfma_f32_16x16x32_bf16 v[30:33], v[164:167], v[212:215], 0
	v_mfma_f32_16x16x32_bf16 v[22:25], v[172:175], v[212:215], 0
	v_mfma_f32_16x16x32_bf16 v[14:17], v[164:167], v[220:223], 0
	v_mfma_f32_16x16x32_bf16 v[6:9], v[172:175], v[220:223], 0
	v_mfma_f32_16x16x32_bf16 v[62:65], v[168:171], v[200:203], v[62:65]
	v_mfma_f32_16x16x32_bf16 v[54:57], v[176:179], v[200:203], v[54:57]
	v_mfma_f32_16x16x32_bf16 v[46:49], v[168:171], v[208:211], v[46:49]
	v_mfma_f32_16x16x32_bf16 v[38:41], v[176:179], v[208:211], v[38:41]
	v_mfma_f32_16x16x32_bf16 v[30:33], v[168:171], v[216:219], v[30:33]
	v_mfma_f32_16x16x32_bf16 v[22:25], v[176:179], v[216:219], v[22:25]
	v_mfma_f32_16x16x32_bf16 v[14:17], v[168:171], v[224:227], v[14:17]
	v_mfma_f32_16x16x32_bf16 v[6:9], v[176:179], v[224:227], v[6:9]
	s_setprio 0
	s_setprio 1
	v_mfma_f32_16x16x32_bf16 v[58:61], v[180:183], v[196:199], 0
	v_mfma_f32_16x16x32_bf16 v[50:53], v[188:191], v[196:199], 0
	v_mfma_f32_16x16x32_bf16 v[42:45], v[180:183], v[204:207], 0
	v_mfma_f32_16x16x32_bf16 v[34:37], v[188:191], v[204:207], 0
	v_mfma_f32_16x16x32_bf16 v[26:29], v[180:183], v[212:215], 0
	v_mfma_f32_16x16x32_bf16 v[18:21], v[188:191], v[212:215], 0
	v_mfma_f32_16x16x32_bf16 v[10:13], v[180:183], v[220:223], 0
	v_mfma_f32_16x16x32_bf16 v[2:5], v[188:191], v[220:223], 0
	v_mfma_f32_16x16x32_bf16 v[58:61], v[184:187], v[200:203], v[58:61]
	v_mfma_f32_16x16x32_bf16 v[50:53], v[192:195], v[200:203], v[50:53]
	v_mfma_f32_16x16x32_bf16 v[42:45], v[184:187], v[208:211], v[42:45]
	v_mfma_f32_16x16x32_bf16 v[34:37], v[192:195], v[208:211], v[34:37]
	v_mfma_f32_16x16x32_bf16 v[26:29], v[184:187], v[216:219], v[26:29]
	v_mfma_f32_16x16x32_bf16 v[18:21], v[192:195], v[216:219], v[18:21]
	v_mfma_f32_16x16x32_bf16 v[10:13], v[184:187], v[224:227], v[10:13]
	v_mfma_f32_16x16x32_bf16 v[2:5], v[192:195], v[224:227], v[2:5]
	s_barrier
	s_setprio 0
	s_add_u32 s98, s94, 0x40000
	s_addc_u32 s99, s95, 0
	s_add_i32 s7, 0, 0x18000
	s_add_i32 s47, 0, 0x1c000
	s_mov_b32 m0, s59
	ds_read_b128 v[164:167], v232
	global_load_lds_dwordx4 v130, s[98:99]
	s_mov_b32 m0, s60
	ds_read_b128 v[168:171], v232 offset:1024
	global_load_lds_dwordx4 v134, s[98:99]
	ds_read_b128 v[172:175], v232 offset:2048
	ds_read_b128 v[176:179], v232 offset:3072
	ds_read_b128 v[180:183], v233
	ds_read_b128 v[184:187], v233 offset:1024
	ds_read_b128 v[188:191], v233 offset:2048
	ds_read_b128 v[192:195], v233 offset:3072
	ds_read_b128 v[196:199], v160 offset:32768
	ds_read_b128 v[200:203], v160 offset:33792
	ds_read_b128 v[204:207], v160 offset:34816
	ds_read_b128 v[208:211], v160 offset:35840
	ds_read_b128 v[212:215], v160 offset:36864
	ds_read_b128 v[216:219], v160 offset:37888
	ds_read_b128 v[220:223], v160 offset:38912
	ds_read_b128 v[224:227], v160 offset:39936
	s_waitcnt vmcnt(8)
	s_waitcnt lgkmcnt(0)
	s_setprio 1
	s_barrier
	v_mfma_f32_16x16x32_bf16 v[122:125], v[164:167], v[196:199], v[122:125]
	v_mfma_f32_16x16x32_bf16 v[118:121], v[172:175], v[196:199], v[118:121]
	v_mfma_f32_16x16x32_bf16 v[110:113], v[164:167], v[204:207], v[110:113]
	v_mfma_f32_16x16x32_bf16 v[102:105], v[172:175], v[204:207], v[102:105]
	v_mfma_f32_16x16x32_bf16 v[94:97], v[164:167], v[212:215], v[94:97]
	v_mfma_f32_16x16x32_bf16 v[86:89], v[172:175], v[212:215], v[86:89]
	v_mfma_f32_16x16x32_bf16 v[78:81], v[164:167], v[220:223], v[78:81]
	v_mfma_f32_16x16x32_bf16 v[70:73], v[172:175], v[220:223], v[70:73]
	v_mfma_f32_16x16x32_bf16 v[122:125], v[168:171], v[200:203], v[122:125]
	v_mfma_f32_16x16x32_bf16 v[118:121], v[176:179], v[200:203], v[118:121]
	v_mfma_f32_16x16x32_bf16 v[110:113], v[168:171], v[208:211], v[110:113]
	v_mfma_f32_16x16x32_bf16 v[102:105], v[176:179], v[208:211], v[102:105]
	v_mfma_f32_16x16x32_bf16 v[94:97], v[168:171], v[216:219], v[94:97]
	v_mfma_f32_16x16x32_bf16 v[86:89], v[176:179], v[216:219], v[86:89]
	v_mfma_f32_16x16x32_bf16 v[78:81], v[168:171], v[224:227], v[78:81]
	v_mfma_f32_16x16x32_bf16 v[70:73], v[176:179], v[224:227], v[70:73]
	s_setprio 0
	s_setprio 1
	v_mfma_f32_16x16x32_bf16 v[126:129], v[180:183], v[196:199], v[126:129]
	v_mfma_f32_16x16x32_bf16 v[114:117], v[188:191], v[196:199], v[114:117]
	v_mfma_f32_16x16x32_bf16 v[106:109], v[180:183], v[204:207], v[106:109]
	v_mfma_f32_16x16x32_bf16 v[98:101], v[188:191], v[204:207], v[98:101]
	v_mfma_f32_16x16x32_bf16 v[90:93], v[180:183], v[212:215], v[90:93]
	v_mfma_f32_16x16x32_bf16 v[82:85], v[188:191], v[212:215], v[82:85]
	v_mfma_f32_16x16x32_bf16 v[74:77], v[180:183], v[220:223], v[74:77]
	v_mfma_f32_16x16x32_bf16 v[66:69], v[188:191], v[220:223], v[66:69]
	v_mfma_f32_16x16x32_bf16 v[126:129], v[184:187], v[200:203], v[126:129]
	v_mfma_f32_16x16x32_bf16 v[114:117], v[192:195], v[200:203], v[114:117]
	v_mfma_f32_16x16x32_bf16 v[106:109], v[184:187], v[208:211], v[106:109]
	v_mfma_f32_16x16x32_bf16 v[98:101], v[192:195], v[208:211], v[98:101]
	v_mfma_f32_16x16x32_bf16 v[90:93], v[184:187], v[216:219], v[90:93]
	v_mfma_f32_16x16x32_bf16 v[82:85], v[192:195], v[216:219], v[82:85]
	v_mfma_f32_16x16x32_bf16 v[74:77], v[184:187], v[224:227], v[74:77]
	v_mfma_f32_16x16x32_bf16 v[66:69], v[192:195], v[224:227], v[66:69]
	s_barrier
	s_setprio 0
	s_add_u32 s96, s96, 0x80
	s_addc_u32 s97, s97, 0
	s_add_u32 s98, s96, 0x40000
	s_addc_u32 s99, s97, 0
	s_add_u32 s94, s94, 0x80
	s_addc_u32 s95, s95, 0
	s_add_i32 s7, s7, s25
	s_mov_b32 m0, s7
	ds_read_b128 v[196:199], v160 offset:49152
	global_load_lds_dwordx4 v132, s[96:97]
	s_add_i32 m0, s7, 0x2000
	s_add_i32 s7, s47, s25
	global_load_lds_dwordx4 v136, s[96:97]
	s_mov_b32 m0, s7
	ds_read_b128 v[200:203], v160 offset:50176
	global_load_lds_dwordx4 v132, s[98:99]
	s_add_i32 m0, s7, 0x2000
	ds_read_b128 v[204:207], v160 offset:51200
	global_load_lds_dwordx4 v136, s[98:99]
	s_mov_b32 m0, s66
	ds_read_b128 v[208:211], v160 offset:52224
	global_load_lds_dwordx4 v130, s[94:95]
	s_mov_b32 m0, s67
	ds_read_b128 v[212:215], v160 offset:53248
	global_load_lds_dwordx4 v134, s[94:95]
	ds_read_b128 v[216:219], v160 offset:54272
	ds_read_b128 v[220:223], v160 offset:55296
	ds_read_b128 v[224:227], v160 offset:56320
	s_waitcnt vmcnt(8)
	s_waitcnt lgkmcnt(0)
	s_setprio 1
	s_barrier
	v_mfma_f32_16x16x32_bf16 v[62:65], v[164:167], v[196:199], v[62:65]
	v_mfma_f32_16x16x32_bf16 v[54:57], v[172:175], v[196:199], v[54:57]
	v_mfma_f32_16x16x32_bf16 v[46:49], v[164:167], v[204:207], v[46:49]
	v_mfma_f32_16x16x32_bf16 v[38:41], v[172:175], v[204:207], v[38:41]
	v_mfma_f32_16x16x32_bf16 v[30:33], v[164:167], v[212:215], v[30:33]
	v_mfma_f32_16x16x32_bf16 v[22:25], v[172:175], v[212:215], v[22:25]
	v_mfma_f32_16x16x32_bf16 v[14:17], v[164:167], v[220:223], v[14:17]
	v_mfma_f32_16x16x32_bf16 v[6:9], v[172:175], v[220:223], v[6:9]
	v_mfma_f32_16x16x32_bf16 v[62:65], v[168:171], v[200:203], v[62:65]
	v_mfma_f32_16x16x32_bf16 v[54:57], v[176:179], v[200:203], v[54:57]
	v_mfma_f32_16x16x32_bf16 v[46:49], v[168:171], v[208:211], v[46:49]
	v_mfma_f32_16x16x32_bf16 v[38:41], v[176:179], v[208:211], v[38:41]
	v_mfma_f32_16x16x32_bf16 v[30:33], v[168:171], v[216:219], v[30:33]
	v_mfma_f32_16x16x32_bf16 v[22:25], v[176:179], v[216:219], v[22:25]
	v_mfma_f32_16x16x32_bf16 v[14:17], v[168:171], v[224:227], v[14:17]
	v_mfma_f32_16x16x32_bf16 v[6:9], v[176:179], v[224:227], v[6:9]
	s_setprio 0
	s_setprio 1
	v_mfma_f32_16x16x32_bf16 v[58:61], v[180:183], v[196:199], v[58:61]
	v_mfma_f32_16x16x32_bf16 v[50:53], v[188:191], v[196:199], v[50:53]
	v_mfma_f32_16x16x32_bf16 v[42:45], v[180:183], v[204:207], v[42:45]
	v_mfma_f32_16x16x32_bf16 v[34:37], v[188:191], v[204:207], v[34:37]
	v_mfma_f32_16x16x32_bf16 v[26:29], v[180:183], v[212:215], v[26:29]
	v_mfma_f32_16x16x32_bf16 v[18:21], v[188:191], v[212:215], v[18:21]
	v_mfma_f32_16x16x32_bf16 v[10:13], v[180:183], v[220:223], v[10:13]
	v_mfma_f32_16x16x32_bf16 v[2:5], v[188:191], v[220:223], v[2:5]
	v_mfma_f32_16x16x32_bf16 v[58:61], v[184:187], v[200:203], v[58:61]
	v_mfma_f32_16x16x32_bf16 v[50:53], v[192:195], v[200:203], v[50:53]
	v_mfma_f32_16x16x32_bf16 v[42:45], v[184:187], v[208:211], v[42:45]
	v_mfma_f32_16x16x32_bf16 v[34:37], v[192:195], v[208:211], v[34:37]
	v_mfma_f32_16x16x32_bf16 v[26:29], v[184:187], v[216:219], v[26:29]
	v_mfma_f32_16x16x32_bf16 v[18:21], v[192:195], v[216:219], v[18:21]
	v_mfma_f32_16x16x32_bf16 v[10:13], v[184:187], v[224:227], v[10:13]
	v_mfma_f32_16x16x32_bf16 v[2:5], v[192:195], v[224:227], v[2:5]
	s_barrier
	s_setprio 0
	s_mov_b32 s7, s45
	s_add_u32 s88, s88, 0x100
	s_addc_u32 s89, s89, 0
	s_add_u32 s86, s86, 0x100
	s_addc_u32 s87, s87, 0
	s_cmp_ge_i32 s45, s101
	s_cbranch_scc1 .Lmy_kexit_3
.LBB0_768:
	s_add_u32 s98, s86, 0xfffc0080
	s_addc_u32 s99, s87, -1
	s_cmp_eq_u32 s7, s100
	s_cselect_b64 s[94:95], s[90:91], s[98:99]
	s_cselect_b64 s[96:97], s[92:93], s[88:89]
	s_add_i32 s45, s7, 2
	s_add_i32 m0, s49, 0xc000
	ds_read_b128 v[164:167], v230
	global_load_lds_dwordx4 v144, s[86:87]
	s_add_i32 m0, s49, 0xe000
	ds_read_b128 v[168:171], v230 offset:1024
	global_load_lds_dwordx4 v142, s[86:87]
	ds_read_b128 v[172:175], v230 offset:2048
	ds_read_b128 v[176:179], v230 offset:3072
	ds_read_b128 v[180:183], v231
	ds_read_b128 v[184:187], v231 offset:1024
	ds_read_b128 v[188:191], v231 offset:2048
	ds_read_b128 v[192:195], v231 offset:3072
	ds_read_b128 v[196:199], v160
	ds_read_b128 v[200:203], v160 offset:1024
	ds_read_b128 v[204:207], v160 offset:2048
	ds_read_b128 v[208:211], v160 offset:3072
	ds_read_b128 v[212:215], v160 offset:4096
	ds_read_b128 v[216:219], v160 offset:5120
	ds_read_b128 v[220:223], v160 offset:6144
	ds_read_b128 v[224:227], v160 offset:7168
	s_waitcnt vmcnt(8)
	s_waitcnt lgkmcnt(0)
	s_setprio 1
	s_barrier
	v_mfma_f32_16x16x32_bf16 v[122:125], v[164:167], v[196:199], v[122:125]
	v_mfma_f32_16x16x32_bf16 v[118:121], v[172:175], v[196:199], v[118:121]
	v_mfma_f32_16x16x32_bf16 v[110:113], v[164:167], v[204:207], v[110:113]
	v_mfma_f32_16x16x32_bf16 v[102:105], v[172:175], v[204:207], v[102:105]
	v_mfma_f32_16x16x32_bf16 v[94:97], v[164:167], v[212:215], v[94:97]
	v_mfma_f32_16x16x32_bf16 v[86:89], v[172:175], v[212:215], v[86:89]
	v_mfma_f32_16x16x32_bf16 v[78:81], v[164:167], v[220:223], v[78:81]
	v_mfma_f32_16x16x32_bf16 v[70:73], v[172:175], v[220:223], v[70:73]
	v_mfma_f32_16x16x32_bf16 v[122:125], v[168:171], v[200:203], v[122:125]
	v_mfma_f32_16x16x32_bf16 v[118:121], v[176:179], v[200:203], v[118:121]
	v_mfma_f32_16x16x32_bf16 v[110:113], v[168:171], v[208:211], v[110:113]
	v_mfma_f32_16x16x32_bf16 v[102:105], v[176:179], v[208:211], v[102:105]
	v_mfma_f32_16x16x32_bf16 v[94:97], v[168:171], v[216:219], v[94:97]
	v_mfma_f32_16x16x32_bf16 v[86:89], v[176:179], v[216:219], v[86:89]
	v_mfma_f32_16x16x32_bf16 v[78:81], v[168:171], v[224:227], v[78:81]
	v_mfma_f32_16x16x32_bf16 v[70:73], v[176:179], v[224:227], v[70:73]
	s_setprio 0
	s_setprio 1
	v_mfma_f32_16x16x32_bf16 v[126:129], v[180:183], v[196:199], v[126:129]
	v_mfma_f32_16x16x32_bf16 v[114:117], v[188:191], v[196:199], v[114:117]
	v_mfma_f32_16x16x32_bf16 v[106:109], v[180:183], v[204:207], v[106:109]
	v_mfma_f32_16x16x32_bf16 v[98:101], v[188:191], v[204:207], v[98:101]
	v_mfma_f32_16x16x32_bf16 v[90:93], v[180:183], v[212:215], v[90:93]
	v_mfma_f32_16x16x32_bf16 v[82:85], v[188:191], v[212:215], v[82:85]
	v_mfma_f32_16x16x32_bf16 v[74:77], v[180:183], v[220:223], v[74:77]
	v_mfma_f32_16x16x32_bf16 v[66:69], v[188:191], v[220:223], v[66:69]
	v_mfma_f32_16x16x32_bf16 v[126:129], v[184:187], v[200:203], v[126:129]
	v_mfma_f32_16x16x32_bf16 v[114:117], v[192:195], v[200:203], v[114:117]
	v_mfma_f32_16x16x32_bf16 v[106:109], v[184:187], v[208:211], v[106:109]
	v_mfma_f32_16x16x32_bf16 v[98:101], v[192:195], v[208:211], v[98:101]
	v_mfma_f32_16x16x32_bf16 v[90:93], v[184:187], v[216:219], v[90:93]
	v_mfma_f32_16x16x32_bf16 v[82:85], v[192:195], v[216:219], v[82:85]
	v_mfma_f32_16x16x32_bf16 v[74:77], v[184:187], v[224:227], v[74:77]
	v_mfma_f32_16x16x32_bf16 v[66:69], v[192:195], v[224:227], v[66:69]
	s_barrier
	s_setprio 0
	s_add_u32 s98, s96, 0x40000
	s_addc_u32 s99, s97, 0
	s_add_i32 s7, s76, s25
	s_mov_b32 m0, s7
	ds_read_b128 v[196:199], v160 offset:16384
	global_load_lds_dwordx4 v132, s[96:97]
	s_add_i32 m0, s7, 0x2000
	s_add_i32 s7, s77, s25
	global_load_lds_dwordx4 v136, s[96:97]
	s_mov_b32 m0, s7
	ds_read_b128 v[200:203], v160 offset:17408
	global_load_lds_dwordx4 v132, s[98:99]
	s_add_i32 m0, s7, 0x2000
	ds_read_b128 v[204:207], v160 offset:18432
	global_load_lds_dwordx4 v136, s[98:99]
	s_mov_b32 m0, s49
	ds_read_b128 v[208:211], v160 offset:19456
	global_load_lds_dwordx4 v130, s[94:95]
	s_mov_b32 m0, s58
	ds_read_b128 v[212:215], v160 offset:20480
	global_load_lds_dwordx4 v134, s[94:95]
	ds_read_b128 v[216:219], v160 offset:21504
	ds_read_b128 v[220:223], v160 offset:22528
	ds_read_b128 v[224:227], v160 offset:23552
	s_waitcnt vmcnt(8)
	s_waitcnt lgkmcnt(0)
	s_setprio 1
	s_barrier
	v_mfma_f32_16x16x32_bf16 v[62:65], v[164:167], v[196:199], v[62:65]
	v_mfma_f32_16x16x32_bf16 v[54:57], v[172:175], v[196:199], v[54:57]
	v_mfma_f32_16x16x32_bf16 v[46:49], v[164:167], v[204:207], v[46:49]
	v_mfma_f32_16x16x32_bf16 v[38:41], v[172:175], v[204:207], v[38:41]
	v_mfma_f32_16x16x32_bf16 v[30:33], v[164:167], v[212:215], v[30:33]
	v_mfma_f32_16x16x32_bf16 v[22:25], v[172:175], v[212:215], v[22:25]
	v_mfma_f32_16x16x32_bf16 v[14:17], v[164:167], v[220:223], v[14:17]
	v_mfma_f32_16x16x32_bf16 v[6:9], v[172:175], v[220:223], v[6:9]
	v_mfma_f32_16x16x32_bf16 v[62:65], v[168:171], v[200:203], v[62:65]
	v_mfma_f32_16x16x32_bf16 v[54:57], v[176:179], v[200:203], v[54:57]
	v_mfma_f32_16x16x32_bf16 v[46:49], v[168:171], v[208:211], v[46:49]
	v_mfma_f32_16x16x32_bf16 v[38:41], v[176:179], v[208:211], v[38:41]
	v_mfma_f32_16x16x32_bf16 v[30:33], v[168:171], v[216:219], v[30:33]
	v_mfma_f32_16x16x32_bf16 v[22:25], v[176:179], v[216:219], v[22:25]
	v_mfma_f32_16x16x32_bf16 v[14:17], v[168:171], v[224:227], v[14:17]
	v_mfma_f32_16x16x32_bf16 v[6:9], v[176:179], v[224:227], v[6:9]
	s_setprio 0
	s_setprio 1
	v_mfma_f32_16x16x32_bf16 v[58:61], v[180:183], v[196:199], v[58:61]
	v_mfma_f32_16x16x32_bf16 v[50:53], v[188:191], v[196:199], v[50:53]
	v_mfma_f32_16x16x32_bf16 v[42:45], v[180:183], v[204:207], v[42:45]
	v_mfma_f32_16x16x32_bf16 v[34:37], v[188:191], v[204:207], v[34:37]
	v_mfma_f32_16x16x32_bf16 v[26:29], v[180:183], v[212:215], v[26:29]
	v_mfma_f32_16x16x32_bf16 v[18:21], v[188:191], v[212:215], v[18:21]
	v_mfma_f32_16x16x32_bf16 v[10:13], v[180:183], v[220:223], v[10:13]
	v_mfma_f32_16x16x32_bf16 v[2:5], v[188:191], v[220:223], v[2:5]
	v_mfma_f32_16x16x32_bf16 v[58:61], v[184:187], v[200:203], v[58:61]
	v_mfma_f32_16x16x32_bf16 v[50:53], v[192:195], v[200:203], v[50:53]
	v_mfma_f32_16x16x32_bf16 v[42:45], v[184:187], v[208:211], v[42:45]
	v_mfma_f32_16x16x32_bf16 v[34:37], v[192:195], v[208:211], v[34:37]
	v_mfma_f32_16x16x32_bf16 v[26:29], v[184:187], v[216:219], v[26:29]
	v_mfma_f32_16x16x32_bf16 v[18:21], v[192:195], v[216:219], v[18:21]
	v_mfma_f32_16x16x32_bf16 v[10:13], v[184:187], v[224:227], v[10:13]
	v_mfma_f32_16x16x32_bf16 v[2:5], v[192:195], v[224:227], v[2:5]
	s_barrier
	s_setprio 0
	s_add_u32 s98, s94, 0x40000
	s_addc_u32 s99, s95, 0
	s_add_i32 s7, 0, 0x18000
	s_add_i32 s47, 0, 0x1c000
	s_mov_b32 m0, s59
	ds_read_b128 v[164:167], v232
	global_load_lds_dwordx4 v130, s[98:99]
	s_mov_b32 m0, s60
	ds_read_b128 v[168:171], v232 offset:1024
	global_load_lds_dwordx4 v134, s[98:99]
	ds_read_b128 v[172:175], v232 offset:2048
	ds_read_b128 v[176:179], v232 offset:3072
	ds_read_b128 v[180:183], v233
	ds_read_b128 v[184:187], v233 offset:1024
	ds_read_b128 v[188:191], v233 offset:2048
	ds_read_b128 v[192:195], v233 offset:3072
	ds_read_b128 v[196:199], v160 offset:32768
	ds_read_b128 v[200:203], v160 offset:33792
	ds_read_b128 v[204:207], v160 offset:34816
	ds_read_b128 v[208:211], v160 offset:35840
	ds_read_b128 v[212:215], v160 offset:36864
	ds_read_b128 v[216:219], v160 offset:37888
	ds_read_b128 v[220:223], v160 offset:38912
	ds_read_b128 v[224:227], v160 offset:39936
	s_waitcnt vmcnt(8)
	s_waitcnt lgkmcnt(0)
	s_setprio 1
	s_barrier
	v_mfma_f32_16x16x32_bf16 v[122:125], v[164:167], v[196:199], v[122:125]
	v_mfma_f32_16x16x32_bf16 v[118:121], v[172:175], v[196:199], v[118:121]
	v_mfma_f32_16x16x32_bf16 v[110:113], v[164:167], v[204:207], v[110:113]
	v_mfma_f32_16x16x32_bf16 v[102:105], v[172:175], v[204:207], v[102:105]
	v_mfma_f32_16x16x32_bf16 v[94:97], v[164:167], v[212:215], v[94:97]
	v_mfma_f32_16x16x32_bf16 v[86:89], v[172:175], v[212:215], v[86:89]
	v_mfma_f32_16x16x32_bf16 v[78:81], v[164:167], v[220:223], v[78:81]
	v_mfma_f32_16x16x32_bf16 v[70:73], v[172:175], v[220:223], v[70:73]
	v_mfma_f32_16x16x32_bf16 v[122:125], v[168:171], v[200:203], v[122:125]
	v_mfma_f32_16x16x32_bf16 v[118:121], v[176:179], v[200:203], v[118:121]
	v_mfma_f32_16x16x32_bf16 v[110:113], v[168:171], v[208:211], v[110:113]
	v_mfma_f32_16x16x32_bf16 v[102:105], v[176:179], v[208:211], v[102:105]
	v_mfma_f32_16x16x32_bf16 v[94:97], v[168:171], v[216:219], v[94:97]
	v_mfma_f32_16x16x32_bf16 v[86:89], v[176:179], v[216:219], v[86:89]
	v_mfma_f32_16x16x32_bf16 v[78:81], v[168:171], v[224:227], v[78:81]
	v_mfma_f32_16x16x32_bf16 v[70:73], v[176:179], v[224:227], v[70:73]
	s_setprio 0
	s_setprio 1
	v_mfma_f32_16x16x32_bf16 v[126:129], v[180:183], v[196:199], v[126:129]
	v_mfma_f32_16x16x32_bf16 v[114:117], v[188:191], v[196:199], v[114:117]
	v_mfma_f32_16x16x32_bf16 v[106:109], v[180:183], v[204:207], v[106:109]
	v_mfma_f32_16x16x32_bf16 v[98:101], v[188:191], v[204:207], v[98:101]
	v_mfma_f32_16x16x32_bf16 v[90:93], v[180:183], v[212:215], v[90:93]
	v_mfma_f32_16x16x32_bf16 v[82:85], v[188:191], v[212:215], v[82:85]
	v_mfma_f32_16x16x32_bf16 v[74:77], v[180:183], v[220:223], v[74:77]
	v_mfma_f32_16x16x32_bf16 v[66:69], v[188:191], v[220:223], v[66:69]
	v_mfma_f32_16x16x32_bf16 v[126:129], v[184:187], v[200:203], v[126:129]
	v_mfma_f32_16x16x32_bf16 v[114:117], v[192:195], v[200:203], v[114:117]
	v_mfma_f32_16x16x32_bf16 v[106:109], v[184:187], v[208:211], v[106:109]
	v_mfma_f32_16x16x32_bf16 v[98:101], v[192:195], v[208:211], v[98:101]
	v_mfma_f32_16x16x32_bf16 v[90:93], v[184:187], v[216:219], v[90:93]
	v_mfma_f32_16x16x32_bf16 v[82:85], v[192:195], v[216:219], v[82:85]
	v_mfma_f32_16x16x32_bf16 v[74:77], v[184:187], v[224:227], v[74:77]
	v_mfma_f32_16x16x32_bf16 v[66:69], v[192:195], v[224:227], v[66:69]
	s_barrier
	s_setprio 0
	s_add_u32 s96, s96, 0x80
	s_addc_u32 s97, s97, 0
	s_add_u32 s98, s96, 0x40000
	s_addc_u32 s99, s97, 0
	s_add_u32 s94, s94, 0x80
	s_addc_u32 s95, s95, 0
	s_add_i32 s7, s7, s25
	s_mov_b32 m0, s7
	ds_read_b128 v[196:199], v160 offset:49152
	global_load_lds_dwordx4 v132, s[96:97]
	s_add_i32 m0, s7, 0x2000
	s_add_i32 s7, s47, s25
	global_load_lds_dwordx4 v136, s[96:97]
	s_mov_b32 m0, s7
	ds_read_b128 v[200:203], v160 offset:50176
	global_load_lds_dwordx4 v132, s[98:99]
	s_add_i32 m0, s7, 0x2000
	ds_read_b128 v[204:207], v160 offset:51200
	global_load_lds_dwordx4 v136, s[98:99]
	s_mov_b32 m0, s66
	ds_read_b128 v[208:211], v160 offset:52224
	global_load_lds_dwordx4 v130, s[94:95]
	s_mov_b32 m0, s67
	ds_read_b128 v[212:215], v160 offset:53248
	global_load_lds_dwordx4 v134, s[94:95]
	ds_read_b128 v[216:219], v160 offset:54272
	ds_read_b128 v[220:223], v160 offset:55296
	ds_read_b128 v[224:227], v160 offset:56320
	s_waitcnt vmcnt(8)
	s_waitcnt lgkmcnt(0)
	s_setprio 1
	s_barrier
	v_mfma_f32_16x16x32_bf16 v[62:65], v[164:167], v[196:199], v[62:65]
	v_mfma_f32_16x16x32_bf16 v[54:57], v[172:175], v[196:199], v[54:57]
	v_mfma_f32_16x16x32_bf16 v[46:49], v[164:167], v[204:207], v[46:49]
	v_mfma_f32_16x16x32_bf16 v[38:41], v[172:175], v[204:207], v[38:41]
	v_mfma_f32_16x16x32_bf16 v[30:33], v[164:167], v[212:215], v[30:33]
	v_mfma_f32_16x16x32_bf16 v[22:25], v[172:175], v[212:215], v[22:25]
	v_mfma_f32_16x16x32_bf16 v[14:17], v[164:167], v[220:223], v[14:17]
	v_mfma_f32_16x16x32_bf16 v[6:9], v[172:175], v[220:223], v[6:9]
	v_mfma_f32_16x16x32_bf16 v[62:65], v[168:171], v[200:203], v[62:65]
	v_mfma_f32_16x16x32_bf16 v[54:57], v[176:179], v[200:203], v[54:57]
	v_mfma_f32_16x16x32_bf16 v[46:49], v[168:171], v[208:211], v[46:49]
	v_mfma_f32_16x16x32_bf16 v[38:41], v[176:179], v[208:211], v[38:41]
	v_mfma_f32_16x16x32_bf16 v[30:33], v[168:171], v[216:219], v[30:33]
	v_mfma_f32_16x16x32_bf16 v[22:25], v[176:179], v[216:219], v[22:25]
	v_mfma_f32_16x16x32_bf16 v[14:17], v[168:171], v[224:227], v[14:17]
	v_mfma_f32_16x16x32_bf16 v[6:9], v[176:179], v[224:227], v[6:9]
	s_setprio 0
	s_setprio 1
	v_mfma_f32_16x16x32_bf16 v[58:61], v[180:183], v[196:199], v[58:61]
	v_mfma_f32_16x16x32_bf16 v[50:53], v[188:191], v[196:199], v[50:53]
	v_mfma_f32_16x16x32_bf16 v[42:45], v[180:183], v[204:207], v[42:45]
	v_mfma_f32_16x16x32_bf16 v[34:37], v[188:191], v[204:207], v[34:37]
	v_mfma_f32_16x16x32_bf16 v[26:29], v[180:183], v[212:215], v[26:29]
	v_mfma_f32_16x16x32_bf16 v[18:21], v[188:191], v[212:215], v[18:21]
	v_mfma_f32_16x16x32_bf16 v[10:13], v[180:183], v[220:223], v[10:13]
	v_mfma_f32_16x16x32_bf16 v[2:5], v[188:191], v[220:223], v[2:5]
	v_mfma_f32_16x16x32_bf16 v[58:61], v[184:187], v[200:203], v[58:61]
	v_mfma_f32_16x16x32_bf16 v[50:53], v[192:195], v[200:203], v[50:53]
	v_mfma_f32_16x16x32_bf16 v[42:45], v[184:187], v[208:211], v[42:45]
	v_mfma_f32_16x16x32_bf16 v[34:37], v[192:195], v[208:211], v[34:37]
	v_mfma_f32_16x16x32_bf16 v[26:29], v[184:187], v[216:219], v[26:29]
	v_mfma_f32_16x16x32_bf16 v[18:21], v[192:195], v[216:219], v[18:21]
	v_mfma_f32_16x16x32_bf16 v[10:13], v[184:187], v[224:227], v[10:13]
	v_mfma_f32_16x16x32_bf16 v[2:5], v[192:195], v[224:227], v[2:5]
	s_barrier
	s_setprio 0
	s_mov_b32 s7, s45
	s_add_u32 s88, s88, 0x100
	s_addc_u32 s89, s89, 0
	s_add_u32 s86, s86, 0x100
	s_addc_u32 s87, s87, 0
	s_cmp_ge_i32 s45, s101
	s_cbranch_scc0 .LBB0_768

.Lmy_nb_4:
	s_nop 0
	v_readfirstlane_b32 s86, v152
	v_readfirstlane_b32 s87, v153
	v_readfirstlane_b32 s88, v150
	v_readfirstlane_b32 s89, v151
	v_readfirstlane_b32 s90, v146
	v_readfirstlane_b32 s91, v147
	v_readfirstlane_b32 s92, v148
	v_readfirstlane_b32 s93, v149
	v_readfirstlane_b32 s100, v154
	v_readfirstlane_b32 s101, v138
	v_add_u32_e32 v230, s74, v141
	v_add_u32_e32 v231, s75, v141
	v_add_u32_e32 v232, 0x18000, v141
	v_add_u32_e32 v233, 0x1c000, v141
	s_add_u32 s98, s86, 0xfffc0080
	s_addc_u32 s99, s87, -1
	s_cmp_eq_u32 s7, s100
	s_cselect_b64 s[94:95], s[90:91], s[98:99]
	s_cselect_b64 s[96:97], s[92:93], s[88:89]
	s_add_i32 s47, s7, 2
	s_mov_b32 m0, s76
	ds_read_b128 v[164:167], v230
	global_load_lds_dwordx4 v144, s[86:87]
	s_mov_b32 m0, s77
	ds_read_b128 v[168:171], v230 offset:1024
	global_load_lds_dwordx4 v142, s[86:87]
	ds_read_b128 v[172:175], v230 offset:2048
	ds_read_b128 v[176:179], v230 offset:3072
	ds_read_b128 v[180:183], v231
	ds_read_b128 v[184:187], v231 offset:1024
	ds_read_b128 v[188:191], v231 offset:2048
	ds_read_b128 v[192:195], v231 offset:3072
	ds_read_b128 v[196:199], v160
	ds_read_b128 v[200:203], v160 offset:1024
	ds_read_b128 v[204:207], v160 offset:2048
	ds_read_b128 v[208:211], v160 offset:3072
	ds_read_b128 v[212:215], v160 offset:4096
	ds_read_b128 v[216:219], v160 offset:5120
	ds_read_b128 v[220:223], v160 offset:6144
	ds_read_b128 v[224:227], v160 offset:7168
	s_waitcnt vmcnt(8)
	s_waitcnt lgkmcnt(0)
	s_setprio 1
	s_barrier
	v_mfma_f32_16x16x32_bf16 v[122:125], v[164:167], v[196:199], 0
	v_mfma_f32_16x16x32_bf16 v[118:121], v[172:175], v[196:199], 0
	v_mfma_f32_16x16x32_bf16 v[110:113], v[164:167], v[204:207], 0
	v_mfma_f32_16x16x32_bf16 v[102:105], v[172:175], v[204:207], 0
	v_mfma_f32_16x16x32_bf16 v[94:97], v[164:167], v[212:215], 0
	v_mfma_f32_16x16x32_bf16 v[86:89], v[172:175], v[212:215], 0
	v_mfma_f32_16x16x32_bf16 v[78:81], v[164:167], v[220:223], 0
	v_mfma_f32_16x16x32_bf16 v[70:73], v[172:175], v[220:223], 0
	v_mfma_f32_16x16x32_bf16 v[122:125], v[168:171], v[200:203], v[122:125]
	v_mfma_f32_16x16x32_bf16 v[118:121], v[176:179], v[200:203], v[118:121]
	v_mfma_f32_16x16x32_bf16 v[110:113], v[168:171], v[208:211], v[110:113]
	v_mfma_f32_16x16x32_bf16 v[102:105], v[176:179], v[208:211], v[102:105]
	v_mfma_f32_16x16x32_bf16 v[94:97], v[168:171], v[216:219], v[94:97]
	v_mfma_f32_16x16x32_bf16 v[86:89], v[176:179], v[216:219], v[86:89]
	v_mfma_f32_16x16x32_bf16 v[78:81], v[168:171], v[224:227], v[78:81]
	v_mfma_f32_16x16x32_bf16 v[70:73], v[176:179], v[224:227], v[70:73]
	s_setprio 0
	s_setprio 1
	v_mfma_f32_16x16x32_bf16 v[126:129], v[180:183], v[196:199], 0
	v_mfma_f32_16x16x32_bf16 v[114:117], v[188:191], v[196:199], 0
	v_mfma_f32_16x16x32_bf16 v[106:109], v[180:183], v[204:207], 0
	v_mfma_f32_16x16x32_bf16 v[98:101], v[188:191], v[204:207], 0
	v_mfma_f32_16x16x32_bf16 v[90:93], v[180:183], v[212:215], 0
	v_mfma_f32_16x16x32_bf16 v[82:85], v[188:191], v[212:215], 0
	v_mfma_f32_16x16x32_bf16 v[74:77], v[180:183], v[220:223], 0
	v_mfma_f32_16x16x32_bf16 v[66:69], v[188:191], v[220:223], 0
	v_mfma_f32_16x16x32_bf16 v[126:129], v[184:187], v[200:203], v[126:129]
	v_mfma_f32_16x16x32_bf16 v[114:117], v[192:195], v[200:203], v[114:117]
	v_mfma_f32_16x16x32_bf16 v[106:109], v[184:187], v[208:211], v[106:109]
	v_mfma_f32_16x16x32_bf16 v[98:101], v[192:195], v[208:211], v[98:101]
	v_mfma_f32_16x16x32_bf16 v[90:93], v[184:187], v[216:219], v[90:93]
	v_mfma_f32_16x16x32_bf16 v[82:85], v[192:195], v[216:219], v[82:85]
	v_mfma_f32_16x16x32_bf16 v[74:77], v[184:187], v[224:227], v[74:77]
	v_mfma_f32_16x16x32_bf16 v[66:69], v[192:195], v[224:227], v[66:69]
	s_barrier
	s_setprio 0
	s_add_u32 s98, s96, 0x40000
	s_addc_u32 s99, s97, 0
	s_mov_b32 m0, s78
	ds_read_b128 v[196:199], v160 offset:16384
	global_load_lds_dwordx4 v132, s[96:97]
	s_mov_b32 m0, s79
	s_add_i32 s7, s75, s29
	global_load_lds_dwordx4 v136, s[96:97]
	s_mov_b32 m0, s7
	ds_read_b128 v[200:203], v160 offset:17408
	global_load_lds_dwordx4 v132, s[98:99]
	s_add_i32 m0, s7, 0x2000
	ds_read_b128 v[204:207], v160 offset:18432
	global_load_lds_dwordx4 v136, s[98:99]
	s_mov_b32 m0, s51
	ds_read_b128 v[208:211], v160 offset:19456
	global_load_lds_dwordx4 v130, s[94:95]
	s_mov_b32 m0, s60
	ds_read_b128 v[212:215], v160 offset:20480
	global_load_lds_dwordx4 v134, s[94:95]
	ds_read_b128 v[216:219], v160 offset:21504
	ds_read_b128 v[220:223], v160 offset:22528
	ds_read_b128 v[224:227], v160 offset:23552
	s_waitcnt vmcnt(8)
	s_waitcnt lgkmcnt(0)
	s_setprio 1
	s_barrier
	v_mfma_f32_16x16x32_bf16 v[62:65], v[164:167], v[196:199], 0
	v_mfma_f32_16x16x32_bf16 v[54:57], v[172:175], v[196:199], 0
	v_mfma_f32_16x16x32_bf16 v[46:49], v[164:167], v[204:207], 0
	v_mfma_f32_16x16x32_bf16 v[38:41], v[172:175], v[204:207], 0
	v_mfma_f32_16x16x32_bf16 v[30:33], v[164:167], v[212:215], 0
	v_mfma_f32_16x16x32_bf16 v[22:25], v[172:175], v[212:215], 0
	v_mfma_f32_16x16x32_bf16 v[14:17], v[164:167], v[220:223], 0
	v_mfma_f32_16x16x32_bf16 v[6:9], v[172:175], v[220:223], 0
	v_mfma_f32_16x16x32_bf16 v[62:65], v[168:171], v[200:203], v[62:65]
	v_mfma_f32_16x16x32_bf16 v[54:57], v[176:179], v[200:203], v[54:57]
	v_mfma_f32_16x16x32_bf16 v[46:49], v[168:171], v[208:211], v[46:49]
	v_mfma_f32_16x16x32_bf16 v[38:41], v[176:179], v[208:211], v[38:41]
	v_mfma_f32_16x16x32_bf16 v[30:33], v[168:171], v[216:219], v[30:33]
	v_mfma_f32_16x16x32_bf16 v[22:25], v[176:179], v[216:219], v[22:25]
	v_mfma_f32_16x16x32_bf16 v[14:17], v[168:171], v[224:227], v[14:17]
	v_mfma_f32_16x16x32_bf16 v[6:9], v[176:179], v[224:227], v[6:9]
	s_setprio 0
	s_setprio 1
	v_mfma_f32_16x16x32_bf16 v[58:61], v[180:183], v[196:199], 0
	v_mfma_f32_16x16x32_bf16 v[50:53], v[188:191], v[196:199], 0
	v_mfma_f32_16x16x32_bf16 v[42:45], v[180:183], v[204:207], 0
	v_mfma_f32_16x16x32_bf16 v[34:37], v[188:191], v[204:207], 0
	v_mfma_f32_16x16x32_bf16 v[26:29], v[180:183], v[212:215], 0
	v_mfma_f32_16x16x32_bf16 v[18:21], v[188:191], v[212:215], 0
	v_mfma_f32_16x16x32_bf16 v[10:13], v[180:183], v[220:223], 0
	v_mfma_f32_16x16x32_bf16 v[2:5], v[188:191], v[220:223], 0
	v_mfma_f32_16x16x32_bf16 v[58:61], v[184:187], v[200:203], v[58:61]
	v_mfma_f32_16x16x32_bf16 v[50:53], v[192:195], v[200:203], v[50:53]
	v_mfma_f32_16x16x32_bf16 v[42:45], v[184:187], v[208:211], v[42:45]
	v_mfma_f32_16x16x32_bf16 v[34:37], v[192:195], v[208:211], v[34:37]
	v_mfma_f32_16x16x32_bf16 v[26:29], v[184:187], v[216:219], v[26:29]
	v_mfma_f32_16x16x32_bf16 v[18:21], v[192:195], v[216:219], v[18:21]
	v_mfma_f32_16x16x32_bf16 v[10:13], v[184:187], v[224:227], v[10:13]
	v_mfma_f32_16x16x32_bf16 v[2:5], v[192:195], v[224:227], v[2:5]
	s_barrier
	s_setprio 0
	s_add_u32 s98, s94, 0x40000
	s_addc_u32 s99, s95, 0
	s_add_i32 s7, 0, 0x18000
	s_add_i32 s49, 0, 0x1c000
	s_mov_b32 m0, s61
	ds_read_b128 v[164:167], v232
	global_load_lds_dwordx4 v130, s[98:99]
	s_mov_b32 m0, s62
	ds_read_b128 v[168:171], v232 offset:1024
	global_load_lds_dwordx4 v134, s[98:99]
	ds_read_b128 v[172:175], v232 offset:2048
	ds_read_b128 v[176:179], v232 offset:3072
	ds_read_b128 v[180:183], v233
	ds_read_b128 v[184:187], v233 offset:1024
	ds_read_b128 v[188:191], v233 offset:2048
	ds_read_b128 v[192:195], v233 offset:3072
	ds_read_b128 v[196:199], v160 offset:32768
	ds_read_b128 v[200:203], v160 offset:33792
	ds_read_b128 v[204:207], v160 offset:34816
	ds_read_b128 v[208:211], v160 offset:35840
	ds_read_b128 v[212:215], v160 offset:36864
	ds_read_b128 v[216:219], v160 offset:37888
	ds_read_b128 v[220:223], v160 offset:38912
	ds_read_b128 v[224:227], v160 offset:39936
	s_waitcnt vmcnt(8)
	s_waitcnt lgkmcnt(0)
	s_setprio 1
	s_barrier
	v_mfma_f32_16x16x32_bf16 v[122:125], v[164:167], v[196:199], v[122:125]
	v_mfma_f32_16x16x32_bf16 v[118:121], v[172:175], v[196:199], v[118:121]
	v_mfma_f32_16x16x32_bf16 v[110:113], v[164:167], v[204:207], v[110:113]
	v_mfma_f32_16x16x32_bf16 v[102:105], v[172:175], v[204:207], v[102:105]
	v_mfma_f32_16x16x32_bf16 v[94:97], v[164:167], v[212:215], v[94:97]
	v_mfma_f32_16x16x32_bf16 v[86:89], v[172:175], v[212:215], v[86:89]
	v_mfma_f32_16x16x32_bf16 v[78:81], v[164:167], v[220:223], v[78:81]
	v_mfma_f32_16x16x32_bf16 v[70:73], v[172:175], v[220:223], v[70:73]
	v_mfma_f32_16x16x32_bf16 v[122:125], v[168:171], v[200:203], v[122:125]
	v_mfma_f32_16x16x32_bf16 v[118:121], v[176:179], v[200:203], v[118:121]
	v_mfma_f32_16x16x32_bf16 v[110:113], v[168:171], v[208:211], v[110:113]
	v_mfma_f32_16x16x32_bf16 v[102:105], v[176:179], v[208:211], v[102:105]
	v_mfma_f32_16x16x32_bf16 v[94:97], v[168:171], v[216:219], v[94:97]
	v_mfma_f32_16x16x32_bf16 v[86:89], v[176:179], v[216:219], v[86:89]
	v_mfma_f32_16x16x32_bf16 v[78:81], v[168:171], v[224:227], v[78:81]
	v_mfma_f32_16x16x32_bf16 v[70:73], v[176:179], v[224:227], v[70:73]
	s_setprio 0
	s_setprio 1
	v_mfma_f32_16x16x32_bf16 v[126:129], v[180:183], v[196:199], v[126:129]
	v_mfma_f32_16x16x32_bf16 v[114:117], v[188:191], v[196:199], v[114:117]
	v_mfma_f32_16x16x32_bf16 v[106:109], v[180:183], v[204:207], v[106:109]
	v_mfma_f32_16x16x32_bf16 v[98:101], v[188:191], v[204:207], v[98:101]
	v_mfma_f32_16x16x32_bf16 v[90:93], v[180:183], v[212:215], v[90:93]
	v_mfma_f32_16x16x32_bf16 v[82:85], v[188:191], v[212:215], v[82:85]
	v_mfma_f32_16x16x32_bf16 v[74:77], v[180:183], v[220:223], v[74:77]
	v_mfma_f32_16x16x32_bf16 v[66:69], v[188:191], v[220:223], v[66:69]
	v_mfma_f32_16x16x32_bf16 v[126:129], v[184:187], v[200:203], v[126:129]
	v_mfma_f32_16x16x32_bf16 v[114:117], v[192:195], v[200:203], v[114:117]
	v_mfma_f32_16x16x32_bf16 v[106:109], v[184:187], v[208:211], v[106:109]
	v_mfma_f32_16x16x32_bf16 v[98:101], v[192:195], v[208:211], v[98:101]
	v_mfma_f32_16x16x32_bf16 v[90:93], v[184:187], v[216:219], v[90:93]
	v_mfma_f32_16x16x32_bf16 v[82:85], v[192:195], v[216:219], v[82:85]
	v_mfma_f32_16x16x32_bf16 v[74:77], v[184:187], v[224:227], v[74:77]
	v_mfma_f32_16x16x32_bf16 v[66:69], v[192:195], v[224:227], v[66:69]
	s_barrier
	s_setprio 0
	s_add_u32 s96, s96, 0x80
	s_addc_u32 s97, s97, 0
	s_add_u32 s98, s96, 0x40000
	s_addc_u32 s99, s97, 0
	s_add_u32 s94, s94, 0x80
	s_addc_u32 s95, s95, 0
	s_add_i32 s7, s7, s29
	s_mov_b32 m0, s7
	ds_read_b128 v[196:199], v160 offset:49152
	global_load_lds_dwordx4 v132, s[96:97]
	s_add_i32 m0, s7, 0x2000
	s_add_i32 s7, s49, s29
	global_load_lds_dwordx4 v136, s[96:97]
	s_mov_b32 m0, s7
	ds_read_b128 v[200:203], v160 offset:50176
	global_load_lds_dwordx4 v132, s[98:99]
	s_add_i32 m0, s7, 0x2000
	ds_read_b128 v[204:207], v160 offset:51200
	global_load_lds_dwordx4 v136, s[98:99]
	s_mov_b32 m0, s63
	ds_read_b128 v[208:211], v160 offset:52224
	global_load_lds_dwordx4 v130, s[94:95]
	s_mov_b32 m0, s64
	ds_read_b128 v[212:215], v160 offset:53248
	global_load_lds_dwordx4 v134, s[94:95]
	ds_read_b128 v[216:219], v160 offset:54272
	ds_read_b128 v[220:223], v160 offset:55296
	ds_read_b128 v[224:227], v160 offset:56320
	s_waitcnt vmcnt(8)
	s_waitcnt lgkmcnt(0)
	s_setprio 1
	s_barrier
	v_mfma_f32_16x16x32_bf16 v[62:65], v[164:167], v[196:199], v[62:65]
	v_mfma_f32_16x16x32_bf16 v[54:57], v[172:175], v[196:199], v[54:57]
	v_mfma_f32_16x16x32_bf16 v[46:49], v[164:167], v[204:207], v[46:49]
	v_mfma_f32_16x16x32_bf16 v[38:41], v[172:175], v[204:207], v[38:41]
	v_mfma_f32_16x16x32_bf16 v[30:33], v[164:167], v[212:215], v[30:33]
	v_mfma_f32_16x16x32_bf16 v[22:25], v[172:175], v[212:215], v[22:25]
	v_mfma_f32_16x16x32_bf16 v[14:17], v[164:167], v[220:223], v[14:17]
	v_mfma_f32_16x16x32_bf16 v[6:9], v[172:175], v[220:223], v[6:9]
	v_mfma_f32_16x16x32_bf16 v[62:65], v[168:171], v[200:203], v[62:65]
	v_mfma_f32_16x16x32_bf16 v[54:57], v[176:179], v[200:203], v[54:57]
	v_mfma_f32_16x16x32_bf16 v[46:49], v[168:171], v[208:211], v[46:49]
	v_mfma_f32_16x16x32_bf16 v[38:41], v[176:179], v[208:211], v[38:41]
	v_mfma_f32_16x16x32_bf16 v[30:33], v[168:171], v[216:219], v[30:33]
	v_mfma_f32_16x16x32_bf16 v[22:25], v[176:179], v[216:219], v[22:25]
	v_mfma_f32_16x16x32_bf16 v[14:17], v[168:171], v[224:227], v[14:17]
	v_mfma_f32_16x16x32_bf16 v[6:9], v[176:179], v[224:227], v[6:9]
	s_setprio 0
	s_setprio 1
	v_mfma_f32_16x16x32_bf16 v[58:61], v[180:183], v[196:199], v[58:61]
	v_mfma_f32_16x16x32_bf16 v[50:53], v[188:191], v[196:199], v[50:53]
	v_mfma_f32_16x16x32_bf16 v[42:45], v[180:183], v[204:207], v[42:45]
	v_mfma_f32_16x16x32_bf16 v[34:37], v[188:191], v[204:207], v[34:37]
	v_mfma_f32_16x16x32_bf16 v[26:29], v[180:183], v[212:215], v[26:29]
	v_mfma_f32_16x16x32_bf16 v[18:21], v[188:191], v[212:215], v[18:21]
	v_mfma_f32_16x16x32_bf16 v[10:13], v[180:183], v[220:223], v[10:13]
	v_mfma_f32_16x16x32_bf16 v[2:5], v[188:191], v[220:223], v[2:5]
	v_mfma_f32_16x16x32_bf16 v[58:61], v[184:187], v[200:203], v[58:61]
	v_mfma_f32_16x16x32_bf16 v[50:53], v[192:195], v[200:203], v[50:53]
	v_mfma_f32_16x16x32_bf16 v[42:45], v[184:187], v[208:211], v[42:45]
	v_mfma_f32_16x16x32_bf16 v[34:37], v[192:195], v[208:211], v[34:37]
	v_mfma_f32_16x16x32_bf16 v[26:29], v[184:187], v[216:219], v[26:29]
	v_mfma_f32_16x16x32_bf16 v[18:21], v[192:195], v[216:219], v[18:21]
	v_mfma_f32_16x16x32_bf16 v[10:13], v[184:187], v[224:227], v[10:13]
	v_mfma_f32_16x16x32_bf16 v[2:5], v[192:195], v[224:227], v[2:5]
	s_barrier
	s_setprio 0
	s_mov_b32 s7, s47
	s_add_u32 s88, s88, 0x100
	s_addc_u32 s89, s89, 0
	s_add_u32 s86, s86, 0x100
	s_addc_u32 s87, s87, 0
	s_cmp_ge_i32 s47, s101
	s_cbranch_scc1 .Lmy_kexit_4
.LBB0_949:
	s_add_u32 s98, s86, 0xfffc0080
	s_addc_u32 s99, s87, -1
	s_cmp_eq_u32 s7, s100
	s_cselect_b64 s[94:95], s[90:91], s[98:99]
	s_cselect_b64 s[96:97], s[92:93], s[88:89]
	s_add_i32 s47, s7, 2
	s_mov_b32 m0, s76
	ds_read_b128 v[164:167], v230
	global_load_lds_dwordx4 v144, s[86:87]
	s_mov_b32 m0, s77
	ds_read_b128 v[168:171], v230 offset:1024
	global_load_lds_dwordx4 v142, s[86:87]
	ds_read_b128 v[172:175], v230 offset:2048
	ds_read_b128 v[176:179], v230 offset:3072
	ds_read_b128 v[180:183], v231
	ds_read_b128 v[184:187], v231 offset:1024
	ds_read_b128 v[188:191], v231 offset:2048
	ds_read_b128 v[192:195], v231 offset:3072
	ds_read_b128 v[196:199], v160
	ds_read_b128 v[200:203], v160 offset:1024
	ds_read_b128 v[204:207], v160 offset:2048
	ds_read_b128 v[208:211], v160 offset:3072
	ds_read_b128 v[212:215], v160 offset:4096
	ds_read_b128 v[216:219], v160 offset:5120
	ds_read_b128 v[220:223], v160 offset:6144
	ds_read_b128 v[224:227], v160 offset:7168
	s_waitcnt vmcnt(8)
	s_waitcnt lgkmcnt(0)
	s_setprio 1
	s_barrier
	v_mfma_f32_16x16x32_bf16 v[122:125], v[164:167], v[196:199], v[122:125]
	v_mfma_f32_16x16x32_bf16 v[118:121], v[172:175], v[196:199], v[118:121]
	v_mfma_f32_16x16x32_bf16 v[110:113], v[164:167], v[204:207], v[110:113]
	v_mfma_f32_16x16x32_bf16 v[102:105], v[172:175], v[204:207], v[102:105]
	v_mfma_f32_16x16x32_bf16 v[94:97], v[164:167], v[212:215], v[94:97]
	v_mfma_f32_16x16x32_bf16 v[86:89], v[172:175], v[212:215], v[86:89]
	v_mfma_f32_16x16x32_bf16 v[78:81], v[164:167], v[220:223], v[78:81]
	v_mfma_f32_16x16x32_bf16 v[70:73], v[172:175], v[220:223], v[70:73]
	v_mfma_f32_16x16x32_bf16 v[122:125], v[168:171], v[200:203], v[122:125]
	v_mfma_f32_16x16x32_bf16 v[118:121], v[176:179], v[200:203], v[118:121]
	v_mfma_f32_16x16x32_bf16 v[110:113], v[168:171], v[208:211], v[110:113]
	v_mfma_f32_16x16x32_bf16 v[102:105], v[176:179], v[208:211], v[102:105]
	v_mfma_f32_16x16x32_bf16 v[94:97], v[168:171], v[216:219], v[94:97]
	v_mfma_f32_16x16x32_bf16 v[86:89], v[176:179], v[216:219], v[86:89]
	v_mfma_f32_16x16x32_bf16 v[78:81], v[168:171], v[224:227], v[78:81]
	v_mfma_f32_16x16x32_bf16 v[70:73], v[176:179], v[224:227], v[70:73]
	s_setprio 0
	s_setprio 1
	v_mfma_f32_16x16x32_bf16 v[126:129], v[180:183], v[196:199], v[126:129]
	v_mfma_f32_16x16x32_bf16 v[114:117], v[188:191], v[196:199], v[114:117]
	v_mfma_f32_16x16x32_bf16 v[106:109], v[180:183], v[204:207], v[106:109]
	v_mfma_f32_16x16x32_bf16 v[98:101], v[188:191], v[204:207], v[98:101]
	v_mfma_f32_16x16x32_bf16 v[90:93], v[180:183], v[212:215], v[90:93]
	v_mfma_f32_16x16x32_bf16 v[82:85], v[188:191], v[212:215], v[82:85]
	v_mfma_f32_16x16x32_bf16 v[74:77], v[180:183], v[220:223], v[74:77]
	v_mfma_f32_16x16x32_bf16 v[66:69], v[188:191], v[220:223], v[66:69]
	v_mfma_f32_16x16x32_bf16 v[126:129], v[184:187], v[200:203], v[126:129]
	v_mfma_f32_16x16x32_bf16 v[114:117], v[192:195], v[200:203], v[114:117]
	v_mfma_f32_16x16x32_bf16 v[106:109], v[184:187], v[208:211], v[106:109]
	v_mfma_f32_16x16x32_bf16 v[98:101], v[192:195], v[208:211], v[98:101]
	v_mfma_f32_16x16x32_bf16 v[90:93], v[184:187], v[216:219], v[90:93]
	v_mfma_f32_16x16x32_bf16 v[82:85], v[192:195], v[216:219], v[82:85]
	v_mfma_f32_16x16x32_bf16 v[74:77], v[184:187], v[224:227], v[74:77]
	v_mfma_f32_16x16x32_bf16 v[66:69], v[192:195], v[224:227], v[66:69]
	s_barrier
	s_setprio 0
	s_add_u32 s98, s96, 0x40000
	s_addc_u32 s99, s97, 0
	s_mov_b32 m0, s78
	ds_read_b128 v[196:199], v160 offset:16384
	global_load_lds_dwordx4 v132, s[96:97]
	s_mov_b32 m0, s79
	s_add_i32 s7, s75, s29
	global_load_lds_dwordx4 v136, s[96:97]
	s_mov_b32 m0, s7
	ds_read_b128 v[200:203], v160 offset:17408
	global_load_lds_dwordx4 v132, s[98:99]
	s_add_i32 m0, s7, 0x2000
	ds_read_b128 v[204:207], v160 offset:18432
	global_load_lds_dwordx4 v136, s[98:99]
	s_mov_b32 m0, s51
	ds_read_b128 v[208:211], v160 offset:19456
	global_load_lds_dwordx4 v130, s[94:95]
	s_mov_b32 m0, s60
	ds_read_b128 v[212:215], v160 offset:20480
	global_load_lds_dwordx4 v134, s[94:95]
	ds_read_b128 v[216:219], v160 offset:21504
	ds_read_b128 v[220:223], v160 offset:22528
	ds_read_b128 v[224:227], v160 offset:23552
	s_waitcnt vmcnt(8)
	s_waitcnt lgkmcnt(0)
	s_setprio 1
	s_barrier
	v_mfma_f32_16x16x32_bf16 v[62:65], v[164:167], v[196:199], v[62:65]
	v_mfma_f32_16x16x32_bf16 v[54:57], v[172:175], v[196:199], v[54:57]
	v_mfma_f32_16x16x32_bf16 v[46:49], v[164:167], v[204:207], v[46:49]
	v_mfma_f32_16x16x32_bf16 v[38:41], v[172:175], v[204:207], v[38:41]
	v_mfma_f32_16x16x32_bf16 v[30:33], v[164:167], v[212:215], v[30:33]
	v_mfma_f32_16x16x32_bf16 v[22:25], v[172:175], v[212:215], v[22:25]
	v_mfma_f32_16x16x32_bf16 v[14:17], v[164:167], v[220:223], v[14:17]
	v_mfma_f32_16x16x32_bf16 v[6:9], v[172:175], v[220:223], v[6:9]
	v_mfma_f32_16x16x32_bf16 v[62:65], v[168:171], v[200:203], v[62:65]
	v_mfma_f32_16x16x32_bf16 v[54:57], v[176:179], v[200:203], v[54:57]
	v_mfma_f32_16x16x32_bf16 v[46:49], v[168:171], v[208:211], v[46:49]
	v_mfma_f32_16x16x32_bf16 v[38:41], v[176:179], v[208:211], v[38:41]
	v_mfma_f32_16x16x32_bf16 v[30:33], v[168:171], v[216:219], v[30:33]
	v_mfma_f32_16x16x32_bf16 v[22:25], v[176:179], v[216:219], v[22:25]
	v_mfma_f32_16x16x32_bf16 v[14:17], v[168:171], v[224:227], v[14:17]
	v_mfma_f32_16x16x32_bf16 v[6:9], v[176:179], v[224:227], v[6:9]
	s_setprio 0
	s_setprio 1
	v_mfma_f32_16x16x32_bf16 v[58:61], v[180:183], v[196:199], v[58:61]
	v_mfma_f32_16x16x32_bf16 v[50:53], v[188:191], v[196:199], v[50:53]
	v_mfma_f32_16x16x32_bf16 v[42:45], v[180:183], v[204:207], v[42:45]
	v_mfma_f32_16x16x32_bf16 v[34:37], v[188:191], v[204:207], v[34:37]
	v_mfma_f32_16x16x32_bf16 v[26:29], v[180:183], v[212:215], v[26:29]
	v_mfma_f32_16x16x32_bf16 v[18:21], v[188:191], v[212:215], v[18:21]
	v_mfma_f32_16x16x32_bf16 v[10:13], v[180:183], v[220:223], v[10:13]
	v_mfma_f32_16x16x32_bf16 v[2:5], v[188:191], v[220:223], v[2:5]
	v_mfma_f32_16x16x32_bf16 v[58:61], v[184:187], v[200:203], v[58:61]
	v_mfma_f32_16x16x32_bf16 v[50:53], v[192:195], v[200:203], v[50:53]
	v_mfma_f32_16x16x32_bf16 v[42:45], v[184:187], v[208:211], v[42:45]
	v_mfma_f32_16x16x32_bf16 v[34:37], v[192:195], v[208:211], v[34:37]
	v_mfma_f32_16x16x32_bf16 v[26:29], v[184:187], v[216:219], v[26:29]
	v_mfma_f32_16x16x32_bf16 v[18:21], v[192:195], v[216:219], v[18:21]
	v_mfma_f32_16x16x32_bf16 v[10:13], v[184:187], v[224:227], v[10:13]
	v_mfma_f32_16x16x32_bf16 v[2:5], v[192:195], v[224:227], v[2:5]
	s_barrier
	s_setprio 0
	s_add_u32 s98, s94, 0x40000
	s_addc_u32 s99, s95, 0
	s_add_i32 s7, 0, 0x18000
	s_add_i32 s49, 0, 0x1c000
	s_mov_b32 m0, s61
	ds_read_b128 v[164:167], v232
	global_load_lds_dwordx4 v130, s[98:99]
	s_mov_b32 m0, s62
	ds_read_b128 v[168:171], v232 offset:1024
	global_load_lds_dwordx4 v134, s[98:99]
	ds_read_b128 v[172:175], v232 offset:2048
	ds_read_b128 v[176:179], v232 offset:3072
	ds_read_b128 v[180:183], v233
	ds_read_b128 v[184:187], v233 offset:1024
	ds_read_b128 v[188:191], v233 offset:2048
	ds_read_b128 v[192:195], v233 offset:3072
	ds_read_b128 v[196:199], v160 offset:32768
	ds_read_b128 v[200:203], v160 offset:33792
	ds_read_b128 v[204:207], v160 offset:34816
	ds_read_b128 v[208:211], v160 offset:35840
	ds_read_b128 v[212:215], v160 offset:36864
	ds_read_b128 v[216:219], v160 offset:37888
	ds_read_b128 v[220:223], v160 offset:38912
	ds_read_b128 v[224:227], v160 offset:39936
	s_waitcnt vmcnt(8)
	s_waitcnt lgkmcnt(0)
	s_setprio 1
	s_barrier
	v_mfma_f32_16x16x32_bf16 v[122:125], v[164:167], v[196:199], v[122:125]
	v_mfma_f32_16x16x32_bf16 v[118:121], v[172:175], v[196:199], v[118:121]
	v_mfma_f32_16x16x32_bf16 v[110:113], v[164:167], v[204:207], v[110:113]
	v_mfma_f32_16x16x32_bf16 v[102:105], v[172:175], v[204:207], v[102:105]
	v_mfma_f32_16x16x32_bf16 v[94:97], v[164:167], v[212:215], v[94:97]
	v_mfma_f32_16x16x32_bf16 v[86:89], v[172:175], v[212:215], v[86:89]
	v_mfma_f32_16x16x32_bf16 v[78:81], v[164:167], v[220:223], v[78:81]
	v_mfma_f32_16x16x32_bf16 v[70:73], v[172:175], v[220:223], v[70:73]
	v_mfma_f32_16x16x32_bf16 v[122:125], v[168:171], v[200:203], v[122:125]
	v_mfma_f32_16x16x32_bf16 v[118:121], v[176:179], v[200:203], v[118:121]
	v_mfma_f32_16x16x32_bf16 v[110:113], v[168:171], v[208:211], v[110:113]
	v_mfma_f32_16x16x32_bf16 v[102:105], v[176:179], v[208:211], v[102:105]
	v_mfma_f32_16x16x32_bf16 v[94:97], v[168:171], v[216:219], v[94:97]
	v_mfma_f32_16x16x32_bf16 v[86:89], v[176:179], v[216:219], v[86:89]
	v_mfma_f32_16x16x32_bf16 v[78:81], v[168:171], v[224:227], v[78:81]
	v_mfma_f32_16x16x32_bf16 v[70:73], v[176:179], v[224:227], v[70:73]
	s_setprio 0
	s_setprio 1
	v_mfma_f32_16x16x32_bf16 v[126:129], v[180:183], v[196:199], v[126:129]
	v_mfma_f32_16x16x32_bf16 v[114:117], v[188:191], v[196:199], v[114:117]
	v_mfma_f32_16x16x32_bf16 v[106:109], v[180:183], v[204:207], v[106:109]
	v_mfma_f32_16x16x32_bf16 v[98:101], v[188:191], v[204:207], v[98:101]
	v_mfma_f32_16x16x32_bf16 v[90:93], v[180:183], v[212:215], v[90:93]
	v_mfma_f32_16x16x32_bf16 v[82:85], v[188:191], v[212:215], v[82:85]
	v_mfma_f32_16x16x32_bf16 v[74:77], v[180:183], v[220:223], v[74:77]
	v_mfma_f32_16x16x32_bf16 v[66:69], v[188:191], v[220:223], v[66:69]
	v_mfma_f32_16x16x32_bf16 v[126:129], v[184:187], v[200:203], v[126:129]
	v_mfma_f32_16x16x32_bf16 v[114:117], v[192:195], v[200:203], v[114:117]
	v_mfma_f32_16x16x32_bf16 v[106:109], v[184:187], v[208:211], v[106:109]
	v_mfma_f32_16x16x32_bf16 v[98:101], v[192:195], v[208:211], v[98:101]
	v_mfma_f32_16x16x32_bf16 v[90:93], v[184:187], v[216:219], v[90:93]
	v_mfma_f32_16x16x32_bf16 v[82:85], v[192:195], v[216:219], v[82:85]
	v_mfma_f32_16x16x32_bf16 v[74:77], v[184:187], v[224:227], v[74:77]
	v_mfma_f32_16x16x32_bf16 v[66:69], v[192:195], v[224:227], v[66:69]
	s_barrier
	s_setprio 0
	s_add_u32 s96, s96, 0x80
	s_addc_u32 s97, s97, 0
	s_add_u32 s98, s96, 0x40000
	s_addc_u32 s99, s97, 0
	s_add_u32 s94, s94, 0x80
	s_addc_u32 s95, s95, 0
	s_add_i32 s7, s7, s29
	s_mov_b32 m0, s7
	ds_read_b128 v[196:199], v160 offset:49152
	global_load_lds_dwordx4 v132, s[96:97]
	s_add_i32 m0, s7, 0x2000
	s_add_i32 s7, s49, s29
	global_load_lds_dwordx4 v136, s[96:97]
	s_mov_b32 m0, s7
	ds_read_b128 v[200:203], v160 offset:50176
	global_load_lds_dwordx4 v132, s[98:99]
	s_add_i32 m0, s7, 0x2000
	ds_read_b128 v[204:207], v160 offset:51200
	global_load_lds_dwordx4 v136, s[98:99]
	s_mov_b32 m0, s63
	ds_read_b128 v[208:211], v160 offset:52224
	global_load_lds_dwordx4 v130, s[94:95]
	s_mov_b32 m0, s64
	ds_read_b128 v[212:215], v160 offset:53248
	global_load_lds_dwordx4 v134, s[94:95]
	ds_read_b128 v[216:219], v160 offset:54272
	ds_read_b128 v[220:223], v160 offset:55296
	ds_read_b128 v[224:227], v160 offset:56320
	s_waitcnt vmcnt(8)
	s_waitcnt lgkmcnt(0)
	s_setprio 1
	s_barrier
	v_mfma_f32_16x16x32_bf16 v[62:65], v[164:167], v[196:199], v[62:65]
	v_mfma_f32_16x16x32_bf16 v[54:57], v[172:175], v[196:199], v[54:57]
	v_mfma_f32_16x16x32_bf16 v[46:49], v[164:167], v[204:207], v[46:49]
	v_mfma_f32_16x16x32_bf16 v[38:41], v[172:175], v[204:207], v[38:41]
	v_mfma_f32_16x16x32_bf16 v[30:33], v[164:167], v[212:215], v[30:33]
	v_mfma_f32_16x16x32_bf16 v[22:25], v[172:175], v[212:215], v[22:25]
	v_mfma_f32_16x16x32_bf16 v[14:17], v[164:167], v[220:223], v[14:17]
	v_mfma_f32_16x16x32_bf16 v[6:9], v[172:175], v[220:223], v[6:9]
	v_mfma_f32_16x16x32_bf16 v[62:65], v[168:171], v[200:203], v[62:65]
	v_mfma_f32_16x16x32_bf16 v[54:57], v[176:179], v[200:203], v[54:57]
	v_mfma_f32_16x16x32_bf16 v[46:49], v[168:171], v[208:211], v[46:49]
	v_mfma_f32_16x16x32_bf16 v[38:41], v[176:179], v[208:211], v[38:41]
	v_mfma_f32_16x16x32_bf16 v[30:33], v[168:171], v[216:219], v[30:33]
	v_mfma_f32_16x16x32_bf16 v[22:25], v[176:179], v[216:219], v[22:25]
	v_mfma_f32_16x16x32_bf16 v[14:17], v[168:171], v[224:227], v[14:17]
	v_mfma_f32_16x16x32_bf16 v[6:9], v[176:179], v[224:227], v[6:9]
	s_setprio 0
	s_setprio 1
	v_mfma_f32_16x16x32_bf16 v[58:61], v[180:183], v[196:199], v[58:61]
	v_mfma_f32_16x16x32_bf16 v[50:53], v[188:191], v[196:199], v[50:53]
	v_mfma_f32_16x16x32_bf16 v[42:45], v[180:183], v[204:207], v[42:45]
	v_mfma_f32_16x16x32_bf16 v[34:37], v[188:191], v[204:207], v[34:37]
	v_mfma_f32_16x16x32_bf16 v[26:29], v[180:183], v[212:215], v[26:29]
	v_mfma_f32_16x16x32_bf16 v[18:21], v[188:191], v[212:215], v[18:21]
	v_mfma_f32_16x16x32_bf16 v[10:13], v[180:183], v[220:223], v[10:13]
	v_mfma_f32_16x16x32_bf16 v[2:5], v[188:191], v[220:223], v[2:5]
	v_mfma_f32_16x16x32_bf16 v[58:61], v[184:187], v[200:203], v[58:61]
	v_mfma_f32_16x16x32_bf16 v[50:53], v[192:195], v[200:203], v[50:53]
	v_mfma_f32_16x16x32_bf16 v[42:45], v[184:187], v[208:211], v[42:45]
	v_mfma_f32_16x16x32_bf16 v[34:37], v[192:195], v[208:211], v[34:37]
	v_mfma_f32_16x16x32_bf16 v[26:29], v[184:187], v[216:219], v[26:29]
	v_mfma_f32_16x16x32_bf16 v[18:21], v[192:195], v[216:219], v[18:21]
	v_mfma_f32_16x16x32_bf16 v[10:13], v[184:187], v[224:227], v[10:13]
	v_mfma_f32_16x16x32_bf16 v[2:5], v[192:195], v[224:227], v[2:5]
	s_barrier
	s_setprio 0
	s_mov_b32 s7, s47
	s_add_u32 s88, s88, 0x100
	s_addc_u32 s89, s89, 0
	s_add_u32 s86, s86, 0x100
	s_addc_u32 s87, s87, 0
	s_cmp_ge_i32 s47, s101
	s_cbranch_scc0 .LBB0_949

.Lmy_nb_5:
	s_nop 0
	v_readfirstlane_b32 s86, v150
	v_readfirstlane_b32 s87, v151
	v_readfirstlane_b32 s88, v152
	v_readfirstlane_b32 s89, v153
	v_readfirstlane_b32 s90, v146
	v_readfirstlane_b32 s91, v147
	v_readfirstlane_b32 s92, v148
	v_readfirstlane_b32 s93, v149
	v_readfirstlane_b32 s100, v138
	v_readfirstlane_b32 s101, v156
	v_add_u32_e32 v230, s67, v141
	v_add_u32_e32 v231, s68, v141
	v_add_u32_e32 v232, 0x18000, v141
	v_add_u32_e32 v233, 0x1c000, v141
	s_add_u32 s98, s86, 0x100
	s_addc_u32 s99, s87, 0
	s_cmp_eq_u32 s6, s100
	s_cselect_b64 s[94:95], s[90:91], s[98:99]
	s_cselect_b64 s[96:97], s[92:93], s[88:89]
	s_add_i32 s7, s6, 2
	s_add_i32 m0, s46, 0xc000
	ds_read_b128 v[164:167], v230
	global_load_lds_dwordx4 v144, s[86:87]
	s_add_i32 m0, s46, 0xe000
	ds_read_b128 v[168:171], v230 offset:1024
	global_load_lds_dwordx4 v142, s[86:87]
	ds_read_b128 v[172:175], v230 offset:2048
	ds_read_b128 v[176:179], v230 offset:3072
	ds_read_b128 v[180:183], v231
	ds_read_b128 v[184:187], v231 offset:1024
	ds_read_b128 v[188:191], v231 offset:2048
	ds_read_b128 v[192:195], v231 offset:3072
	ds_read_b128 v[196:199], v160
	ds_read_b128 v[200:203], v160 offset:1024
	ds_read_b128 v[204:207], v160 offset:2048
	ds_read_b128 v[208:211], v160 offset:3072
	ds_read_b128 v[212:215], v160 offset:4096
	ds_read_b128 v[216:219], v160 offset:5120
	ds_read_b128 v[220:223], v160 offset:6144
	ds_read_b128 v[224:227], v160 offset:7168
	s_waitcnt vmcnt(8)
	s_waitcnt lgkmcnt(0)
	s_setprio 1
	s_barrier
	v_mfma_f32_16x16x32_bf16 v[122:125], v[164:167], v[196:199], 0
	v_mfma_f32_16x16x32_bf16 v[118:121], v[172:175], v[196:199], 0
	v_mfma_f32_16x16x32_bf16 v[110:113], v[164:167], v[204:207], 0
	v_mfma_f32_16x16x32_bf16 v[102:105], v[172:175], v[204:207], 0
	v_mfma_f32_16x16x32_bf16 v[94:97], v[164:167], v[212:215], 0
	v_mfma_f32_16x16x32_bf16 v[86:89], v[172:175], v[212:215], 0
	v_mfma_f32_16x16x32_bf16 v[78:81], v[164:167], v[220:223], 0
	v_mfma_f32_16x16x32_bf16 v[70:73], v[172:175], v[220:223], 0
	v_mfma_f32_16x16x32_bf16 v[122:125], v[168:171], v[200:203], v[122:125]
	v_mfma_f32_16x16x32_bf16 v[118:121], v[176:179], v[200:203], v[118:121]
	v_mfma_f32_16x16x32_bf16 v[110:113], v[168:171], v[208:211], v[110:113]
	v_mfma_f32_16x16x32_bf16 v[102:105], v[176:179], v[208:211], v[102:105]
	v_mfma_f32_16x16x32_bf16 v[94:97], v[168:171], v[216:219], v[94:97]
	v_mfma_f32_16x16x32_bf16 v[86:89], v[176:179], v[216:219], v[86:89]
	v_mfma_f32_16x16x32_bf16 v[78:81], v[168:171], v[224:227], v[78:81]
	v_mfma_f32_16x16x32_bf16 v[70:73], v[176:179], v[224:227], v[70:73]
	s_setprio 0
	s_setprio 1
	v_mfma_f32_16x16x32_bf16 v[126:129], v[180:183], v[196:199], 0
	v_mfma_f32_16x16x32_bf16 v[114:117], v[188:191], v[196:199], 0
	v_mfma_f32_16x16x32_bf16 v[106:109], v[180:183], v[204:207], 0
	v_mfma_f32_16x16x32_bf16 v[98:101], v[188:191], v[204:207], 0
	v_mfma_f32_16x16x32_bf16 v[90:93], v[180:183], v[212:215], 0
	v_mfma_f32_16x16x32_bf16 v[82:85], v[188:191], v[212:215], 0
	v_mfma_f32_16x16x32_bf16 v[74:77], v[180:183], v[220:223], 0
	v_mfma_f32_16x16x32_bf16 v[66:69], v[188:191], v[220:223], 0
	v_mfma_f32_16x16x32_bf16 v[126:129], v[184:187], v[200:203], v[126:129]
	v_mfma_f32_16x16x32_bf16 v[114:117], v[192:195], v[200:203], v[114:117]
	v_mfma_f32_16x16x32_bf16 v[106:109], v[184:187], v[208:211], v[106:109]
	v_mfma_f32_16x16x32_bf16 v[98:101], v[192:195], v[208:211], v[98:101]
	v_mfma_f32_16x16x32_bf16 v[90:93], v[184:187], v[216:219], v[90:93]
	v_mfma_f32_16x16x32_bf16 v[82:85], v[192:195], v[216:219], v[82:85]
	v_mfma_f32_16x16x32_bf16 v[74:77], v[184:187], v[224:227], v[74:77]
	v_mfma_f32_16x16x32_bf16 v[66:69], v[192:195], v[224:227], v[66:69]
	s_barrier
	s_setprio 0
	s_add_u32 s98, s96, 0xb0000
	s_addc_u32 s99, s97, 0
	s_add_i32 s6, s67, s23
	s_mov_b32 m0, s6
	ds_read_b128 v[196:199], v160 offset:16384
	global_load_lds_dwordx4 v132, s[96:97]
	s_add_i32 m0, s6, 0x2000
	s_add_i32 s6, s68, s23
	global_load_lds_dwordx4 v136, s[96:97]
	s_mov_b32 m0, s6
	ds_read_b128 v[200:203], v160 offset:17408
	global_load_lds_dwordx4 v132, s[98:99]
	s_add_i32 m0, s6, 0x2000
	ds_read_b128 v[204:207], v160 offset:18432
	global_load_lds_dwordx4 v136, s[98:99]
	s_mov_b32 m0, s46
	ds_read_b128 v[208:211], v160 offset:19456
	global_load_lds_dwordx4 v130, s[94:95]
	s_mov_b32 m0, s47
	ds_read_b128 v[212:215], v160 offset:20480
	global_load_lds_dwordx4 v134, s[94:95]
	ds_read_b128 v[216:219], v160 offset:21504
	ds_read_b128 v[220:223], v160 offset:22528
	ds_read_b128 v[224:227], v160 offset:23552
	s_waitcnt vmcnt(8)
	s_waitcnt lgkmcnt(0)
	s_setprio 1
	s_barrier
	v_mfma_f32_16x16x32_bf16 v[62:65], v[164:167], v[196:199], 0
	v_mfma_f32_16x16x32_bf16 v[54:57], v[172:175], v[196:199], 0
	v_mfma_f32_16x16x32_bf16 v[46:49], v[164:167], v[204:207], 0
	v_mfma_f32_16x16x32_bf16 v[38:41], v[172:175], v[204:207], 0
	v_mfma_f32_16x16x32_bf16 v[30:33], v[164:167], v[212:215], 0
	v_mfma_f32_16x16x32_bf16 v[22:25], v[172:175], v[212:215], 0
	v_mfma_f32_16x16x32_bf16 v[14:17], v[164:167], v[220:223], 0
	v_mfma_f32_16x16x32_bf16 v[6:9], v[172:175], v[220:223], 0
	v_mfma_f32_16x16x32_bf16 v[62:65], v[168:171], v[200:203], v[62:65]
	v_mfma_f32_16x16x32_bf16 v[54:57], v[176:179], v[200:203], v[54:57]
	v_mfma_f32_16x16x32_bf16 v[46:49], v[168:171], v[208:211], v[46:49]
	v_mfma_f32_16x16x32_bf16 v[38:41], v[176:179], v[208:211], v[38:41]
	v_mfma_f32_16x16x32_bf16 v[30:33], v[168:171], v[216:219], v[30:33]
	v_mfma_f32_16x16x32_bf16 v[22:25], v[176:179], v[216:219], v[22:25]
	v_mfma_f32_16x16x32_bf16 v[14:17], v[168:171], v[224:227], v[14:17]
	v_mfma_f32_16x16x32_bf16 v[6:9], v[176:179], v[224:227], v[6:9]
	s_setprio 0
	s_setprio 1
	v_mfma_f32_16x16x32_bf16 v[58:61], v[180:183], v[196:199], 0
	v_mfma_f32_16x16x32_bf16 v[50:53], v[188:191], v[196:199], 0
	v_mfma_f32_16x16x32_bf16 v[42:45], v[180:183], v[204:207], 0
	v_mfma_f32_16x16x32_bf16 v[34:37], v[188:191], v[204:207], 0
	v_mfma_f32_16x16x32_bf16 v[26:29], v[180:183], v[212:215], 0
	v_mfma_f32_16x16x32_bf16 v[18:21], v[188:191], v[212:215], 0
	v_mfma_f32_16x16x32_bf16 v[10:13], v[180:183], v[220:223], 0
	v_mfma_f32_16x16x32_bf16 v[2:5], v[188:191], v[220:223], 0
	v_mfma_f32_16x16x32_bf16 v[58:61], v[184:187], v[200:203], v[58:61]
	v_mfma_f32_16x16x32_bf16 v[50:53], v[192:195], v[200:203], v[50:53]
	v_mfma_f32_16x16x32_bf16 v[42:45], v[184:187], v[208:211], v[42:45]
	v_mfma_f32_16x16x32_bf16 v[34:37], v[192:195], v[208:211], v[34:37]
	v_mfma_f32_16x16x32_bf16 v[26:29], v[184:187], v[216:219], v[26:29]
	v_mfma_f32_16x16x32_bf16 v[18:21], v[192:195], v[216:219], v[18:21]
	v_mfma_f32_16x16x32_bf16 v[10:13], v[184:187], v[224:227], v[10:13]
	v_mfma_f32_16x16x32_bf16 v[2:5], v[192:195], v[224:227], v[2:5]
	s_barrier
	s_setprio 0
	s_add_u32 s98, s94, 0xb0000
	s_addc_u32 s99, s95, 0
	s_add_i32 s6, 0, 0x18000
	s_add_i32 s29, 0, 0x1c000
	s_mov_b32 m0, s48
	ds_read_b128 v[164:167], v232
	global_load_lds_dwordx4 v130, s[98:99]
	s_mov_b32 m0, s49
	ds_read_b128 v[168:171], v232 offset:1024
	global_load_lds_dwordx4 v134, s[98:99]
	ds_read_b128 v[172:175], v232 offset:2048
	ds_read_b128 v[176:179], v232 offset:3072
	ds_read_b128 v[180:183], v233
	ds_read_b128 v[184:187], v233 offset:1024
	ds_read_b128 v[188:191], v233 offset:2048
	ds_read_b128 v[192:195], v233 offset:3072
	ds_read_b128 v[196:199], v160 offset:32768
	ds_read_b128 v[200:203], v160 offset:33792
	ds_read_b128 v[204:207], v160 offset:34816
	ds_read_b128 v[208:211], v160 offset:35840
	ds_read_b128 v[212:215], v160 offset:36864
	ds_read_b128 v[216:219], v160 offset:37888
	ds_read_b128 v[220:223], v160 offset:38912
	ds_read_b128 v[224:227], v160 offset:39936
	s_waitcnt vmcnt(8)
	s_waitcnt lgkmcnt(0)
	s_setprio 1
	s_barrier
	v_mfma_f32_16x16x32_bf16 v[122:125], v[164:167], v[196:199], v[122:125]
	v_mfma_f32_16x16x32_bf16 v[118:121], v[172:175], v[196:199], v[118:121]
	v_mfma_f32_16x16x32_bf16 v[110:113], v[164:167], v[204:207], v[110:113]
	v_mfma_f32_16x16x32_bf16 v[102:105], v[172:175], v[204:207], v[102:105]
	v_mfma_f32_16x16x32_bf16 v[94:97], v[164:167], v[212:215], v[94:97]
	v_mfma_f32_16x16x32_bf16 v[86:89], v[172:175], v[212:215], v[86:89]
	v_mfma_f32_16x16x32_bf16 v[78:81], v[164:167], v[220:223], v[78:81]
	v_mfma_f32_16x16x32_bf16 v[70:73], v[172:175], v[220:223], v[70:73]
	v_mfma_f32_16x16x32_bf16 v[122:125], v[168:171], v[200:203], v[122:125]
	v_mfma_f32_16x16x32_bf16 v[118:121], v[176:179], v[200:203], v[118:121]
	v_mfma_f32_16x16x32_bf16 v[110:113], v[168:171], v[208:211], v[110:113]
	v_mfma_f32_16x16x32_bf16 v[102:105], v[176:179], v[208:211], v[102:105]
	v_mfma_f32_16x16x32_bf16 v[94:97], v[168:171], v[216:219], v[94:97]
	v_mfma_f32_16x16x32_bf16 v[86:89], v[176:179], v[216:219], v[86:89]
	v_mfma_f32_16x16x32_bf16 v[78:81], v[168:171], v[224:227], v[78:81]
	v_mfma_f32_16x16x32_bf16 v[70:73], v[176:179], v[224:227], v[70:73]
	s_setprio 0
	s_setprio 1
	v_mfma_f32_16x16x32_bf16 v[126:129], v[180:183], v[196:199], v[126:129]
	v_mfma_f32_16x16x32_bf16 v[114:117], v[188:191], v[196:199], v[114:117]
	v_mfma_f32_16x16x32_bf16 v[106:109], v[180:183], v[204:207], v[106:109]
	v_mfma_f32_16x16x32_bf16 v[98:101], v[188:191], v[204:207], v[98:101]
	v_mfma_f32_16x16x32_bf16 v[90:93], v[180:183], v[212:215], v[90:93]
	v_mfma_f32_16x16x32_bf16 v[82:85], v[188:191], v[212:215], v[82:85]
	v_mfma_f32_16x16x32_bf16 v[74:77], v[180:183], v[220:223], v[74:77]
	v_mfma_f32_16x16x32_bf16 v[66:69], v[188:191], v[220:223], v[66:69]
	v_mfma_f32_16x16x32_bf16 v[126:129], v[184:187], v[200:203], v[126:129]
	v_mfma_f32_16x16x32_bf16 v[114:117], v[192:195], v[200:203], v[114:117]
	v_mfma_f32_16x16x32_bf16 v[106:109], v[184:187], v[208:211], v[106:109]
	v_mfma_f32_16x16x32_bf16 v[98:101], v[192:195], v[208:211], v[98:101]
	v_mfma_f32_16x16x32_bf16 v[90:93], v[184:187], v[216:219], v[90:93]
	v_mfma_f32_16x16x32_bf16 v[82:85], v[192:195], v[216:219], v[82:85]
	v_mfma_f32_16x16x32_bf16 v[74:77], v[184:187], v[224:227], v[74:77]
	v_mfma_f32_16x16x32_bf16 v[66:69], v[192:195], v[224:227], v[66:69]
	s_barrier
	s_setprio 0
	s_add_u32 s96, s96, 0x80
	s_addc_u32 s97, s97, 0
	s_add_u32 s98, s96, 0xb0000
	s_addc_u32 s99, s97, 0
	s_add_u32 s94, s94, 0x80
	s_addc_u32 s95, s95, 0
	s_add_i32 s6, s6, s23
	s_mov_b32 m0, s6
	ds_read_b128 v[196:199], v160 offset:49152
	global_load_lds_dwordx4 v132, s[96:97]
	s_add_i32 m0, s6, 0x2000
	s_add_i32 s6, s29, s23
	global_load_lds_dwordx4 v136, s[96:97]
	s_mov_b32 m0, s6
	ds_read_b128 v[200:203], v160 offset:50176
	global_load_lds_dwordx4 v132, s[98:99]
	s_add_i32 m0, s6, 0x2000
	ds_read_b128 v[204:207], v160 offset:51200
	global_load_lds_dwordx4 v136, s[98:99]
	s_mov_b32 m0, s59
	ds_read_b128 v[208:211], v160 offset:52224
	global_load_lds_dwordx4 v130, s[94:95]
	s_mov_b32 m0, s60
	ds_read_b128 v[212:215], v160 offset:53248
	global_load_lds_dwordx4 v134, s[94:95]
	ds_read_b128 v[216:219], v160 offset:54272
	ds_read_b128 v[220:223], v160 offset:55296
	ds_read_b128 v[224:227], v160 offset:56320
	s_waitcnt vmcnt(8)
	s_waitcnt lgkmcnt(0)
	s_setprio 1
	s_barrier
	v_mfma_f32_16x16x32_bf16 v[62:65], v[164:167], v[196:199], v[62:65]
	v_mfma_f32_16x16x32_bf16 v[54:57], v[172:175], v[196:199], v[54:57]
	v_mfma_f32_16x16x32_bf16 v[46:49], v[164:167], v[204:207], v[46:49]
	v_mfma_f32_16x16x32_bf16 v[38:41], v[172:175], v[204:207], v[38:41]
	v_mfma_f32_16x16x32_bf16 v[30:33], v[164:167], v[212:215], v[30:33]
	v_mfma_f32_16x16x32_bf16 v[22:25], v[172:175], v[212:215], v[22:25]
	v_mfma_f32_16x16x32_bf16 v[14:17], v[164:167], v[220:223], v[14:17]
	v_mfma_f32_16x16x32_bf16 v[6:9], v[172:175], v[220:223], v[6:9]
	v_mfma_f32_16x16x32_bf16 v[62:65], v[168:171], v[200:203], v[62:65]
	v_mfma_f32_16x16x32_bf16 v[54:57], v[176:179], v[200:203], v[54:57]
	v_mfma_f32_16x16x32_bf16 v[46:49], v[168:171], v[208:211], v[46:49]
	v_mfma_f32_16x16x32_bf16 v[38:41], v[176:179], v[208:211], v[38:41]
	v_mfma_f32_16x16x32_bf16 v[30:33], v[168:171], v[216:219], v[30:33]
	v_mfma_f32_16x16x32_bf16 v[22:25], v[176:179], v[216:219], v[22:25]
	v_mfma_f32_16x16x32_bf16 v[14:17], v[168:171], v[224:227], v[14:17]
	v_mfma_f32_16x16x32_bf16 v[6:9], v[176:179], v[224:227], v[6:9]
	s_setprio 0
	s_setprio 1
	v_mfma_f32_16x16x32_bf16 v[58:61], v[180:183], v[196:199], v[58:61]
	v_mfma_f32_16x16x32_bf16 v[50:53], v[188:191], v[196:199], v[50:53]
	v_mfma_f32_16x16x32_bf16 v[42:45], v[180:183], v[204:207], v[42:45]
	v_mfma_f32_16x16x32_bf16 v[34:37], v[188:191], v[204:207], v[34:37]
	v_mfma_f32_16x16x32_bf16 v[26:29], v[180:183], v[212:215], v[26:29]
	v_mfma_f32_16x16x32_bf16 v[18:21], v[188:191], v[212:215], v[18:21]
	v_mfma_f32_16x16x32_bf16 v[10:13], v[180:183], v[220:223], v[10:13]
	v_mfma_f32_16x16x32_bf16 v[2:5], v[188:191], v[220:223], v[2:5]
	v_mfma_f32_16x16x32_bf16 v[58:61], v[184:187], v[200:203], v[58:61]
	v_mfma_f32_16x16x32_bf16 v[50:53], v[192:195], v[200:203], v[50:53]
	v_mfma_f32_16x16x32_bf16 v[42:45], v[184:187], v[208:211], v[42:45]
	v_mfma_f32_16x16x32_bf16 v[34:37], v[192:195], v[208:211], v[34:37]
	v_mfma_f32_16x16x32_bf16 v[26:29], v[184:187], v[216:219], v[26:29]
	v_mfma_f32_16x16x32_bf16 v[18:21], v[192:195], v[216:219], v[18:21]
	v_mfma_f32_16x16x32_bf16 v[10:13], v[184:187], v[224:227], v[10:13]
	v_mfma_f32_16x16x32_bf16 v[2:5], v[192:195], v[224:227], v[2:5]
	s_barrier
	s_setprio 0
	s_mov_b32 s6, s7
	s_add_u32 s88, s88, 0x100
	s_addc_u32 s89, s89, 0
	s_add_u32 s86, s86, 0x100
	s_addc_u32 s87, s87, 0
	s_cmp_ge_i32 s7, s101
	s_cbranch_scc1 .Lmy_kexit_5
.LBB0_1080:
	s_add_u32 s98, s86, 0x100
	s_addc_u32 s99, s87, 0
	s_cmp_eq_u32 s6, s100
	s_cselect_b64 s[94:95], s[90:91], s[98:99]
	s_cselect_b64 s[96:97], s[92:93], s[88:89]
	s_add_i32 s7, s6, 2
	s_add_i32 m0, s46, 0xc000
	ds_read_b128 v[164:167], v230
	global_load_lds_dwordx4 v144, s[86:87]
	s_add_i32 m0, s46, 0xe000
	ds_read_b128 v[168:171], v230 offset:1024
	global_load_lds_dwordx4 v142, s[86:87]
	ds_read_b128 v[172:175], v230 offset:2048
	ds_read_b128 v[176:179], v230 offset:3072
	ds_read_b128 v[180:183], v231
	ds_read_b128 v[184:187], v231 offset:1024
	ds_read_b128 v[188:191], v231 offset:2048
	ds_read_b128 v[192:195], v231 offset:3072
	ds_read_b128 v[196:199], v160
	ds_read_b128 v[200:203], v160 offset:1024
	ds_read_b128 v[204:207], v160 offset:2048
	ds_read_b128 v[208:211], v160 offset:3072
	ds_read_b128 v[212:215], v160 offset:4096
	ds_read_b128 v[216:219], v160 offset:5120
	ds_read_b128 v[220:223], v160 offset:6144
	ds_read_b128 v[224:227], v160 offset:7168
	s_waitcnt vmcnt(8)
	s_waitcnt lgkmcnt(0)
	s_setprio 1
	s_barrier
	v_mfma_f32_16x16x32_bf16 v[122:125], v[164:167], v[196:199], v[122:125]
	v_mfma_f32_16x16x32_bf16 v[118:121], v[172:175], v[196:199], v[118:121]
	v_mfma_f32_16x16x32_bf16 v[110:113], v[164:167], v[204:207], v[110:113]
	v_mfma_f32_16x16x32_bf16 v[102:105], v[172:175], v[204:207], v[102:105]
	v_mfma_f32_16x16x32_bf16 v[94:97], v[164:167], v[212:215], v[94:97]
	v_mfma_f32_16x16x32_bf16 v[86:89], v[172:175], v[212:215], v[86:89]
	v_mfma_f32_16x16x32_bf16 v[78:81], v[164:167], v[220:223], v[78:81]
	v_mfma_f32_16x16x32_bf16 v[70:73], v[172:175], v[220:223], v[70:73]
	v_mfma_f32_16x16x32_bf16 v[122:125], v[168:171], v[200:203], v[122:125]
	v_mfma_f32_16x16x32_bf16 v[118:121], v[176:179], v[200:203], v[118:121]
	v_mfma_f32_16x16x32_bf16 v[110:113], v[168:171], v[208:211], v[110:113]
	v_mfma_f32_16x16x32_bf16 v[102:105], v[176:179], v[208:211], v[102:105]
	v_mfma_f32_16x16x32_bf16 v[94:97], v[168:171], v[216:219], v[94:97]
	v_mfma_f32_16x16x32_bf16 v[86:89], v[176:179], v[216:219], v[86:89]
	v_mfma_f32_16x16x32_bf16 v[78:81], v[168:171], v[224:227], v[78:81]
	v_mfma_f32_16x16x32_bf16 v[70:73], v[176:179], v[224:227], v[70:73]
	s_setprio 0
	s_setprio 1
	v_mfma_f32_16x16x32_bf16 v[126:129], v[180:183], v[196:199], v[126:129]
	v_mfma_f32_16x16x32_bf16 v[114:117], v[188:191], v[196:199], v[114:117]
	v_mfma_f32_16x16x32_bf16 v[106:109], v[180:183], v[204:207], v[106:109]
	v_mfma_f32_16x16x32_bf16 v[98:101], v[188:191], v[204:207], v[98:101]
	v_mfma_f32_16x16x32_bf16 v[90:93], v[180:183], v[212:215], v[90:93]
	v_mfma_f32_16x16x32_bf16 v[82:85], v[188:191], v[212:215], v[82:85]
	v_mfma_f32_16x16x32_bf16 v[74:77], v[180:183], v[220:223], v[74:77]
	v_mfma_f32_16x16x32_bf16 v[66:69], v[188:191], v[220:223], v[66:69]
	v_mfma_f32_16x16x32_bf16 v[126:129], v[184:187], v[200:203], v[126:129]
	v_mfma_f32_16x16x32_bf16 v[114:117], v[192:195], v[200:203], v[114:117]
	v_mfma_f32_16x16x32_bf16 v[106:109], v[184:187], v[208:211], v[106:109]
	v_mfma_f32_16x16x32_bf16 v[98:101], v[192:195], v[208:211], v[98:101]
	v_mfma_f32_16x16x32_bf16 v[90:93], v[184:187], v[216:219], v[90:93]
	v_mfma_f32_16x16x32_bf16 v[82:85], v[192:195], v[216:219], v[82:85]
	v_mfma_f32_16x16x32_bf16 v[74:77], v[184:187], v[224:227], v[74:77]
	v_mfma_f32_16x16x32_bf16 v[66:69], v[192:195], v[224:227], v[66:69]
	s_barrier
	s_setprio 0
	s_add_u32 s98, s96, 0xb0000
	s_addc_u32 s99, s97, 0
	s_add_i32 s6, s67, s23
	s_mov_b32 m0, s6
	ds_read_b128 v[196:199], v160 offset:16384
	global_load_lds_dwordx4 v132, s[96:97]
	s_add_i32 m0, s6, 0x2000
	s_add_i32 s6, s68, s23
	global_load_lds_dwordx4 v136, s[96:97]
	s_mov_b32 m0, s6
	ds_read_b128 v[200:203], v160 offset:17408
	global_load_lds_dwordx4 v132, s[98:99]
	s_add_i32 m0, s6, 0x2000
	ds_read_b128 v[204:207], v160 offset:18432
	global_load_lds_dwordx4 v136, s[98:99]
	s_mov_b32 m0, s46
	ds_read_b128 v[208:211], v160 offset:19456
	global_load_lds_dwordx4 v130, s[94:95]
	s_mov_b32 m0, s47
	ds_read_b128 v[212:215], v160 offset:20480
	global_load_lds_dwordx4 v134, s[94:95]
	ds_read_b128 v[216:219], v160 offset:21504
	ds_read_b128 v[220:223], v160 offset:22528
	ds_read_b128 v[224:227], v160 offset:23552
	s_waitcnt vmcnt(8)
	s_waitcnt lgkmcnt(0)
	s_setprio 1
	s_barrier
	v_mfma_f32_16x16x32_bf16 v[62:65], v[164:167], v[196:199], v[62:65]
	v_mfma_f32_16x16x32_bf16 v[54:57], v[172:175], v[196:199], v[54:57]
	v_mfma_f32_16x16x32_bf16 v[46:49], v[164:167], v[204:207], v[46:49]
	v_mfma_f32_16x16x32_bf16 v[38:41], v[172:175], v[204:207], v[38:41]
	v_mfma_f32_16x16x32_bf16 v[30:33], v[164:167], v[212:215], v[30:33]
	v_mfma_f32_16x16x32_bf16 v[22:25], v[172:175], v[212:215], v[22:25]
	v_mfma_f32_16x16x32_bf16 v[14:17], v[164:167], v[220:223], v[14:17]
	v_mfma_f32_16x16x32_bf16 v[6:9], v[172:175], v[220:223], v[6:9]
	v_mfma_f32_16x16x32_bf16 v[62:65], v[168:171], v[200:203], v[62:65]
	v_mfma_f32_16x16x32_bf16 v[54:57], v[176:179], v[200:203], v[54:57]
	v_mfma_f32_16x16x32_bf16 v[46:49], v[168:171], v[208:211], v[46:49]
	v_mfma_f32_16x16x32_bf16 v[38:41], v[176:179], v[208:211], v[38:41]
	v_mfma_f32_16x16x32_bf16 v[30:33], v[168:171], v[216:219], v[30:33]
	v_mfma_f32_16x16x32_bf16 v[22:25], v[176:179], v[216:219], v[22:25]
	v_mfma_f32_16x16x32_bf16 v[14:17], v[168:171], v[224:227], v[14:17]
	v_mfma_f32_16x16x32_bf16 v[6:9], v[176:179], v[224:227], v[6:9]
	s_setprio 0
	s_setprio 1
	v_mfma_f32_16x16x32_bf16 v[58:61], v[180:183], v[196:199], v[58:61]
	v_mfma_f32_16x16x32_bf16 v[50:53], v[188:191], v[196:199], v[50:53]
	v_mfma_f32_16x16x32_bf16 v[42:45], v[180:183], v[204:207], v[42:45]
	v_mfma_f32_16x16x32_bf16 v[34:37], v[188:191], v[204:207], v[34:37]
	v_mfma_f32_16x16x32_bf16 v[26:29], v[180:183], v[212:215], v[26:29]
	v_mfma_f32_16x16x32_bf16 v[18:21], v[188:191], v[212:215], v[18:21]
	v_mfma_f32_16x16x32_bf16 v[10:13], v[180:183], v[220:223], v[10:13]
	v_mfma_f32_16x16x32_bf16 v[2:5], v[188:191], v[220:223], v[2:5]
	v_mfma_f32_16x16x32_bf16 v[58:61], v[184:187], v[200:203], v[58:61]
	v_mfma_f32_16x16x32_bf16 v[50:53], v[192:195], v[200:203], v[50:53]
	v_mfma_f32_16x16x32_bf16 v[42:45], v[184:187], v[208:211], v[42:45]
	v_mfma_f32_16x16x32_bf16 v[34:37], v[192:195], v[208:211], v[34:37]
	v_mfma_f32_16x16x32_bf16 v[26:29], v[184:187], v[216:219], v[26:29]
	v_mfma_f32_16x16x32_bf16 v[18:21], v[192:195], v[216:219], v[18:21]
	v_mfma_f32_16x16x32_bf16 v[10:13], v[184:187], v[224:227], v[10:13]
	v_mfma_f32_16x16x32_bf16 v[2:5], v[192:195], v[224:227], v[2:5]
	s_barrier
	s_setprio 0
	s_add_u32 s98, s94, 0xb0000
	s_addc_u32 s99, s95, 0
	s_add_i32 s6, 0, 0x18000
	s_add_i32 s29, 0, 0x1c000
	s_mov_b32 m0, s48
	ds_read_b128 v[164:167], v232
	global_load_lds_dwordx4 v130, s[98:99]
	s_mov_b32 m0, s49
	ds_read_b128 v[168:171], v232 offset:1024
	global_load_lds_dwordx4 v134, s[98:99]
	ds_read_b128 v[172:175], v232 offset:2048
	ds_read_b128 v[176:179], v232 offset:3072
	ds_read_b128 v[180:183], v233
	ds_read_b128 v[184:187], v233 offset:1024
	ds_read_b128 v[188:191], v233 offset:2048
	ds_read_b128 v[192:195], v233 offset:3072
	ds_read_b128 v[196:199], v160 offset:32768
	ds_read_b128 v[200:203], v160 offset:33792
	ds_read_b128 v[204:207], v160 offset:34816
	ds_read_b128 v[208:211], v160 offset:35840
	ds_read_b128 v[212:215], v160 offset:36864
	ds_read_b128 v[216:219], v160 offset:37888
	ds_read_b128 v[220:223], v160 offset:38912
	ds_read_b128 v[224:227], v160 offset:39936
	s_waitcnt vmcnt(8)
	s_waitcnt lgkmcnt(0)
	s_setprio 1
	s_barrier
	v_mfma_f32_16x16x32_bf16 v[122:125], v[164:167], v[196:199], v[122:125]
	v_mfma_f32_16x16x32_bf16 v[118:121], v[172:175], v[196:199], v[118:121]
	v_mfma_f32_16x16x32_bf16 v[110:113], v[164:167], v[204:207], v[110:113]
	v_mfma_f32_16x16x32_bf16 v[102:105], v[172:175], v[204:207], v[102:105]
	v_mfma_f32_16x16x32_bf16 v[94:97], v[164:167], v[212:215], v[94:97]
	v_mfma_f32_16x16x32_bf16 v[86:89], v[172:175], v[212:215], v[86:89]
	v_mfma_f32_16x16x32_bf16 v[78:81], v[164:167], v[220:223], v[78:81]
	v_mfma_f32_16x16x32_bf16 v[70:73], v[172:175], v[220:223], v[70:73]
	v_mfma_f32_16x16x32_bf16 v[122:125], v[168:171], v[200:203], v[122:125]
	v_mfma_f32_16x16x32_bf16 v[118:121], v[176:179], v[200:203], v[118:121]
	v_mfma_f32_16x16x32_bf16 v[110:113], v[168:171], v[208:211], v[110:113]
	v_mfma_f32_16x16x32_bf16 v[102:105], v[176:179], v[208:211], v[102:105]
	v_mfma_f32_16x16x32_bf16 v[94:97], v[168:171], v[216:219], v[94:97]
	v_mfma_f32_16x16x32_bf16 v[86:89], v[176:179], v[216:219], v[86:89]
	v_mfma_f32_16x16x32_bf16 v[78:81], v[168:171], v[224:227], v[78:81]
	v_mfma_f32_16x16x32_bf16 v[70:73], v[176:179], v[224:227], v[70:73]
	s_setprio 0
	s_setprio 1
	v_mfma_f32_16x16x32_bf16 v[126:129], v[180:183], v[196:199], v[126:129]
	v_mfma_f32_16x16x32_bf16 v[114:117], v[188:191], v[196:199], v[114:117]
	v_mfma_f32_16x16x32_bf16 v[106:109], v[180:183], v[204:207], v[106:109]
	v_mfma_f32_16x16x32_bf16 v[98:101], v[188:191], v[204:207], v[98:101]
	v_mfma_f32_16x16x32_bf16 v[90:93], v[180:183], v[212:215], v[90:93]
	v_mfma_f32_16x16x32_bf16 v[82:85], v[188:191], v[212:215], v[82:85]
	v_mfma_f32_16x16x32_bf16 v[74:77], v[180:183], v[220:223], v[74:77]
	v_mfma_f32_16x16x32_bf16 v[66:69], v[188:191], v[220:223], v[66:69]
	v_mfma_f32_16x16x32_bf16 v[126:129], v[184:187], v[200:203], v[126:129]
	v_mfma_f32_16x16x32_bf16 v[114:117], v[192:195], v[200:203], v[114:117]
	v_mfma_f32_16x16x32_bf16 v[106:109], v[184:187], v[208:211], v[106:109]
	v_mfma_f32_16x16x32_bf16 v[98:101], v[192:195], v[208:211], v[98:101]
	v_mfma_f32_16x16x32_bf16 v[90:93], v[184:187], v[216:219], v[90:93]
	v_mfma_f32_16x16x32_bf16 v[82:85], v[192:195], v[216:219], v[82:85]
	v_mfma_f32_16x16x32_bf16 v[74:77], v[184:187], v[224:227], v[74:77]
	v_mfma_f32_16x16x32_bf16 v[66:69], v[192:195], v[224:227], v[66:69]
	s_barrier
	s_setprio 0
	s_add_u32 s96, s96, 0x80
	s_addc_u32 s97, s97, 0
	s_add_u32 s98, s96, 0xb0000
	s_addc_u32 s99, s97, 0
	s_add_u32 s94, s94, 0x80
	s_addc_u32 s95, s95, 0
	s_add_i32 s6, s6, s23
	s_mov_b32 m0, s6
	ds_read_b128 v[196:199], v160 offset:49152
	global_load_lds_dwordx4 v132, s[96:97]
	s_add_i32 m0, s6, 0x2000
	s_add_i32 s6, s29, s23
	global_load_lds_dwordx4 v136, s[96:97]
	s_mov_b32 m0, s6
	ds_read_b128 v[200:203], v160 offset:50176
	global_load_lds_dwordx4 v132, s[98:99]
	s_add_i32 m0, s6, 0x2000
	ds_read_b128 v[204:207], v160 offset:51200
	global_load_lds_dwordx4 v136, s[98:99]
	s_mov_b32 m0, s59
	ds_read_b128 v[208:211], v160 offset:52224
	global_load_lds_dwordx4 v130, s[94:95]
	s_mov_b32 m0, s60
	ds_read_b128 v[212:215], v160 offset:53248
	global_load_lds_dwordx4 v134, s[94:95]
	ds_read_b128 v[216:219], v160 offset:54272
	ds_read_b128 v[220:223], v160 offset:55296
	ds_read_b128 v[224:227], v160 offset:56320
	s_waitcnt vmcnt(8)
	s_waitcnt lgkmcnt(0)
	s_setprio 1
	s_barrier
	v_mfma_f32_16x16x32_bf16 v[62:65], v[164:167], v[196:199], v[62:65]
	v_mfma_f32_16x16x32_bf16 v[54:57], v[172:175], v[196:199], v[54:57]
	v_mfma_f32_16x16x32_bf16 v[46:49], v[164:167], v[204:207], v[46:49]
	v_mfma_f32_16x16x32_bf16 v[38:41], v[172:175], v[204:207], v[38:41]
	v_mfma_f32_16x16x32_bf16 v[30:33], v[164:167], v[212:215], v[30:33]
	v_mfma_f32_16x16x32_bf16 v[22:25], v[172:175], v[212:215], v[22:25]
	v_mfma_f32_16x16x32_bf16 v[14:17], v[164:167], v[220:223], v[14:17]
	v_mfma_f32_16x16x32_bf16 v[6:9], v[172:175], v[220:223], v[6:9]
	v_mfma_f32_16x16x32_bf16 v[62:65], v[168:171], v[200:203], v[62:65]
	v_mfma_f32_16x16x32_bf16 v[54:57], v[176:179], v[200:203], v[54:57]
	v_mfma_f32_16x16x32_bf16 v[46:49], v[168:171], v[208:211], v[46:49]
	v_mfma_f32_16x16x32_bf16 v[38:41], v[176:179], v[208:211], v[38:41]
	v_mfma_f32_16x16x32_bf16 v[30:33], v[168:171], v[216:219], v[30:33]
	v_mfma_f32_16x16x32_bf16 v[22:25], v[176:179], v[216:219], v[22:25]
	v_mfma_f32_16x16x32_bf16 v[14:17], v[168:171], v[224:227], v[14:17]
	v_mfma_f32_16x16x32_bf16 v[6:9], v[176:179], v[224:227], v[6:9]
	s_setprio 0
	s_setprio 1
	v_mfma_f32_16x16x32_bf16 v[58:61], v[180:183], v[196:199], v[58:61]
	v_mfma_f32_16x16x32_bf16 v[50:53], v[188:191], v[196:199], v[50:53]
	v_mfma_f32_16x16x32_bf16 v[42:45], v[180:183], v[204:207], v[42:45]
	v_mfma_f32_16x16x32_bf16 v[34:37], v[188:191], v[204:207], v[34:37]
	v_mfma_f32_16x16x32_bf16 v[26:29], v[180:183], v[212:215], v[26:29]
	v_mfma_f32_16x16x32_bf16 v[18:21], v[188:191], v[212:215], v[18:21]
	v_mfma_f32_16x16x32_bf16 v[10:13], v[180:183], v[220:223], v[10:13]
	v_mfma_f32_16x16x32_bf16 v[2:5], v[188:191], v[220:223], v[2:5]
	v_mfma_f32_16x16x32_bf16 v[58:61], v[184:187], v[200:203], v[58:61]
	v_mfma_f32_16x16x32_bf16 v[50:53], v[192:195], v[200:203], v[50:53]
	v_mfma_f32_16x16x32_bf16 v[42:45], v[184:187], v[208:211], v[42:45]
	v_mfma_f32_16x16x32_bf16 v[34:37], v[192:195], v[208:211], v[34:37]
	v_mfma_f32_16x16x32_bf16 v[26:29], v[184:187], v[216:219], v[26:29]
	v_mfma_f32_16x16x32_bf16 v[18:21], v[192:195], v[216:219], v[18:21]
	v_mfma_f32_16x16x32_bf16 v[10:13], v[184:187], v[224:227], v[10:13]
	v_mfma_f32_16x16x32_bf16 v[2:5], v[192:195], v[224:227], v[2:5]
	s_barrier
	s_setprio 0
	s_mov_b32 s6, s7
	s_add_u32 s88, s88, 0x100
	s_addc_u32 s89, s89, 0
	s_add_u32 s86, s86, 0x100
	s_addc_u32 s87, s87, 0
	s_cmp_ge_i32 s7, s101
	s_cbranch_scc0 .LBB0_1080

.Lmy_nb_7:
	s_nop 0
	v_readfirstlane_b32 s86, v150
	v_readfirstlane_b32 s87, v151
	v_readfirstlane_b32 s88, v152
	v_readfirstlane_b32 s89, v153
	v_readfirstlane_b32 s90, v146
	v_readfirstlane_b32 s91, v147
	v_readfirstlane_b32 s92, v148
	v_readfirstlane_b32 s93, v149
	v_readfirstlane_b32 s100, v138
	v_readfirstlane_b32 s101, v156
	v_add_u32_e32 v230, s67, v141
	v_add_u32_e32 v231, s70, v141
	v_add_u32_e32 v232, 0x18000, v141
	v_add_u32_e32 v233, 0x1c000, v141
	s_add_u32 s98, s86, 0x100
	s_addc_u32 s99, s87, 0
	s_cmp_eq_u32 s6, s100
	s_cselect_b64 s[94:95], s[90:91], s[98:99]
	s_cselect_b64 s[96:97], s[92:93], s[88:89]
	s_add_i32 s7, s6, 2
	s_add_i32 m0, s46, 0xc000
	ds_read_b128 v[164:167], v230
	global_load_lds_dwordx4 v144, s[86:87]
	s_add_i32 m0, s46, 0xe000
	ds_read_b128 v[168:171], v230 offset:1024
	global_load_lds_dwordx4 v142, s[86:87]
	ds_read_b128 v[172:175], v230 offset:2048
	ds_read_b128 v[176:179], v230 offset:3072
	ds_read_b128 v[180:183], v231
	ds_read_b128 v[184:187], v231 offset:1024
	ds_read_b128 v[188:191], v231 offset:2048
	ds_read_b128 v[192:195], v231 offset:3072
	ds_read_b128 v[196:199], v160
	ds_read_b128 v[200:203], v160 offset:1024
	ds_read_b128 v[204:207], v160 offset:2048
	ds_read_b128 v[208:211], v160 offset:3072
	ds_read_b128 v[212:215], v160 offset:4096
	ds_read_b128 v[216:219], v160 offset:5120
	ds_read_b128 v[220:223], v160 offset:6144
	ds_read_b128 v[224:227], v160 offset:7168
	s_waitcnt vmcnt(8)
	s_waitcnt lgkmcnt(0)
	s_setprio 1
	s_barrier
	v_mfma_f32_16x16x32_bf16 v[122:125], v[164:167], v[196:199], 0
	v_mfma_f32_16x16x32_bf16 v[118:121], v[172:175], v[196:199], 0
	v_mfma_f32_16x16x32_bf16 v[110:113], v[164:167], v[204:207], 0
	v_mfma_f32_16x16x32_bf16 v[102:105], v[172:175], v[204:207], 0
	v_mfma_f32_16x16x32_bf16 v[94:97], v[164:167], v[212:215], 0
	v_mfma_f32_16x16x32_bf16 v[86:89], v[172:175], v[212:215], 0
	v_mfma_f32_16x16x32_bf16 v[78:81], v[164:167], v[220:223], 0
	v_mfma_f32_16x16x32_bf16 v[70:73], v[172:175], v[220:223], 0
	v_mfma_f32_16x16x32_bf16 v[122:125], v[168:171], v[200:203], v[122:125]
	v_mfma_f32_16x16x32_bf16 v[118:121], v[176:179], v[200:203], v[118:121]
	v_mfma_f32_16x16x32_bf16 v[110:113], v[168:171], v[208:211], v[110:113]
	v_mfma_f32_16x16x32_bf16 v[102:105], v[176:179], v[208:211], v[102:105]
	v_mfma_f32_16x16x32_bf16 v[94:97], v[168:171], v[216:219], v[94:97]
	v_mfma_f32_16x16x32_bf16 v[86:89], v[176:179], v[216:219], v[86:89]
	v_mfma_f32_16x16x32_bf16 v[78:81], v[168:171], v[224:227], v[78:81]
	v_mfma_f32_16x16x32_bf16 v[70:73], v[176:179], v[224:227], v[70:73]
	s_setprio 0
	s_setprio 1
	v_mfma_f32_16x16x32_bf16 v[126:129], v[180:183], v[196:199], 0
	v_mfma_f32_16x16x32_bf16 v[114:117], v[188:191], v[196:199], 0
	v_mfma_f32_16x16x32_bf16 v[106:109], v[180:183], v[204:207], 0
	v_mfma_f32_16x16x32_bf16 v[98:101], v[188:191], v[204:207], 0
	v_mfma_f32_16x16x32_bf16 v[90:93], v[180:183], v[212:215], 0
	v_mfma_f32_16x16x32_bf16 v[82:85], v[188:191], v[212:215], 0
	v_mfma_f32_16x16x32_bf16 v[74:77], v[180:183], v[220:223], 0
	v_mfma_f32_16x16x32_bf16 v[66:69], v[188:191], v[220:223], 0
	v_mfma_f32_16x16x32_bf16 v[126:129], v[184:187], v[200:203], v[126:129]
	v_mfma_f32_16x16x32_bf16 v[114:117], v[192:195], v[200:203], v[114:117]
	v_mfma_f32_16x16x32_bf16 v[106:109], v[184:187], v[208:211], v[106:109]
	v_mfma_f32_16x16x32_bf16 v[98:101], v[192:195], v[208:211], v[98:101]
	v_mfma_f32_16x16x32_bf16 v[90:93], v[184:187], v[216:219], v[90:93]
	v_mfma_f32_16x16x32_bf16 v[82:85], v[192:195], v[216:219], v[82:85]
	v_mfma_f32_16x16x32_bf16 v[74:77], v[184:187], v[224:227], v[74:77]
	v_mfma_f32_16x16x32_bf16 v[66:69], v[192:195], v[224:227], v[66:69]
	s_barrier
	s_setprio 0
	s_add_u32 s98, s96, 0xb0000
	s_addc_u32 s99, s97, 0
	s_add_i32 s6, s67, s23
	s_mov_b32 m0, s6
	ds_read_b128 v[196:199], v160 offset:16384
	global_load_lds_dwordx4 v132, s[96:97]
	s_add_i32 m0, s6, 0x2000
	s_add_i32 s6, s70, s23
	global_load_lds_dwordx4 v136, s[96:97]
	s_mov_b32 m0, s6
	ds_read_b128 v[200:203], v160 offset:17408
	global_load_lds_dwordx4 v132, s[98:99]
	s_add_i32 m0, s6, 0x2000
	ds_read_b128 v[204:207], v160 offset:18432
	global_load_lds_dwordx4 v136, s[98:99]
	s_mov_b32 m0, s46
	ds_read_b128 v[208:211], v160 offset:19456
	global_load_lds_dwordx4 v130, s[94:95]
	s_mov_b32 m0, s47
	ds_read_b128 v[212:215], v160 offset:20480
	global_load_lds_dwordx4 v134, s[94:95]
	ds_read_b128 v[216:219], v160 offset:21504
	ds_read_b128 v[220:223], v160 offset:22528
	ds_read_b128 v[224:227], v160 offset:23552
	s_waitcnt vmcnt(8)
	s_waitcnt lgkmcnt(0)
	s_setprio 1
	s_barrier
	v_mfma_f32_16x16x32_bf16 v[62:65], v[164:167], v[196:199], 0
	v_mfma_f32_16x16x32_bf16 v[54:57], v[172:175], v[196:199], 0
	v_mfma_f32_16x16x32_bf16 v[46:49], v[164:167], v[204:207], 0
	v_mfma_f32_16x16x32_bf16 v[38:41], v[172:175], v[204:207], 0
	v_mfma_f32_16x16x32_bf16 v[30:33], v[164:167], v[212:215], 0
	v_mfma_f32_16x16x32_bf16 v[22:25], v[172:175], v[212:215], 0
	v_mfma_f32_16x16x32_bf16 v[14:17], v[164:167], v[220:223], 0
	v_mfma_f32_16x16x32_bf16 v[6:9], v[172:175], v[220:223], 0
	v_mfma_f32_16x16x32_bf16 v[62:65], v[168:171], v[200:203], v[62:65]
	v_mfma_f32_16x16x32_bf16 v[54:57], v[176:179], v[200:203], v[54:57]
	v_mfma_f32_16x16x32_bf16 v[46:49], v[168:171], v[208:211], v[46:49]
	v_mfma_f32_16x16x32_bf16 v[38:41], v[176:179], v[208:211], v[38:41]
	v_mfma_f32_16x16x32_bf16 v[30:33], v[168:171], v[216:219], v[30:33]
	v_mfma_f32_16x16x32_bf16 v[22:25], v[176:179], v[216:219], v[22:25]
	v_mfma_f32_16x16x32_bf16 v[14:17], v[168:171], v[224:227], v[14:17]
	v_mfma_f32_16x16x32_bf16 v[6:9], v[176:179], v[224:227], v[6:9]
	s_setprio 0
	s_setprio 1
	v_mfma_f32_16x16x32_bf16 v[58:61], v[180:183], v[196:199], 0
	v_mfma_f32_16x16x32_bf16 v[50:53], v[188:191], v[196:199], 0
	v_mfma_f32_16x16x32_bf16 v[42:45], v[180:183], v[204:207], 0
	v_mfma_f32_16x16x32_bf16 v[34:37], v[188:191], v[204:207], 0
	v_mfma_f32_16x16x32_bf16 v[26:29], v[180:183], v[212:215], 0
	v_mfma_f32_16x16x32_bf16 v[18:21], v[188:191], v[212:215], 0
	v_mfma_f32_16x16x32_bf16 v[10:13], v[180:183], v[220:223], 0
	v_mfma_f32_16x16x32_bf16 v[2:5], v[188:191], v[220:223], 0
	v_mfma_f32_16x16x32_bf16 v[58:61], v[184:187], v[200:203], v[58:61]
	v_mfma_f32_16x16x32_bf16 v[50:53], v[192:195], v[200:203], v[50:53]
	v_mfma_f32_16x16x32_bf16 v[42:45], v[184:187], v[208:211], v[42:45]
	v_mfma_f32_16x16x32_bf16 v[34:37], v[192:195], v[208:211], v[34:37]
	v_mfma_f32_16x16x32_bf16 v[26:29], v[184:187], v[216:219], v[26:29]
	v_mfma_f32_16x16x32_bf16 v[18:21], v[192:195], v[216:219], v[18:21]
	v_mfma_f32_16x16x32_bf16 v[10:13], v[184:187], v[224:227], v[10:13]
	v_mfma_f32_16x16x32_bf16 v[2:5], v[192:195], v[224:227], v[2:5]
	s_barrier
	s_setprio 0
	s_add_u32 s98, s94, 0xb0000
	s_addc_u32 s99, s95, 0
	s_add_i32 s6, 0, 0x18000
	s_add_i32 s29, 0, 0x1c000
	s_mov_b32 m0, s48
	ds_read_b128 v[164:167], v232
	global_load_lds_dwordx4 v130, s[98:99]
	s_mov_b32 m0, s49
	ds_read_b128 v[168:171], v232 offset:1024
	global_load_lds_dwordx4 v134, s[98:99]
	ds_read_b128 v[172:175], v232 offset:2048
	ds_read_b128 v[176:179], v232 offset:3072
	ds_read_b128 v[180:183], v233
	ds_read_b128 v[184:187], v233 offset:1024
	ds_read_b128 v[188:191], v233 offset:2048
	ds_read_b128 v[192:195], v233 offset:3072
	ds_read_b128 v[196:199], v160 offset:32768
	ds_read_b128 v[200:203], v160 offset:33792
	ds_read_b128 v[204:207], v160 offset:34816
	ds_read_b128 v[208:211], v160 offset:35840
	ds_read_b128 v[212:215], v160 offset:36864
	ds_read_b128 v[216:219], v160 offset:37888
	ds_read_b128 v[220:223], v160 offset:38912
	ds_read_b128 v[224:227], v160 offset:39936
	s_waitcnt vmcnt(8)
	s_waitcnt lgkmcnt(0)
	s_setprio 1
	s_barrier
	v_mfma_f32_16x16x32_bf16 v[122:125], v[164:167], v[196:199], v[122:125]
	v_mfma_f32_16x16x32_bf16 v[118:121], v[172:175], v[196:199], v[118:121]
	v_mfma_f32_16x16x32_bf16 v[110:113], v[164:167], v[204:207], v[110:113]
	v_mfma_f32_16x16x32_bf16 v[102:105], v[172:175], v[204:207], v[102:105]
	v_mfma_f32_16x16x32_bf16 v[94:97], v[164:167], v[212:215], v[94:97]
	v_mfma_f32_16x16x32_bf16 v[86:89], v[172:175], v[212:215], v[86:89]
	v_mfma_f32_16x16x32_bf16 v[78:81], v[164:167], v[220:223], v[78:81]
	v_mfma_f32_16x16x32_bf16 v[70:73], v[172:175], v[220:223], v[70:73]
	v_mfma_f32_16x16x32_bf16 v[122:125], v[168:171], v[200:203], v[122:125]
	v_mfma_f32_16x16x32_bf16 v[118:121], v[176:179], v[200:203], v[118:121]
	v_mfma_f32_16x16x32_bf16 v[110:113], v[168:171], v[208:211], v[110:113]
	v_mfma_f32_16x16x32_bf16 v[102:105], v[176:179], v[208:211], v[102:105]
	v_mfma_f32_16x16x32_bf16 v[94:97], v[168:171], v[216:219], v[94:97]
	v_mfma_f32_16x16x32_bf16 v[86:89], v[176:179], v[216:219], v[86:89]
	v_mfma_f32_16x16x32_bf16 v[78:81], v[168:171], v[224:227], v[78:81]
	v_mfma_f32_16x16x32_bf16 v[70:73], v[176:179], v[224:227], v[70:73]
	s_setprio 0
	s_setprio 1
	v_mfma_f32_16x16x32_bf16 v[126:129], v[180:183], v[196:199], v[126:129]
	v_mfma_f32_16x16x32_bf16 v[114:117], v[188:191], v[196:199], v[114:117]
	v_mfma_f32_16x16x32_bf16 v[106:109], v[180:183], v[204:207], v[106:109]
	v_mfma_f32_16x16x32_bf16 v[98:101], v[188:191], v[204:207], v[98:101]
	v_mfma_f32_16x16x32_bf16 v[90:93], v[180:183], v[212:215], v[90:93]
	v_mfma_f32_16x16x32_bf16 v[82:85], v[188:191], v[212:215], v[82:85]
	v_mfma_f32_16x16x32_bf16 v[74:77], v[180:183], v[220:223], v[74:77]
	v_mfma_f32_16x16x32_bf16 v[66:69], v[188:191], v[220:223], v[66:69]
	v_mfma_f32_16x16x32_bf16 v[126:129], v[184:187], v[200:203], v[126:129]
	v_mfma_f32_16x16x32_bf16 v[114:117], v[192:195], v[200:203], v[114:117]
	v_mfma_f32_16x16x32_bf16 v[106:109], v[184:187], v[208:211], v[106:109]
	v_mfma_f32_16x16x32_bf16 v[98:101], v[192:195], v[208:211], v[98:101]
	v_mfma_f32_16x16x32_bf16 v[90:93], v[184:187], v[216:219], v[90:93]
	v_mfma_f32_16x16x32_bf16 v[82:85], v[192:195], v[216:219], v[82:85]
	v_mfma_f32_16x16x32_bf16 v[74:77], v[184:187], v[224:227], v[74:77]
	v_mfma_f32_16x16x32_bf16 v[66:69], v[192:195], v[224:227], v[66:69]
	s_barrier
	s_setprio 0
	s_add_u32 s96, s96, 0x80
	s_addc_u32 s97, s97, 0
	s_add_u32 s98, s96, 0xb0000
	s_addc_u32 s99, s97, 0
	s_add_u32 s94, s94, 0x80
	s_addc_u32 s95, s95, 0
	s_add_i32 s6, s6, s23
	s_mov_b32 m0, s6
	ds_read_b128 v[196:199], v160 offset:49152
	global_load_lds_dwordx4 v132, s[96:97]
	s_add_i32 m0, s6, 0x2000
	s_add_i32 s6, s29, s23
	global_load_lds_dwordx4 v136, s[96:97]
	s_mov_b32 m0, s6
	ds_read_b128 v[200:203], v160 offset:50176
	global_load_lds_dwordx4 v132, s[98:99]
	s_add_i32 m0, s6, 0x2000
	ds_read_b128 v[204:207], v160 offset:51200
	global_load_lds_dwordx4 v136, s[98:99]
	s_mov_b32 m0, s59
	ds_read_b128 v[208:211], v160 offset:52224
	global_load_lds_dwordx4 v130, s[94:95]
	s_mov_b32 m0, s60
	ds_read_b128 v[212:215], v160 offset:53248
	global_load_lds_dwordx4 v134, s[94:95]
	ds_read_b128 v[216:219], v160 offset:54272
	ds_read_b128 v[220:223], v160 offset:55296
	ds_read_b128 v[224:227], v160 offset:56320
	s_waitcnt vmcnt(8)
	s_waitcnt lgkmcnt(0)
	s_setprio 1
	s_barrier
	v_mfma_f32_16x16x32_bf16 v[62:65], v[164:167], v[196:199], v[62:65]
	v_mfma_f32_16x16x32_bf16 v[54:57], v[172:175], v[196:199], v[54:57]
	v_mfma_f32_16x16x32_bf16 v[46:49], v[164:167], v[204:207], v[46:49]
	v_mfma_f32_16x16x32_bf16 v[38:41], v[172:175], v[204:207], v[38:41]
	v_mfma_f32_16x16x32_bf16 v[30:33], v[164:167], v[212:215], v[30:33]
	v_mfma_f32_16x16x32_bf16 v[22:25], v[172:175], v[212:215], v[22:25]
	v_mfma_f32_16x16x32_bf16 v[14:17], v[164:167], v[220:223], v[14:17]
	v_mfma_f32_16x16x32_bf16 v[6:9], v[172:175], v[220:223], v[6:9]
	v_mfma_f32_16x16x32_bf16 v[62:65], v[168:171], v[200:203], v[62:65]
	v_mfma_f32_16x16x32_bf16 v[54:57], v[176:179], v[200:203], v[54:57]
	v_mfma_f32_16x16x32_bf16 v[46:49], v[168:171], v[208:211], v[46:49]
	v_mfma_f32_16x16x32_bf16 v[38:41], v[176:179], v[208:211], v[38:41]
	v_mfma_f32_16x16x32_bf16 v[30:33], v[168:171], v[216:219], v[30:33]
	v_mfma_f32_16x16x32_bf16 v[22:25], v[176:179], v[216:219], v[22:25]
	v_mfma_f32_16x16x32_bf16 v[14:17], v[168:171], v[224:227], v[14:17]
	v_mfma_f32_16x16x32_bf16 v[6:9], v[176:179], v[224:227], v[6:9]
	s_setprio 0
	s_setprio 1
	v_mfma_f32_16x16x32_bf16 v[58:61], v[180:183], v[196:199], v[58:61]
	v_mfma_f32_16x16x32_bf16 v[50:53], v[188:191], v[196:199], v[50:53]
	v_mfma_f32_16x16x32_bf16 v[42:45], v[180:183], v[204:207], v[42:45]
	v_mfma_f32_16x16x32_bf16 v[34:37], v[188:191], v[204:207], v[34:37]
	v_mfma_f32_16x16x32_bf16 v[26:29], v[180:183], v[212:215], v[26:29]
	v_mfma_f32_16x16x32_bf16 v[18:21], v[188:191], v[212:215], v[18:21]
	v_mfma_f32_16x16x32_bf16 v[10:13], v[180:183], v[220:223], v[10:13]
	v_mfma_f32_16x16x32_bf16 v[2:5], v[188:191], v[220:223], v[2:5]
	v_mfma_f32_16x16x32_bf16 v[58:61], v[184:187], v[200:203], v[58:61]
	v_mfma_f32_16x16x32_bf16 v[50:53], v[192:195], v[200:203], v[50:53]
	v_mfma_f32_16x16x32_bf16 v[42:45], v[184:187], v[208:211], v[42:45]
	v_mfma_f32_16x16x32_bf16 v[34:37], v[192:195], v[208:211], v[34:37]
	v_mfma_f32_16x16x32_bf16 v[26:29], v[184:187], v[216:219], v[26:29]
	v_mfma_f32_16x16x32_bf16 v[18:21], v[192:195], v[216:219], v[18:21]
	v_mfma_f32_16x16x32_bf16 v[10:13], v[184:187], v[224:227], v[10:13]
	v_mfma_f32_16x16x32_bf16 v[2:5], v[192:195], v[224:227], v[2:5]
	s_barrier
	s_setprio 0
	s_mov_b32 s6, s7
	s_add_u32 s88, s88, 0x100
	s_addc_u32 s89, s89, 0
	s_add_u32 s86, s86, 0x100
	s_addc_u32 s87, s87, 0
	s_cmp_ge_i32 s7, s101
	s_cbranch_scc1 .Lmy_kexit_7
.LBB0_1392:
	s_add_u32 s98, s86, 0x100
	s_addc_u32 s99, s87, 0
	s_cmp_eq_u32 s6, s100
	s_cselect_b64 s[94:95], s[90:91], s[98:99]
	s_cselect_b64 s[96:97], s[92:93], s[88:89]
	s_add_i32 s7, s6, 2
	s_add_i32 m0, s46, 0xc000
	ds_read_b128 v[164:167], v230
	global_load_lds_dwordx4 v144, s[86:87]
	s_add_i32 m0, s46, 0xe000
	ds_read_b128 v[168:171], v230 offset:1024
	global_load_lds_dwordx4 v142, s[86:87]
	ds_read_b128 v[172:175], v230 offset:2048
	ds_read_b128 v[176:179], v230 offset:3072
	ds_read_b128 v[180:183], v231
	ds_read_b128 v[184:187], v231 offset:1024
	ds_read_b128 v[188:191], v231 offset:2048
	ds_read_b128 v[192:195], v231 offset:3072
	ds_read_b128 v[196:199], v160
	ds_read_b128 v[200:203], v160 offset:1024
	ds_read_b128 v[204:207], v160 offset:2048
	ds_read_b128 v[208:211], v160 offset:3072
	ds_read_b128 v[212:215], v160 offset:4096
	ds_read_b128 v[216:219], v160 offset:5120
	ds_read_b128 v[220:223], v160 offset:6144
	ds_read_b128 v[224:227], v160 offset:7168
	s_waitcnt vmcnt(8)
	s_waitcnt lgkmcnt(0)
	s_setprio 1
	s_barrier
	v_mfma_f32_16x16x32_bf16 v[122:125], v[164:167], v[196:199], v[122:125]
	v_mfma_f32_16x16x32_bf16 v[118:121], v[172:175], v[196:199], v[118:121]
	v_mfma_f32_16x16x32_bf16 v[110:113], v[164:167], v[204:207], v[110:113]
	v_mfma_f32_16x16x32_bf16 v[102:105], v[172:175], v[204:207], v[102:105]
	v_mfma_f32_16x16x32_bf16 v[94:97], v[164:167], v[212:215], v[94:97]
	v_mfma_f32_16x16x32_bf16 v[86:89], v[172:175], v[212:215], v[86:89]
	v_mfma_f32_16x16x32_bf16 v[78:81], v[164:167], v[220:223], v[78:81]
	v_mfma_f32_16x16x32_bf16 v[70:73], v[172:175], v[220:223], v[70:73]
	v_mfma_f32_16x16x32_bf16 v[122:125], v[168:171], v[200:203], v[122:125]
	v_mfma_f32_16x16x32_bf16 v[118:121], v[176:179], v[200:203], v[118:121]
	v_mfma_f32_16x16x32_bf16 v[110:113], v[168:171], v[208:211], v[110:113]
	v_mfma_f32_16x16x32_bf16 v[102:105], v[176:179], v[208:211], v[102:105]
	v_mfma_f32_16x16x32_bf16 v[94:97], v[168:171], v[216:219], v[94:97]
	v_mfma_f32_16x16x32_bf16 v[86:89], v[176:179], v[216:219], v[86:89]
	v_mfma_f32_16x16x32_bf16 v[78:81], v[168:171], v[224:227], v[78:81]
	v_mfma_f32_16x16x32_bf16 v[70:73], v[176:179], v[224:227], v[70:73]
	s_setprio 0
	s_setprio 1
	v_mfma_f32_16x16x32_bf16 v[126:129], v[180:183], v[196:199], v[126:129]
	v_mfma_f32_16x16x32_bf16 v[114:117], v[188:191], v[196:199], v[114:117]
	v_mfma_f32_16x16x32_bf16 v[106:109], v[180:183], v[204:207], v[106:109]
	v_mfma_f32_16x16x32_bf16 v[98:101], v[188:191], v[204:207], v[98:101]
	v_mfma_f32_16x16x32_bf16 v[90:93], v[180:183], v[212:215], v[90:93]
	v_mfma_f32_16x16x32_bf16 v[82:85], v[188:191], v[212:215], v[82:85]
	v_mfma_f32_16x16x32_bf16 v[74:77], v[180:183], v[220:223], v[74:77]
	v_mfma_f32_16x16x32_bf16 v[66:69], v[188:191], v[220:223], v[66:69]
	v_mfma_f32_16x16x32_bf16 v[126:129], v[184:187], v[200:203], v[126:129]
	v_mfma_f32_16x16x32_bf16 v[114:117], v[192:195], v[200:203], v[114:117]
	v_mfma_f32_16x16x32_bf16 v[106:109], v[184:187], v[208:211], v[106:109]
	v_mfma_f32_16x16x32_bf16 v[98:101], v[192:195], v[208:211], v[98:101]
	v_mfma_f32_16x16x32_bf16 v[90:93], v[184:187], v[216:219], v[90:93]
	v_mfma_f32_16x16x32_bf16 v[82:85], v[192:195], v[216:219], v[82:85]
	v_mfma_f32_16x16x32_bf16 v[74:77], v[184:187], v[224:227], v[74:77]
	v_mfma_f32_16x16x32_bf16 v[66:69], v[192:195], v[224:227], v[66:69]
	s_barrier
	s_setprio 0
	s_add_u32 s98, s96, 0xb0000
	s_addc_u32 s99, s97, 0
	s_add_i32 s6, s67, s23
	s_mov_b32 m0, s6
	ds_read_b128 v[196:199], v160 offset:16384
	global_load_lds_dwordx4 v132, s[96:97]
	s_add_i32 m0, s6, 0x2000
	s_add_i32 s6, s70, s23
	global_load_lds_dwordx4 v136, s[96:97]
	s_mov_b32 m0, s6
	ds_read_b128 v[200:203], v160 offset:17408
	global_load_lds_dwordx4 v132, s[98:99]
	s_add_i32 m0, s6, 0x2000
	ds_read_b128 v[204:207], v160 offset:18432
	global_load_lds_dwordx4 v136, s[98:99]
	s_mov_b32 m0, s46
	ds_read_b128 v[208:211], v160 offset:19456
	global_load_lds_dwordx4 v130, s[94:95]
	s_mov_b32 m0, s47
	ds_read_b128 v[212:215], v160 offset:20480
	global_load_lds_dwordx4 v134, s[94:95]
	ds_read_b128 v[216:219], v160 offset:21504
	ds_read_b128 v[220:223], v160 offset:22528
	ds_read_b128 v[224:227], v160 offset:23552
	s_waitcnt vmcnt(8)
	s_waitcnt lgkmcnt(0)
	s_setprio 1
	s_barrier
	v_mfma_f32_16x16x32_bf16 v[62:65], v[164:167], v[196:199], v[62:65]
	v_mfma_f32_16x16x32_bf16 v[54:57], v[172:175], v[196:199], v[54:57]
	v_mfma_f32_16x16x32_bf16 v[46:49], v[164:167], v[204:207], v[46:49]
	v_mfma_f32_16x16x32_bf16 v[38:41], v[172:175], v[204:207], v[38:41]
	v_mfma_f32_16x16x32_bf16 v[30:33], v[164:167], v[212:215], v[30:33]
	v_mfma_f32_16x16x32_bf16 v[22:25], v[172:175], v[212:215], v[22:25]
	v_mfma_f32_16x16x32_bf16 v[14:17], v[164:167], v[220:223], v[14:17]
	v_mfma_f32_16x16x32_bf16 v[6:9], v[172:175], v[220:223], v[6:9]
	v_mfma_f32_16x16x32_bf16 v[62:65], v[168:171], v[200:203], v[62:65]
	v_mfma_f32_16x16x32_bf16 v[54:57], v[176:179], v[200:203], v[54:57]
	v_mfma_f32_16x16x32_bf16 v[46:49], v[168:171], v[208:211], v[46:49]
	v_mfma_f32_16x16x32_bf16 v[38:41], v[176:179], v[208:211], v[38:41]
	v_mfma_f32_16x16x32_bf16 v[30:33], v[168:171], v[216:219], v[30:33]
	v_mfma_f32_16x16x32_bf16 v[22:25], v[176:179], v[216:219], v[22:25]
	v_mfma_f32_16x16x32_bf16 v[14:17], v[168:171], v[224:227], v[14:17]
	v_mfma_f32_16x16x32_bf16 v[6:9], v[176:179], v[224:227], v[6:9]
	s_setprio 0
	s_setprio 1
	v_mfma_f32_16x16x32_bf16 v[58:61], v[180:183], v[196:199], v[58:61]
	v_mfma_f32_16x16x32_bf16 v[50:53], v[188:191], v[196:199], v[50:53]
	v_mfma_f32_16x16x32_bf16 v[42:45], v[180:183], v[204:207], v[42:45]
	v_mfma_f32_16x16x32_bf16 v[34:37], v[188:191], v[204:207], v[34:37]
	v_mfma_f32_16x16x32_bf16 v[26:29], v[180:183], v[212:215], v[26:29]
	v_mfma_f32_16x16x32_bf16 v[18:21], v[188:191], v[212:215], v[18:21]
	v_mfma_f32_16x16x32_bf16 v[10:13], v[180:183], v[220:223], v[10:13]
	v_mfma_f32_16x16x32_bf16 v[2:5], v[188:191], v[220:223], v[2:5]
	v_mfma_f32_16x16x32_bf16 v[58:61], v[184:187], v[200:203], v[58:61]
	v_mfma_f32_16x16x32_bf16 v[50:53], v[192:195], v[200:203], v[50:53]
	v_mfma_f32_16x16x32_bf16 v[42:45], v[184:187], v[208:211], v[42:45]
	v_mfma_f32_16x16x32_bf16 v[34:37], v[192:195], v[208:211], v[34:37]
	v_mfma_f32_16x16x32_bf16 v[26:29], v[184:187], v[216:219], v[26:29]
	v_mfma_f32_16x16x32_bf16 v[18:21], v[192:195], v[216:219], v[18:21]
	v_mfma_f32_16x16x32_bf16 v[10:13], v[184:187], v[224:227], v[10:13]
	v_mfma_f32_16x16x32_bf16 v[2:5], v[192:195], v[224:227], v[2:5]
	s_barrier
	s_setprio 0
	s_add_u32 s98, s94, 0xb0000
	s_addc_u32 s99, s95, 0
	s_add_i32 s6, 0, 0x18000
	s_add_i32 s29, 0, 0x1c000
	s_mov_b32 m0, s48
	ds_read_b128 v[164:167], v232
	global_load_lds_dwordx4 v130, s[98:99]
	s_mov_b32 m0, s49
	ds_read_b128 v[168:171], v232 offset:1024
	global_load_lds_dwordx4 v134, s[98:99]
	ds_read_b128 v[172:175], v232 offset:2048
	ds_read_b128 v[176:179], v232 offset:3072
	ds_read_b128 v[180:183], v233
	ds_read_b128 v[184:187], v233 offset:1024
	ds_read_b128 v[188:191], v233 offset:2048
	ds_read_b128 v[192:195], v233 offset:3072
	ds_read_b128 v[196:199], v160 offset:32768
	ds_read_b128 v[200:203], v160 offset:33792
	ds_read_b128 v[204:207], v160 offset:34816
	ds_read_b128 v[208:211], v160 offset:35840
	ds_read_b128 v[212:215], v160 offset:36864
	ds_read_b128 v[216:219], v160 offset:37888
	ds_read_b128 v[220:223], v160 offset:38912
	ds_read_b128 v[224:227], v160 offset:39936
	s_waitcnt vmcnt(8)
	s_waitcnt lgkmcnt(0)
	s_setprio 1
	s_barrier
	v_mfma_f32_16x16x32_bf16 v[122:125], v[164:167], v[196:199], v[122:125]
	v_mfma_f32_16x16x32_bf16 v[118:121], v[172:175], v[196:199], v[118:121]
	v_mfma_f32_16x16x32_bf16 v[110:113], v[164:167], v[204:207], v[110:113]
	v_mfma_f32_16x16x32_bf16 v[102:105], v[172:175], v[204:207], v[102:105]
	v_mfma_f32_16x16x32_bf16 v[94:97], v[164:167], v[212:215], v[94:97]
	v_mfma_f32_16x16x32_bf16 v[86:89], v[172:175], v[212:215], v[86:89]
	v_mfma_f32_16x16x32_bf16 v[78:81], v[164:167], v[220:223], v[78:81]
	v_mfma_f32_16x16x32_bf16 v[70:73], v[172:175], v[220:223], v[70:73]
	v_mfma_f32_16x16x32_bf16 v[122:125], v[168:171], v[200:203], v[122:125]
	v_mfma_f32_16x16x32_bf16 v[118:121], v[176:179], v[200:203], v[118:121]
	v_mfma_f32_16x16x32_bf16 v[110:113], v[168:171], v[208:211], v[110:113]
	v_mfma_f32_16x16x32_bf16 v[102:105], v[176:179], v[208:211], v[102:105]
	v_mfma_f32_16x16x32_bf16 v[94:97], v[168:171], v[216:219], v[94:97]
	v_mfma_f32_16x16x32_bf16 v[86:89], v[176:179], v[216:219], v[86:89]
	v_mfma_f32_16x16x32_bf16 v[78:81], v[168:171], v[224:227], v[78:81]
	v_mfma_f32_16x16x32_bf16 v[70:73], v[176:179], v[224:227], v[70:73]
	s_setprio 0
	s_setprio 1
	v_mfma_f32_16x16x32_bf16 v[126:129], v[180:183], v[196:199], v[126:129]
	v_mfma_f32_16x16x32_bf16 v[114:117], v[188:191], v[196:199], v[114:117]
	v_mfma_f32_16x16x32_bf16 v[106:109], v[180:183], v[204:207], v[106:109]
	v_mfma_f32_16x16x32_bf16 v[98:101], v[188:191], v[204:207], v[98:101]
	v_mfma_f32_16x16x32_bf16 v[90:93], v[180:183], v[212:215], v[90:93]
	v_mfma_f32_16x16x32_bf16 v[82:85], v[188:191], v[212:215], v[82:85]
	v_mfma_f32_16x16x32_bf16 v[74:77], v[180:183], v[220:223], v[74:77]
	v_mfma_f32_16x16x32_bf16 v[66:69], v[188:191], v[220:223], v[66:69]
	v_mfma_f32_16x16x32_bf16 v[126:129], v[184:187], v[200:203], v[126:129]
	v_mfma_f32_16x16x32_bf16 v[114:117], v[192:195], v[200:203], v[114:117]
	v_mfma_f32_16x16x32_bf16 v[106:109], v[184:187], v[208:211], v[106:109]
	v_mfma_f32_16x16x32_bf16 v[98:101], v[192:195], v[208:211], v[98:101]
	v_mfma_f32_16x16x32_bf16 v[90:93], v[184:187], v[216:219], v[90:93]
	v_mfma_f32_16x16x32_bf16 v[82:85], v[192:195], v[216:219], v[82:85]
	v_mfma_f32_16x16x32_bf16 v[74:77], v[184:187], v[224:227], v[74:77]
	v_mfma_f32_16x16x32_bf16 v[66:69], v[192:195], v[224:227], v[66:69]
	s_barrier
	s_setprio 0
	s_add_u32 s96, s96, 0x80
	s_addc_u32 s97, s97, 0
	s_add_u32 s98, s96, 0xb0000
	s_addc_u32 s99, s97, 0
	s_add_u32 s94, s94, 0x80
	s_addc_u32 s95, s95, 0
	s_add_i32 s6, s6, s23
	s_mov_b32 m0, s6
	ds_read_b128 v[196:199], v160 offset:49152
	global_load_lds_dwordx4 v132, s[96:97]
	s_add_i32 m0, s6, 0x2000
	s_add_i32 s6, s29, s23
	global_load_lds_dwordx4 v136, s[96:97]
	s_mov_b32 m0, s6
	ds_read_b128 v[200:203], v160 offset:50176
	global_load_lds_dwordx4 v132, s[98:99]
	s_add_i32 m0, s6, 0x2000
	ds_read_b128 v[204:207], v160 offset:51200
	global_load_lds_dwordx4 v136, s[98:99]
	s_mov_b32 m0, s59
	ds_read_b128 v[208:211], v160 offset:52224
	global_load_lds_dwordx4 v130, s[94:95]
	s_mov_b32 m0, s60
	ds_read_b128 v[212:215], v160 offset:53248
	global_load_lds_dwordx4 v134, s[94:95]
	ds_read_b128 v[216:219], v160 offset:54272
	ds_read_b128 v[220:223], v160 offset:55296
	ds_read_b128 v[224:227], v160 offset:56320
	s_waitcnt vmcnt(8)
	s_waitcnt lgkmcnt(0)
	s_setprio 1
	s_barrier
	v_mfma_f32_16x16x32_bf16 v[62:65], v[164:167], v[196:199], v[62:65]
	v_mfma_f32_16x16x32_bf16 v[54:57], v[172:175], v[196:199], v[54:57]
	v_mfma_f32_16x16x32_bf16 v[46:49], v[164:167], v[204:207], v[46:49]
	v_mfma_f32_16x16x32_bf16 v[38:41], v[172:175], v[204:207], v[38:41]
	v_mfma_f32_16x16x32_bf16 v[30:33], v[164:167], v[212:215], v[30:33]
	v_mfma_f32_16x16x32_bf16 v[22:25], v[172:175], v[212:215], v[22:25]
	v_mfma_f32_16x16x32_bf16 v[14:17], v[164:167], v[220:223], v[14:17]
	v_mfma_f32_16x16x32_bf16 v[6:9], v[172:175], v[220:223], v[6:9]
	v_mfma_f32_16x16x32_bf16 v[62:65], v[168:171], v[200:203], v[62:65]
	v_mfma_f32_16x16x32_bf16 v[54:57], v[176:179], v[200:203], v[54:57]
	v_mfma_f32_16x16x32_bf16 v[46:49], v[168:171], v[208:211], v[46:49]
	v_mfma_f32_16x16x32_bf16 v[38:41], v[176:179], v[208:211], v[38:41]
	v_mfma_f32_16x16x32_bf16 v[30:33], v[168:171], v[216:219], v[30:33]
	v_mfma_f32_16x16x32_bf16 v[22:25], v[176:179], v[216:219], v[22:25]
	v_mfma_f32_16x16x32_bf16 v[14:17], v[168:171], v[224:227], v[14:17]
	v_mfma_f32_16x16x32_bf16 v[6:9], v[176:179], v[224:227], v[6:9]
	s_setprio 0
	s_setprio 1
	v_mfma_f32_16x16x32_bf16 v[58:61], v[180:183], v[196:199], v[58:61]
	v_mfma_f32_16x16x32_bf16 v[50:53], v[188:191], v[196:199], v[50:53]
	v_mfma_f32_16x16x32_bf16 v[42:45], v[180:183], v[204:207], v[42:45]
	v_mfma_f32_16x16x32_bf16 v[34:37], v[188:191], v[204:207], v[34:37]
	v_mfma_f32_16x16x32_bf16 v[26:29], v[180:183], v[212:215], v[26:29]
	v_mfma_f32_16x16x32_bf16 v[18:21], v[188:191], v[212:215], v[18:21]
	v_mfma_f32_16x16x32_bf16 v[10:13], v[180:183], v[220:223], v[10:13]
	v_mfma_f32_16x16x32_bf16 v[2:5], v[188:191], v[220:223], v[2:5]
	v_mfma_f32_16x16x32_bf16 v[58:61], v[184:187], v[200:203], v[58:61]
	v_mfma_f32_16x16x32_bf16 v[50:53], v[192:195], v[200:203], v[50:53]
	v_mfma_f32_16x16x32_bf16 v[42:45], v[184:187], v[208:211], v[42:45]
	v_mfma_f32_16x16x32_bf16 v[34:37], v[192:195], v[208:211], v[34:37]
	v_mfma_f32_16x16x32_bf16 v[26:29], v[184:187], v[216:219], v[26:29]
	v_mfma_f32_16x16x32_bf16 v[18:21], v[192:195], v[216:219], v[18:21]
	v_mfma_f32_16x16x32_bf16 v[10:13], v[184:187], v[224:227], v[10:13]
	v_mfma_f32_16x16x32_bf16 v[2:5], v[192:195], v[224:227], v[2:5]
	s_barrier
	s_setprio 0
	s_mov_b32 s6, s7
	s_add_u32 s88, s88, 0x100
	s_addc_u32 s89, s89, 0
	s_add_u32 s86, s86, 0x100
	s_addc_u32 s87, s87, 0
	s_cmp_ge_i32 s7, s101
	s_cbranch_scc0 .LBB0_1392

.Lmy_nb_8:
	s_nop 0
	v_readfirstlane_b32 s86, v154
	v_readfirstlane_b32 s87, v155
	v_readfirstlane_b32 s88, v152
	v_readfirstlane_b32 s89, v153
	v_readfirstlane_b32 s90, v148
	v_readfirstlane_b32 s91, v149
	v_readfirstlane_b32 s92, v150
	v_readfirstlane_b32 s93, v151
	v_readfirstlane_b32 s100, v138
	v_readfirstlane_b32 s101, v141
	v_add_u32_e32 v230, s71, v160
	v_add_u32_e32 v231, s72, v160
	v_add_u32_e32 v232, 0x18000, v160
	v_add_u32_e32 v233, 0x1c000, v160
	s_add_u32 s98, s86, 0xfffc0080
	s_addc_u32 s99, s87, -1
	s_cmp_eq_u32 s7, s100
	s_cselect_b64 s[94:95], s[90:91], s[98:99]
	s_cselect_b64 s[96:97], s[92:93], s[88:89]
	s_add_i32 s47, s7, 2
	s_mov_b32 m0, s74
	ds_read_b128 v[156:159], v230
	global_load_lds_dwordx4 v144, s[86:87]
	s_mov_b32 m0, s75
	ds_read_b128 v[166:169], v230 offset:1024
	global_load_lds_dwordx4 v142, s[86:87]
	ds_read_b128 v[170:173], v230 offset:2048
	ds_read_b128 v[174:177], v230 offset:3072
	ds_read_b128 v[178:181], v231
	ds_read_b128 v[182:185], v231 offset:1024
	ds_read_b128 v[186:189], v231 offset:2048
	ds_read_b128 v[190:193], v231 offset:3072
	ds_read_b128 v[194:197], v163
	ds_read_b128 v[198:201], v163 offset:1024
	ds_read_b128 v[202:205], v163 offset:2048
	ds_read_b128 v[206:209], v163 offset:3072
	ds_read_b128 v[210:213], v163 offset:4096
	ds_read_b128 v[214:217], v163 offset:5120
	ds_read_b128 v[218:221], v163 offset:6144
	ds_read_b128 v[222:225], v163 offset:7168
	s_waitcnt vmcnt(8)
	s_waitcnt lgkmcnt(0)
	s_setprio 1
	s_barrier
	v_mfma_f32_16x16x32_bf16 v[122:125], v[156:159], v[194:197], 0
	v_mfma_f32_16x16x32_bf16 v[118:121], v[170:173], v[194:197], 0
	v_mfma_f32_16x16x32_bf16 v[110:113], v[156:159], v[202:205], 0
	v_mfma_f32_16x16x32_bf16 v[102:105], v[170:173], v[202:205], 0
	v_mfma_f32_16x16x32_bf16 v[94:97], v[156:159], v[210:213], 0
	v_mfma_f32_16x16x32_bf16 v[86:89], v[170:173], v[210:213], 0
	v_mfma_f32_16x16x32_bf16 v[78:81], v[156:159], v[218:221], 0
	v_mfma_f32_16x16x32_bf16 v[70:73], v[170:173], v[218:221], 0
	v_mfma_f32_16x16x32_bf16 v[122:125], v[166:169], v[198:201], v[122:125]
	v_mfma_f32_16x16x32_bf16 v[118:121], v[174:177], v[198:201], v[118:121]
	v_mfma_f32_16x16x32_bf16 v[110:113], v[166:169], v[206:209], v[110:113]
	v_mfma_f32_16x16x32_bf16 v[102:105], v[174:177], v[206:209], v[102:105]
	v_mfma_f32_16x16x32_bf16 v[94:97], v[166:169], v[214:217], v[94:97]
	v_mfma_f32_16x16x32_bf16 v[86:89], v[174:177], v[214:217], v[86:89]
	v_mfma_f32_16x16x32_bf16 v[78:81], v[166:169], v[222:225], v[78:81]
	v_mfma_f32_16x16x32_bf16 v[70:73], v[174:177], v[222:225], v[70:73]
	s_setprio 0
	s_setprio 1
	v_mfma_f32_16x16x32_bf16 v[126:129], v[178:181], v[194:197], 0
	v_mfma_f32_16x16x32_bf16 v[114:117], v[186:189], v[194:197], 0
	v_mfma_f32_16x16x32_bf16 v[106:109], v[178:181], v[202:205], 0
	v_mfma_f32_16x16x32_bf16 v[98:101], v[186:189], v[202:205], 0
	v_mfma_f32_16x16x32_bf16 v[90:93], v[178:181], v[210:213], 0
	v_mfma_f32_16x16x32_bf16 v[82:85], v[186:189], v[210:213], 0
	v_mfma_f32_16x16x32_bf16 v[74:77], v[178:181], v[218:221], 0
	v_mfma_f32_16x16x32_bf16 v[66:69], v[186:189], v[218:221], 0
	v_mfma_f32_16x16x32_bf16 v[126:129], v[182:185], v[198:201], v[126:129]
	v_mfma_f32_16x16x32_bf16 v[114:117], v[190:193], v[198:201], v[114:117]
	v_mfma_f32_16x16x32_bf16 v[106:109], v[182:185], v[206:209], v[106:109]
	v_mfma_f32_16x16x32_bf16 v[98:101], v[190:193], v[206:209], v[98:101]
	v_mfma_f32_16x16x32_bf16 v[90:93], v[182:185], v[214:217], v[90:93]
	v_mfma_f32_16x16x32_bf16 v[82:85], v[190:193], v[214:217], v[82:85]
	v_mfma_f32_16x16x32_bf16 v[74:77], v[182:185], v[222:225], v[74:77]
	v_mfma_f32_16x16x32_bf16 v[66:69], v[190:193], v[222:225], v[66:69]
	s_barrier
	s_setprio 0
	s_add_u32 s98, s96, 0x40000
	s_addc_u32 s99, s97, 0
	s_add_i32 s7, s71, s29
	s_mov_b32 m0, s7
	ds_read_b128 v[194:197], v163 offset:16384
	global_load_lds_dwordx4 v132, s[96:97]
	s_add_i32 m0, s7, 0x2000
	s_add_i32 s7, s72, s29
	global_load_lds_dwordx4 v136, s[96:97]
	s_mov_b32 m0, s7
	ds_read_b128 v[198:201], v163 offset:17408
	global_load_lds_dwordx4 v132, s[98:99]
	s_add_i32 m0, s7, 0x2000
	ds_read_b128 v[202:205], v163 offset:18432
	global_load_lds_dwordx4 v136, s[98:99]
	s_mov_b32 m0, s51
	ds_read_b128 v[206:209], v163 offset:19456
	global_load_lds_dwordx4 v130, s[94:95]
	s_mov_b32 m0, s60
	ds_read_b128 v[210:213], v163 offset:20480
	global_load_lds_dwordx4 v134, s[94:95]
	ds_read_b128 v[214:217], v163 offset:21504
	ds_read_b128 v[218:221], v163 offset:22528
	ds_read_b128 v[222:225], v163 offset:23552
	s_waitcnt vmcnt(8)
	s_waitcnt lgkmcnt(0)
	s_setprio 1
	s_barrier
	v_mfma_f32_16x16x32_bf16 v[62:65], v[156:159], v[194:197], 0
	v_mfma_f32_16x16x32_bf16 v[54:57], v[170:173], v[194:197], 0
	v_mfma_f32_16x16x32_bf16 v[46:49], v[156:159], v[202:205], 0
	v_mfma_f32_16x16x32_bf16 v[38:41], v[170:173], v[202:205], 0
	v_mfma_f32_16x16x32_bf16 v[30:33], v[156:159], v[210:213], 0
	v_mfma_f32_16x16x32_bf16 v[22:25], v[170:173], v[210:213], 0
	v_mfma_f32_16x16x32_bf16 v[14:17], v[156:159], v[218:221], 0
	v_mfma_f32_16x16x32_bf16 v[6:9], v[170:173], v[218:221], 0
	v_mfma_f32_16x16x32_bf16 v[62:65], v[166:169], v[198:201], v[62:65]
	v_mfma_f32_16x16x32_bf16 v[54:57], v[174:177], v[198:201], v[54:57]
	v_mfma_f32_16x16x32_bf16 v[46:49], v[166:169], v[206:209], v[46:49]
	v_mfma_f32_16x16x32_bf16 v[38:41], v[174:177], v[206:209], v[38:41]
	v_mfma_f32_16x16x32_bf16 v[30:33], v[166:169], v[214:217], v[30:33]
	v_mfma_f32_16x16x32_bf16 v[22:25], v[174:177], v[214:217], v[22:25]
	v_mfma_f32_16x16x32_bf16 v[14:17], v[166:169], v[222:225], v[14:17]
	v_mfma_f32_16x16x32_bf16 v[6:9], v[174:177], v[222:225], v[6:9]
	s_setprio 0
	s_setprio 1
	v_mfma_f32_16x16x32_bf16 v[58:61], v[178:181], v[194:197], 0
	v_mfma_f32_16x16x32_bf16 v[50:53], v[186:189], v[194:197], 0
	v_mfma_f32_16x16x32_bf16 v[42:45], v[178:181], v[202:205], 0
	v_mfma_f32_16x16x32_bf16 v[34:37], v[186:189], v[202:205], 0
	v_mfma_f32_16x16x32_bf16 v[26:29], v[178:181], v[210:213], 0
	v_mfma_f32_16x16x32_bf16 v[18:21], v[186:189], v[210:213], 0
	v_mfma_f32_16x16x32_bf16 v[10:13], v[178:181], v[218:221], 0
	v_mfma_f32_16x16x32_bf16 v[2:5], v[186:189], v[218:221], 0
	v_mfma_f32_16x16x32_bf16 v[58:61], v[182:185], v[198:201], v[58:61]
	v_mfma_f32_16x16x32_bf16 v[50:53], v[190:193], v[198:201], v[50:53]
	v_mfma_f32_16x16x32_bf16 v[42:45], v[182:185], v[206:209], v[42:45]
	v_mfma_f32_16x16x32_bf16 v[34:37], v[190:193], v[206:209], v[34:37]
	v_mfma_f32_16x16x32_bf16 v[26:29], v[182:185], v[214:217], v[26:29]
	v_mfma_f32_16x16x32_bf16 v[18:21], v[190:193], v[214:217], v[18:21]
	v_mfma_f32_16x16x32_bf16 v[10:13], v[182:185], v[222:225], v[10:13]
	v_mfma_f32_16x16x32_bf16 v[2:5], v[190:193], v[222:225], v[2:5]
	s_barrier
	s_setprio 0
	s_add_u32 s98, s94, 0x40000
	s_addc_u32 s99, s95, 0
	s_add_i32 s7, 0, 0x18000
	s_add_i32 s49, 0, 0x1c000
	s_mov_b32 m0, s61
	ds_read_b128 v[156:159], v232
	global_load_lds_dwordx4 v130, s[98:99]
	s_mov_b32 m0, s62
	ds_read_b128 v[166:169], v232 offset:1024
	global_load_lds_dwordx4 v134, s[98:99]
	ds_read_b128 v[170:173], v232 offset:2048
	ds_read_b128 v[174:177], v232 offset:3072
	ds_read_b128 v[178:181], v233
	ds_read_b128 v[182:185], v233 offset:1024
	ds_read_b128 v[186:189], v233 offset:2048
	ds_read_b128 v[190:193], v233 offset:3072
	ds_read_b128 v[194:197], v163 offset:32768
	ds_read_b128 v[198:201], v163 offset:33792
	ds_read_b128 v[202:205], v163 offset:34816
	ds_read_b128 v[206:209], v163 offset:35840
	ds_read_b128 v[210:213], v163 offset:36864
	ds_read_b128 v[214:217], v163 offset:37888
	ds_read_b128 v[218:221], v163 offset:38912
	ds_read_b128 v[222:225], v163 offset:39936
	s_waitcnt vmcnt(8)
	s_waitcnt lgkmcnt(0)
	s_setprio 1
	s_barrier
	v_mfma_f32_16x16x32_bf16 v[122:125], v[156:159], v[194:197], v[122:125]
	v_mfma_f32_16x16x32_bf16 v[118:121], v[170:173], v[194:197], v[118:121]
	v_mfma_f32_16x16x32_bf16 v[110:113], v[156:159], v[202:205], v[110:113]
	v_mfma_f32_16x16x32_bf16 v[102:105], v[170:173], v[202:205], v[102:105]
	v_mfma_f32_16x16x32_bf16 v[94:97], v[156:159], v[210:213], v[94:97]
	v_mfma_f32_16x16x32_bf16 v[86:89], v[170:173], v[210:213], v[86:89]
	v_mfma_f32_16x16x32_bf16 v[78:81], v[156:159], v[218:221], v[78:81]
	v_mfma_f32_16x16x32_bf16 v[70:73], v[170:173], v[218:221], v[70:73]
	v_mfma_f32_16x16x32_bf16 v[122:125], v[166:169], v[198:201], v[122:125]
	v_mfma_f32_16x16x32_bf16 v[118:121], v[174:177], v[198:201], v[118:121]
	v_mfma_f32_16x16x32_bf16 v[110:113], v[166:169], v[206:209], v[110:113]
	v_mfma_f32_16x16x32_bf16 v[102:105], v[174:177], v[206:209], v[102:105]
	v_mfma_f32_16x16x32_bf16 v[94:97], v[166:169], v[214:217], v[94:97]
	v_mfma_f32_16x16x32_bf16 v[86:89], v[174:177], v[214:217], v[86:89]
	v_mfma_f32_16x16x32_bf16 v[78:81], v[166:169], v[222:225], v[78:81]
	v_mfma_f32_16x16x32_bf16 v[70:73], v[174:177], v[222:225], v[70:73]
	s_setprio 0
	s_setprio 1
	v_mfma_f32_16x16x32_bf16 v[126:129], v[178:181], v[194:197], v[126:129]
	v_mfma_f32_16x16x32_bf16 v[114:117], v[186:189], v[194:197], v[114:117]
	v_mfma_f32_16x16x32_bf16 v[106:109], v[178:181], v[202:205], v[106:109]
	v_mfma_f32_16x16x32_bf16 v[98:101], v[186:189], v[202:205], v[98:101]
	v_mfma_f32_16x16x32_bf16 v[90:93], v[178:181], v[210:213], v[90:93]
	v_mfma_f32_16x16x32_bf16 v[82:85], v[186:189], v[210:213], v[82:85]
	v_mfma_f32_16x16x32_bf16 v[74:77], v[178:181], v[218:221], v[74:77]
	v_mfma_f32_16x16x32_bf16 v[66:69], v[186:189], v[218:221], v[66:69]
	v_mfma_f32_16x16x32_bf16 v[126:129], v[182:185], v[198:201], v[126:129]
	v_mfma_f32_16x16x32_bf16 v[114:117], v[190:193], v[198:201], v[114:117]
	v_mfma_f32_16x16x32_bf16 v[106:109], v[182:185], v[206:209], v[106:109]
	v_mfma_f32_16x16x32_bf16 v[98:101], v[190:193], v[206:209], v[98:101]
	v_mfma_f32_16x16x32_bf16 v[90:93], v[182:185], v[214:217], v[90:93]
	v_mfma_f32_16x16x32_bf16 v[82:85], v[190:193], v[214:217], v[82:85]
	v_mfma_f32_16x16x32_bf16 v[74:77], v[182:185], v[222:225], v[74:77]
	v_mfma_f32_16x16x32_bf16 v[66:69], v[190:193], v[222:225], v[66:69]
	s_barrier
	s_setprio 0
	s_add_u32 s96, s96, 0x80
	s_addc_u32 s97, s97, 0
	s_add_u32 s98, s96, 0x40000
	s_addc_u32 s99, s97, 0
	s_add_u32 s94, s94, 0x80
	s_addc_u32 s95, s95, 0
	s_add_i32 s7, s7, s29
	s_mov_b32 m0, s7
	ds_read_b128 v[194:197], v163 offset:49152
	global_load_lds_dwordx4 v132, s[96:97]
	s_add_i32 m0, s7, 0x2000
	s_add_i32 s7, s49, s29
	global_load_lds_dwordx4 v136, s[96:97]
	s_mov_b32 m0, s7
	ds_read_b128 v[198:201], v163 offset:50176
	global_load_lds_dwordx4 v132, s[98:99]
	s_add_i32 m0, s7, 0x2000
	ds_read_b128 v[202:205], v163 offset:51200
	global_load_lds_dwordx4 v136, s[98:99]
	s_mov_b32 m0, s63
	ds_read_b128 v[206:209], v163 offset:52224
	global_load_lds_dwordx4 v130, s[94:95]
	s_mov_b32 m0, s64
	ds_read_b128 v[210:213], v163 offset:53248
	global_load_lds_dwordx4 v134, s[94:95]
	ds_read_b128 v[214:217], v163 offset:54272
	ds_read_b128 v[218:221], v163 offset:55296
	ds_read_b128 v[222:225], v163 offset:56320
	s_waitcnt vmcnt(8)
	s_waitcnt lgkmcnt(0)
	s_setprio 1
	s_barrier
	v_mfma_f32_16x16x32_bf16 v[62:65], v[156:159], v[194:197], v[62:65]
	v_mfma_f32_16x16x32_bf16 v[54:57], v[170:173], v[194:197], v[54:57]
	v_mfma_f32_16x16x32_bf16 v[46:49], v[156:159], v[202:205], v[46:49]
	v_mfma_f32_16x16x32_bf16 v[38:41], v[170:173], v[202:205], v[38:41]
	v_mfma_f32_16x16x32_bf16 v[30:33], v[156:159], v[210:213], v[30:33]
	v_mfma_f32_16x16x32_bf16 v[22:25], v[170:173], v[210:213], v[22:25]
	v_mfma_f32_16x16x32_bf16 v[14:17], v[156:159], v[218:221], v[14:17]
	v_mfma_f32_16x16x32_bf16 v[6:9], v[170:173], v[218:221], v[6:9]
	v_mfma_f32_16x16x32_bf16 v[62:65], v[166:169], v[198:201], v[62:65]
	v_mfma_f32_16x16x32_bf16 v[54:57], v[174:177], v[198:201], v[54:57]
	v_mfma_f32_16x16x32_bf16 v[46:49], v[166:169], v[206:209], v[46:49]
	v_mfma_f32_16x16x32_bf16 v[38:41], v[174:177], v[206:209], v[38:41]
	v_mfma_f32_16x16x32_bf16 v[30:33], v[166:169], v[214:217], v[30:33]
	v_mfma_f32_16x16x32_bf16 v[22:25], v[174:177], v[214:217], v[22:25]
	v_mfma_f32_16x16x32_bf16 v[14:17], v[166:169], v[222:225], v[14:17]
	v_mfma_f32_16x16x32_bf16 v[6:9], v[174:177], v[222:225], v[6:9]
	s_setprio 0
	s_setprio 1
	v_mfma_f32_16x16x32_bf16 v[58:61], v[178:181], v[194:197], v[58:61]
	v_mfma_f32_16x16x32_bf16 v[50:53], v[186:189], v[194:197], v[50:53]
	v_mfma_f32_16x16x32_bf16 v[42:45], v[178:181], v[202:205], v[42:45]
	v_mfma_f32_16x16x32_bf16 v[34:37], v[186:189], v[202:205], v[34:37]
	v_mfma_f32_16x16x32_bf16 v[26:29], v[178:181], v[210:213], v[26:29]
	v_mfma_f32_16x16x32_bf16 v[18:21], v[186:189], v[210:213], v[18:21]
	v_mfma_f32_16x16x32_bf16 v[10:13], v[178:181], v[218:221], v[10:13]
	v_mfma_f32_16x16x32_bf16 v[2:5], v[186:189], v[218:221], v[2:5]
	v_mfma_f32_16x16x32_bf16 v[58:61], v[182:185], v[198:201], v[58:61]
	v_mfma_f32_16x16x32_bf16 v[50:53], v[190:193], v[198:201], v[50:53]
	v_mfma_f32_16x16x32_bf16 v[42:45], v[182:185], v[206:209], v[42:45]
	v_mfma_f32_16x16x32_bf16 v[34:37], v[190:193], v[206:209], v[34:37]
	v_mfma_f32_16x16x32_bf16 v[26:29], v[182:185], v[214:217], v[26:29]
	v_mfma_f32_16x16x32_bf16 v[18:21], v[190:193], v[214:217], v[18:21]
	v_mfma_f32_16x16x32_bf16 v[10:13], v[182:185], v[222:225], v[10:13]
	v_mfma_f32_16x16x32_bf16 v[2:5], v[190:193], v[222:225], v[2:5]
	s_barrier
	s_setprio 0
	s_mov_b32 s7, s47
	s_add_u32 s88, s88, 0x100
	s_addc_u32 s89, s89, 0
	s_add_u32 s86, s86, 0x100
	s_addc_u32 s87, s87, 0
	s_cmp_ge_i32 s47, s101
	s_cbranch_scc1 .Lmy_kexit_8
.LBB0_1573:
	s_add_u32 s98, s86, 0xfffc0080
	s_addc_u32 s99, s87, -1
	s_cmp_eq_u32 s7, s100
	s_cselect_b64 s[94:95], s[90:91], s[98:99]
	s_cselect_b64 s[96:97], s[92:93], s[88:89]
	s_add_i32 s47, s7, 2
	s_mov_b32 m0, s74
	ds_read_b128 v[156:159], v230
	global_load_lds_dwordx4 v144, s[86:87]
	s_mov_b32 m0, s75
	ds_read_b128 v[166:169], v230 offset:1024
	global_load_lds_dwordx4 v142, s[86:87]
	ds_read_b128 v[170:173], v230 offset:2048
	ds_read_b128 v[174:177], v230 offset:3072
	ds_read_b128 v[178:181], v231
	ds_read_b128 v[182:185], v231 offset:1024
	ds_read_b128 v[186:189], v231 offset:2048
	ds_read_b128 v[190:193], v231 offset:3072
	ds_read_b128 v[194:197], v163
	ds_read_b128 v[198:201], v163 offset:1024
	ds_read_b128 v[202:205], v163 offset:2048
	ds_read_b128 v[206:209], v163 offset:3072
	ds_read_b128 v[210:213], v163 offset:4096
	ds_read_b128 v[214:217], v163 offset:5120
	ds_read_b128 v[218:221], v163 offset:6144
	ds_read_b128 v[222:225], v163 offset:7168
	s_waitcnt vmcnt(8)
	s_waitcnt lgkmcnt(0)
	s_setprio 1
	s_barrier
	v_mfma_f32_16x16x32_bf16 v[122:125], v[156:159], v[194:197], v[122:125]
	v_mfma_f32_16x16x32_bf16 v[118:121], v[170:173], v[194:197], v[118:121]
	v_mfma_f32_16x16x32_bf16 v[110:113], v[156:159], v[202:205], v[110:113]
	v_mfma_f32_16x16x32_bf16 v[102:105], v[170:173], v[202:205], v[102:105]
	v_mfma_f32_16x16x32_bf16 v[94:97], v[156:159], v[210:213], v[94:97]
	v_mfma_f32_16x16x32_bf16 v[86:89], v[170:173], v[210:213], v[86:89]
	v_mfma_f32_16x16x32_bf16 v[78:81], v[156:159], v[218:221], v[78:81]
	v_mfma_f32_16x16x32_bf16 v[70:73], v[170:173], v[218:221], v[70:73]
	v_mfma_f32_16x16x32_bf16 v[122:125], v[166:169], v[198:201], v[122:125]
	v_mfma_f32_16x16x32_bf16 v[118:121], v[174:177], v[198:201], v[118:121]
	v_mfma_f32_16x16x32_bf16 v[110:113], v[166:169], v[206:209], v[110:113]
	v_mfma_f32_16x16x32_bf16 v[102:105], v[174:177], v[206:209], v[102:105]
	v_mfma_f32_16x16x32_bf16 v[94:97], v[166:169], v[214:217], v[94:97]
	v_mfma_f32_16x16x32_bf16 v[86:89], v[174:177], v[214:217], v[86:89]
	v_mfma_f32_16x16x32_bf16 v[78:81], v[166:169], v[222:225], v[78:81]
	v_mfma_f32_16x16x32_bf16 v[70:73], v[174:177], v[222:225], v[70:73]
	s_setprio 0
	s_setprio 1
	v_mfma_f32_16x16x32_bf16 v[126:129], v[178:181], v[194:197], v[126:129]
	v_mfma_f32_16x16x32_bf16 v[114:117], v[186:189], v[194:197], v[114:117]
	v_mfma_f32_16x16x32_bf16 v[106:109], v[178:181], v[202:205], v[106:109]
	v_mfma_f32_16x16x32_bf16 v[98:101], v[186:189], v[202:205], v[98:101]
	v_mfma_f32_16x16x32_bf16 v[90:93], v[178:181], v[210:213], v[90:93]
	v_mfma_f32_16x16x32_bf16 v[82:85], v[186:189], v[210:213], v[82:85]
	v_mfma_f32_16x16x32_bf16 v[74:77], v[178:181], v[218:221], v[74:77]
	v_mfma_f32_16x16x32_bf16 v[66:69], v[186:189], v[218:221], v[66:69]
	v_mfma_f32_16x16x32_bf16 v[126:129], v[182:185], v[198:201], v[126:129]
	v_mfma_f32_16x16x32_bf16 v[114:117], v[190:193], v[198:201], v[114:117]
	v_mfma_f32_16x16x32_bf16 v[106:109], v[182:185], v[206:209], v[106:109]
	v_mfma_f32_16x16x32_bf16 v[98:101], v[190:193], v[206:209], v[98:101]
	v_mfma_f32_16x16x32_bf16 v[90:93], v[182:185], v[214:217], v[90:93]
	v_mfma_f32_16x16x32_bf16 v[82:85], v[190:193], v[214:217], v[82:85]
	v_mfma_f32_16x16x32_bf16 v[74:77], v[182:185], v[222:225], v[74:77]
	v_mfma_f32_16x16x32_bf16 v[66:69], v[190:193], v[222:225], v[66:69]
	s_barrier
	s_setprio 0
	s_add_u32 s98, s96, 0x40000
	s_addc_u32 s99, s97, 0
	s_add_i32 s7, s71, s29
	s_mov_b32 m0, s7
	ds_read_b128 v[194:197], v163 offset:16384
	global_load_lds_dwordx4 v132, s[96:97]
	s_add_i32 m0, s7, 0x2000
	s_add_i32 s7, s72, s29
	global_load_lds_dwordx4 v136, s[96:97]
	s_mov_b32 m0, s7
	ds_read_b128 v[198:201], v163 offset:17408
	global_load_lds_dwordx4 v132, s[98:99]
	s_add_i32 m0, s7, 0x2000
	ds_read_b128 v[202:205], v163 offset:18432
	global_load_lds_dwordx4 v136, s[98:99]
	s_mov_b32 m0, s51
	ds_read_b128 v[206:209], v163 offset:19456
	global_load_lds_dwordx4 v130, s[94:95]
	s_mov_b32 m0, s60
	ds_read_b128 v[210:213], v163 offset:20480
	global_load_lds_dwordx4 v134, s[94:95]
	ds_read_b128 v[214:217], v163 offset:21504
	ds_read_b128 v[218:221], v163 offset:22528
	ds_read_b128 v[222:225], v163 offset:23552
	s_waitcnt vmcnt(8)
	s_waitcnt lgkmcnt(0)
	s_setprio 1
	s_barrier
	v_mfma_f32_16x16x32_bf16 v[62:65], v[156:159], v[194:197], v[62:65]
	v_mfma_f32_16x16x32_bf16 v[54:57], v[170:173], v[194:197], v[54:57]
	v_mfma_f32_16x16x32_bf16 v[46:49], v[156:159], v[202:205], v[46:49]
	v_mfma_f32_16x16x32_bf16 v[38:41], v[170:173], v[202:205], v[38:41]
	v_mfma_f32_16x16x32_bf16 v[30:33], v[156:159], v[210:213], v[30:33]
	v_mfma_f32_16x16x32_bf16 v[22:25], v[170:173], v[210:213], v[22:25]
	v_mfma_f32_16x16x32_bf16 v[14:17], v[156:159], v[218:221], v[14:17]
	v_mfma_f32_16x16x32_bf16 v[6:9], v[170:173], v[218:221], v[6:9]
	v_mfma_f32_16x16x32_bf16 v[62:65], v[166:169], v[198:201], v[62:65]
	v_mfma_f32_16x16x32_bf16 v[54:57], v[174:177], v[198:201], v[54:57]
	v_mfma_f32_16x16x32_bf16 v[46:49], v[166:169], v[206:209], v[46:49]
	v_mfma_f32_16x16x32_bf16 v[38:41], v[174:177], v[206:209], v[38:41]
	v_mfma_f32_16x16x32_bf16 v[30:33], v[166:169], v[214:217], v[30:33]
	v_mfma_f32_16x16x32_bf16 v[22:25], v[174:177], v[214:217], v[22:25]
	v_mfma_f32_16x16x32_bf16 v[14:17], v[166:169], v[222:225], v[14:17]
	v_mfma_f32_16x16x32_bf16 v[6:9], v[174:177], v[222:225], v[6:9]
	s_setprio 0
	s_setprio 1
	v_mfma_f32_16x16x32_bf16 v[58:61], v[178:181], v[194:197], v[58:61]
	v_mfma_f32_16x16x32_bf16 v[50:53], v[186:189], v[194:197], v[50:53]
	v_mfma_f32_16x16x32_bf16 v[42:45], v[178:181], v[202:205], v[42:45]
	v_mfma_f32_16x16x32_bf16 v[34:37], v[186:189], v[202:205], v[34:37]
	v_mfma_f32_16x16x32_bf16 v[26:29], v[178:181], v[210:213], v[26:29]
	v_mfma_f32_16x16x32_bf16 v[18:21], v[186:189], v[210:213], v[18:21]
	v_mfma_f32_16x16x32_bf16 v[10:13], v[178:181], v[218:221], v[10:13]
	v_mfma_f32_16x16x32_bf16 v[2:5], v[186:189], v[218:221], v[2:5]
	v_mfma_f32_16x16x32_bf16 v[58:61], v[182:185], v[198:201], v[58:61]
	v_mfma_f32_16x16x32_bf16 v[50:53], v[190:193], v[198:201], v[50:53]
	v_mfma_f32_16x16x32_bf16 v[42:45], v[182:185], v[206:209], v[42:45]
	v_mfma_f32_16x16x32_bf16 v[34:37], v[190:193], v[206:209], v[34:37]
	v_mfma_f32_16x16x32_bf16 v[26:29], v[182:185], v[214:217], v[26:29]
	v_mfma_f32_16x16x32_bf16 v[18:21], v[190:193], v[214:217], v[18:21]
	v_mfma_f32_16x16x32_bf16 v[10:13], v[182:185], v[222:225], v[10:13]
	v_mfma_f32_16x16x32_bf16 v[2:5], v[190:193], v[222:225], v[2:5]
	s_barrier
	s_setprio 0
	s_add_u32 s98, s94, 0x40000
	s_addc_u32 s99, s95, 0
	s_add_i32 s7, 0, 0x18000
	s_add_i32 s49, 0, 0x1c000
	s_mov_b32 m0, s61
	ds_read_b128 v[156:159], v232
	global_load_lds_dwordx4 v130, s[98:99]
	s_mov_b32 m0, s62
	ds_read_b128 v[166:169], v232 offset:1024
	global_load_lds_dwordx4 v134, s[98:99]
	ds_read_b128 v[170:173], v232 offset:2048
	ds_read_b128 v[174:177], v232 offset:3072
	ds_read_b128 v[178:181], v233
	ds_read_b128 v[182:185], v233 offset:1024
	ds_read_b128 v[186:189], v233 offset:2048
	ds_read_b128 v[190:193], v233 offset:3072
	ds_read_b128 v[194:197], v163 offset:32768
	ds_read_b128 v[198:201], v163 offset:33792
	ds_read_b128 v[202:205], v163 offset:34816
	ds_read_b128 v[206:209], v163 offset:35840
	ds_read_b128 v[210:213], v163 offset:36864
	ds_read_b128 v[214:217], v163 offset:37888
	ds_read_b128 v[218:221], v163 offset:38912
	ds_read_b128 v[222:225], v163 offset:39936
	s_waitcnt vmcnt(8)
	s_waitcnt lgkmcnt(0)
	s_setprio 1
	s_barrier
	v_mfma_f32_16x16x32_bf16 v[122:125], v[156:159], v[194:197], v[122:125]
	v_mfma_f32_16x16x32_bf16 v[118:121], v[170:173], v[194:197], v[118:121]
	v_mfma_f32_16x16x32_bf16 v[110:113], v[156:159], v[202:205], v[110:113]
	v_mfma_f32_16x16x32_bf16 v[102:105], v[170:173], v[202:205], v[102:105]
	v_mfma_f32_16x16x32_bf16 v[94:97], v[156:159], v[210:213], v[94:97]
	v_mfma_f32_16x16x32_bf16 v[86:89], v[170:173], v[210:213], v[86:89]
	v_mfma_f32_16x16x32_bf16 v[78:81], v[156:159], v[218:221], v[78:81]
	v_mfma_f32_16x16x32_bf16 v[70:73], v[170:173], v[218:221], v[70:73]
	v_mfma_f32_16x16x32_bf16 v[122:125], v[166:169], v[198:201], v[122:125]
	v_mfma_f32_16x16x32_bf16 v[118:121], v[174:177], v[198:201], v[118:121]
	v_mfma_f32_16x16x32_bf16 v[110:113], v[166:169], v[206:209], v[110:113]
	v_mfma_f32_16x16x32_bf16 v[102:105], v[174:177], v[206:209], v[102:105]
	v_mfma_f32_16x16x32_bf16 v[94:97], v[166:169], v[214:217], v[94:97]
	v_mfma_f32_16x16x32_bf16 v[86:89], v[174:177], v[214:217], v[86:89]
	v_mfma_f32_16x16x32_bf16 v[78:81], v[166:169], v[222:225], v[78:81]
	v_mfma_f32_16x16x32_bf16 v[70:73], v[174:177], v[222:225], v[70:73]
	s_setprio 0
	s_setprio 1
	v_mfma_f32_16x16x32_bf16 v[126:129], v[178:181], v[194:197], v[126:129]
	v_mfma_f32_16x16x32_bf16 v[114:117], v[186:189], v[194:197], v[114:117]
	v_mfma_f32_16x16x32_bf16 v[106:109], v[178:181], v[202:205], v[106:109]
	v_mfma_f32_16x16x32_bf16 v[98:101], v[186:189], v[202:205], v[98:101]
	v_mfma_f32_16x16x32_bf16 v[90:93], v[178:181], v[210:213], v[90:93]
	v_mfma_f32_16x16x32_bf16 v[82:85], v[186:189], v[210:213], v[82:85]
	v_mfma_f32_16x16x32_bf16 v[74:77], v[178:181], v[218:221], v[74:77]
	v_mfma_f32_16x16x32_bf16 v[66:69], v[186:189], v[218:221], v[66:69]
	v_mfma_f32_16x16x32_bf16 v[126:129], v[182:185], v[198:201], v[126:129]
	v_mfma_f32_16x16x32_bf16 v[114:117], v[190:193], v[198:201], v[114:117]
	v_mfma_f32_16x16x32_bf16 v[106:109], v[182:185], v[206:209], v[106:109]
	v_mfma_f32_16x16x32_bf16 v[98:101], v[190:193], v[206:209], v[98:101]
	v_mfma_f32_16x16x32_bf16 v[90:93], v[182:185], v[214:217], v[90:93]
	v_mfma_f32_16x16x32_bf16 v[82:85], v[190:193], v[214:217], v[82:85]
	v_mfma_f32_16x16x32_bf16 v[74:77], v[182:185], v[222:225], v[74:77]
	v_mfma_f32_16x16x32_bf16 v[66:69], v[190:193], v[222:225], v[66:69]
	s_barrier
	s_setprio 0
	s_add_u32 s96, s96, 0x80
	s_addc_u32 s97, s97, 0
	s_add_u32 s98, s96, 0x40000
	s_addc_u32 s99, s97, 0
	s_add_u32 s94, s94, 0x80
	s_addc_u32 s95, s95, 0
	s_add_i32 s7, s7, s29
	s_mov_b32 m0, s7
	ds_read_b128 v[194:197], v163 offset:49152
	global_load_lds_dwordx4 v132, s[96:97]
	s_add_i32 m0, s7, 0x2000
	s_add_i32 s7, s49, s29
	global_load_lds_dwordx4 v136, s[96:97]
	s_mov_b32 m0, s7
	ds_read_b128 v[198:201], v163 offset:50176
	global_load_lds_dwordx4 v132, s[98:99]
	s_add_i32 m0, s7, 0x2000
	ds_read_b128 v[202:205], v163 offset:51200
	global_load_lds_dwordx4 v136, s[98:99]
	s_mov_b32 m0, s63
	ds_read_b128 v[206:209], v163 offset:52224
	global_load_lds_dwordx4 v130, s[94:95]
	s_mov_b32 m0, s64
	ds_read_b128 v[210:213], v163 offset:53248
	global_load_lds_dwordx4 v134, s[94:95]
	ds_read_b128 v[214:217], v163 offset:54272
	ds_read_b128 v[218:221], v163 offset:55296
	ds_read_b128 v[222:225], v163 offset:56320
	s_waitcnt vmcnt(8)
	s_waitcnt lgkmcnt(0)
	s_setprio 1
	s_barrier
	v_mfma_f32_16x16x32_bf16 v[62:65], v[156:159], v[194:197], v[62:65]
	v_mfma_f32_16x16x32_bf16 v[54:57], v[170:173], v[194:197], v[54:57]
	v_mfma_f32_16x16x32_bf16 v[46:49], v[156:159], v[202:205], v[46:49]
	v_mfma_f32_16x16x32_bf16 v[38:41], v[170:173], v[202:205], v[38:41]
	v_mfma_f32_16x16x32_bf16 v[30:33], v[156:159], v[210:213], v[30:33]
	v_mfma_f32_16x16x32_bf16 v[22:25], v[170:173], v[210:213], v[22:25]
	v_mfma_f32_16x16x32_bf16 v[14:17], v[156:159], v[218:221], v[14:17]
	v_mfma_f32_16x16x32_bf16 v[6:9], v[170:173], v[218:221], v[6:9]
	v_mfma_f32_16x16x32_bf16 v[62:65], v[166:169], v[198:201], v[62:65]
	v_mfma_f32_16x16x32_bf16 v[54:57], v[174:177], v[198:201], v[54:57]
	v_mfma_f32_16x16x32_bf16 v[46:49], v[166:169], v[206:209], v[46:49]
	v_mfma_f32_16x16x32_bf16 v[38:41], v[174:177], v[206:209], v[38:41]
	v_mfma_f32_16x16x32_bf16 v[30:33], v[166:169], v[214:217], v[30:33]
	v_mfma_f32_16x16x32_bf16 v[22:25], v[174:177], v[214:217], v[22:25]
	v_mfma_f32_16x16x32_bf16 v[14:17], v[166:169], v[222:225], v[14:17]
	v_mfma_f32_16x16x32_bf16 v[6:9], v[174:177], v[222:225], v[6:9]
	s_setprio 0
	s_setprio 1
	v_mfma_f32_16x16x32_bf16 v[58:61], v[178:181], v[194:197], v[58:61]
	v_mfma_f32_16x16x32_bf16 v[50:53], v[186:189], v[194:197], v[50:53]
	v_mfma_f32_16x16x32_bf16 v[42:45], v[178:181], v[202:205], v[42:45]
	v_mfma_f32_16x16x32_bf16 v[34:37], v[186:189], v[202:205], v[34:37]
	v_mfma_f32_16x16x32_bf16 v[26:29], v[178:181], v[210:213], v[26:29]
	v_mfma_f32_16x16x32_bf16 v[18:21], v[186:189], v[210:213], v[18:21]
	v_mfma_f32_16x16x32_bf16 v[10:13], v[178:181], v[218:221], v[10:13]
	v_mfma_f32_16x16x32_bf16 v[2:5], v[186:189], v[218:221], v[2:5]
	v_mfma_f32_16x16x32_bf16 v[58:61], v[182:185], v[198:201], v[58:61]
	v_mfma_f32_16x16x32_bf16 v[50:53], v[190:193], v[198:201], v[50:53]
	v_mfma_f32_16x16x32_bf16 v[42:45], v[182:185], v[206:209], v[42:45]
	v_mfma_f32_16x16x32_bf16 v[34:37], v[190:193], v[206:209], v[34:37]
	v_mfma_f32_16x16x32_bf16 v[26:29], v[182:185], v[214:217], v[26:29]
	v_mfma_f32_16x16x32_bf16 v[18:21], v[190:193], v[214:217], v[18:21]
	v_mfma_f32_16x16x32_bf16 v[10:13], v[182:185], v[222:225], v[10:13]
	v_mfma_f32_16x16x32_bf16 v[2:5], v[190:193], v[222:225], v[2:5]
	s_barrier
	s_setprio 0
	s_mov_b32 s7, s47
	s_add_u32 s88, s88, 0x100
	s_addc_u32 s89, s89, 0
	s_add_u32 s86, s86, 0x100
	s_addc_u32 s87, s87, 0
	s_cmp_ge_i32 s47, s101
	s_cbranch_scc0 .LBB0_1573

.Lmy_nb_9:
	s_nop 0
	v_readfirstlane_b32 s86, v152
	v_readfirstlane_b32 s87, v153
	v_readfirstlane_b32 s88, v150
	v_readfirstlane_b32 s89, v151
	v_readfirstlane_b32 s90, v146
	v_readfirstlane_b32 s91, v147
	v_readfirstlane_b32 s92, v148
	v_readfirstlane_b32 s93, v149
	v_readfirstlane_b32 s100, v154
	v_readfirstlane_b32 s101, v138
	v_add_u32_e32 v230, s74, v141
	v_add_u32_e32 v231, s75, v141
	v_add_u32_e32 v232, 0x18000, v141
	v_add_u32_e32 v233, 0x1c000, v141
	s_add_u32 s98, s86, 0xfffc0080
	s_addc_u32 s99, s87, -1
	s_cmp_eq_u32 s5, s100
	s_cselect_b64 s[94:95], s[90:91], s[98:99]
	s_cselect_b64 s[96:97], s[92:93], s[88:89]
	s_add_i32 s29, s5, 2
	s_add_i32 m0, s47, 0xc000
	ds_read_b128 v[164:167], v230
	global_load_lds_dwordx4 v144, s[86:87]
	s_add_i32 m0, s47, 0xe000
	ds_read_b128 v[168:171], v230 offset:1024
	global_load_lds_dwordx4 v142, s[86:87]
	ds_read_b128 v[172:175], v230 offset:2048
	ds_read_b128 v[176:179], v230 offset:3072
	ds_read_b128 v[180:183], v231
	ds_read_b128 v[184:187], v231 offset:1024
	ds_read_b128 v[188:191], v231 offset:2048
	ds_read_b128 v[192:195], v231 offset:3072
	ds_read_b128 v[196:199], v160
	ds_read_b128 v[200:203], v160 offset:1024
	ds_read_b128 v[204:207], v160 offset:2048
	ds_read_b128 v[208:211], v160 offset:3072
	ds_read_b128 v[212:215], v160 offset:4096
	ds_read_b128 v[216:219], v160 offset:5120
	ds_read_b128 v[220:223], v160 offset:6144
	ds_read_b128 v[224:227], v160 offset:7168
	s_waitcnt vmcnt(8)
	s_waitcnt lgkmcnt(0)
	s_setprio 1
	s_barrier
	v_mfma_f32_16x16x32_bf16 v[122:125], v[164:167], v[196:199], 0
	v_mfma_f32_16x16x32_bf16 v[118:121], v[172:175], v[196:199], 0
	v_mfma_f32_16x16x32_bf16 v[110:113], v[164:167], v[204:207], 0
	v_mfma_f32_16x16x32_bf16 v[102:105], v[172:175], v[204:207], 0
	v_mfma_f32_16x16x32_bf16 v[94:97], v[164:167], v[212:215], 0
	v_mfma_f32_16x16x32_bf16 v[86:89], v[172:175], v[212:215], 0
	v_mfma_f32_16x16x32_bf16 v[78:81], v[164:167], v[220:223], 0
	v_mfma_f32_16x16x32_bf16 v[70:73], v[172:175], v[220:223], 0
	v_mfma_f32_16x16x32_bf16 v[122:125], v[168:171], v[200:203], v[122:125]
	v_mfma_f32_16x16x32_bf16 v[118:121], v[176:179], v[200:203], v[118:121]
	v_mfma_f32_16x16x32_bf16 v[110:113], v[168:171], v[208:211], v[110:113]
	v_mfma_f32_16x16x32_bf16 v[102:105], v[176:179], v[208:211], v[102:105]
	v_mfma_f32_16x16x32_bf16 v[94:97], v[168:171], v[216:219], v[94:97]
	v_mfma_f32_16x16x32_bf16 v[86:89], v[176:179], v[216:219], v[86:89]
	v_mfma_f32_16x16x32_bf16 v[78:81], v[168:171], v[224:227], v[78:81]
	v_mfma_f32_16x16x32_bf16 v[70:73], v[176:179], v[224:227], v[70:73]
	s_setprio 0
	s_setprio 1
	v_mfma_f32_16x16x32_bf16 v[126:129], v[180:183], v[196:199], 0
	v_mfma_f32_16x16x32_bf16 v[114:117], v[188:191], v[196:199], 0
	v_mfma_f32_16x16x32_bf16 v[106:109], v[180:183], v[204:207], 0
	v_mfma_f32_16x16x32_bf16 v[98:101], v[188:191], v[204:207], 0
	v_mfma_f32_16x16x32_bf16 v[90:93], v[180:183], v[212:215], 0
	v_mfma_f32_16x16x32_bf16 v[82:85], v[188:191], v[212:215], 0
	v_mfma_f32_16x16x32_bf16 v[74:77], v[180:183], v[220:223], 0
	v_mfma_f32_16x16x32_bf16 v[66:69], v[188:191], v[220:223], 0
	v_mfma_f32_16x16x32_bf16 v[126:129], v[184:187], v[200:203], v[126:129]
	v_mfma_f32_16x16x32_bf16 v[114:117], v[192:195], v[200:203], v[114:117]
	v_mfma_f32_16x16x32_bf16 v[106:109], v[184:187], v[208:211], v[106:109]
	v_mfma_f32_16x16x32_bf16 v[98:101], v[192:195], v[208:211], v[98:101]
	v_mfma_f32_16x16x32_bf16 v[90:93], v[184:187], v[216:219], v[90:93]
	v_mfma_f32_16x16x32_bf16 v[82:85], v[192:195], v[216:219], v[82:85]
	v_mfma_f32_16x16x32_bf16 v[74:77], v[184:187], v[224:227], v[74:77]
	v_mfma_f32_16x16x32_bf16 v[66:69], v[192:195], v[224:227], v[66:69]
	s_barrier
	s_setprio 0
	s_add_u32 s98, s96, 0x40000
	s_addc_u32 s99, s97, 0
	s_add_i32 s5, s74, s23
	s_mov_b32 m0, s5
	ds_read_b128 v[196:199], v160 offset:16384
	global_load_lds_dwordx4 v132, s[96:97]
	s_add_i32 m0, s5, 0x2000
	s_add_i32 s5, s75, s23
	global_load_lds_dwordx4 v136, s[96:97]
	s_mov_b32 m0, s5
	ds_read_b128 v[200:203], v160 offset:17408
	global_load_lds_dwordx4 v132, s[98:99]
	s_add_i32 m0, s5, 0x2000
	ds_read_b128 v[204:207], v160 offset:18432
	global_load_lds_dwordx4 v136, s[98:99]
	s_mov_b32 m0, s47
	ds_read_b128 v[208:211], v160 offset:19456
	global_load_lds_dwordx4 v130, s[94:95]
	s_mov_b32 m0, s56
	ds_read_b128 v[212:215], v160 offset:20480
	global_load_lds_dwordx4 v134, s[94:95]
	ds_read_b128 v[216:219], v160 offset:21504
	ds_read_b128 v[220:223], v160 offset:22528
	ds_read_b128 v[224:227], v160 offset:23552
	s_waitcnt vmcnt(8)
	s_waitcnt lgkmcnt(0)
	s_setprio 1
	s_barrier
	v_mfma_f32_16x16x32_bf16 v[62:65], v[164:167], v[196:199], 0
	v_mfma_f32_16x16x32_bf16 v[54:57], v[172:175], v[196:199], 0
	v_mfma_f32_16x16x32_bf16 v[46:49], v[164:167], v[204:207], 0
	v_mfma_f32_16x16x32_bf16 v[38:41], v[172:175], v[204:207], 0
	v_mfma_f32_16x16x32_bf16 v[30:33], v[164:167], v[212:215], 0
	v_mfma_f32_16x16x32_bf16 v[22:25], v[172:175], v[212:215], 0
	v_mfma_f32_16x16x32_bf16 v[14:17], v[164:167], v[220:223], 0
	v_mfma_f32_16x16x32_bf16 v[6:9], v[172:175], v[220:223], 0
	v_mfma_f32_16x16x32_bf16 v[62:65], v[168:171], v[200:203], v[62:65]
	v_mfma_f32_16x16x32_bf16 v[54:57], v[176:179], v[200:203], v[54:57]
	v_mfma_f32_16x16x32_bf16 v[46:49], v[168:171], v[208:211], v[46:49]
	v_mfma_f32_16x16x32_bf16 v[38:41], v[176:179], v[208:211], v[38:41]
	v_mfma_f32_16x16x32_bf16 v[30:33], v[168:171], v[216:219], v[30:33]
	v_mfma_f32_16x16x32_bf16 v[22:25], v[176:179], v[216:219], v[22:25]
	v_mfma_f32_16x16x32_bf16 v[14:17], v[168:171], v[224:227], v[14:17]
	v_mfma_f32_16x16x32_bf16 v[6:9], v[176:179], v[224:227], v[6:9]
	s_setprio 0
	s_setprio 1
	v_mfma_f32_16x16x32_bf16 v[58:61], v[180:183], v[196:199], 0
	v_mfma_f32_16x16x32_bf16 v[50:53], v[188:191], v[196:199], 0
	v_mfma_f32_16x16x32_bf16 v[42:45], v[180:183], v[204:207], 0
	v_mfma_f32_16x16x32_bf16 v[34:37], v[188:191], v[204:207], 0
	v_mfma_f32_16x16x32_bf16 v[26:29], v[180:183], v[212:215], 0
	v_mfma_f32_16x16x32_bf16 v[18:21], v[188:191], v[212:215], 0
	v_mfma_f32_16x16x32_bf16 v[10:13], v[180:183], v[220:223], 0
	v_mfma_f32_16x16x32_bf16 v[2:5], v[188:191], v[220:223], 0
	v_mfma_f32_16x16x32_bf16 v[58:61], v[184:187], v[200:203], v[58:61]
	v_mfma_f32_16x16x32_bf16 v[50:53], v[192:195], v[200:203], v[50:53]
	v_mfma_f32_16x16x32_bf16 v[42:45], v[184:187], v[208:211], v[42:45]
	v_mfma_f32_16x16x32_bf16 v[34:37], v[192:195], v[208:211], v[34:37]
	v_mfma_f32_16x16x32_bf16 v[26:29], v[184:187], v[216:219], v[26:29]
	v_mfma_f32_16x16x32_bf16 v[18:21], v[192:195], v[216:219], v[18:21]
	v_mfma_f32_16x16x32_bf16 v[10:13], v[184:187], v[224:227], v[10:13]
	v_mfma_f32_16x16x32_bf16 v[2:5], v[192:195], v[224:227], v[2:5]
	s_barrier
	s_setprio 0
	s_add_u32 s98, s94, 0x40000
	s_addc_u32 s99, s95, 0
	s_add_i32 s5, 0, 0x18000
	s_add_i32 s45, 0, 0x1c000
	s_mov_b32 m0, s57
	ds_read_b128 v[164:167], v232
	global_load_lds_dwordx4 v130, s[98:99]
	s_mov_b32 m0, s58
	ds_read_b128 v[168:171], v232 offset:1024
	global_load_lds_dwordx4 v134, s[98:99]
	ds_read_b128 v[172:175], v232 offset:2048
	ds_read_b128 v[176:179], v232 offset:3072
	ds_read_b128 v[180:183], v233
	ds_read_b128 v[184:187], v233 offset:1024
	ds_read_b128 v[188:191], v233 offset:2048
	ds_read_b128 v[192:195], v233 offset:3072
	ds_read_b128 v[196:199], v160 offset:32768
	ds_read_b128 v[200:203], v160 offset:33792
	ds_read_b128 v[204:207], v160 offset:34816
	ds_read_b128 v[208:211], v160 offset:35840
	ds_read_b128 v[212:215], v160 offset:36864
	ds_read_b128 v[216:219], v160 offset:37888
	ds_read_b128 v[220:223], v160 offset:38912
	ds_read_b128 v[224:227], v160 offset:39936
	s_waitcnt vmcnt(8)
	s_waitcnt lgkmcnt(0)
	s_setprio 1
	s_barrier
	v_mfma_f32_16x16x32_bf16 v[122:125], v[164:167], v[196:199], v[122:125]
	v_mfma_f32_16x16x32_bf16 v[118:121], v[172:175], v[196:199], v[118:121]
	v_mfma_f32_16x16x32_bf16 v[110:113], v[164:167], v[204:207], v[110:113]
	v_mfma_f32_16x16x32_bf16 v[102:105], v[172:175], v[204:207], v[102:105]
	v_mfma_f32_16x16x32_bf16 v[94:97], v[164:167], v[212:215], v[94:97]
	v_mfma_f32_16x16x32_bf16 v[86:89], v[172:175], v[212:215], v[86:89]
	v_mfma_f32_16x16x32_bf16 v[78:81], v[164:167], v[220:223], v[78:81]
	v_mfma_f32_16x16x32_bf16 v[70:73], v[172:175], v[220:223], v[70:73]
	v_mfma_f32_16x16x32_bf16 v[122:125], v[168:171], v[200:203], v[122:125]
	v_mfma_f32_16x16x32_bf16 v[118:121], v[176:179], v[200:203], v[118:121]
	v_mfma_f32_16x16x32_bf16 v[110:113], v[168:171], v[208:211], v[110:113]
	v_mfma_f32_16x16x32_bf16 v[102:105], v[176:179], v[208:211], v[102:105]
	v_mfma_f32_16x16x32_bf16 v[94:97], v[168:171], v[216:219], v[94:97]
	v_mfma_f32_16x16x32_bf16 v[86:89], v[176:179], v[216:219], v[86:89]
	v_mfma_f32_16x16x32_bf16 v[78:81], v[168:171], v[224:227], v[78:81]
	v_mfma_f32_16x16x32_bf16 v[70:73], v[176:179], v[224:227], v[70:73]
	s_setprio 0
	s_setprio 1
	v_mfma_f32_16x16x32_bf16 v[126:129], v[180:183], v[196:199], v[126:129]
	v_mfma_f32_16x16x32_bf16 v[114:117], v[188:191], v[196:199], v[114:117]
	v_mfma_f32_16x16x32_bf16 v[106:109], v[180:183], v[204:207], v[106:109]
	v_mfma_f32_16x16x32_bf16 v[98:101], v[188:191], v[204:207], v[98:101]
	v_mfma_f32_16x16x32_bf16 v[90:93], v[180:183], v[212:215], v[90:93]
	v_mfma_f32_16x16x32_bf16 v[82:85], v[188:191], v[212:215], v[82:85]
	v_mfma_f32_16x16x32_bf16 v[74:77], v[180:183], v[220:223], v[74:77]
	v_mfma_f32_16x16x32_bf16 v[66:69], v[188:191], v[220:223], v[66:69]
	v_mfma_f32_16x16x32_bf16 v[126:129], v[184:187], v[200:203], v[126:129]
	v_mfma_f32_16x16x32_bf16 v[114:117], v[192:195], v[200:203], v[114:117]
	v_mfma_f32_16x16x32_bf16 v[106:109], v[184:187], v[208:211], v[106:109]
	v_mfma_f32_16x16x32_bf16 v[98:101], v[192:195], v[208:211], v[98:101]
	v_mfma_f32_16x16x32_bf16 v[90:93], v[184:187], v[216:219], v[90:93]
	v_mfma_f32_16x16x32_bf16 v[82:85], v[192:195], v[216:219], v[82:85]
	v_mfma_f32_16x16x32_bf16 v[74:77], v[184:187], v[224:227], v[74:77]
	v_mfma_f32_16x16x32_bf16 v[66:69], v[192:195], v[224:227], v[66:69]
	s_barrier
	s_setprio 0
	s_add_u32 s96, s96, 0x80
	s_addc_u32 s97, s97, 0
	s_add_u32 s98, s96, 0x40000
	s_addc_u32 s99, s97, 0
	s_add_u32 s94, s94, 0x80
	s_addc_u32 s95, s95, 0
	s_add_i32 s5, s5, s23
	s_mov_b32 m0, s5
	ds_read_b128 v[196:199], v160 offset:49152
	global_load_lds_dwordx4 v132, s[96:97]
	s_add_i32 m0, s5, 0x2000
	s_add_i32 s5, s45, s23
	global_load_lds_dwordx4 v136, s[96:97]
	s_mov_b32 m0, s5
	ds_read_b128 v[200:203], v160 offset:50176
	global_load_lds_dwordx4 v132, s[98:99]
	s_add_i32 m0, s5, 0x2000
	ds_read_b128 v[204:207], v160 offset:51200
	global_load_lds_dwordx4 v136, s[98:99]
	s_mov_b32 m0, s64
	ds_read_b128 v[208:211], v160 offset:52224
	global_load_lds_dwordx4 v130, s[94:95]
	s_mov_b32 m0, s65
	ds_read_b128 v[212:215], v160 offset:53248
	global_load_lds_dwordx4 v134, s[94:95]
	ds_read_b128 v[216:219], v160 offset:54272
	ds_read_b128 v[220:223], v160 offset:55296
	ds_read_b128 v[224:227], v160 offset:56320
	s_waitcnt vmcnt(8)
	s_waitcnt lgkmcnt(0)
	s_setprio 1
	s_barrier
	v_mfma_f32_16x16x32_bf16 v[62:65], v[164:167], v[196:199], v[62:65]
	v_mfma_f32_16x16x32_bf16 v[54:57], v[172:175], v[196:199], v[54:57]
	v_mfma_f32_16x16x32_bf16 v[46:49], v[164:167], v[204:207], v[46:49]
	v_mfma_f32_16x16x32_bf16 v[38:41], v[172:175], v[204:207], v[38:41]
	v_mfma_f32_16x16x32_bf16 v[30:33], v[164:167], v[212:215], v[30:33]
	v_mfma_f32_16x16x32_bf16 v[22:25], v[172:175], v[212:215], v[22:25]
	v_mfma_f32_16x16x32_bf16 v[14:17], v[164:167], v[220:223], v[14:17]
	v_mfma_f32_16x16x32_bf16 v[6:9], v[172:175], v[220:223], v[6:9]
	v_mfma_f32_16x16x32_bf16 v[62:65], v[168:171], v[200:203], v[62:65]
	v_mfma_f32_16x16x32_bf16 v[54:57], v[176:179], v[200:203], v[54:57]
	v_mfma_f32_16x16x32_bf16 v[46:49], v[168:171], v[208:211], v[46:49]
	v_mfma_f32_16x16x32_bf16 v[38:41], v[176:179], v[208:211], v[38:41]
	v_mfma_f32_16x16x32_bf16 v[30:33], v[168:171], v[216:219], v[30:33]
	v_mfma_f32_16x16x32_bf16 v[22:25], v[176:179], v[216:219], v[22:25]
	v_mfma_f32_16x16x32_bf16 v[14:17], v[168:171], v[224:227], v[14:17]
	v_mfma_f32_16x16x32_bf16 v[6:9], v[176:179], v[224:227], v[6:9]
	s_setprio 0
	s_setprio 1
	v_mfma_f32_16x16x32_bf16 v[58:61], v[180:183], v[196:199], v[58:61]
	v_mfma_f32_16x16x32_bf16 v[50:53], v[188:191], v[196:199], v[50:53]
	v_mfma_f32_16x16x32_bf16 v[42:45], v[180:183], v[204:207], v[42:45]
	v_mfma_f32_16x16x32_bf16 v[34:37], v[188:191], v[204:207], v[34:37]
	v_mfma_f32_16x16x32_bf16 v[26:29], v[180:183], v[212:215], v[26:29]
	v_mfma_f32_16x16x32_bf16 v[18:21], v[188:191], v[212:215], v[18:21]
	v_mfma_f32_16x16x32_bf16 v[10:13], v[180:183], v[220:223], v[10:13]
	v_mfma_f32_16x16x32_bf16 v[2:5], v[188:191], v[220:223], v[2:5]
	v_mfma_f32_16x16x32_bf16 v[58:61], v[184:187], v[200:203], v[58:61]
	v_mfma_f32_16x16x32_bf16 v[50:53], v[192:195], v[200:203], v[50:53]
	v_mfma_f32_16x16x32_bf16 v[42:45], v[184:187], v[208:211], v[42:45]
	v_mfma_f32_16x16x32_bf16 v[34:37], v[192:195], v[208:211], v[34:37]
	v_mfma_f32_16x16x32_bf16 v[26:29], v[184:187], v[216:219], v[26:29]
	v_mfma_f32_16x16x32_bf16 v[18:21], v[192:195], v[216:219], v[18:21]
	v_mfma_f32_16x16x32_bf16 v[10:13], v[184:187], v[224:227], v[10:13]
	v_mfma_f32_16x16x32_bf16 v[2:5], v[192:195], v[224:227], v[2:5]
	s_barrier
	s_setprio 0
	s_mov_b32 s5, s29
	s_add_u32 s88, s88, 0x100
	s_addc_u32 s89, s89, 0
	s_add_u32 s86, s86, 0x100
	s_addc_u32 s87, s87, 0
	s_cmp_ge_i32 s29, s101
	s_cbranch_scc1 .Lmy_kexit_9
.LBB0_1763:
	s_add_u32 s98, s86, 0xfffc0080
	s_addc_u32 s99, s87, -1
	s_cmp_eq_u32 s5, s100
	s_cselect_b64 s[94:95], s[90:91], s[98:99]
	s_cselect_b64 s[96:97], s[92:93], s[88:89]
	s_add_i32 s29, s5, 2
	s_add_i32 m0, s47, 0xc000
	ds_read_b128 v[164:167], v230
	global_load_lds_dwordx4 v144, s[86:87]
	s_add_i32 m0, s47, 0xe000
	ds_read_b128 v[168:171], v230 offset:1024
	global_load_lds_dwordx4 v142, s[86:87]
	ds_read_b128 v[172:175], v230 offset:2048
	ds_read_b128 v[176:179], v230 offset:3072
	ds_read_b128 v[180:183], v231
	ds_read_b128 v[184:187], v231 offset:1024
	ds_read_b128 v[188:191], v231 offset:2048
	ds_read_b128 v[192:195], v231 offset:3072
	ds_read_b128 v[196:199], v160
	ds_read_b128 v[200:203], v160 offset:1024
	ds_read_b128 v[204:207], v160 offset:2048
	ds_read_b128 v[208:211], v160 offset:3072
	ds_read_b128 v[212:215], v160 offset:4096
	ds_read_b128 v[216:219], v160 offset:5120
	ds_read_b128 v[220:223], v160 offset:6144
	ds_read_b128 v[224:227], v160 offset:7168
	s_waitcnt vmcnt(8)
	s_waitcnt lgkmcnt(0)
	s_setprio 1
	s_barrier
	v_mfma_f32_16x16x32_bf16 v[122:125], v[164:167], v[196:199], v[122:125]
	v_mfma_f32_16x16x32_bf16 v[118:121], v[172:175], v[196:199], v[118:121]
	v_mfma_f32_16x16x32_bf16 v[110:113], v[164:167], v[204:207], v[110:113]
	v_mfma_f32_16x16x32_bf16 v[102:105], v[172:175], v[204:207], v[102:105]
	v_mfma_f32_16x16x32_bf16 v[94:97], v[164:167], v[212:215], v[94:97]
	v_mfma_f32_16x16x32_bf16 v[86:89], v[172:175], v[212:215], v[86:89]
	v_mfma_f32_16x16x32_bf16 v[78:81], v[164:167], v[220:223], v[78:81]
	v_mfma_f32_16x16x32_bf16 v[70:73], v[172:175], v[220:223], v[70:73]
	v_mfma_f32_16x16x32_bf16 v[122:125], v[168:171], v[200:203], v[122:125]
	v_mfma_f32_16x16x32_bf16 v[118:121], v[176:179], v[200:203], v[118:121]
	v_mfma_f32_16x16x32_bf16 v[110:113], v[168:171], v[208:211], v[110:113]
	v_mfma_f32_16x16x32_bf16 v[102:105], v[176:179], v[208:211], v[102:105]
	v_mfma_f32_16x16x32_bf16 v[94:97], v[168:171], v[216:219], v[94:97]
	v_mfma_f32_16x16x32_bf16 v[86:89], v[176:179], v[216:219], v[86:89]
	v_mfma_f32_16x16x32_bf16 v[78:81], v[168:171], v[224:227], v[78:81]
	v_mfma_f32_16x16x32_bf16 v[70:73], v[176:179], v[224:227], v[70:73]
	s_setprio 0
	s_setprio 1
	v_mfma_f32_16x16x32_bf16 v[126:129], v[180:183], v[196:199], v[126:129]
	v_mfma_f32_16x16x32_bf16 v[114:117], v[188:191], v[196:199], v[114:117]
	v_mfma_f32_16x16x32_bf16 v[106:109], v[180:183], v[204:207], v[106:109]
	v_mfma_f32_16x16x32_bf16 v[98:101], v[188:191], v[204:207], v[98:101]
	v_mfma_f32_16x16x32_bf16 v[90:93], v[180:183], v[212:215], v[90:93]
	v_mfma_f32_16x16x32_bf16 v[82:85], v[188:191], v[212:215], v[82:85]
	v_mfma_f32_16x16x32_bf16 v[74:77], v[180:183], v[220:223], v[74:77]
	v_mfma_f32_16x16x32_bf16 v[66:69], v[188:191], v[220:223], v[66:69]
	v_mfma_f32_16x16x32_bf16 v[126:129], v[184:187], v[200:203], v[126:129]
	v_mfma_f32_16x16x32_bf16 v[114:117], v[192:195], v[200:203], v[114:117]
	v_mfma_f32_16x16x32_bf16 v[106:109], v[184:187], v[208:211], v[106:109]
	v_mfma_f32_16x16x32_bf16 v[98:101], v[192:195], v[208:211], v[98:101]
	v_mfma_f32_16x16x32_bf16 v[90:93], v[184:187], v[216:219], v[90:93]
	v_mfma_f32_16x16x32_bf16 v[82:85], v[192:195], v[216:219], v[82:85]
	v_mfma_f32_16x16x32_bf16 v[74:77], v[184:187], v[224:227], v[74:77]
	v_mfma_f32_16x16x32_bf16 v[66:69], v[192:195], v[224:227], v[66:69]
	s_barrier
	s_setprio 0
	s_add_u32 s98, s96, 0x40000
	s_addc_u32 s99, s97, 0
	s_add_i32 s5, s74, s23
	s_mov_b32 m0, s5
	ds_read_b128 v[196:199], v160 offset:16384
	global_load_lds_dwordx4 v132, s[96:97]
	s_add_i32 m0, s5, 0x2000
	s_add_i32 s5, s75, s23
	global_load_lds_dwordx4 v136, s[96:97]
	s_mov_b32 m0, s5
	ds_read_b128 v[200:203], v160 offset:17408
	global_load_lds_dwordx4 v132, s[98:99]
	s_add_i32 m0, s5, 0x2000
	ds_read_b128 v[204:207], v160 offset:18432
	global_load_lds_dwordx4 v136, s[98:99]
	s_mov_b32 m0, s47
	ds_read_b128 v[208:211], v160 offset:19456
	global_load_lds_dwordx4 v130, s[94:95]
	s_mov_b32 m0, s56
	ds_read_b128 v[212:215], v160 offset:20480
	global_load_lds_dwordx4 v134, s[94:95]
	ds_read_b128 v[216:219], v160 offset:21504
	ds_read_b128 v[220:223], v160 offset:22528
	ds_read_b128 v[224:227], v160 offset:23552
	s_waitcnt vmcnt(8)
	s_waitcnt lgkmcnt(0)
	s_setprio 1
	s_barrier
	v_mfma_f32_16x16x32_bf16 v[62:65], v[164:167], v[196:199], v[62:65]
	v_mfma_f32_16x16x32_bf16 v[54:57], v[172:175], v[196:199], v[54:57]
	v_mfma_f32_16x16x32_bf16 v[46:49], v[164:167], v[204:207], v[46:49]
	v_mfma_f32_16x16x32_bf16 v[38:41], v[172:175], v[204:207], v[38:41]
	v_mfma_f32_16x16x32_bf16 v[30:33], v[164:167], v[212:215], v[30:33]
	v_mfma_f32_16x16x32_bf16 v[22:25], v[172:175], v[212:215], v[22:25]
	v_mfma_f32_16x16x32_bf16 v[14:17], v[164:167], v[220:223], v[14:17]
	v_mfma_f32_16x16x32_bf16 v[6:9], v[172:175], v[220:223], v[6:9]
	v_mfma_f32_16x16x32_bf16 v[62:65], v[168:171], v[200:203], v[62:65]
	v_mfma_f32_16x16x32_bf16 v[54:57], v[176:179], v[200:203], v[54:57]
	v_mfma_f32_16x16x32_bf16 v[46:49], v[168:171], v[208:211], v[46:49]
	v_mfma_f32_16x16x32_bf16 v[38:41], v[176:179], v[208:211], v[38:41]
	v_mfma_f32_16x16x32_bf16 v[30:33], v[168:171], v[216:219], v[30:33]
	v_mfma_f32_16x16x32_bf16 v[22:25], v[176:179], v[216:219], v[22:25]
	v_mfma_f32_16x16x32_bf16 v[14:17], v[168:171], v[224:227], v[14:17]
	v_mfma_f32_16x16x32_bf16 v[6:9], v[176:179], v[224:227], v[6:9]
	s_setprio 0
	s_setprio 1
	v_mfma_f32_16x16x32_bf16 v[58:61], v[180:183], v[196:199], v[58:61]
	v_mfma_f32_16x16x32_bf16 v[50:53], v[188:191], v[196:199], v[50:53]
	v_mfma_f32_16x16x32_bf16 v[42:45], v[180:183], v[204:207], v[42:45]
	v_mfma_f32_16x16x32_bf16 v[34:37], v[188:191], v[204:207], v[34:37]
	v_mfma_f32_16x16x32_bf16 v[26:29], v[180:183], v[212:215], v[26:29]
	v_mfma_f32_16x16x32_bf16 v[18:21], v[188:191], v[212:215], v[18:21]
	v_mfma_f32_16x16x32_bf16 v[10:13], v[180:183], v[220:223], v[10:13]
	v_mfma_f32_16x16x32_bf16 v[2:5], v[188:191], v[220:223], v[2:5]
	v_mfma_f32_16x16x32_bf16 v[58:61], v[184:187], v[200:203], v[58:61]
	v_mfma_f32_16x16x32_bf16 v[50:53], v[192:195], v[200:203], v[50:53]
	v_mfma_f32_16x16x32_bf16 v[42:45], v[184:187], v[208:211], v[42:45]
	v_mfma_f32_16x16x32_bf16 v[34:37], v[192:195], v[208:211], v[34:37]
	v_mfma_f32_16x16x32_bf16 v[26:29], v[184:187], v[216:219], v[26:29]
	v_mfma_f32_16x16x32_bf16 v[18:21], v[192:195], v[216:219], v[18:21]
	v_mfma_f32_16x16x32_bf16 v[10:13], v[184:187], v[224:227], v[10:13]
	v_mfma_f32_16x16x32_bf16 v[2:5], v[192:195], v[224:227], v[2:5]
	s_barrier
	s_setprio 0
	s_add_u32 s98, s94, 0x40000
	s_addc_u32 s99, s95, 0
	s_add_i32 s5, 0, 0x18000
	s_add_i32 s45, 0, 0x1c000
	s_mov_b32 m0, s57
	ds_read_b128 v[164:167], v232
	global_load_lds_dwordx4 v130, s[98:99]
	s_mov_b32 m0, s58
	ds_read_b128 v[168:171], v232 offset:1024
	global_load_lds_dwordx4 v134, s[98:99]
	ds_read_b128 v[172:175], v232 offset:2048
	ds_read_b128 v[176:179], v232 offset:3072
	ds_read_b128 v[180:183], v233
	ds_read_b128 v[184:187], v233 offset:1024
	ds_read_b128 v[188:191], v233 offset:2048
	ds_read_b128 v[192:195], v233 offset:3072
	ds_read_b128 v[196:199], v160 offset:32768
	ds_read_b128 v[200:203], v160 offset:33792
	ds_read_b128 v[204:207], v160 offset:34816
	ds_read_b128 v[208:211], v160 offset:35840
	ds_read_b128 v[212:215], v160 offset:36864
	ds_read_b128 v[216:219], v160 offset:37888
	ds_read_b128 v[220:223], v160 offset:38912
	ds_read_b128 v[224:227], v160 offset:39936
	s_waitcnt vmcnt(8)
	s_waitcnt lgkmcnt(0)
	s_setprio 1
	s_barrier
	v_mfma_f32_16x16x32_bf16 v[122:125], v[164:167], v[196:199], v[122:125]
	v_mfma_f32_16x16x32_bf16 v[118:121], v[172:175], v[196:199], v[118:121]
	v_mfma_f32_16x16x32_bf16 v[110:113], v[164:167], v[204:207], v[110:113]
	v_mfma_f32_16x16x32_bf16 v[102:105], v[172:175], v[204:207], v[102:105]
	v_mfma_f32_16x16x32_bf16 v[94:97], v[164:167], v[212:215], v[94:97]
	v_mfma_f32_16x16x32_bf16 v[86:89], v[172:175], v[212:215], v[86:89]
	v_mfma_f32_16x16x32_bf16 v[78:81], v[164:167], v[220:223], v[78:81]
	v_mfma_f32_16x16x32_bf16 v[70:73], v[172:175], v[220:223], v[70:73]
	v_mfma_f32_16x16x32_bf16 v[122:125], v[168:171], v[200:203], v[122:125]
	v_mfma_f32_16x16x32_bf16 v[118:121], v[176:179], v[200:203], v[118:121]
	v_mfma_f32_16x16x32_bf16 v[110:113], v[168:171], v[208:211], v[110:113]
	v_mfma_f32_16x16x32_bf16 v[102:105], v[176:179], v[208:211], v[102:105]
	v_mfma_f32_16x16x32_bf16 v[94:97], v[168:171], v[216:219], v[94:97]
	v_mfma_f32_16x16x32_bf16 v[86:89], v[176:179], v[216:219], v[86:89]
	v_mfma_f32_16x16x32_bf16 v[78:81], v[168:171], v[224:227], v[78:81]
	v_mfma_f32_16x16x32_bf16 v[70:73], v[176:179], v[224:227], v[70:73]
	s_setprio 0
	s_setprio 1
	v_mfma_f32_16x16x32_bf16 v[126:129], v[180:183], v[196:199], v[126:129]
	v_mfma_f32_16x16x32_bf16 v[114:117], v[188:191], v[196:199], v[114:117]
	v_mfma_f32_16x16x32_bf16 v[106:109], v[180:183], v[204:207], v[106:109]
	v_mfma_f32_16x16x32_bf16 v[98:101], v[188:191], v[204:207], v[98:101]
	v_mfma_f32_16x16x32_bf16 v[90:93], v[180:183], v[212:215], v[90:93]
	v_mfma_f32_16x16x32_bf16 v[82:85], v[188:191], v[212:215], v[82:85]
	v_mfma_f32_16x16x32_bf16 v[74:77], v[180:183], v[220:223], v[74:77]
	v_mfma_f32_16x16x32_bf16 v[66:69], v[188:191], v[220:223], v[66:69]
	v_mfma_f32_16x16x32_bf16 v[126:129], v[184:187], v[200:203], v[126:129]
	v_mfma_f32_16x16x32_bf16 v[114:117], v[192:195], v[200:203], v[114:117]
	v_mfma_f32_16x16x32_bf16 v[106:109], v[184:187], v[208:211], v[106:109]
	v_mfma_f32_16x16x32_bf16 v[98:101], v[192:195], v[208:211], v[98:101]
	v_mfma_f32_16x16x32_bf16 v[90:93], v[184:187], v[216:219], v[90:93]
	v_mfma_f32_16x16x32_bf16 v[82:85], v[192:195], v[216:219], v[82:85]
	v_mfma_f32_16x16x32_bf16 v[74:77], v[184:187], v[224:227], v[74:77]
	v_mfma_f32_16x16x32_bf16 v[66:69], v[192:195], v[224:227], v[66:69]
	s_barrier
	s_setprio 0
	s_add_u32 s96, s96, 0x80
	s_addc_u32 s97, s97, 0
	s_add_u32 s98, s96, 0x40000
	s_addc_u32 s99, s97, 0
	s_add_u32 s94, s94, 0x80
	s_addc_u32 s95, s95, 0
	s_add_i32 s5, s5, s23
	s_mov_b32 m0, s5
	ds_read_b128 v[196:199], v160 offset:49152
	global_load_lds_dwordx4 v132, s[96:97]
	s_add_i32 m0, s5, 0x2000
	s_add_i32 s5, s45, s23
	global_load_lds_dwordx4 v136, s[96:97]
	s_mov_b32 m0, s5
	ds_read_b128 v[200:203], v160 offset:50176
	global_load_lds_dwordx4 v132, s[98:99]
	s_add_i32 m0, s5, 0x2000
	ds_read_b128 v[204:207], v160 offset:51200
	global_load_lds_dwordx4 v136, s[98:99]
	s_mov_b32 m0, s64
	ds_read_b128 v[208:211], v160 offset:52224
	global_load_lds_dwordx4 v130, s[94:95]
	s_mov_b32 m0, s65
	ds_read_b128 v[212:215], v160 offset:53248
	global_load_lds_dwordx4 v134, s[94:95]
	ds_read_b128 v[216:219], v160 offset:54272
	ds_read_b128 v[220:223], v160 offset:55296
	ds_read_b128 v[224:227], v160 offset:56320
	s_waitcnt vmcnt(8)
	s_waitcnt lgkmcnt(0)
	s_setprio 1
	s_barrier
	v_mfma_f32_16x16x32_bf16 v[62:65], v[164:167], v[196:199], v[62:65]
	v_mfma_f32_16x16x32_bf16 v[54:57], v[172:175], v[196:199], v[54:57]
	v_mfma_f32_16x16x32_bf16 v[46:49], v[164:167], v[204:207], v[46:49]
	v_mfma_f32_16x16x32_bf16 v[38:41], v[172:175], v[204:207], v[38:41]
	v_mfma_f32_16x16x32_bf16 v[30:33], v[164:167], v[212:215], v[30:33]
	v_mfma_f32_16x16x32_bf16 v[22:25], v[172:175], v[212:215], v[22:25]
	v_mfma_f32_16x16x32_bf16 v[14:17], v[164:167], v[220:223], v[14:17]
	v_mfma_f32_16x16x32_bf16 v[6:9], v[172:175], v[220:223], v[6:9]
	v_mfma_f32_16x16x32_bf16 v[62:65], v[168:171], v[200:203], v[62:65]
	v_mfma_f32_16x16x32_bf16 v[54:57], v[176:179], v[200:203], v[54:57]
	v_mfma_f32_16x16x32_bf16 v[46:49], v[168:171], v[208:211], v[46:49]
	v_mfma_f32_16x16x32_bf16 v[38:41], v[176:179], v[208:211], v[38:41]
	v_mfma_f32_16x16x32_bf16 v[30:33], v[168:171], v[216:219], v[30:33]
	v_mfma_f32_16x16x32_bf16 v[22:25], v[176:179], v[216:219], v[22:25]
	v_mfma_f32_16x16x32_bf16 v[14:17], v[168:171], v[224:227], v[14:17]
	v_mfma_f32_16x16x32_bf16 v[6:9], v[176:179], v[224:227], v[6:9]
	s_setprio 0
	s_setprio 1
	v_mfma_f32_16x16x32_bf16 v[58:61], v[180:183], v[196:199], v[58:61]
	v_mfma_f32_16x16x32_bf16 v[50:53], v[188:191], v[196:199], v[50:53]
	v_mfma_f32_16x16x32_bf16 v[42:45], v[180:183], v[204:207], v[42:45]
	v_mfma_f32_16x16x32_bf16 v[34:37], v[188:191], v[204:207], v[34:37]
	v_mfma_f32_16x16x32_bf16 v[26:29], v[180:183], v[212:215], v[26:29]
	v_mfma_f32_16x16x32_bf16 v[18:21], v[188:191], v[212:215], v[18:21]
	v_mfma_f32_16x16x32_bf16 v[10:13], v[180:183], v[220:223], v[10:13]
	v_mfma_f32_16x16x32_bf16 v[2:5], v[188:191], v[220:223], v[2:5]
	v_mfma_f32_16x16x32_bf16 v[58:61], v[184:187], v[200:203], v[58:61]
	v_mfma_f32_16x16x32_bf16 v[50:53], v[192:195], v[200:203], v[50:53]
	v_mfma_f32_16x16x32_bf16 v[42:45], v[184:187], v[208:211], v[42:45]
	v_mfma_f32_16x16x32_bf16 v[34:37], v[192:195], v[208:211], v[34:37]
	v_mfma_f32_16x16x32_bf16 v[26:29], v[184:187], v[216:219], v[26:29]
	v_mfma_f32_16x16x32_bf16 v[18:21], v[192:195], v[216:219], v[18:21]
	v_mfma_f32_16x16x32_bf16 v[10:13], v[184:187], v[224:227], v[10:13]
	v_mfma_f32_16x16x32_bf16 v[2:5], v[192:195], v[224:227], v[2:5]
	s_barrier
	s_setprio 0
	s_mov_b32 s5, s29
	s_add_u32 s88, s88, 0x100
	s_addc_u32 s89, s89, 0
	s_add_u32 s86, s86, 0x100
	s_addc_u32 s87, s87, 0
	s_cmp_ge_i32 s29, s101
	s_cbranch_scc0 .LBB0_1763

.Lmy_nb_10:
	s_nop 0
	v_readfirstlane_b32 s86, v152
	v_readfirstlane_b32 s87, v153
	v_readfirstlane_b32 s88, v150
	v_readfirstlane_b32 s89, v151
	v_readfirstlane_b32 s90, v146
	v_readfirstlane_b32 s91, v147
	v_readfirstlane_b32 s92, v148
	v_readfirstlane_b32 s93, v149
	v_readfirstlane_b32 s100, v154
	v_readfirstlane_b32 s101, v138
	v_add_u32_e32 v230, s72, v141
	v_add_u32_e32 v231, s73, v141
	v_add_u32_e32 v232, 0x18000, v141
	v_add_u32_e32 v233, 0x1c000, v141
	s_add_u32 s98, s86, 0xfffc0080
	s_addc_u32 s99, s87, -1
	s_cmp_eq_u32 s5, s100
	s_cselect_b64 s[94:95], s[90:91], s[98:99]
	s_cselect_b64 s[96:97], s[92:93], s[88:89]
	s_add_i32 s45, s5, 2
	s_mov_b32 m0, s74
	ds_read_b128 v[164:167], v230
	global_load_lds_dwordx4 v144, s[86:87]
	s_mov_b32 m0, s75
	ds_read_b128 v[168:171], v230 offset:1024
	global_load_lds_dwordx4 v142, s[86:87]
	ds_read_b128 v[172:175], v230 offset:2048
	ds_read_b128 v[176:179], v230 offset:3072
	ds_read_b128 v[180:183], v231
	ds_read_b128 v[184:187], v231 offset:1024
	ds_read_b128 v[188:191], v231 offset:2048
	ds_read_b128 v[192:195], v231 offset:3072
	ds_read_b128 v[196:199], v160
	ds_read_b128 v[200:203], v160 offset:1024
	ds_read_b128 v[204:207], v160 offset:2048
	ds_read_b128 v[208:211], v160 offset:3072
	ds_read_b128 v[212:215], v160 offset:4096
	ds_read_b128 v[216:219], v160 offset:5120
	ds_read_b128 v[220:223], v160 offset:6144
	ds_read_b128 v[224:227], v160 offset:7168
	s_waitcnt vmcnt(8)
	s_waitcnt lgkmcnt(0)
	s_setprio 1
	s_barrier
	v_mfma_f32_16x16x32_bf16 v[122:125], v[164:167], v[196:199], 0
	v_mfma_f32_16x16x32_bf16 v[118:121], v[172:175], v[196:199], 0
	v_mfma_f32_16x16x32_bf16 v[110:113], v[164:167], v[204:207], 0
	v_mfma_f32_16x16x32_bf16 v[102:105], v[172:175], v[204:207], 0
	v_mfma_f32_16x16x32_bf16 v[94:97], v[164:167], v[212:215], 0
	v_mfma_f32_16x16x32_bf16 v[86:89], v[172:175], v[212:215], 0
	v_mfma_f32_16x16x32_bf16 v[78:81], v[164:167], v[220:223], 0
	v_mfma_f32_16x16x32_bf16 v[70:73], v[172:175], v[220:223], 0
	v_mfma_f32_16x16x32_bf16 v[122:125], v[168:171], v[200:203], v[122:125]
	v_mfma_f32_16x16x32_bf16 v[118:121], v[176:179], v[200:203], v[118:121]
	v_mfma_f32_16x16x32_bf16 v[110:113], v[168:171], v[208:211], v[110:113]
	v_mfma_f32_16x16x32_bf16 v[102:105], v[176:179], v[208:211], v[102:105]
	v_mfma_f32_16x16x32_bf16 v[94:97], v[168:171], v[216:219], v[94:97]
	v_mfma_f32_16x16x32_bf16 v[86:89], v[176:179], v[216:219], v[86:89]
	v_mfma_f32_16x16x32_bf16 v[78:81], v[168:171], v[224:227], v[78:81]
	v_mfma_f32_16x16x32_bf16 v[70:73], v[176:179], v[224:227], v[70:73]
	s_setprio 0
	s_setprio 1
	v_mfma_f32_16x16x32_bf16 v[126:129], v[180:183], v[196:199], 0
	v_mfma_f32_16x16x32_bf16 v[114:117], v[188:191], v[196:199], 0
	v_mfma_f32_16x16x32_bf16 v[106:109], v[180:183], v[204:207], 0
	v_mfma_f32_16x16x32_bf16 v[98:101], v[188:191], v[204:207], 0
	v_mfma_f32_16x16x32_bf16 v[90:93], v[180:183], v[212:215], 0
	v_mfma_f32_16x16x32_bf16 v[82:85], v[188:191], v[212:215], 0
	v_mfma_f32_16x16x32_bf16 v[74:77], v[180:183], v[220:223], 0
	v_mfma_f32_16x16x32_bf16 v[66:69], v[188:191], v[220:223], 0
	v_mfma_f32_16x16x32_bf16 v[126:129], v[184:187], v[200:203], v[126:129]
	v_mfma_f32_16x16x32_bf16 v[114:117], v[192:195], v[200:203], v[114:117]
	v_mfma_f32_16x16x32_bf16 v[106:109], v[184:187], v[208:211], v[106:109]
	v_mfma_f32_16x16x32_bf16 v[98:101], v[192:195], v[208:211], v[98:101]
	v_mfma_f32_16x16x32_bf16 v[90:93], v[184:187], v[216:219], v[90:93]
	v_mfma_f32_16x16x32_bf16 v[82:85], v[192:195], v[216:219], v[82:85]
	v_mfma_f32_16x16x32_bf16 v[74:77], v[184:187], v[224:227], v[74:77]
	v_mfma_f32_16x16x32_bf16 v[66:69], v[192:195], v[224:227], v[66:69]
	s_barrier
	s_setprio 0
	s_add_u32 s98, s96, 0x40000
	s_addc_u32 s99, s97, 0
	s_mov_b32 m0, s76
	ds_read_b128 v[196:199], v160 offset:16384
	global_load_lds_dwordx4 v132, s[96:97]
	s_mov_b32 m0, s77
	s_add_i32 s5, s73, s25
	global_load_lds_dwordx4 v136, s[96:97]
	s_mov_b32 m0, s5
	ds_read_b128 v[200:203], v160 offset:17408
	global_load_lds_dwordx4 v132, s[98:99]
	s_add_i32 m0, s5, 0x2000
	ds_read_b128 v[204:207], v160 offset:18432
	global_load_lds_dwordx4 v136, s[98:99]
	s_mov_b32 m0, s49
	ds_read_b128 v[208:211], v160 offset:19456
	global_load_lds_dwordx4 v130, s[94:95]
	s_mov_b32 m0, s58
	ds_read_b128 v[212:215], v160 offset:20480
	global_load_lds_dwordx4 v134, s[94:95]
	ds_read_b128 v[216:219], v160 offset:21504
	ds_read_b128 v[220:223], v160 offset:22528
	ds_read_b128 v[224:227], v160 offset:23552
	s_waitcnt vmcnt(8)
	s_waitcnt lgkmcnt(0)
	s_setprio 1
	s_barrier
	v_mfma_f32_16x16x32_bf16 v[62:65], v[164:167], v[196:199], 0
	v_mfma_f32_16x16x32_bf16 v[54:57], v[172:175], v[196:199], 0
	v_mfma_f32_16x16x32_bf16 v[46:49], v[164:167], v[204:207], 0
	v_mfma_f32_16x16x32_bf16 v[38:41], v[172:175], v[204:207], 0
	v_mfma_f32_16x16x32_bf16 v[30:33], v[164:167], v[212:215], 0
	v_mfma_f32_16x16x32_bf16 v[22:25], v[172:175], v[212:215], 0
	v_mfma_f32_16x16x32_bf16 v[14:17], v[164:167], v[220:223], 0
	v_mfma_f32_16x16x32_bf16 v[6:9], v[172:175], v[220:223], 0
	v_mfma_f32_16x16x32_bf16 v[62:65], v[168:171], v[200:203], v[62:65]
	v_mfma_f32_16x16x32_bf16 v[54:57], v[176:179], v[200:203], v[54:57]
	v_mfma_f32_16x16x32_bf16 v[46:49], v[168:171], v[208:211], v[46:49]
	v_mfma_f32_16x16x32_bf16 v[38:41], v[176:179], v[208:211], v[38:41]
	v_mfma_f32_16x16x32_bf16 v[30:33], v[168:171], v[216:219], v[30:33]
	v_mfma_f32_16x16x32_bf16 v[22:25], v[176:179], v[216:219], v[22:25]
	v_mfma_f32_16x16x32_bf16 v[14:17], v[168:171], v[224:227], v[14:17]
	v_mfma_f32_16x16x32_bf16 v[6:9], v[176:179], v[224:227], v[6:9]
	s_setprio 0
	s_setprio 1
	v_mfma_f32_16x16x32_bf16 v[58:61], v[180:183], v[196:199], 0
	v_mfma_f32_16x16x32_bf16 v[50:53], v[188:191], v[196:199], 0
	v_mfma_f32_16x16x32_bf16 v[42:45], v[180:183], v[204:207], 0
	v_mfma_f32_16x16x32_bf16 v[34:37], v[188:191], v[204:207], 0
	v_mfma_f32_16x16x32_bf16 v[26:29], v[180:183], v[212:215], 0
	v_mfma_f32_16x16x32_bf16 v[18:21], v[188:191], v[212:215], 0
	v_mfma_f32_16x16x32_bf16 v[10:13], v[180:183], v[220:223], 0
	v_mfma_f32_16x16x32_bf16 v[2:5], v[188:191], v[220:223], 0
	v_mfma_f32_16x16x32_bf16 v[58:61], v[184:187], v[200:203], v[58:61]
	v_mfma_f32_16x16x32_bf16 v[50:53], v[192:195], v[200:203], v[50:53]
	v_mfma_f32_16x16x32_bf16 v[42:45], v[184:187], v[208:211], v[42:45]
	v_mfma_f32_16x16x32_bf16 v[34:37], v[192:195], v[208:211], v[34:37]
	v_mfma_f32_16x16x32_bf16 v[26:29], v[184:187], v[216:219], v[26:29]
	v_mfma_f32_16x16x32_bf16 v[18:21], v[192:195], v[216:219], v[18:21]
	v_mfma_f32_16x16x32_bf16 v[10:13], v[184:187], v[224:227], v[10:13]
	v_mfma_f32_16x16x32_bf16 v[2:5], v[192:195], v[224:227], v[2:5]
	s_barrier
	s_setprio 0
	s_add_u32 s98, s94, 0x40000
	s_addc_u32 s99, s95, 0
	s_add_i32 s5, 0, 0x18000
	s_add_i32 s47, 0, 0x1c000
	s_mov_b32 m0, s59
	ds_read_b128 v[164:167], v232
	global_load_lds_dwordx4 v130, s[98:99]
	s_mov_b32 m0, s60
	ds_read_b128 v[168:171], v232 offset:1024
	global_load_lds_dwordx4 v134, s[98:99]
	ds_read_b128 v[172:175], v232 offset:2048
	ds_read_b128 v[176:179], v232 offset:3072
	ds_read_b128 v[180:183], v233
	ds_read_b128 v[184:187], v233 offset:1024
	ds_read_b128 v[188:191], v233 offset:2048
	ds_read_b128 v[192:195], v233 offset:3072
	ds_read_b128 v[196:199], v160 offset:32768
	ds_read_b128 v[200:203], v160 offset:33792
	ds_read_b128 v[204:207], v160 offset:34816
	ds_read_b128 v[208:211], v160 offset:35840
	ds_read_b128 v[212:215], v160 offset:36864
	ds_read_b128 v[216:219], v160 offset:37888
	ds_read_b128 v[220:223], v160 offset:38912
	ds_read_b128 v[224:227], v160 offset:39936
	s_waitcnt vmcnt(8)
	s_waitcnt lgkmcnt(0)
	s_setprio 1
	s_barrier
	v_mfma_f32_16x16x32_bf16 v[122:125], v[164:167], v[196:199], v[122:125]
	v_mfma_f32_16x16x32_bf16 v[118:121], v[172:175], v[196:199], v[118:121]
	v_mfma_f32_16x16x32_bf16 v[110:113], v[164:167], v[204:207], v[110:113]
	v_mfma_f32_16x16x32_bf16 v[102:105], v[172:175], v[204:207], v[102:105]
	v_mfma_f32_16x16x32_bf16 v[94:97], v[164:167], v[212:215], v[94:97]
	v_mfma_f32_16x16x32_bf16 v[86:89], v[172:175], v[212:215], v[86:89]
	v_mfma_f32_16x16x32_bf16 v[78:81], v[164:167], v[220:223], v[78:81]
	v_mfma_f32_16x16x32_bf16 v[70:73], v[172:175], v[220:223], v[70:73]
	v_mfma_f32_16x16x32_bf16 v[122:125], v[168:171], v[200:203], v[122:125]
	v_mfma_f32_16x16x32_bf16 v[118:121], v[176:179], v[200:203], v[118:121]
	v_mfma_f32_16x16x32_bf16 v[110:113], v[168:171], v[208:211], v[110:113]
	v_mfma_f32_16x16x32_bf16 v[102:105], v[176:179], v[208:211], v[102:105]
	v_mfma_f32_16x16x32_bf16 v[94:97], v[168:171], v[216:219], v[94:97]
	v_mfma_f32_16x16x32_bf16 v[86:89], v[176:179], v[216:219], v[86:89]
	v_mfma_f32_16x16x32_bf16 v[78:81], v[168:171], v[224:227], v[78:81]
	v_mfma_f32_16x16x32_bf16 v[70:73], v[176:179], v[224:227], v[70:73]
	s_setprio 0
	s_setprio 1
	v_mfma_f32_16x16x32_bf16 v[126:129], v[180:183], v[196:199], v[126:129]
	v_mfma_f32_16x16x32_bf16 v[114:117], v[188:191], v[196:199], v[114:117]
	v_mfma_f32_16x16x32_bf16 v[106:109], v[180:183], v[204:207], v[106:109]
	v_mfma_f32_16x16x32_bf16 v[98:101], v[188:191], v[204:207], v[98:101]
	v_mfma_f32_16x16x32_bf16 v[90:93], v[180:183], v[212:215], v[90:93]
	v_mfma_f32_16x16x32_bf16 v[82:85], v[188:191], v[212:215], v[82:85]
	v_mfma_f32_16x16x32_bf16 v[74:77], v[180:183], v[220:223], v[74:77]
	v_mfma_f32_16x16x32_bf16 v[66:69], v[188:191], v[220:223], v[66:69]
	v_mfma_f32_16x16x32_bf16 v[126:129], v[184:187], v[200:203], v[126:129]
	v_mfma_f32_16x16x32_bf16 v[114:117], v[192:195], v[200:203], v[114:117]
	v_mfma_f32_16x16x32_bf16 v[106:109], v[184:187], v[208:211], v[106:109]
	v_mfma_f32_16x16x32_bf16 v[98:101], v[192:195], v[208:211], v[98:101]
	v_mfma_f32_16x16x32_bf16 v[90:93], v[184:187], v[216:219], v[90:93]
	v_mfma_f32_16x16x32_bf16 v[82:85], v[192:195], v[216:219], v[82:85]
	v_mfma_f32_16x16x32_bf16 v[74:77], v[184:187], v[224:227], v[74:77]
	v_mfma_f32_16x16x32_bf16 v[66:69], v[192:195], v[224:227], v[66:69]
	s_barrier
	s_setprio 0
	s_add_u32 s96, s96, 0x80
	s_addc_u32 s97, s97, 0
	s_add_u32 s98, s96, 0x40000
	s_addc_u32 s99, s97, 0
	s_add_u32 s94, s94, 0x80
	s_addc_u32 s95, s95, 0
	s_add_i32 s5, s5, s25
	s_mov_b32 m0, s5
	ds_read_b128 v[196:199], v160 offset:49152
	global_load_lds_dwordx4 v132, s[96:97]
	s_add_i32 m0, s5, 0x2000
	s_add_i32 s5, s47, s25
	global_load_lds_dwordx4 v136, s[96:97]
	s_mov_b32 m0, s5
	ds_read_b128 v[200:203], v160 offset:50176
	global_load_lds_dwordx4 v132, s[98:99]
	s_add_i32 m0, s5, 0x2000
	ds_read_b128 v[204:207], v160 offset:51200
	global_load_lds_dwordx4 v136, s[98:99]
	s_mov_b32 m0, s61
	ds_read_b128 v[208:211], v160 offset:52224
	global_load_lds_dwordx4 v130, s[94:95]
	s_mov_b32 m0, s62
	ds_read_b128 v[212:215], v160 offset:53248
	global_load_lds_dwordx4 v134, s[94:95]
	ds_read_b128 v[216:219], v160 offset:54272
	ds_read_b128 v[220:223], v160 offset:55296
	ds_read_b128 v[224:227], v160 offset:56320
	s_waitcnt vmcnt(8)
	s_waitcnt lgkmcnt(0)
	s_setprio 1
	s_barrier
	v_mfma_f32_16x16x32_bf16 v[62:65], v[164:167], v[196:199], v[62:65]
	v_mfma_f32_16x16x32_bf16 v[54:57], v[172:175], v[196:199], v[54:57]
	v_mfma_f32_16x16x32_bf16 v[46:49], v[164:167], v[204:207], v[46:49]
	v_mfma_f32_16x16x32_bf16 v[38:41], v[172:175], v[204:207], v[38:41]
	v_mfma_f32_16x16x32_bf16 v[30:33], v[164:167], v[212:215], v[30:33]
	v_mfma_f32_16x16x32_bf16 v[22:25], v[172:175], v[212:215], v[22:25]
	v_mfma_f32_16x16x32_bf16 v[14:17], v[164:167], v[220:223], v[14:17]
	v_mfma_f32_16x16x32_bf16 v[6:9], v[172:175], v[220:223], v[6:9]
	v_mfma_f32_16x16x32_bf16 v[62:65], v[168:171], v[200:203], v[62:65]
	v_mfma_f32_16x16x32_bf16 v[54:57], v[176:179], v[200:203], v[54:57]
	v_mfma_f32_16x16x32_bf16 v[46:49], v[168:171], v[208:211], v[46:49]
	v_mfma_f32_16x16x32_bf16 v[38:41], v[176:179], v[208:211], v[38:41]
	v_mfma_f32_16x16x32_bf16 v[30:33], v[168:171], v[216:219], v[30:33]
	v_mfma_f32_16x16x32_bf16 v[22:25], v[176:179], v[216:219], v[22:25]
	v_mfma_f32_16x16x32_bf16 v[14:17], v[168:171], v[224:227], v[14:17]
	v_mfma_f32_16x16x32_bf16 v[6:9], v[176:179], v[224:227], v[6:9]
	s_setprio 0
	s_setprio 1
	v_mfma_f32_16x16x32_bf16 v[58:61], v[180:183], v[196:199], v[58:61]
	v_mfma_f32_16x16x32_bf16 v[50:53], v[188:191], v[196:199], v[50:53]
	v_mfma_f32_16x16x32_bf16 v[42:45], v[180:183], v[204:207], v[42:45]
	v_mfma_f32_16x16x32_bf16 v[34:37], v[188:191], v[204:207], v[34:37]
	v_mfma_f32_16x16x32_bf16 v[26:29], v[180:183], v[212:215], v[26:29]
	v_mfma_f32_16x16x32_bf16 v[18:21], v[188:191], v[212:215], v[18:21]
	v_mfma_f32_16x16x32_bf16 v[10:13], v[180:183], v[220:223], v[10:13]
	v_mfma_f32_16x16x32_bf16 v[2:5], v[188:191], v[220:223], v[2:5]
	v_mfma_f32_16x16x32_bf16 v[58:61], v[184:187], v[200:203], v[58:61]
	v_mfma_f32_16x16x32_bf16 v[50:53], v[192:195], v[200:203], v[50:53]
	v_mfma_f32_16x16x32_bf16 v[42:45], v[184:187], v[208:211], v[42:45]
	v_mfma_f32_16x16x32_bf16 v[34:37], v[192:195], v[208:211], v[34:37]
	v_mfma_f32_16x16x32_bf16 v[26:29], v[184:187], v[216:219], v[26:29]
	v_mfma_f32_16x16x32_bf16 v[18:21], v[192:195], v[216:219], v[18:21]
	v_mfma_f32_16x16x32_bf16 v[10:13], v[184:187], v[224:227], v[10:13]
	v_mfma_f32_16x16x32_bf16 v[2:5], v[192:195], v[224:227], v[2:5]
	s_barrier
	s_setprio 0
	s_mov_b32 s5, s45
	s_add_u32 s88, s88, 0x100
	s_addc_u32 s89, s89, 0
	s_add_u32 s86, s86, 0x100
	s_addc_u32 s87, s87, 0
	s_cmp_ge_i32 s45, s101
	s_cbranch_scc1 .Lmy_kexit_10
.LBB0_1944:
	s_add_u32 s98, s86, 0xfffc0080
	s_addc_u32 s99, s87, -1
	s_cmp_eq_u32 s5, s100
	s_cselect_b64 s[94:95], s[90:91], s[98:99]
	s_cselect_b64 s[96:97], s[92:93], s[88:89]
	s_add_i32 s45, s5, 2
	s_mov_b32 m0, s74
	ds_read_b128 v[164:167], v230
	global_load_lds_dwordx4 v144, s[86:87]
	s_mov_b32 m0, s75
	ds_read_b128 v[168:171], v230 offset:1024
	global_load_lds_dwordx4 v142, s[86:87]
	ds_read_b128 v[172:175], v230 offset:2048
	ds_read_b128 v[176:179], v230 offset:3072
	ds_read_b128 v[180:183], v231
	ds_read_b128 v[184:187], v231 offset:1024
	ds_read_b128 v[188:191], v231 offset:2048
	ds_read_b128 v[192:195], v231 offset:3072
	ds_read_b128 v[196:199], v160
	ds_read_b128 v[200:203], v160 offset:1024
	ds_read_b128 v[204:207], v160 offset:2048
	ds_read_b128 v[208:211], v160 offset:3072
	ds_read_b128 v[212:215], v160 offset:4096
	ds_read_b128 v[216:219], v160 offset:5120
	ds_read_b128 v[220:223], v160 offset:6144
	ds_read_b128 v[224:227], v160 offset:7168
	s_waitcnt vmcnt(8)
	s_waitcnt lgkmcnt(0)
	s_setprio 1
	s_barrier
	v_mfma_f32_16x16x32_bf16 v[122:125], v[164:167], v[196:199], v[122:125]
	v_mfma_f32_16x16x32_bf16 v[118:121], v[172:175], v[196:199], v[118:121]
	v_mfma_f32_16x16x32_bf16 v[110:113], v[164:167], v[204:207], v[110:113]
	v_mfma_f32_16x16x32_bf16 v[102:105], v[172:175], v[204:207], v[102:105]
	v_mfma_f32_16x16x32_bf16 v[94:97], v[164:167], v[212:215], v[94:97]
	v_mfma_f32_16x16x32_bf16 v[86:89], v[172:175], v[212:215], v[86:89]
	v_mfma_f32_16x16x32_bf16 v[78:81], v[164:167], v[220:223], v[78:81]
	v_mfma_f32_16x16x32_bf16 v[70:73], v[172:175], v[220:223], v[70:73]
	v_mfma_f32_16x16x32_bf16 v[122:125], v[168:171], v[200:203], v[122:125]
	v_mfma_f32_16x16x32_bf16 v[118:121], v[176:179], v[200:203], v[118:121]
	v_mfma_f32_16x16x32_bf16 v[110:113], v[168:171], v[208:211], v[110:113]
	v_mfma_f32_16x16x32_bf16 v[102:105], v[176:179], v[208:211], v[102:105]
	v_mfma_f32_16x16x32_bf16 v[94:97], v[168:171], v[216:219], v[94:97]
	v_mfma_f32_16x16x32_bf16 v[86:89], v[176:179], v[216:219], v[86:89]
	v_mfma_f32_16x16x32_bf16 v[78:81], v[168:171], v[224:227], v[78:81]
	v_mfma_f32_16x16x32_bf16 v[70:73], v[176:179], v[224:227], v[70:73]
	s_setprio 0
	s_setprio 1
	v_mfma_f32_16x16x32_bf16 v[126:129], v[180:183], v[196:199], v[126:129]
	v_mfma_f32_16x16x32_bf16 v[114:117], v[188:191], v[196:199], v[114:117]
	v_mfma_f32_16x16x32_bf16 v[106:109], v[180:183], v[204:207], v[106:109]
	v_mfma_f32_16x16x32_bf16 v[98:101], v[188:191], v[204:207], v[98:101]
	v_mfma_f32_16x16x32_bf16 v[90:93], v[180:183], v[212:215], v[90:93]
	v_mfma_f32_16x16x32_bf16 v[82:85], v[188:191], v[212:215], v[82:85]
	v_mfma_f32_16x16x32_bf16 v[74:77], v[180:183], v[220:223], v[74:77]
	v_mfma_f32_16x16x32_bf16 v[66:69], v[188:191], v[220:223], v[66:69]
	v_mfma_f32_16x16x32_bf16 v[126:129], v[184:187], v[200:203], v[126:129]
	v_mfma_f32_16x16x32_bf16 v[114:117], v[192:195], v[200:203], v[114:117]
	v_mfma_f32_16x16x32_bf16 v[106:109], v[184:187], v[208:211], v[106:109]
	v_mfma_f32_16x16x32_bf16 v[98:101], v[192:195], v[208:211], v[98:101]
	v_mfma_f32_16x16x32_bf16 v[90:93], v[184:187], v[216:219], v[90:93]
	v_mfma_f32_16x16x32_bf16 v[82:85], v[192:195], v[216:219], v[82:85]
	v_mfma_f32_16x16x32_bf16 v[74:77], v[184:187], v[224:227], v[74:77]
	v_mfma_f32_16x16x32_bf16 v[66:69], v[192:195], v[224:227], v[66:69]
	s_barrier
	s_setprio 0
	s_add_u32 s98, s96, 0x40000
	s_addc_u32 s99, s97, 0
	s_mov_b32 m0, s76
	ds_read_b128 v[196:199], v160 offset:16384
	global_load_lds_dwordx4 v132, s[96:97]
	s_mov_b32 m0, s77
	s_add_i32 s5, s73, s25
	global_load_lds_dwordx4 v136, s[96:97]
	s_mov_b32 m0, s5
	ds_read_b128 v[200:203], v160 offset:17408
	global_load_lds_dwordx4 v132, s[98:99]
	s_add_i32 m0, s5, 0x2000
	ds_read_b128 v[204:207], v160 offset:18432
	global_load_lds_dwordx4 v136, s[98:99]
	s_mov_b32 m0, s49
	ds_read_b128 v[208:211], v160 offset:19456
	global_load_lds_dwordx4 v130, s[94:95]
	s_mov_b32 m0, s58
	ds_read_b128 v[212:215], v160 offset:20480
	global_load_lds_dwordx4 v134, s[94:95]
	ds_read_b128 v[216:219], v160 offset:21504
	ds_read_b128 v[220:223], v160 offset:22528
	ds_read_b128 v[224:227], v160 offset:23552
	s_waitcnt vmcnt(8)
	s_waitcnt lgkmcnt(0)
	s_setprio 1
	s_barrier
	v_mfma_f32_16x16x32_bf16 v[62:65], v[164:167], v[196:199], v[62:65]
	v_mfma_f32_16x16x32_bf16 v[54:57], v[172:175], v[196:199], v[54:57]
	v_mfma_f32_16x16x32_bf16 v[46:49], v[164:167], v[204:207], v[46:49]
	v_mfma_f32_16x16x32_bf16 v[38:41], v[172:175], v[204:207], v[38:41]
	v_mfma_f32_16x16x32_bf16 v[30:33], v[164:167], v[212:215], v[30:33]
	v_mfma_f32_16x16x32_bf16 v[22:25], v[172:175], v[212:215], v[22:25]
	v_mfma_f32_16x16x32_bf16 v[14:17], v[164:167], v[220:223], v[14:17]
	v_mfma_f32_16x16x32_bf16 v[6:9], v[172:175], v[220:223], v[6:9]
	v_mfma_f32_16x16x32_bf16 v[62:65], v[168:171], v[200:203], v[62:65]
	v_mfma_f32_16x16x32_bf16 v[54:57], v[176:179], v[200:203], v[54:57]
	v_mfma_f32_16x16x32_bf16 v[46:49], v[168:171], v[208:211], v[46:49]
	v_mfma_f32_16x16x32_bf16 v[38:41], v[176:179], v[208:211], v[38:41]
	v_mfma_f32_16x16x32_bf16 v[30:33], v[168:171], v[216:219], v[30:33]
	v_mfma_f32_16x16x32_bf16 v[22:25], v[176:179], v[216:219], v[22:25]
	v_mfma_f32_16x16x32_bf16 v[14:17], v[168:171], v[224:227], v[14:17]
	v_mfma_f32_16x16x32_bf16 v[6:9], v[176:179], v[224:227], v[6:9]
	s_setprio 0
	s_setprio 1
	v_mfma_f32_16x16x32_bf16 v[58:61], v[180:183], v[196:199], v[58:61]
	v_mfma_f32_16x16x32_bf16 v[50:53], v[188:191], v[196:199], v[50:53]
	v_mfma_f32_16x16x32_bf16 v[42:45], v[180:183], v[204:207], v[42:45]
	v_mfma_f32_16x16x32_bf16 v[34:37], v[188:191], v[204:207], v[34:37]
	v_mfma_f32_16x16x32_bf16 v[26:29], v[180:183], v[212:215], v[26:29]
	v_mfma_f32_16x16x32_bf16 v[18:21], v[188:191], v[212:215], v[18:21]
	v_mfma_f32_16x16x32_bf16 v[10:13], v[180:183], v[220:223], v[10:13]
	v_mfma_f32_16x16x32_bf16 v[2:5], v[188:191], v[220:223], v[2:5]
	v_mfma_f32_16x16x32_bf16 v[58:61], v[184:187], v[200:203], v[58:61]
	v_mfma_f32_16x16x32_bf16 v[50:53], v[192:195], v[200:203], v[50:53]
	v_mfma_f32_16x16x32_bf16 v[42:45], v[184:187], v[208:211], v[42:45]
	v_mfma_f32_16x16x32_bf16 v[34:37], v[192:195], v[208:211], v[34:37]
	v_mfma_f32_16x16x32_bf16 v[26:29], v[184:187], v[216:219], v[26:29]
	v_mfma_f32_16x16x32_bf16 v[18:21], v[192:195], v[216:219], v[18:21]
	v_mfma_f32_16x16x32_bf16 v[10:13], v[184:187], v[224:227], v[10:13]
	v_mfma_f32_16x16x32_bf16 v[2:5], v[192:195], v[224:227], v[2:5]
	s_barrier
	s_setprio 0
	s_add_u32 s98, s94, 0x40000
	s_addc_u32 s99, s95, 0
	s_add_i32 s5, 0, 0x18000
	s_add_i32 s47, 0, 0x1c000
	s_mov_b32 m0, s59
	ds_read_b128 v[164:167], v232
	global_load_lds_dwordx4 v130, s[98:99]
	s_mov_b32 m0, s60
	ds_read_b128 v[168:171], v232 offset:1024
	global_load_lds_dwordx4 v134, s[98:99]
	ds_read_b128 v[172:175], v232 offset:2048
	ds_read_b128 v[176:179], v232 offset:3072
	ds_read_b128 v[180:183], v233
	ds_read_b128 v[184:187], v233 offset:1024
	ds_read_b128 v[188:191], v233 offset:2048
	ds_read_b128 v[192:195], v233 offset:3072
	ds_read_b128 v[196:199], v160 offset:32768
	ds_read_b128 v[200:203], v160 offset:33792
	ds_read_b128 v[204:207], v160 offset:34816
	ds_read_b128 v[208:211], v160 offset:35840
	ds_read_b128 v[212:215], v160 offset:36864
	ds_read_b128 v[216:219], v160 offset:37888
	ds_read_b128 v[220:223], v160 offset:38912
	ds_read_b128 v[224:227], v160 offset:39936
	s_waitcnt vmcnt(8)
	s_waitcnt lgkmcnt(0)
	s_setprio 1
	s_barrier
	v_mfma_f32_16x16x32_bf16 v[122:125], v[164:167], v[196:199], v[122:125]
	v_mfma_f32_16x16x32_bf16 v[118:121], v[172:175], v[196:199], v[118:121]
	v_mfma_f32_16x16x32_bf16 v[110:113], v[164:167], v[204:207], v[110:113]
	v_mfma_f32_16x16x32_bf16 v[102:105], v[172:175], v[204:207], v[102:105]
	v_mfma_f32_16x16x32_bf16 v[94:97], v[164:167], v[212:215], v[94:97]
	v_mfma_f32_16x16x32_bf16 v[86:89], v[172:175], v[212:215], v[86:89]
	v_mfma_f32_16x16x32_bf16 v[78:81], v[164:167], v[220:223], v[78:81]
	v_mfma_f32_16x16x32_bf16 v[70:73], v[172:175], v[220:223], v[70:73]
	v_mfma_f32_16x16x32_bf16 v[122:125], v[168:171], v[200:203], v[122:125]
	v_mfma_f32_16x16x32_bf16 v[118:121], v[176:179], v[200:203], v[118:121]
	v_mfma_f32_16x16x32_bf16 v[110:113], v[168:171], v[208:211], v[110:113]
	v_mfma_f32_16x16x32_bf16 v[102:105], v[176:179], v[208:211], v[102:105]
	v_mfma_f32_16x16x32_bf16 v[94:97], v[168:171], v[216:219], v[94:97]
	v_mfma_f32_16x16x32_bf16 v[86:89], v[176:179], v[216:219], v[86:89]
	v_mfma_f32_16x16x32_bf16 v[78:81], v[168:171], v[224:227], v[78:81]
	v_mfma_f32_16x16x32_bf16 v[70:73], v[176:179], v[224:227], v[70:73]
	s_setprio 0
	s_setprio 1
	v_mfma_f32_16x16x32_bf16 v[126:129], v[180:183], v[196:199], v[126:129]
	v_mfma_f32_16x16x32_bf16 v[114:117], v[188:191], v[196:199], v[114:117]
	v_mfma_f32_16x16x32_bf16 v[106:109], v[180:183], v[204:207], v[106:109]
	v_mfma_f32_16x16x32_bf16 v[98:101], v[188:191], v[204:207], v[98:101]
	v_mfma_f32_16x16x32_bf16 v[90:93], v[180:183], v[212:215], v[90:93]
	v_mfma_f32_16x16x32_bf16 v[82:85], v[188:191], v[212:215], v[82:85]
	v_mfma_f32_16x16x32_bf16 v[74:77], v[180:183], v[220:223], v[74:77]
	v_mfma_f32_16x16x32_bf16 v[66:69], v[188:191], v[220:223], v[66:69]
	v_mfma_f32_16x16x32_bf16 v[126:129], v[184:187], v[200:203], v[126:129]
	v_mfma_f32_16x16x32_bf16 v[114:117], v[192:195], v[200:203], v[114:117]
	v_mfma_f32_16x16x32_bf16 v[106:109], v[184:187], v[208:211], v[106:109]
	v_mfma_f32_16x16x32_bf16 v[98:101], v[192:195], v[208:211], v[98:101]
	v_mfma_f32_16x16x32_bf16 v[90:93], v[184:187], v[216:219], v[90:93]
	v_mfma_f32_16x16x32_bf16 v[82:85], v[192:195], v[216:219], v[82:85]
	v_mfma_f32_16x16x32_bf16 v[74:77], v[184:187], v[224:227], v[74:77]
	v_mfma_f32_16x16x32_bf16 v[66:69], v[192:195], v[224:227], v[66:69]
	s_barrier
	s_setprio 0
	s_add_u32 s96, s96, 0x80
	s_addc_u32 s97, s97, 0
	s_add_u32 s98, s96, 0x40000
	s_addc_u32 s99, s97, 0
	s_add_u32 s94, s94, 0x80
	s_addc_u32 s95, s95, 0
	s_add_i32 s5, s5, s25
	s_mov_b32 m0, s5
	ds_read_b128 v[196:199], v160 offset:49152
	global_load_lds_dwordx4 v132, s[96:97]
	s_add_i32 m0, s5, 0x2000
	s_add_i32 s5, s47, s25
	global_load_lds_dwordx4 v136, s[96:97]
	s_mov_b32 m0, s5
	ds_read_b128 v[200:203], v160 offset:50176
	global_load_lds_dwordx4 v132, s[98:99]
	s_add_i32 m0, s5, 0x2000
	ds_read_b128 v[204:207], v160 offset:51200
	global_load_lds_dwordx4 v136, s[98:99]
	s_mov_b32 m0, s61
	ds_read_b128 v[208:211], v160 offset:52224
	global_load_lds_dwordx4 v130, s[94:95]
	s_mov_b32 m0, s62
	ds_read_b128 v[212:215], v160 offset:53248
	global_load_lds_dwordx4 v134, s[94:95]
	ds_read_b128 v[216:219], v160 offset:54272
	ds_read_b128 v[220:223], v160 offset:55296
	ds_read_b128 v[224:227], v160 offset:56320
	s_waitcnt vmcnt(8)
	s_waitcnt lgkmcnt(0)
	s_setprio 1
	s_barrier
	v_mfma_f32_16x16x32_bf16 v[62:65], v[164:167], v[196:199], v[62:65]
	v_mfma_f32_16x16x32_bf16 v[54:57], v[172:175], v[196:199], v[54:57]
	v_mfma_f32_16x16x32_bf16 v[46:49], v[164:167], v[204:207], v[46:49]
	v_mfma_f32_16x16x32_bf16 v[38:41], v[172:175], v[204:207], v[38:41]
	v_mfma_f32_16x16x32_bf16 v[30:33], v[164:167], v[212:215], v[30:33]
	v_mfma_f32_16x16x32_bf16 v[22:25], v[172:175], v[212:215], v[22:25]
	v_mfma_f32_16x16x32_bf16 v[14:17], v[164:167], v[220:223], v[14:17]
	v_mfma_f32_16x16x32_bf16 v[6:9], v[172:175], v[220:223], v[6:9]
	v_mfma_f32_16x16x32_bf16 v[62:65], v[168:171], v[200:203], v[62:65]
	v_mfma_f32_16x16x32_bf16 v[54:57], v[176:179], v[200:203], v[54:57]
	v_mfma_f32_16x16x32_bf16 v[46:49], v[168:171], v[208:211], v[46:49]
	v_mfma_f32_16x16x32_bf16 v[38:41], v[176:179], v[208:211], v[38:41]
	v_mfma_f32_16x16x32_bf16 v[30:33], v[168:171], v[216:219], v[30:33]
	v_mfma_f32_16x16x32_bf16 v[22:25], v[176:179], v[216:219], v[22:25]
	v_mfma_f32_16x16x32_bf16 v[14:17], v[168:171], v[224:227], v[14:17]
	v_mfma_f32_16x16x32_bf16 v[6:9], v[176:179], v[224:227], v[6:9]
	s_setprio 0
	s_setprio 1
	v_mfma_f32_16x16x32_bf16 v[58:61], v[180:183], v[196:199], v[58:61]
	v_mfma_f32_16x16x32_bf16 v[50:53], v[188:191], v[196:199], v[50:53]
	v_mfma_f32_16x16x32_bf16 v[42:45], v[180:183], v[204:207], v[42:45]
	v_mfma_f32_16x16x32_bf16 v[34:37], v[188:191], v[204:207], v[34:37]
	v_mfma_f32_16x16x32_bf16 v[26:29], v[180:183], v[212:215], v[26:29]
	v_mfma_f32_16x16x32_bf16 v[18:21], v[188:191], v[212:215], v[18:21]
	v_mfma_f32_16x16x32_bf16 v[10:13], v[180:183], v[220:223], v[10:13]
	v_mfma_f32_16x16x32_bf16 v[2:5], v[188:191], v[220:223], v[2:5]
	v_mfma_f32_16x16x32_bf16 v[58:61], v[184:187], v[200:203], v[58:61]
	v_mfma_f32_16x16x32_bf16 v[50:53], v[192:195], v[200:203], v[50:53]
	v_mfma_f32_16x16x32_bf16 v[42:45], v[184:187], v[208:211], v[42:45]
	v_mfma_f32_16x16x32_bf16 v[34:37], v[192:195], v[208:211], v[34:37]
	v_mfma_f32_16x16x32_bf16 v[26:29], v[184:187], v[216:219], v[26:29]
	v_mfma_f32_16x16x32_bf16 v[18:21], v[192:195], v[216:219], v[18:21]
	v_mfma_f32_16x16x32_bf16 v[10:13], v[184:187], v[224:227], v[10:13]
	v_mfma_f32_16x16x32_bf16 v[2:5], v[192:195], v[224:227], v[2:5]
	s_barrier
	s_setprio 0
	s_mov_b32 s5, s45
	s_add_u32 s88, s88, 0x100
	s_addc_u32 s89, s89, 0
	s_add_u32 s86, s86, 0x100
	s_addc_u32 s87, s87, 0
	s_cmp_ge_i32 s45, s101
	s_cbranch_scc0 .LBB0_1944

.Lmy_nb_11:
	s_nop 0
	v_readfirstlane_b32 s86, v150
	v_readfirstlane_b32 s87, v151
	v_readfirstlane_b32 s88, v152
	v_readfirstlane_b32 s89, v153
	v_readfirstlane_b32 s90, v146
	v_readfirstlane_b32 s91, v147
	v_readfirstlane_b32 s92, v148
	v_readfirstlane_b32 s93, v149
	v_readfirstlane_b32 s100, v138
	v_readfirstlane_b32 s101, v156
	v_add_u32_e32 v230, s65, v141
	v_add_u32_e32 v231, s66, v141
	v_add_u32_e32 v232, 0x18000, v141
	v_add_u32_e32 v233, 0x1c000, v141
	s_add_u32 s98, s86, 0x100
	s_addc_u32 s99, s87, 0
	s_cmp_eq_u32 s4, s100
	s_cselect_b64 s[94:95], s[90:91], s[98:99]
	s_cselect_b64 s[96:97], s[92:93], s[88:89]
	s_add_i32 s5, s4, 2
	s_add_i32 m0, s44, 0xc000
	ds_read_b128 v[164:167], v230
	global_load_lds_dwordx4 v144, s[86:87]
	s_add_i32 m0, s44, 0xe000
	ds_read_b128 v[168:171], v230 offset:1024
	global_load_lds_dwordx4 v142, s[86:87]
	ds_read_b128 v[172:175], v230 offset:2048
	ds_read_b128 v[176:179], v230 offset:3072
	ds_read_b128 v[180:183], v231
	ds_read_b128 v[184:187], v231 offset:1024
	ds_read_b128 v[188:191], v231 offset:2048
	ds_read_b128 v[192:195], v231 offset:3072
	ds_read_b128 v[196:199], v160
	ds_read_b128 v[200:203], v160 offset:1024
	ds_read_b128 v[204:207], v160 offset:2048
	ds_read_b128 v[208:211], v160 offset:3072
	ds_read_b128 v[212:215], v160 offset:4096
	ds_read_b128 v[216:219], v160 offset:5120
	ds_read_b128 v[220:223], v160 offset:6144
	ds_read_b128 v[224:227], v160 offset:7168
	s_waitcnt vmcnt(8)
	s_waitcnt lgkmcnt(0)
	s_setprio 1
	s_barrier
	v_mfma_f32_16x16x32_bf16 v[122:125], v[164:167], v[196:199], 0
	v_mfma_f32_16x16x32_bf16 v[118:121], v[172:175], v[196:199], 0
	v_mfma_f32_16x16x32_bf16 v[110:113], v[164:167], v[204:207], 0
	v_mfma_f32_16x16x32_bf16 v[102:105], v[172:175], v[204:207], 0
	v_mfma_f32_16x16x32_bf16 v[94:97], v[164:167], v[212:215], 0
	v_mfma_f32_16x16x32_bf16 v[86:89], v[172:175], v[212:215], 0
	v_mfma_f32_16x16x32_bf16 v[78:81], v[164:167], v[220:223], 0
	v_mfma_f32_16x16x32_bf16 v[70:73], v[172:175], v[220:223], 0
	v_mfma_f32_16x16x32_bf16 v[122:125], v[168:171], v[200:203], v[122:125]
	v_mfma_f32_16x16x32_bf16 v[118:121], v[176:179], v[200:203], v[118:121]
	v_mfma_f32_16x16x32_bf16 v[110:113], v[168:171], v[208:211], v[110:113]
	v_mfma_f32_16x16x32_bf16 v[102:105], v[176:179], v[208:211], v[102:105]
	v_mfma_f32_16x16x32_bf16 v[94:97], v[168:171], v[216:219], v[94:97]
	v_mfma_f32_16x16x32_bf16 v[86:89], v[176:179], v[216:219], v[86:89]
	v_mfma_f32_16x16x32_bf16 v[78:81], v[168:171], v[224:227], v[78:81]
	v_mfma_f32_16x16x32_bf16 v[70:73], v[176:179], v[224:227], v[70:73]
	s_setprio 0
	s_setprio 1
	v_mfma_f32_16x16x32_bf16 v[126:129], v[180:183], v[196:199], 0
	v_mfma_f32_16x16x32_bf16 v[114:117], v[188:191], v[196:199], 0
	v_mfma_f32_16x16x32_bf16 v[106:109], v[180:183], v[204:207], 0
	v_mfma_f32_16x16x32_bf16 v[98:101], v[188:191], v[204:207], 0
	v_mfma_f32_16x16x32_bf16 v[90:93], v[180:183], v[212:215], 0
	v_mfma_f32_16x16x32_bf16 v[82:85], v[188:191], v[212:215], 0
	v_mfma_f32_16x16x32_bf16 v[74:77], v[180:183], v[220:223], 0
	v_mfma_f32_16x16x32_bf16 v[66:69], v[188:191], v[220:223], 0
	v_mfma_f32_16x16x32_bf16 v[126:129], v[184:187], v[200:203], v[126:129]
	v_mfma_f32_16x16x32_bf16 v[114:117], v[192:195], v[200:203], v[114:117]
	v_mfma_f32_16x16x32_bf16 v[106:109], v[184:187], v[208:211], v[106:109]
	v_mfma_f32_16x16x32_bf16 v[98:101], v[192:195], v[208:211], v[98:101]
	v_mfma_f32_16x16x32_bf16 v[90:93], v[184:187], v[216:219], v[90:93]
	v_mfma_f32_16x16x32_bf16 v[82:85], v[192:195], v[216:219], v[82:85]
	v_mfma_f32_16x16x32_bf16 v[74:77], v[184:187], v[224:227], v[74:77]
	v_mfma_f32_16x16x32_bf16 v[66:69], v[192:195], v[224:227], v[66:69]
	s_barrier
	s_setprio 0
	s_add_u32 s98, s96, 0xb0000
	s_addc_u32 s99, s97, 0
	s_add_i32 s4, s65, s21
	s_mov_b32 m0, s4
	ds_read_b128 v[196:199], v160 offset:16384
	global_load_lds_dwordx4 v132, s[96:97]
	s_add_i32 m0, s4, 0x2000
	s_add_i32 s4, s66, s21
	global_load_lds_dwordx4 v136, s[96:97]
	s_mov_b32 m0, s4
	ds_read_b128 v[200:203], v160 offset:17408
	global_load_lds_dwordx4 v132, s[98:99]
	s_add_i32 m0, s4, 0x2000
	ds_read_b128 v[204:207], v160 offset:18432
	global_load_lds_dwordx4 v136, s[98:99]
	s_mov_b32 m0, s44
	ds_read_b128 v[208:211], v160 offset:19456
	global_load_lds_dwordx4 v130, s[94:95]
	s_mov_b32 m0, s45
	ds_read_b128 v[212:215], v160 offset:20480
	global_load_lds_dwordx4 v134, s[94:95]
	ds_read_b128 v[216:219], v160 offset:21504
	ds_read_b128 v[220:223], v160 offset:22528
	ds_read_b128 v[224:227], v160 offset:23552
	s_waitcnt vmcnt(8)
	s_waitcnt lgkmcnt(0)
	s_setprio 1
	s_barrier
	v_mfma_f32_16x16x32_bf16 v[62:65], v[164:167], v[196:199], 0
	v_mfma_f32_16x16x32_bf16 v[54:57], v[172:175], v[196:199], 0
	v_mfma_f32_16x16x32_bf16 v[46:49], v[164:167], v[204:207], 0
	v_mfma_f32_16x16x32_bf16 v[38:41], v[172:175], v[204:207], 0
	v_mfma_f32_16x16x32_bf16 v[30:33], v[164:167], v[212:215], 0
	v_mfma_f32_16x16x32_bf16 v[22:25], v[172:175], v[212:215], 0
	v_mfma_f32_16x16x32_bf16 v[14:17], v[164:167], v[220:223], 0
	v_mfma_f32_16x16x32_bf16 v[6:9], v[172:175], v[220:223], 0
	v_mfma_f32_16x16x32_bf16 v[62:65], v[168:171], v[200:203], v[62:65]
	v_mfma_f32_16x16x32_bf16 v[54:57], v[176:179], v[200:203], v[54:57]
	v_mfma_f32_16x16x32_bf16 v[46:49], v[168:171], v[208:211], v[46:49]
	v_mfma_f32_16x16x32_bf16 v[38:41], v[176:179], v[208:211], v[38:41]
	v_mfma_f32_16x16x32_bf16 v[30:33], v[168:171], v[216:219], v[30:33]
	v_mfma_f32_16x16x32_bf16 v[22:25], v[176:179], v[216:219], v[22:25]
	v_mfma_f32_16x16x32_bf16 v[14:17], v[168:171], v[224:227], v[14:17]
	v_mfma_f32_16x16x32_bf16 v[6:9], v[176:179], v[224:227], v[6:9]
	s_setprio 0
	s_setprio 1
	v_mfma_f32_16x16x32_bf16 v[58:61], v[180:183], v[196:199], 0
	v_mfma_f32_16x16x32_bf16 v[50:53], v[188:191], v[196:199], 0
	v_mfma_f32_16x16x32_bf16 v[42:45], v[180:183], v[204:207], 0
	v_mfma_f32_16x16x32_bf16 v[34:37], v[188:191], v[204:207], 0
	v_mfma_f32_16x16x32_bf16 v[26:29], v[180:183], v[212:215], 0
	v_mfma_f32_16x16x32_bf16 v[18:21], v[188:191], v[212:215], 0
	v_mfma_f32_16x16x32_bf16 v[10:13], v[180:183], v[220:223], 0
	v_mfma_f32_16x16x32_bf16 v[2:5], v[188:191], v[220:223], 0
	v_mfma_f32_16x16x32_bf16 v[58:61], v[184:187], v[200:203], v[58:61]
	v_mfma_f32_16x16x32_bf16 v[50:53], v[192:195], v[200:203], v[50:53]
	v_mfma_f32_16x16x32_bf16 v[42:45], v[184:187], v[208:211], v[42:45]
	v_mfma_f32_16x16x32_bf16 v[34:37], v[192:195], v[208:211], v[34:37]
	v_mfma_f32_16x16x32_bf16 v[26:29], v[184:187], v[216:219], v[26:29]
	v_mfma_f32_16x16x32_bf16 v[18:21], v[192:195], v[216:219], v[18:21]
	v_mfma_f32_16x16x32_bf16 v[10:13], v[184:187], v[224:227], v[10:13]
	v_mfma_f32_16x16x32_bf16 v[2:5], v[192:195], v[224:227], v[2:5]
	s_barrier
	s_setprio 0
	s_add_u32 s98, s94, 0xb0000
	s_addc_u32 s99, s95, 0
	s_add_i32 s4, 0, 0x18000
	s_add_i32 s25, 0, 0x1c000
	s_mov_b32 m0, s46
	ds_read_b128 v[164:167], v232
	global_load_lds_dwordx4 v130, s[98:99]
	s_mov_b32 m0, s47
	ds_read_b128 v[168:171], v232 offset:1024
	global_load_lds_dwordx4 v134, s[98:99]
	ds_read_b128 v[172:175], v232 offset:2048
	ds_read_b128 v[176:179], v232 offset:3072
	ds_read_b128 v[180:183], v233
	ds_read_b128 v[184:187], v233 offset:1024
	ds_read_b128 v[188:191], v233 offset:2048
	ds_read_b128 v[192:195], v233 offset:3072
	ds_read_b128 v[196:199], v160 offset:32768
	ds_read_b128 v[200:203], v160 offset:33792
	ds_read_b128 v[204:207], v160 offset:34816
	ds_read_b128 v[208:211], v160 offset:35840
	ds_read_b128 v[212:215], v160 offset:36864
	ds_read_b128 v[216:219], v160 offset:37888
	ds_read_b128 v[220:223], v160 offset:38912
	ds_read_b128 v[224:227], v160 offset:39936
	s_waitcnt vmcnt(8)
	s_waitcnt lgkmcnt(0)
	s_setprio 1
	s_barrier
	v_mfma_f32_16x16x32_bf16 v[122:125], v[164:167], v[196:199], v[122:125]
	v_mfma_f32_16x16x32_bf16 v[118:121], v[172:175], v[196:199], v[118:121]
	v_mfma_f32_16x16x32_bf16 v[110:113], v[164:167], v[204:207], v[110:113]
	v_mfma_f32_16x16x32_bf16 v[102:105], v[172:175], v[204:207], v[102:105]
	v_mfma_f32_16x16x32_bf16 v[94:97], v[164:167], v[212:215], v[94:97]
	v_mfma_f32_16x16x32_bf16 v[86:89], v[172:175], v[212:215], v[86:89]
	v_mfma_f32_16x16x32_bf16 v[78:81], v[164:167], v[220:223], v[78:81]
	v_mfma_f32_16x16x32_bf16 v[70:73], v[172:175], v[220:223], v[70:73]
	v_mfma_f32_16x16x32_bf16 v[122:125], v[168:171], v[200:203], v[122:125]
	v_mfma_f32_16x16x32_bf16 v[118:121], v[176:179], v[200:203], v[118:121]
	v_mfma_f32_16x16x32_bf16 v[110:113], v[168:171], v[208:211], v[110:113]
	v_mfma_f32_16x16x32_bf16 v[102:105], v[176:179], v[208:211], v[102:105]
	v_mfma_f32_16x16x32_bf16 v[94:97], v[168:171], v[216:219], v[94:97]
	v_mfma_f32_16x16x32_bf16 v[86:89], v[176:179], v[216:219], v[86:89]
	v_mfma_f32_16x16x32_bf16 v[78:81], v[168:171], v[224:227], v[78:81]
	v_mfma_f32_16x16x32_bf16 v[70:73], v[176:179], v[224:227], v[70:73]
	s_setprio 0
	s_setprio 1
	v_mfma_f32_16x16x32_bf16 v[126:129], v[180:183], v[196:199], v[126:129]
	v_mfma_f32_16x16x32_bf16 v[114:117], v[188:191], v[196:199], v[114:117]
	v_mfma_f32_16x16x32_bf16 v[106:109], v[180:183], v[204:207], v[106:109]
	v_mfma_f32_16x16x32_bf16 v[98:101], v[188:191], v[204:207], v[98:101]
	v_mfma_f32_16x16x32_bf16 v[90:93], v[180:183], v[212:215], v[90:93]
	v_mfma_f32_16x16x32_bf16 v[82:85], v[188:191], v[212:215], v[82:85]
	v_mfma_f32_16x16x32_bf16 v[74:77], v[180:183], v[220:223], v[74:77]
	v_mfma_f32_16x16x32_bf16 v[66:69], v[188:191], v[220:223], v[66:69]
	v_mfma_f32_16x16x32_bf16 v[126:129], v[184:187], v[200:203], v[126:129]
	v_mfma_f32_16x16x32_bf16 v[114:117], v[192:195], v[200:203], v[114:117]
	v_mfma_f32_16x16x32_bf16 v[106:109], v[184:187], v[208:211], v[106:109]
	v_mfma_f32_16x16x32_bf16 v[98:101], v[192:195], v[208:211], v[98:101]
	v_mfma_f32_16x16x32_bf16 v[90:93], v[184:187], v[216:219], v[90:93]
	v_mfma_f32_16x16x32_bf16 v[82:85], v[192:195], v[216:219], v[82:85]
	v_mfma_f32_16x16x32_bf16 v[74:77], v[184:187], v[224:227], v[74:77]
	v_mfma_f32_16x16x32_bf16 v[66:69], v[192:195], v[224:227], v[66:69]
	s_barrier
	s_setprio 0
	s_add_u32 s96, s96, 0x80
	s_addc_u32 s97, s97, 0
	s_add_u32 s98, s96, 0xb0000
	s_addc_u32 s99, s97, 0
	s_add_u32 s94, s94, 0x80
	s_addc_u32 s95, s95, 0
	s_add_i32 s4, s4, s21
	s_mov_b32 m0, s4
	ds_read_b128 v[196:199], v160 offset:49152
	global_load_lds_dwordx4 v132, s[96:97]
	s_add_i32 m0, s4, 0x2000
	s_add_i32 s4, s25, s21
	global_load_lds_dwordx4 v136, s[96:97]
	s_mov_b32 m0, s4
	ds_read_b128 v[200:203], v160 offset:50176
	global_load_lds_dwordx4 v132, s[98:99]
	s_add_i32 m0, s4, 0x2000
	ds_read_b128 v[204:207], v160 offset:51200
	global_load_lds_dwordx4 v136, s[98:99]
	s_mov_b32 m0, s57
	ds_read_b128 v[208:211], v160 offset:52224
	global_load_lds_dwordx4 v130, s[94:95]
	s_mov_b32 m0, s58
	ds_read_b128 v[212:215], v160 offset:53248
	global_load_lds_dwordx4 v134, s[94:95]
	ds_read_b128 v[216:219], v160 offset:54272
	ds_read_b128 v[220:223], v160 offset:55296
	ds_read_b128 v[224:227], v160 offset:56320
	s_waitcnt vmcnt(8)
	s_waitcnt lgkmcnt(0)
	s_setprio 1
	s_barrier
	v_mfma_f32_16x16x32_bf16 v[62:65], v[164:167], v[196:199], v[62:65]
	v_mfma_f32_16x16x32_bf16 v[54:57], v[172:175], v[196:199], v[54:57]
	v_mfma_f32_16x16x32_bf16 v[46:49], v[164:167], v[204:207], v[46:49]
	v_mfma_f32_16x16x32_bf16 v[38:41], v[172:175], v[204:207], v[38:41]
	v_mfma_f32_16x16x32_bf16 v[30:33], v[164:167], v[212:215], v[30:33]
	v_mfma_f32_16x16x32_bf16 v[22:25], v[172:175], v[212:215], v[22:25]
	v_mfma_f32_16x16x32_bf16 v[14:17], v[164:167], v[220:223], v[14:17]
	v_mfma_f32_16x16x32_bf16 v[6:9], v[172:175], v[220:223], v[6:9]
	v_mfma_f32_16x16x32_bf16 v[62:65], v[168:171], v[200:203], v[62:65]
	v_mfma_f32_16x16x32_bf16 v[54:57], v[176:179], v[200:203], v[54:57]
	v_mfma_f32_16x16x32_bf16 v[46:49], v[168:171], v[208:211], v[46:49]
	v_mfma_f32_16x16x32_bf16 v[38:41], v[176:179], v[208:211], v[38:41]
	v_mfma_f32_16x16x32_bf16 v[30:33], v[168:171], v[216:219], v[30:33]
	v_mfma_f32_16x16x32_bf16 v[22:25], v[176:179], v[216:219], v[22:25]
	v_mfma_f32_16x16x32_bf16 v[14:17], v[168:171], v[224:227], v[14:17]
	v_mfma_f32_16x16x32_bf16 v[6:9], v[176:179], v[224:227], v[6:9]
	s_setprio 0
	s_setprio 1
	v_mfma_f32_16x16x32_bf16 v[58:61], v[180:183], v[196:199], v[58:61]
	v_mfma_f32_16x16x32_bf16 v[50:53], v[188:191], v[196:199], v[50:53]
	v_mfma_f32_16x16x32_bf16 v[42:45], v[180:183], v[204:207], v[42:45]
	v_mfma_f32_16x16x32_bf16 v[34:37], v[188:191], v[204:207], v[34:37]
	v_mfma_f32_16x16x32_bf16 v[26:29], v[180:183], v[212:215], v[26:29]
	v_mfma_f32_16x16x32_bf16 v[18:21], v[188:191], v[212:215], v[18:21]
	v_mfma_f32_16x16x32_bf16 v[10:13], v[180:183], v[220:223], v[10:13]
	v_mfma_f32_16x16x32_bf16 v[2:5], v[188:191], v[220:223], v[2:5]
	v_mfma_f32_16x16x32_bf16 v[58:61], v[184:187], v[200:203], v[58:61]
	v_mfma_f32_16x16x32_bf16 v[50:53], v[192:195], v[200:203], v[50:53]
	v_mfma_f32_16x16x32_bf16 v[42:45], v[184:187], v[208:211], v[42:45]
	v_mfma_f32_16x16x32_bf16 v[34:37], v[192:195], v[208:211], v[34:37]
	v_mfma_f32_16x16x32_bf16 v[26:29], v[184:187], v[216:219], v[26:29]
	v_mfma_f32_16x16x32_bf16 v[18:21], v[192:195], v[216:219], v[18:21]
	v_mfma_f32_16x16x32_bf16 v[10:13], v[184:187], v[224:227], v[10:13]
	v_mfma_f32_16x16x32_bf16 v[2:5], v[192:195], v[224:227], v[2:5]
	s_barrier
	s_setprio 0
	s_mov_b32 s4, s5
	s_add_u32 s88, s88, 0x100
	s_addc_u32 s89, s89, 0
	s_add_u32 s86, s86, 0x100
	s_addc_u32 s87, s87, 0
	s_cmp_ge_i32 s5, s101
	s_cbranch_scc1 .Lmy_kexit_11
.LBB0_2075:
	s_add_u32 s98, s86, 0x100
	s_addc_u32 s99, s87, 0
	s_cmp_eq_u32 s4, s100
	s_cselect_b64 s[94:95], s[90:91], s[98:99]
	s_cselect_b64 s[96:97], s[92:93], s[88:89]
	s_add_i32 s5, s4, 2
	s_add_i32 m0, s44, 0xc000
	ds_read_b128 v[164:167], v230
	global_load_lds_dwordx4 v144, s[86:87]
	s_add_i32 m0, s44, 0xe000
	ds_read_b128 v[168:171], v230 offset:1024
	global_load_lds_dwordx4 v142, s[86:87]
	ds_read_b128 v[172:175], v230 offset:2048
	ds_read_b128 v[176:179], v230 offset:3072
	ds_read_b128 v[180:183], v231
	ds_read_b128 v[184:187], v231 offset:1024
	ds_read_b128 v[188:191], v231 offset:2048
	ds_read_b128 v[192:195], v231 offset:3072
	ds_read_b128 v[196:199], v160
	ds_read_b128 v[200:203], v160 offset:1024
	ds_read_b128 v[204:207], v160 offset:2048
	ds_read_b128 v[208:211], v160 offset:3072
	ds_read_b128 v[212:215], v160 offset:4096
	ds_read_b128 v[216:219], v160 offset:5120
	ds_read_b128 v[220:223], v160 offset:6144
	ds_read_b128 v[224:227], v160 offset:7168
	s_waitcnt vmcnt(8)
	s_waitcnt lgkmcnt(0)
	s_setprio 1
	s_barrier
	v_mfma_f32_16x16x32_bf16 v[122:125], v[164:167], v[196:199], v[122:125]
	v_mfma_f32_16x16x32_bf16 v[118:121], v[172:175], v[196:199], v[118:121]
	v_mfma_f32_16x16x32_bf16 v[110:113], v[164:167], v[204:207], v[110:113]
	v_mfma_f32_16x16x32_bf16 v[102:105], v[172:175], v[204:207], v[102:105]
	v_mfma_f32_16x16x32_bf16 v[94:97], v[164:167], v[212:215], v[94:97]
	v_mfma_f32_16x16x32_bf16 v[86:89], v[172:175], v[212:215], v[86:89]
	v_mfma_f32_16x16x32_bf16 v[78:81], v[164:167], v[220:223], v[78:81]
	v_mfma_f32_16x16x32_bf16 v[70:73], v[172:175], v[220:223], v[70:73]
	v_mfma_f32_16x16x32_bf16 v[122:125], v[168:171], v[200:203], v[122:125]
	v_mfma_f32_16x16x32_bf16 v[118:121], v[176:179], v[200:203], v[118:121]
	v_mfma_f32_16x16x32_bf16 v[110:113], v[168:171], v[208:211], v[110:113]
	v_mfma_f32_16x16x32_bf16 v[102:105], v[176:179], v[208:211], v[102:105]
	v_mfma_f32_16x16x32_bf16 v[94:97], v[168:171], v[216:219], v[94:97]
	v_mfma_f32_16x16x32_bf16 v[86:89], v[176:179], v[216:219], v[86:89]
	v_mfma_f32_16x16x32_bf16 v[78:81], v[168:171], v[224:227], v[78:81]
	v_mfma_f32_16x16x32_bf16 v[70:73], v[176:179], v[224:227], v[70:73]
	s_setprio 0
	s_setprio 1
	v_mfma_f32_16x16x32_bf16 v[126:129], v[180:183], v[196:199], v[126:129]
	v_mfma_f32_16x16x32_bf16 v[114:117], v[188:191], v[196:199], v[114:117]
	v_mfma_f32_16x16x32_bf16 v[106:109], v[180:183], v[204:207], v[106:109]
	v_mfma_f32_16x16x32_bf16 v[98:101], v[188:191], v[204:207], v[98:101]
	v_mfma_f32_16x16x32_bf16 v[90:93], v[180:183], v[212:215], v[90:93]
	v_mfma_f32_16x16x32_bf16 v[82:85], v[188:191], v[212:215], v[82:85]
	v_mfma_f32_16x16x32_bf16 v[74:77], v[180:183], v[220:223], v[74:77]
	v_mfma_f32_16x16x32_bf16 v[66:69], v[188:191], v[220:223], v[66:69]
	v_mfma_f32_16x16x32_bf16 v[126:129], v[184:187], v[200:203], v[126:129]
	v_mfma_f32_16x16x32_bf16 v[114:117], v[192:195], v[200:203], v[114:117]
	v_mfma_f32_16x16x32_bf16 v[106:109], v[184:187], v[208:211], v[106:109]
	v_mfma_f32_16x16x32_bf16 v[98:101], v[192:195], v[208:211], v[98:101]
	v_mfma_f32_16x16x32_bf16 v[90:93], v[184:187], v[216:219], v[90:93]
	v_mfma_f32_16x16x32_bf16 v[82:85], v[192:195], v[216:219], v[82:85]
	v_mfma_f32_16x16x32_bf16 v[74:77], v[184:187], v[224:227], v[74:77]
	v_mfma_f32_16x16x32_bf16 v[66:69], v[192:195], v[224:227], v[66:69]
	s_barrier
	s_setprio 0
	s_add_u32 s98, s96, 0xb0000
	s_addc_u32 s99, s97, 0
	s_add_i32 s4, s65, s21
	s_mov_b32 m0, s4
	ds_read_b128 v[196:199], v160 offset:16384
	global_load_lds_dwordx4 v132, s[96:97]
	s_add_i32 m0, s4, 0x2000
	s_add_i32 s4, s66, s21
	global_load_lds_dwordx4 v136, s[96:97]
	s_mov_b32 m0, s4
	ds_read_b128 v[200:203], v160 offset:17408
	global_load_lds_dwordx4 v132, s[98:99]
	s_add_i32 m0, s4, 0x2000
	ds_read_b128 v[204:207], v160 offset:18432
	global_load_lds_dwordx4 v136, s[98:99]
	s_mov_b32 m0, s44
	ds_read_b128 v[208:211], v160 offset:19456
	global_load_lds_dwordx4 v130, s[94:95]
	s_mov_b32 m0, s45
	ds_read_b128 v[212:215], v160 offset:20480
	global_load_lds_dwordx4 v134, s[94:95]
	ds_read_b128 v[216:219], v160 offset:21504
	ds_read_b128 v[220:223], v160 offset:22528
	ds_read_b128 v[224:227], v160 offset:23552
	s_waitcnt vmcnt(8)
	s_waitcnt lgkmcnt(0)
	s_setprio 1
	s_barrier
	v_mfma_f32_16x16x32_bf16 v[62:65], v[164:167], v[196:199], v[62:65]
	v_mfma_f32_16x16x32_bf16 v[54:57], v[172:175], v[196:199], v[54:57]
	v_mfma_f32_16x16x32_bf16 v[46:49], v[164:167], v[204:207], v[46:49]
	v_mfma_f32_16x16x32_bf16 v[38:41], v[172:175], v[204:207], v[38:41]
	v_mfma_f32_16x16x32_bf16 v[30:33], v[164:167], v[212:215], v[30:33]
	v_mfma_f32_16x16x32_bf16 v[22:25], v[172:175], v[212:215], v[22:25]
	v_mfma_f32_16x16x32_bf16 v[14:17], v[164:167], v[220:223], v[14:17]
	v_mfma_f32_16x16x32_bf16 v[6:9], v[172:175], v[220:223], v[6:9]
	v_mfma_f32_16x16x32_bf16 v[62:65], v[168:171], v[200:203], v[62:65]
	v_mfma_f32_16x16x32_bf16 v[54:57], v[176:179], v[200:203], v[54:57]
	v_mfma_f32_16x16x32_bf16 v[46:49], v[168:171], v[208:211], v[46:49]
	v_mfma_f32_16x16x32_bf16 v[38:41], v[176:179], v[208:211], v[38:41]
	v_mfma_f32_16x16x32_bf16 v[30:33], v[168:171], v[216:219], v[30:33]
	v_mfma_f32_16x16x32_bf16 v[22:25], v[176:179], v[216:219], v[22:25]
	v_mfma_f32_16x16x32_bf16 v[14:17], v[168:171], v[224:227], v[14:17]
	v_mfma_f32_16x16x32_bf16 v[6:9], v[176:179], v[224:227], v[6:9]
	s_setprio 0
	s_setprio 1
	v_mfma_f32_16x16x32_bf16 v[58:61], v[180:183], v[196:199], v[58:61]
	v_mfma_f32_16x16x32_bf16 v[50:53], v[188:191], v[196:199], v[50:53]
	v_mfma_f32_16x16x32_bf16 v[42:45], v[180:183], v[204:207], v[42:45]
	v_mfma_f32_16x16x32_bf16 v[34:37], v[188:191], v[204:207], v[34:37]
	v_mfma_f32_16x16x32_bf16 v[26:29], v[180:183], v[212:215], v[26:29]
	v_mfma_f32_16x16x32_bf16 v[18:21], v[188:191], v[212:215], v[18:21]
	v_mfma_f32_16x16x32_bf16 v[10:13], v[180:183], v[220:223], v[10:13]
	v_mfma_f32_16x16x32_bf16 v[2:5], v[188:191], v[220:223], v[2:5]
	v_mfma_f32_16x16x32_bf16 v[58:61], v[184:187], v[200:203], v[58:61]
	v_mfma_f32_16x16x32_bf16 v[50:53], v[192:195], v[200:203], v[50:53]
	v_mfma_f32_16x16x32_bf16 v[42:45], v[184:187], v[208:211], v[42:45]
	v_mfma_f32_16x16x32_bf16 v[34:37], v[192:195], v[208:211], v[34:37]
	v_mfma_f32_16x16x32_bf16 v[26:29], v[184:187], v[216:219], v[26:29]
	v_mfma_f32_16x16x32_bf16 v[18:21], v[192:195], v[216:219], v[18:21]
	v_mfma_f32_16x16x32_bf16 v[10:13], v[184:187], v[224:227], v[10:13]
	v_mfma_f32_16x16x32_bf16 v[2:5], v[192:195], v[224:227], v[2:5]
	s_barrier
	s_setprio 0
	s_add_u32 s98, s94, 0xb0000
	s_addc_u32 s99, s95, 0
	s_add_i32 s4, 0, 0x18000
	s_add_i32 s25, 0, 0x1c000
	s_mov_b32 m0, s46
	ds_read_b128 v[164:167], v232
	global_load_lds_dwordx4 v130, s[98:99]
	s_mov_b32 m0, s47
	ds_read_b128 v[168:171], v232 offset:1024
	global_load_lds_dwordx4 v134, s[98:99]
	ds_read_b128 v[172:175], v232 offset:2048
	ds_read_b128 v[176:179], v232 offset:3072
	ds_read_b128 v[180:183], v233
	ds_read_b128 v[184:187], v233 offset:1024
	ds_read_b128 v[188:191], v233 offset:2048
	ds_read_b128 v[192:195], v233 offset:3072
	ds_read_b128 v[196:199], v160 offset:32768
	ds_read_b128 v[200:203], v160 offset:33792
	ds_read_b128 v[204:207], v160 offset:34816
	ds_read_b128 v[208:211], v160 offset:35840
	ds_read_b128 v[212:215], v160 offset:36864
	ds_read_b128 v[216:219], v160 offset:37888
	ds_read_b128 v[220:223], v160 offset:38912
	ds_read_b128 v[224:227], v160 offset:39936
	s_waitcnt vmcnt(8)
	s_waitcnt lgkmcnt(0)
	s_setprio 1
	s_barrier
	v_mfma_f32_16x16x32_bf16 v[122:125], v[164:167], v[196:199], v[122:125]
	v_mfma_f32_16x16x32_bf16 v[118:121], v[172:175], v[196:199], v[118:121]
	v_mfma_f32_16x16x32_bf16 v[110:113], v[164:167], v[204:207], v[110:113]
	v_mfma_f32_16x16x32_bf16 v[102:105], v[172:175], v[204:207], v[102:105]
	v_mfma_f32_16x16x32_bf16 v[94:97], v[164:167], v[212:215], v[94:97]
	v_mfma_f32_16x16x32_bf16 v[86:89], v[172:175], v[212:215], v[86:89]
	v_mfma_f32_16x16x32_bf16 v[78:81], v[164:167], v[220:223], v[78:81]
	v_mfma_f32_16x16x32_bf16 v[70:73], v[172:175], v[220:223], v[70:73]
	v_mfma_f32_16x16x32_bf16 v[122:125], v[168:171], v[200:203], v[122:125]
	v_mfma_f32_16x16x32_bf16 v[118:121], v[176:179], v[200:203], v[118:121]
	v_mfma_f32_16x16x32_bf16 v[110:113], v[168:171], v[208:211], v[110:113]
	v_mfma_f32_16x16x32_bf16 v[102:105], v[176:179], v[208:211], v[102:105]
	v_mfma_f32_16x16x32_bf16 v[94:97], v[168:171], v[216:219], v[94:97]
	v_mfma_f32_16x16x32_bf16 v[86:89], v[176:179], v[216:219], v[86:89]
	v_mfma_f32_16x16x32_bf16 v[78:81], v[168:171], v[224:227], v[78:81]
	v_mfma_f32_16x16x32_bf16 v[70:73], v[176:179], v[224:227], v[70:73]
	s_setprio 0
	s_setprio 1
	v_mfma_f32_16x16x32_bf16 v[126:129], v[180:183], v[196:199], v[126:129]
	v_mfma_f32_16x16x32_bf16 v[114:117], v[188:191], v[196:199], v[114:117]
	v_mfma_f32_16x16x32_bf16 v[106:109], v[180:183], v[204:207], v[106:109]
	v_mfma_f32_16x16x32_bf16 v[98:101], v[188:191], v[204:207], v[98:101]
	v_mfma_f32_16x16x32_bf16 v[90:93], v[180:183], v[212:215], v[90:93]
	v_mfma_f32_16x16x32_bf16 v[82:85], v[188:191], v[212:215], v[82:85]
	v_mfma_f32_16x16x32_bf16 v[74:77], v[180:183], v[220:223], v[74:77]
	v_mfma_f32_16x16x32_bf16 v[66:69], v[188:191], v[220:223], v[66:69]
	v_mfma_f32_16x16x32_bf16 v[126:129], v[184:187], v[200:203], v[126:129]
	v_mfma_f32_16x16x32_bf16 v[114:117], v[192:195], v[200:203], v[114:117]
	v_mfma_f32_16x16x32_bf16 v[106:109], v[184:187], v[208:211], v[106:109]
	v_mfma_f32_16x16x32_bf16 v[98:101], v[192:195], v[208:211], v[98:101]
	v_mfma_f32_16x16x32_bf16 v[90:93], v[184:187], v[216:219], v[90:93]
	v_mfma_f32_16x16x32_bf16 v[82:85], v[192:195], v[216:219], v[82:85]
	v_mfma_f32_16x16x32_bf16 v[74:77], v[184:187], v[224:227], v[74:77]
	v_mfma_f32_16x16x32_bf16 v[66:69], v[192:195], v[224:227], v[66:69]
	s_barrier
	s_setprio 0
	s_add_u32 s96, s96, 0x80
	s_addc_u32 s97, s97, 0
	s_add_u32 s98, s96, 0xb0000
	s_addc_u32 s99, s97, 0
	s_add_u32 s94, s94, 0x80
	s_addc_u32 s95, s95, 0
	s_add_i32 s4, s4, s21
	s_mov_b32 m0, s4
	ds_read_b128 v[196:199], v160 offset:49152
	global_load_lds_dwordx4 v132, s[96:97]
	s_add_i32 m0, s4, 0x2000
	s_add_i32 s4, s25, s21
	global_load_lds_dwordx4 v136, s[96:97]
	s_mov_b32 m0, s4
	ds_read_b128 v[200:203], v160 offset:50176
	global_load_lds_dwordx4 v132, s[98:99]
	s_add_i32 m0, s4, 0x2000
	ds_read_b128 v[204:207], v160 offset:51200
	global_load_lds_dwordx4 v136, s[98:99]
	s_mov_b32 m0, s57
	ds_read_b128 v[208:211], v160 offset:52224
	global_load_lds_dwordx4 v130, s[94:95]
	s_mov_b32 m0, s58
	ds_read_b128 v[212:215], v160 offset:53248
	global_load_lds_dwordx4 v134, s[94:95]
	ds_read_b128 v[216:219], v160 offset:54272
	ds_read_b128 v[220:223], v160 offset:55296
	ds_read_b128 v[224:227], v160 offset:56320
	s_waitcnt vmcnt(8)
	s_waitcnt lgkmcnt(0)
	s_setprio 1
	s_barrier
	v_mfma_f32_16x16x32_bf16 v[62:65], v[164:167], v[196:199], v[62:65]
	v_mfma_f32_16x16x32_bf16 v[54:57], v[172:175], v[196:199], v[54:57]
	v_mfma_f32_16x16x32_bf16 v[46:49], v[164:167], v[204:207], v[46:49]
	v_mfma_f32_16x16x32_bf16 v[38:41], v[172:175], v[204:207], v[38:41]
	v_mfma_f32_16x16x32_bf16 v[30:33], v[164:167], v[212:215], v[30:33]
	v_mfma_f32_16x16x32_bf16 v[22:25], v[172:175], v[212:215], v[22:25]
	v_mfma_f32_16x16x32_bf16 v[14:17], v[164:167], v[220:223], v[14:17]
	v_mfma_f32_16x16x32_bf16 v[6:9], v[172:175], v[220:223], v[6:9]
	v_mfma_f32_16x16x32_bf16 v[62:65], v[168:171], v[200:203], v[62:65]
	v_mfma_f32_16x16x32_bf16 v[54:57], v[176:179], v[200:203], v[54:57]
	v_mfma_f32_16x16x32_bf16 v[46:49], v[168:171], v[208:211], v[46:49]
	v_mfma_f32_16x16x32_bf16 v[38:41], v[176:179], v[208:211], v[38:41]
	v_mfma_f32_16x16x32_bf16 v[30:33], v[168:171], v[216:219], v[30:33]
	v_mfma_f32_16x16x32_bf16 v[22:25], v[176:179], v[216:219], v[22:25]
	v_mfma_f32_16x16x32_bf16 v[14:17], v[168:171], v[224:227], v[14:17]
	v_mfma_f32_16x16x32_bf16 v[6:9], v[176:179], v[224:227], v[6:9]
	s_setprio 0
	s_setprio 1
	v_mfma_f32_16x16x32_bf16 v[58:61], v[180:183], v[196:199], v[58:61]
	v_mfma_f32_16x16x32_bf16 v[50:53], v[188:191], v[196:199], v[50:53]
	v_mfma_f32_16x16x32_bf16 v[42:45], v[180:183], v[204:207], v[42:45]
	v_mfma_f32_16x16x32_bf16 v[34:37], v[188:191], v[204:207], v[34:37]
	v_mfma_f32_16x16x32_bf16 v[26:29], v[180:183], v[212:215], v[26:29]
	v_mfma_f32_16x16x32_bf16 v[18:21], v[188:191], v[212:215], v[18:21]
	v_mfma_f32_16x16x32_bf16 v[10:13], v[180:183], v[220:223], v[10:13]
	v_mfma_f32_16x16x32_bf16 v[2:5], v[188:191], v[220:223], v[2:5]
	v_mfma_f32_16x16x32_bf16 v[58:61], v[184:187], v[200:203], v[58:61]
	v_mfma_f32_16x16x32_bf16 v[50:53], v[192:195], v[200:203], v[50:53]
	v_mfma_f32_16x16x32_bf16 v[42:45], v[184:187], v[208:211], v[42:45]
	v_mfma_f32_16x16x32_bf16 v[34:37], v[192:195], v[208:211], v[34:37]
	v_mfma_f32_16x16x32_bf16 v[26:29], v[184:187], v[216:219], v[26:29]
	v_mfma_f32_16x16x32_bf16 v[18:21], v[192:195], v[216:219], v[18:21]
	v_mfma_f32_16x16x32_bf16 v[10:13], v[184:187], v[224:227], v[10:13]
	v_mfma_f32_16x16x32_bf16 v[2:5], v[192:195], v[224:227], v[2:5]
	s_barrier
	s_setprio 0
	s_mov_b32 s4, s5
	s_add_u32 s88, s88, 0x100
	s_addc_u32 s89, s89, 0
	s_add_u32 s86, s86, 0x100
	s_addc_u32 s87, s87, 0
	s_cmp_ge_i32 s5, s101
	s_cbranch_scc0 .LBB0_2075
